# speedup vs baseline: 1.1900x; 1.0571x over previous
.LBB0_241:
	ds_read_b128 v[156:159], v150
	ds_read_b128 v[160:163], v150 offset:1024
	ds_read_b128 v[164:167], v150 offset:2048
	ds_read_b128 v[168:171], v150 offset:3072
	s_add_u32 s42, s40, 0xfffc0080
	s_addc_u32 s43, s41, -1
	s_cmp_eq_u32 s70, 12
	s_cselect_b32 s45, s7, s43
	s_cselect_b32 s44, s31, s42
	s_cselect_b32 s43, s29, s69
	s_cselect_b32 s42, s39, s68
	s_mov_b32 m0, s63
	v_lshl_add_u64 v[144:145], s[40:41], 0, v[140:141]
	ds_read_b128 v[172:175], v148
	ds_read_b128 v[176:179], v148 offset:1024
	ds_read_b128 v[180:183], v148 offset:2048
	ds_read_b128 v[184:187], v148 offset:3072
	ds_read_b128 v[188:191], v148 offset:4096
	ds_read_b128 v[192:195], v148 offset:5120
	ds_read_b128 v[196:199], v148 offset:6144
	ds_read_b128 v[200:203], v148 offset:7168
	global_load_lds_dwordx4 v[144:145], off
	v_lshl_add_u64 v[144:145], s[40:41], 0, v[142:143]
	s_mov_b32 m0, s64
	s_nop 0
	global_load_lds_dwordx4 v[144:145], off
	s_waitcnt lgkmcnt(8)
	s_barrier
	s_waitcnt lgkmcnt(0)
	s_setprio 1
	s_waitcnt lgkmcnt(0)
	v_mfma_f32_16x16x32_bf16 v[124:127], v[156:159], v[172:175], v[124:127]
	v_mfma_f32_16x16x32_bf16 v[120:123], v[164:167], v[172:175], v[120:123]
	v_mfma_f32_16x16x32_bf16 v[112:115], v[156:159], v[180:183], v[112:115]
	v_mfma_f32_16x16x32_bf16 v[104:107], v[164:167], v[180:183], v[104:107]
	v_mfma_f32_16x16x32_bf16 v[96:99], v[156:159], v[188:191], v[96:99]
	v_mfma_f32_16x16x32_bf16 v[88:91], v[164:167], v[188:191], v[88:91]
	v_mfma_f32_16x16x32_bf16 v[76:79], v[156:159], v[196:199], v[76:79]
	v_mfma_f32_16x16x32_bf16 v[72:75], v[164:167], v[196:199], v[72:75]
	v_mfma_f32_16x16x32_bf16 v[124:127], v[160:163], v[176:179], v[124:127]
	v_mfma_f32_16x16x32_bf16 v[120:123], v[168:171], v[176:179], v[120:123]
	v_mfma_f32_16x16x32_bf16 v[112:115], v[160:163], v[184:187], v[112:115]
	v_mfma_f32_16x16x32_bf16 v[104:107], v[168:171], v[184:187], v[104:107]
	v_mfma_f32_16x16x32_bf16 v[96:99], v[160:163], v[192:195], v[96:99]
	v_mfma_f32_16x16x32_bf16 v[88:91], v[168:171], v[192:195], v[88:91]
	v_mfma_f32_16x16x32_bf16 v[76:79], v[160:163], v[200:203], v[76:79]
	v_mfma_f32_16x16x32_bf16 v[72:75], v[168:171], v[200:203], v[72:75]
	s_setprio 0
	s_barrier
	s_mov_b32 m0, s47
	v_lshl_add_u64 v[144:145], s[42:43], 0, v[132:133]
	ds_read_b128 v[204:207], v151
	ds_read_b128 v[208:211], v151 offset:1024
	ds_read_b128 v[212:215], v151 offset:2048
	ds_read_b128 v[216:219], v151 offset:3072
	global_load_lds_dwordx4 v[144:145], off
	v_lshl_add_u64 v[220:221], s[42:43], 0, v[128:129]
	s_mov_b32 m0, s48
	s_nop 0
	global_load_lds_dwordx4 v[220:221], off
	s_barrier
	s_waitcnt lgkmcnt(0)
	s_setprio 1
	s_waitcnt lgkmcnt(0)
	v_mfma_f32_16x16x32_bf16 v[116:119], v[204:207], v[172:175], v[116:119]
	v_mfma_f32_16x16x32_bf16 v[108:111], v[212:215], v[172:175], v[108:111]
	v_mfma_f32_16x16x32_bf16 v[100:103], v[204:207], v[180:183], v[100:103]
	v_mfma_f32_16x16x32_bf16 v[92:95], v[212:215], v[180:183], v[92:95]
	v_mfma_f32_16x16x32_bf16 v[84:87], v[204:207], v[188:191], v[84:87]
	v_mfma_f32_16x16x32_bf16 v[80:83], v[212:215], v[188:191], v[80:83]
	v_mfma_f32_16x16x32_bf16 v[68:71], v[204:207], v[196:199], v[68:71]
	v_mfma_f32_16x16x32_bf16 v[64:67], v[212:215], v[196:199], v[64:67]
	v_mfma_f32_16x16x32_bf16 v[116:119], v[208:211], v[176:179], v[116:119]
	v_mfma_f32_16x16x32_bf16 v[108:111], v[216:219], v[176:179], v[108:111]
	v_mfma_f32_16x16x32_bf16 v[100:103], v[208:211], v[184:187], v[100:103]
	v_mfma_f32_16x16x32_bf16 v[92:95], v[216:219], v[184:187], v[92:95]
	v_mfma_f32_16x16x32_bf16 v[84:87], v[208:211], v[192:195], v[84:87]
	v_mfma_f32_16x16x32_bf16 v[80:83], v[216:219], v[192:195], v[80:83]
	v_mfma_f32_16x16x32_bf16 v[68:71], v[208:211], v[200:203], v[68:71]
	v_mfma_f32_16x16x32_bf16 v[64:67], v[216:219], v[200:203], v[64:67]
	s_setprio 0
	s_mov_b32 m0, s46
	v_lshl_add_u64 v[222:223], s[44:45], 0, v[134:135]
	s_barrier
	ds_read_b128 v[172:175], v148 offset:16384
	ds_read_b128 v[176:179], v148 offset:17408
	ds_read_b128 v[180:183], v148 offset:18432
	ds_read_b128 v[184:187], v148 offset:19456
	ds_read_b128 v[188:191], v148 offset:20480
	ds_read_b128 v[192:195], v148 offset:21504
	ds_read_b128 v[196:199], v148 offset:22528
	ds_read_b128 v[200:203], v148 offset:23552
	global_load_lds_dwordx4 v[222:223], off
	v_lshl_add_u64 v[224:225], s[44:45], 0, v[130:131]
	s_mov_b32 m0, s49
	s_nop 0
	global_load_lds_dwordx4 v[224:225], off
	s_barrier
	s_waitcnt lgkmcnt(0)
	s_setprio 1
	s_waitcnt lgkmcnt(0)
	v_mfma_f32_16x16x32_bf16 v[60:63], v[156:159], v[172:175], v[60:63]
	v_mfma_f32_16x16x32_bf16 v[56:59], v[164:167], v[172:175], v[56:59]
	v_mfma_f32_16x16x32_bf16 v[48:51], v[156:159], v[180:183], v[48:51]
	v_mfma_f32_16x16x32_bf16 v[40:43], v[164:167], v[180:183], v[40:43]
	v_mfma_f32_16x16x32_bf16 v[32:35], v[156:159], v[188:191], v[32:35]
	v_mfma_f32_16x16x32_bf16 v[24:27], v[164:167], v[188:191], v[24:27]
	v_mfma_f32_16x16x32_bf16 v[12:15], v[156:159], v[196:199], v[12:15]
	v_mfma_f32_16x16x32_bf16 v[8:11], v[164:167], v[196:199], v[8:11]
	v_mfma_f32_16x16x32_bf16 v[60:63], v[160:163], v[176:179], v[60:63]
	v_mfma_f32_16x16x32_bf16 v[56:59], v[168:171], v[176:179], v[56:59]
	v_mfma_f32_16x16x32_bf16 v[48:51], v[160:163], v[184:187], v[48:51]
	v_mfma_f32_16x16x32_bf16 v[40:43], v[168:171], v[184:187], v[40:43]
	v_mfma_f32_16x16x32_bf16 v[32:35], v[160:163], v[192:195], v[32:35]
	v_mfma_f32_16x16x32_bf16 v[24:27], v[168:171], v[192:195], v[24:27]
	v_mfma_f32_16x16x32_bf16 v[12:15], v[160:163], v[200:203], v[12:15]
	v_mfma_f32_16x16x32_bf16 v[8:11], v[168:171], v[200:203], v[8:11]
	s_setprio 0
	s_barrier
	s_add_u32 s72, s42, 0x40000
	s_addc_u32 s73, s43, 0
	s_mov_b32 m0, s50
	v_lshl_add_u64 v[156:157], s[72:73], 0, v[132:133]
	global_load_lds_dwordx4 v[156:157], off
	v_lshl_add_u64 v[156:157], s[72:73], 0, v[128:129]
	s_mov_b32 m0, s51
	s_nop 0
	global_load_lds_dwordx4 v[156:157], off
	s_waitcnt vmcnt(6)
	s_barrier
	s_setprio 1
	v_mfma_f32_16x16x32_bf16 v[52:55], v[204:207], v[172:175], v[52:55]
	v_mfma_f32_16x16x32_bf16 v[44:47], v[212:215], v[172:175], v[44:47]
	v_mfma_f32_16x16x32_bf16 v[36:39], v[204:207], v[180:183], v[36:39]
	v_mfma_f32_16x16x32_bf16 v[28:31], v[212:215], v[180:183], v[28:31]
	v_mfma_f32_16x16x32_bf16 v[20:23], v[204:207], v[188:191], v[20:23]
	v_mfma_f32_16x16x32_bf16 v[16:19], v[212:215], v[188:191], v[16:19]
	v_mfma_f32_16x16x32_bf16 v[4:7], v[204:207], v[196:199], v[4:7]
	v_mfma_f32_16x16x32_bf16 v[0:3], v[212:215], v[196:199], v[0:3]
	v_mfma_f32_16x16x32_bf16 v[52:55], v[208:211], v[176:179], v[52:55]
	v_mfma_f32_16x16x32_bf16 v[44:47], v[216:219], v[176:179], v[44:47]
	v_mfma_f32_16x16x32_bf16 v[36:39], v[208:211], v[184:187], v[36:39]
	v_mfma_f32_16x16x32_bf16 v[28:31], v[216:219], v[184:187], v[28:31]
	v_mfma_f32_16x16x32_bf16 v[20:23], v[208:211], v[192:195], v[20:23]
	v_mfma_f32_16x16x32_bf16 v[16:19], v[216:219], v[192:195], v[16:19]
	v_mfma_f32_16x16x32_bf16 v[4:7], v[208:211], v[200:203], v[4:7]
	v_mfma_f32_16x16x32_bf16 v[0:3], v[216:219], v[200:203], v[0:3]
	s_setprio 0
	s_barrier
	ds_read_b128 v[156:159], v152
	ds_read_b128 v[160:163], v152 offset:1024
	ds_read_b128 v[164:167], v152 offset:2048
	ds_read_b128 v[168:171], v152 offset:3072
	s_add_u32 s44, s44, 0x40000
	s_addc_u32 s45, s45, 0
	s_mov_b32 m0, s52
	v_lshl_add_u64 v[204:205], s[44:45], 0, v[134:135]
	ds_read_b128 v[172:175], v148 offset:32768
	ds_read_b128 v[176:179], v148 offset:33792
	ds_read_b128 v[180:183], v148 offset:34816
	ds_read_b128 v[184:187], v148 offset:35840
	ds_read_b128 v[188:191], v148 offset:36864
	ds_read_b128 v[192:195], v148 offset:37888
	ds_read_b128 v[196:199], v148 offset:38912
	ds_read_b128 v[200:203], v148 offset:39936
	global_load_lds_dwordx4 v[204:205], off
	v_lshl_add_u64 v[204:205], s[44:45], 0, v[130:131]
	s_mov_b32 m0, s53
	s_nop 0
	global_load_lds_dwordx4 v[204:205], off
	s_waitcnt lgkmcnt(8)
	s_barrier
	s_waitcnt lgkmcnt(0)
	s_setprio 1
	s_waitcnt lgkmcnt(0)
	v_mfma_f32_16x16x32_bf16 v[124:127], v[156:159], v[172:175], v[124:127]
	v_mfma_f32_16x16x32_bf16 v[120:123], v[164:167], v[172:175], v[120:123]
	v_mfma_f32_16x16x32_bf16 v[112:115], v[156:159], v[180:183], v[112:115]
	v_mfma_f32_16x16x32_bf16 v[104:107], v[164:167], v[180:183], v[104:107]
	v_mfma_f32_16x16x32_bf16 v[96:99], v[156:159], v[188:191], v[96:99]
	v_mfma_f32_16x16x32_bf16 v[88:91], v[164:167], v[188:191], v[88:91]
	v_mfma_f32_16x16x32_bf16 v[76:79], v[156:159], v[196:199], v[76:79]
	v_mfma_f32_16x16x32_bf16 v[72:75], v[164:167], v[196:199], v[72:75]
	v_mfma_f32_16x16x32_bf16 v[124:127], v[160:163], v[176:179], v[124:127]
	v_mfma_f32_16x16x32_bf16 v[120:123], v[168:171], v[176:179], v[120:123]
	v_mfma_f32_16x16x32_bf16 v[112:115], v[160:163], v[184:187], v[112:115]
	v_mfma_f32_16x16x32_bf16 v[104:107], v[168:171], v[184:187], v[104:107]
	v_mfma_f32_16x16x32_bf16 v[96:99], v[160:163], v[192:195], v[96:99]
	v_mfma_f32_16x16x32_bf16 v[88:91], v[168:171], v[192:195], v[88:91]
	v_mfma_f32_16x16x32_bf16 v[76:79], v[160:163], v[200:203], v[76:79]
	v_mfma_f32_16x16x32_bf16 v[72:75], v[168:171], v[200:203], v[72:75]
	s_setprio 0
	s_barrier
	s_mov_b32 m0, s57
	v_lshl_add_u64 v[144:145], v[144:145], 0, s[22:23]
	ds_read_b128 v[204:207], v153
	ds_read_b128 v[208:211], v153 offset:1024
	ds_read_b128 v[212:215], v153 offset:2048
	ds_read_b128 v[216:219], v153 offset:3072
	global_load_lds_dwordx4 v[144:145], off
	v_lshl_add_u64 v[144:145], v[220:221], 0, s[22:23]
	s_mov_b32 m0, s58
	s_nop 0
	global_load_lds_dwordx4 v[144:145], off
	s_barrier
	s_waitcnt lgkmcnt(0)
	s_setprio 1
	s_waitcnt lgkmcnt(0)
	v_mfma_f32_16x16x32_bf16 v[116:119], v[204:207], v[172:175], v[116:119]
	v_mfma_f32_16x16x32_bf16 v[108:111], v[212:215], v[172:175], v[108:111]
	v_mfma_f32_16x16x32_bf16 v[100:103], v[204:207], v[180:183], v[100:103]
	v_mfma_f32_16x16x32_bf16 v[92:95], v[212:215], v[180:183], v[92:95]
	v_mfma_f32_16x16x32_bf16 v[84:87], v[204:207], v[188:191], v[84:87]
	v_mfma_f32_16x16x32_bf16 v[80:83], v[212:215], v[188:191], v[80:83]
	v_mfma_f32_16x16x32_bf16 v[68:71], v[204:207], v[196:199], v[68:71]
	v_mfma_f32_16x16x32_bf16 v[64:67], v[212:215], v[196:199], v[64:67]
	v_mfma_f32_16x16x32_bf16 v[116:119], v[208:211], v[176:179], v[116:119]
	v_mfma_f32_16x16x32_bf16 v[108:111], v[216:219], v[176:179], v[108:111]
	v_mfma_f32_16x16x32_bf16 v[100:103], v[208:211], v[184:187], v[100:103]
	v_mfma_f32_16x16x32_bf16 v[92:95], v[216:219], v[184:187], v[92:95]
	v_mfma_f32_16x16x32_bf16 v[84:87], v[208:211], v[192:195], v[84:87]
	v_mfma_f32_16x16x32_bf16 v[80:83], v[216:219], v[192:195], v[80:83]
	v_mfma_f32_16x16x32_bf16 v[68:71], v[208:211], v[200:203], v[68:71]
	v_mfma_f32_16x16x32_bf16 v[64:67], v[216:219], v[200:203], v[64:67]
	s_setprio 0
	s_mov_b32 m0, s59
	v_lshl_add_u64 v[144:145], v[222:223], 0, s[22:23]
	s_barrier
	ds_read_b128 v[172:175], v148 offset:49152
	ds_read_b128 v[176:179], v148 offset:50176
	ds_read_b128 v[180:183], v148 offset:51200
	ds_read_b128 v[184:187], v148 offset:52224
	ds_read_b128 v[188:191], v148 offset:53248
	ds_read_b128 v[192:195], v148 offset:54272
	ds_read_b128 v[196:199], v148 offset:55296
	ds_read_b128 v[200:203], v148 offset:56320
	global_load_lds_dwordx4 v[144:145], off
	v_lshl_add_u64 v[144:145], v[224:225], 0, s[22:23]
	s_mov_b32 m0, s60
	s_nop 0
	global_load_lds_dwordx4 v[144:145], off
	s_barrier
	s_waitcnt lgkmcnt(0)
	s_setprio 1
	s_waitcnt lgkmcnt(0)
	v_mfma_f32_16x16x32_bf16 v[60:63], v[156:159], v[172:175], v[60:63]
	v_mfma_f32_16x16x32_bf16 v[56:59], v[164:167], v[172:175], v[56:59]
	v_mfma_f32_16x16x32_bf16 v[48:51], v[156:159], v[180:183], v[48:51]
	v_mfma_f32_16x16x32_bf16 v[40:43], v[164:167], v[180:183], v[40:43]
	v_mfma_f32_16x16x32_bf16 v[32:35], v[156:159], v[188:191], v[32:35]
	v_mfma_f32_16x16x32_bf16 v[24:27], v[164:167], v[188:191], v[24:27]
	v_mfma_f32_16x16x32_bf16 v[12:15], v[156:159], v[196:199], v[12:15]
	v_mfma_f32_16x16x32_bf16 v[8:11], v[164:167], v[196:199], v[8:11]
	v_mfma_f32_16x16x32_bf16 v[60:63], v[160:163], v[176:179], v[60:63]
	v_mfma_f32_16x16x32_bf16 v[56:59], v[168:171], v[176:179], v[56:59]
	v_mfma_f32_16x16x32_bf16 v[48:51], v[160:163], v[184:187], v[48:51]
	v_mfma_f32_16x16x32_bf16 v[40:43], v[168:171], v[184:187], v[40:43]
	v_mfma_f32_16x16x32_bf16 v[32:35], v[160:163], v[192:195], v[32:35]
	v_mfma_f32_16x16x32_bf16 v[24:27], v[168:171], v[192:195], v[24:27]
	v_mfma_f32_16x16x32_bf16 v[12:15], v[160:163], v[200:203], v[12:15]
	v_mfma_f32_16x16x32_bf16 v[8:11], v[168:171], v[200:203], v[8:11]
	s_setprio 0
	s_barrier
	s_add_u32 s42, s42, 0x40080
	s_addc_u32 s43, s43, 0
	s_mov_b32 m0, s61
	v_lshl_add_u64 v[144:145], s[42:43], 0, v[132:133]
	global_load_lds_dwordx4 v[144:145], off
	v_lshl_add_u64 v[144:145], s[42:43], 0, v[128:129]
	s_mov_b32 m0, s62
	s_nop 0
	global_load_lds_dwordx4 v[144:145], off
	s_waitcnt vmcnt(6)
	s_barrier
	s_setprio 1
	v_mfma_f32_16x16x32_bf16 v[52:55], v[204:207], v[172:175], v[52:55]
	v_mfma_f32_16x16x32_bf16 v[44:47], v[212:215], v[172:175], v[44:47]
	v_mfma_f32_16x16x32_bf16 v[36:39], v[204:207], v[180:183], v[36:39]
	v_mfma_f32_16x16x32_bf16 v[28:31], v[212:215], v[180:183], v[28:31]
	v_mfma_f32_16x16x32_bf16 v[20:23], v[204:207], v[188:191], v[20:23]
	v_mfma_f32_16x16x32_bf16 v[16:19], v[212:215], v[188:191], v[16:19]
	v_mfma_f32_16x16x32_bf16 v[4:7], v[204:207], v[196:199], v[4:7]
	v_mfma_f32_16x16x32_bf16 v[0:3], v[212:215], v[196:199], v[0:3]
	v_mfma_f32_16x16x32_bf16 v[52:55], v[208:211], v[176:179], v[52:55]
	v_mfma_f32_16x16x32_bf16 v[44:47], v[216:219], v[176:179], v[44:47]
	v_mfma_f32_16x16x32_bf16 v[36:39], v[208:211], v[184:187], v[36:39]
	v_mfma_f32_16x16x32_bf16 v[28:31], v[216:219], v[184:187], v[28:31]
	v_mfma_f32_16x16x32_bf16 v[20:23], v[208:211], v[192:195], v[20:23]
	v_mfma_f32_16x16x32_bf16 v[16:19], v[216:219], v[192:195], v[16:19]
	v_mfma_f32_16x16x32_bf16 v[4:7], v[208:211], v[200:203], v[4:7]
	v_mfma_f32_16x16x32_bf16 v[0:3], v[216:219], v[200:203], v[0:3]
	s_setprio 0
	s_add_i32 s70, s70, 2
	s_add_u32 s40, s40, 0x100
	s_addc_u32 s41, s41, 0
	s_add_u32 s68, s68, 0x100
	s_addc_u32 s69, s69, 0
	s_cmp_gt_u32 s70, 13
	s_barrier
	s_cbranch_scc0 .LBB0_241
	s_lshl_b32 s29, s38, 8
	s_add_i32 s29, s29, s56
	v_cvt_pk_bf16_f32 v124, v124, v125
	v_or_b32_e32 v155, s29, v147
	v_lshl_add_u32 v144, s6, 8, v149
	v_lshlrev_b32_e32 v156, 10, v155
	v_cvt_pk_bf16_f32 v125, v126, v127
	v_cvt_pk_bf16_f32 v126, v120, v121
	v_add_u32_e32 v136, v156, v144
	v_cvt_pk_bf16_f32 v116, v116, v117
	v_cvt_pk_bf16_f32 v127, v122, v123
	v_lshl_add_u64 v[120:121], v[136:137], 1, s[10:11]
	global_store_dwordx4 v[120:121], v[124:127], off
	v_add_u32_e32 v120, 0x80, v144
	v_cvt_pk_bf16_f32 v117, v118, v119
	v_cvt_pk_bf16_f32 v118, v108, v109
	v_add_u32_e32 v136, v156, v120
	v_cvt_pk_bf16_f32 v119, v110, v111
	v_lshl_add_u64 v[108:109], v[136:137], 1, s[10:11]
	global_store_dwordx4 v[108:109], v[116:119], off
	v_cvt_pk_bf16_f32 v108, v112, v113
	v_cvt_pk_bf16_f32 v100, v100, v101
	v_or_b32_e32 v116, 0x4000, v156
	v_cvt_pk_bf16_f32 v109, v114, v115
	v_cvt_pk_bf16_f32 v110, v104, v105
	v_add_u32_e32 v136, v116, v144
	v_cvt_pk_bf16_f32 v101, v102, v103
	v_cvt_pk_bf16_f32 v102, v92, v93
	v_cvt_pk_bf16_f32 v111, v106, v107
	v_lshl_add_u64 v[104:105], v[136:137], 1, s[10:11]
	v_add_u32_e32 v136, v116, v120
	v_cvt_pk_bf16_f32 v103, v94, v95
	v_lshl_add_u64 v[92:93], v[136:137], 1, s[10:11]
	global_store_dwordx4 v[104:105], v[108:111], off
	global_store_dwordx4 v[92:93], v[100:103], off
	v_cvt_pk_bf16_f32 v92, v96, v97
	v_cvt_pk_bf16_f32 v84, v84, v85
	v_or_b32_e32 v100, 0x8000, v156
	v_cvt_pk_bf16_f32 v93, v98, v99
	v_cvt_pk_bf16_f32 v94, v88, v89
	v_add_u32_e32 v136, v100, v144
	v_cvt_pk_bf16_f32 v85, v86, v87
	v_cvt_pk_bf16_f32 v86, v80, v81
	v_cvt_pk_bf16_f32 v95, v90, v91
	v_lshl_add_u64 v[88:89], v[136:137], 1, s[10:11]
	v_add_u32_e32 v136, v100, v120
	v_cvt_pk_bf16_f32 v87, v82, v83
	v_lshl_add_u64 v[80:81], v[136:137], 1, s[10:11]
	global_store_dwordx4 v[88:89], v[92:95], off
	global_store_dwordx4 v[80:81], v[84:87], off
	s_add_i32 s6, s29, 0xfff0000
	s_lshr_b32 s6, s6, 6
	s_ashr_i32 s7, s29, 12
	v_cvt_pk_bf16_f32 v84, v76, v77
	s_mul_i32 s31, s7, 3
	v_or_b32_e32 v82, 48, v155
	v_mad_u64_u32 v[80:81], s[6:7], s6, 3, v[138:139]
	v_bitop3_b32 v90, v155, s65, 48 bitop3:0xc8
	v_cvt_pk_bf16_f32 v85, v78, v79
	v_lshlrev_b32_e32 v83, 10, v82
	v_lshl_add_u32 v136, v80, 10, v154
	v_add_lshl_u32 v80, v90, s31, 10
	v_cvt_pk_bf16_f32 v86, v72, v73
	v_ashrrev_i32_e32 v81, 31, v80
	v_cvt_pk_bf16_f32 v87, v74, v75
	v_add_u32_e32 v88, v83, v144
	v_mov_b32_e32 v89, v137
	v_lshl_add_u64 v[88:89], v[88:89], 1, s[10:11]
	v_lshl_add_u64 v[80:81], v[80:81], 2, s[18:19]
	global_store_dwordx4 v[88:89], v[84:87], off
	v_lshl_add_u64 v[80:81], v[80:81], 0, s[24:25]
	v_cmp_gt_i32_e32 vcc, s55, v82
	v_lshl_add_u64 v[84:85], v[136:137], 2, s[20:21]
	v_cmp_lt_u32_e64 s[6:7], s66, v90
	v_cndmask_b32_e32 v80, v84, v80, vcc
	v_cndmask_b32_e64 v82, 0, 1, s[4:5]
	v_cndmask_b32_e64 v84, 0, 1, s[6:7]
	v_cndmask_b32_e32 v84, v82, v84, vcc
	v_cndmask_b32_e32 v81, v85, v81, vcc
	v_and_b32_e32 v84, 1, v84
	v_cmp_eq_u32_e32 vcc, 1, v84
	v_cmp_ne_u64_e64 s[6:7], 0, v[80:81]
	s_and_b64 s[6:7], vcc, s[6:7]
	v_ashrrev_i32_e32 v145, 31, v144
	s_and_saveexec_b64 s[38:39], s[6:7]
	s_cbranch_execz .LBB0_244
	v_lshl_add_u64 v[84:85], v[144:145], 2, v[80:81]
	global_store_dwordx4 v[84:85], v[76:79], off
	global_store_dwordx4 v[84:85], v[72:75], off offset:16

.LBB0_264:
	ds_read_b128 v[158:161], v151
	ds_read_b128 v[162:165], v151 offset:1024
	ds_read_b128 v[166:169], v151 offset:2048
	ds_read_b128 v[170:173], v151 offset:3072
	s_add_u32 s34, s30, 0xfffc0080
	s_addc_u32 s35, s31, -1
	s_cmp_eq_u32 s60, 12
	s_cselect_b32 s37, s5, s35
	s_cselect_b32 s36, s23, s34
	s_cselect_b32 s35, s21, s59
	s_cselect_b32 s34, s29, s58
	s_mov_b32 m0, s54
	v_lshl_add_u64 v[206:207], s[30:31], 0, v[138:139]
	ds_read_b128 v[174:177], v144
	ds_read_b128 v[178:181], v144 offset:1024
	ds_read_b128 v[182:185], v144 offset:2048
	ds_read_b128 v[186:189], v144 offset:3072
	ds_read_b128 v[190:193], v144 offset:4096
	ds_read_b128 v[194:197], v144 offset:5120
	ds_read_b128 v[198:201], v144 offset:6144
	ds_read_b128 v[202:205], v144 offset:7168
	global_load_lds_dwordx4 v[206:207], off
	v_lshl_add_u64 v[206:207], s[30:31], 0, v[140:141]
	s_mov_b32 m0, s55
	s_nop 0
	global_load_lds_dwordx4 v[206:207], off
	s_waitcnt lgkmcnt(8)
	s_barrier
	s_waitcnt lgkmcnt(0)
	s_setprio 1
	s_waitcnt lgkmcnt(0)
	v_mfma_f32_16x16x32_bf16 v[124:127], v[158:161], v[174:177], v[124:127]
	v_mfma_f32_16x16x32_bf16 v[120:123], v[166:169], v[174:177], v[120:123]
	v_mfma_f32_16x16x32_bf16 v[108:111], v[158:161], v[182:185], v[108:111]
	v_mfma_f32_16x16x32_bf16 v[104:107], v[166:169], v[182:185], v[104:107]
	v_mfma_f32_16x16x32_bf16 v[92:95], v[158:161], v[190:193], v[92:95]
	v_mfma_f32_16x16x32_bf16 v[88:91], v[166:169], v[190:193], v[88:91]
	v_mfma_f32_16x16x32_bf16 v[76:79], v[158:161], v[198:201], v[76:79]
	v_mfma_f32_16x16x32_bf16 v[72:75], v[166:169], v[198:201], v[72:75]
	v_mfma_f32_16x16x32_bf16 v[124:127], v[162:165], v[178:181], v[124:127]
	v_mfma_f32_16x16x32_bf16 v[120:123], v[170:173], v[178:181], v[120:123]
	v_mfma_f32_16x16x32_bf16 v[108:111], v[162:165], v[186:189], v[108:111]
	v_mfma_f32_16x16x32_bf16 v[104:107], v[170:173], v[186:189], v[104:107]
	v_mfma_f32_16x16x32_bf16 v[92:95], v[162:165], v[194:197], v[92:95]
	v_mfma_f32_16x16x32_bf16 v[88:91], v[170:173], v[194:197], v[88:91]
	v_mfma_f32_16x16x32_bf16 v[76:79], v[162:165], v[202:205], v[76:79]
	v_mfma_f32_16x16x32_bf16 v[72:75], v[170:173], v[202:205], v[72:75]
	s_setprio 0
	s_barrier
	s_mov_b32 m0, s40
	v_lshl_add_u64 v[222:223], s[34:35], 0, v[130:131]
	ds_read_b128 v[206:209], v152
	ds_read_b128 v[210:213], v152 offset:1024
	ds_read_b128 v[214:217], v152 offset:2048
	ds_read_b128 v[218:221], v152 offset:3072
	global_load_lds_dwordx4 v[222:223], off
	v_lshl_add_u64 v[224:225], s[34:35], 0, v[134:135]
	s_mov_b32 m0, s41
	s_nop 0
	global_load_lds_dwordx4 v[224:225], off
	s_barrier
	s_waitcnt lgkmcnt(0)
	s_setprio 1
	s_waitcnt lgkmcnt(0)
	v_mfma_f32_16x16x32_bf16 v[116:119], v[206:209], v[174:177], v[116:119]
	v_mfma_f32_16x16x32_bf16 v[112:115], v[214:217], v[174:177], v[112:115]
	v_mfma_f32_16x16x32_bf16 v[100:103], v[206:209], v[182:185], v[100:103]
	v_mfma_f32_16x16x32_bf16 v[96:99], v[214:217], v[182:185], v[96:99]
	v_mfma_f32_16x16x32_bf16 v[84:87], v[206:209], v[190:193], v[84:87]
	v_mfma_f32_16x16x32_bf16 v[80:83], v[214:217], v[190:193], v[80:83]
	v_mfma_f32_16x16x32_bf16 v[68:71], v[206:209], v[198:201], v[68:71]
	v_mfma_f32_16x16x32_bf16 v[64:67], v[214:217], v[198:201], v[64:67]
	v_mfma_f32_16x16x32_bf16 v[116:119], v[210:213], v[178:181], v[116:119]
	v_mfma_f32_16x16x32_bf16 v[112:115], v[218:221], v[178:181], v[112:115]
	v_mfma_f32_16x16x32_bf16 v[100:103], v[210:213], v[186:189], v[100:103]
	v_mfma_f32_16x16x32_bf16 v[96:99], v[218:221], v[186:189], v[96:99]
	v_mfma_f32_16x16x32_bf16 v[84:87], v[210:213], v[194:197], v[84:87]
	v_mfma_f32_16x16x32_bf16 v[80:83], v[218:221], v[194:197], v[80:83]
	v_mfma_f32_16x16x32_bf16 v[68:71], v[210:213], v[202:205], v[68:71]
	v_mfma_f32_16x16x32_bf16 v[64:67], v[218:221], v[202:205], v[64:67]
	s_setprio 0
	s_mov_b32 m0, s3
	v_lshl_add_u64 v[226:227], s[36:37], 0, v[128:129]
	s_barrier
	ds_read_b128 v[174:177], v144 offset:16384
	ds_read_b128 v[178:181], v144 offset:17408
	ds_read_b128 v[182:185], v144 offset:18432
	ds_read_b128 v[186:189], v144 offset:19456
	ds_read_b128 v[190:193], v144 offset:20480
	ds_read_b128 v[194:197], v144 offset:21504
	ds_read_b128 v[198:201], v144 offset:22528
	ds_read_b128 v[202:205], v144 offset:23552
	global_load_lds_dwordx4 v[226:227], off
	v_lshl_add_u64 v[228:229], s[36:37], 0, v[132:133]
	s_mov_b32 m0, s42
	s_nop 0
	global_load_lds_dwordx4 v[228:229], off
	s_barrier
	s_waitcnt lgkmcnt(0)
	s_setprio 1
	s_waitcnt lgkmcnt(0)
	v_mfma_f32_16x16x32_bf16 v[60:63], v[158:161], v[174:177], v[60:63]
	v_mfma_f32_16x16x32_bf16 v[56:59], v[166:169], v[174:177], v[56:59]
	v_mfma_f32_16x16x32_bf16 v[44:47], v[158:161], v[182:185], v[44:47]
	v_mfma_f32_16x16x32_bf16 v[40:43], v[166:169], v[182:185], v[40:43]
	v_mfma_f32_16x16x32_bf16 v[28:31], v[158:161], v[190:193], v[28:31]
	v_mfma_f32_16x16x32_bf16 v[24:27], v[166:169], v[190:193], v[24:27]
	v_mfma_f32_16x16x32_bf16 v[12:15], v[158:161], v[198:201], v[12:15]
	v_mfma_f32_16x16x32_bf16 v[8:11], v[166:169], v[198:201], v[8:11]
	v_mfma_f32_16x16x32_bf16 v[60:63], v[162:165], v[178:181], v[60:63]
	v_mfma_f32_16x16x32_bf16 v[56:59], v[170:173], v[178:181], v[56:59]
	v_mfma_f32_16x16x32_bf16 v[44:47], v[162:165], v[186:189], v[44:47]
	v_mfma_f32_16x16x32_bf16 v[40:43], v[170:173], v[186:189], v[40:43]
	v_mfma_f32_16x16x32_bf16 v[28:31], v[162:165], v[194:197], v[28:31]
	v_mfma_f32_16x16x32_bf16 v[24:27], v[170:173], v[194:197], v[24:27]
	v_mfma_f32_16x16x32_bf16 v[12:15], v[162:165], v[202:205], v[12:15]
	v_mfma_f32_16x16x32_bf16 v[8:11], v[170:173], v[202:205], v[8:11]
	s_setprio 0
	s_barrier
	s_add_u32 s62, s34, 0x40000
	s_addc_u32 s63, s35, 0
	s_mov_b32 m0, s43
	v_lshl_add_u64 v[158:159], s[62:63], 0, v[130:131]
	global_load_lds_dwordx4 v[158:159], off
	v_lshl_add_u64 v[158:159], s[62:63], 0, v[134:135]
	s_mov_b32 m0, s44
	s_nop 0
	global_load_lds_dwordx4 v[158:159], off
	s_waitcnt vmcnt(6)
	s_barrier
	s_setprio 1
	v_mfma_f32_16x16x32_bf16 v[52:55], v[206:209], v[174:177], v[52:55]
	v_mfma_f32_16x16x32_bf16 v[48:51], v[214:217], v[174:177], v[48:51]
	v_mfma_f32_16x16x32_bf16 v[36:39], v[206:209], v[182:185], v[36:39]
	v_mfma_f32_16x16x32_bf16 v[32:35], v[214:217], v[182:185], v[32:35]
	v_mfma_f32_16x16x32_bf16 v[20:23], v[206:209], v[190:193], v[20:23]
	v_mfma_f32_16x16x32_bf16 v[16:19], v[214:217], v[190:193], v[16:19]
	v_mfma_f32_16x16x32_bf16 v[4:7], v[206:209], v[198:201], v[4:7]
	v_mfma_f32_16x16x32_bf16 v[0:3], v[214:217], v[198:201], v[0:3]
	v_mfma_f32_16x16x32_bf16 v[52:55], v[210:213], v[178:181], v[52:55]
	v_mfma_f32_16x16x32_bf16 v[48:51], v[218:221], v[178:181], v[48:51]
	v_mfma_f32_16x16x32_bf16 v[36:39], v[210:213], v[186:189], v[36:39]
	v_mfma_f32_16x16x32_bf16 v[32:35], v[218:221], v[186:189], v[32:35]
	v_mfma_f32_16x16x32_bf16 v[20:23], v[210:213], v[194:197], v[20:23]
	v_mfma_f32_16x16x32_bf16 v[16:19], v[218:221], v[194:197], v[16:19]
	v_mfma_f32_16x16x32_bf16 v[4:7], v[210:213], v[202:205], v[4:7]
	v_mfma_f32_16x16x32_bf16 v[0:3], v[218:221], v[202:205], v[0:3]
	s_setprio 0
	s_barrier
	ds_read_b128 v[158:161], v153
	ds_read_b128 v[162:165], v153 offset:1024
	ds_read_b128 v[166:169], v153 offset:2048
	ds_read_b128 v[170:173], v153 offset:3072
	s_add_u32 s36, s36, 0x40000
	s_addc_u32 s37, s37, 0
	s_mov_b32 m0, s45
	v_lshl_add_u64 v[206:207], s[36:37], 0, v[128:129]
	ds_read_b128 v[174:177], v144 offset:32768
	ds_read_b128 v[178:181], v144 offset:33792
	ds_read_b128 v[182:185], v144 offset:34816
	ds_read_b128 v[186:189], v144 offset:35840
	ds_read_b128 v[190:193], v144 offset:36864
	ds_read_b128 v[194:197], v144 offset:37888
	ds_read_b128 v[198:201], v144 offset:38912
	ds_read_b128 v[202:205], v144 offset:39936
	global_load_lds_dwordx4 v[206:207], off
	v_lshl_add_u64 v[206:207], s[36:37], 0, v[132:133]
	s_mov_b32 m0, s46
	s_nop 0
	global_load_lds_dwordx4 v[206:207], off
	s_waitcnt lgkmcnt(8)
	s_barrier
	s_waitcnt lgkmcnt(0)
	s_setprio 1
	s_waitcnt lgkmcnt(0)
	v_mfma_f32_16x16x32_bf16 v[124:127], v[158:161], v[174:177], v[124:127]
	v_mfma_f32_16x16x32_bf16 v[120:123], v[166:169], v[174:177], v[120:123]
	v_mfma_f32_16x16x32_bf16 v[108:111], v[158:161], v[182:185], v[108:111]
	v_mfma_f32_16x16x32_bf16 v[104:107], v[166:169], v[182:185], v[104:107]
	v_mfma_f32_16x16x32_bf16 v[92:95], v[158:161], v[190:193], v[92:95]
	v_mfma_f32_16x16x32_bf16 v[88:91], v[166:169], v[190:193], v[88:91]
	v_mfma_f32_16x16x32_bf16 v[76:79], v[158:161], v[198:201], v[76:79]
	v_mfma_f32_16x16x32_bf16 v[72:75], v[166:169], v[198:201], v[72:75]
	v_mfma_f32_16x16x32_bf16 v[124:127], v[162:165], v[178:181], v[124:127]
	v_mfma_f32_16x16x32_bf16 v[120:123], v[170:173], v[178:181], v[120:123]
	v_mfma_f32_16x16x32_bf16 v[108:111], v[162:165], v[186:189], v[108:111]
	v_mfma_f32_16x16x32_bf16 v[104:107], v[170:173], v[186:189], v[104:107]
	v_mfma_f32_16x16x32_bf16 v[92:95], v[162:165], v[194:197], v[92:95]
	v_mfma_f32_16x16x32_bf16 v[88:91], v[170:173], v[194:197], v[88:91]
	v_mfma_f32_16x16x32_bf16 v[76:79], v[162:165], v[202:205], v[76:79]
	v_mfma_f32_16x16x32_bf16 v[72:75], v[170:173], v[202:205], v[72:75]
	s_setprio 0
	s_barrier
	s_mov_b32 m0, s47
	v_lshl_add_u64 v[222:223], v[222:223], 0, s[6:7]
	ds_read_b128 v[206:209], v154
	ds_read_b128 v[210:213], v154 offset:1024
	ds_read_b128 v[214:217], v154 offset:2048
	ds_read_b128 v[218:221], v154 offset:3072
	global_load_lds_dwordx4 v[222:223], off
	v_lshl_add_u64 v[222:223], v[224:225], 0, s[6:7]
	s_mov_b32 m0, s48
	s_nop 0
	global_load_lds_dwordx4 v[222:223], off
	s_barrier
	s_waitcnt lgkmcnt(0)
	s_setprio 1
	s_waitcnt lgkmcnt(0)
	v_mfma_f32_16x16x32_bf16 v[116:119], v[206:209], v[174:177], v[116:119]
	v_mfma_f32_16x16x32_bf16 v[112:115], v[214:217], v[174:177], v[112:115]
	v_mfma_f32_16x16x32_bf16 v[100:103], v[206:209], v[182:185], v[100:103]
	v_mfma_f32_16x16x32_bf16 v[96:99], v[214:217], v[182:185], v[96:99]
	v_mfma_f32_16x16x32_bf16 v[84:87], v[206:209], v[190:193], v[84:87]
	v_mfma_f32_16x16x32_bf16 v[80:83], v[214:217], v[190:193], v[80:83]
	v_mfma_f32_16x16x32_bf16 v[68:71], v[206:209], v[198:201], v[68:71]
	v_mfma_f32_16x16x32_bf16 v[64:67], v[214:217], v[198:201], v[64:67]
	v_mfma_f32_16x16x32_bf16 v[116:119], v[210:213], v[178:181], v[116:119]
	v_mfma_f32_16x16x32_bf16 v[112:115], v[218:221], v[178:181], v[112:115]
	v_mfma_f32_16x16x32_bf16 v[100:103], v[210:213], v[186:189], v[100:103]
	v_mfma_f32_16x16x32_bf16 v[96:99], v[218:221], v[186:189], v[96:99]
	v_mfma_f32_16x16x32_bf16 v[84:87], v[210:213], v[194:197], v[84:87]
	v_mfma_f32_16x16x32_bf16 v[80:83], v[218:221], v[194:197], v[80:83]
	v_mfma_f32_16x16x32_bf16 v[68:71], v[210:213], v[202:205], v[68:71]
	v_mfma_f32_16x16x32_bf16 v[64:67], v[218:221], v[202:205], v[64:67]
	s_setprio 0
	s_mov_b32 m0, s49
	v_lshl_add_u64 v[222:223], v[226:227], 0, s[6:7]
	s_barrier
	ds_read_b128 v[174:177], v144 offset:49152
	ds_read_b128 v[178:181], v144 offset:50176
	ds_read_b128 v[182:185], v144 offset:51200
	ds_read_b128 v[186:189], v144 offset:52224
	ds_read_b128 v[190:193], v144 offset:53248
	ds_read_b128 v[194:197], v144 offset:54272
	ds_read_b128 v[198:201], v144 offset:55296
	ds_read_b128 v[202:205], v144 offset:56320
	global_load_lds_dwordx4 v[222:223], off
	v_lshl_add_u64 v[222:223], v[228:229], 0, s[6:7]
	s_mov_b32 m0, s50
	s_nop 0
	global_load_lds_dwordx4 v[222:223], off
	s_barrier
	s_waitcnt lgkmcnt(0)
	s_setprio 1
	s_waitcnt lgkmcnt(0)
	v_mfma_f32_16x16x32_bf16 v[60:63], v[158:161], v[174:177], v[60:63]
	v_mfma_f32_16x16x32_bf16 v[56:59], v[166:169], v[174:177], v[56:59]
	v_mfma_f32_16x16x32_bf16 v[44:47], v[158:161], v[182:185], v[44:47]
	v_mfma_f32_16x16x32_bf16 v[40:43], v[166:169], v[182:185], v[40:43]
	v_mfma_f32_16x16x32_bf16 v[28:31], v[158:161], v[190:193], v[28:31]
	v_mfma_f32_16x16x32_bf16 v[24:27], v[166:169], v[190:193], v[24:27]
	v_mfma_f32_16x16x32_bf16 v[12:15], v[158:161], v[198:201], v[12:15]
	v_mfma_f32_16x16x32_bf16 v[8:11], v[166:169], v[198:201], v[8:11]
	v_mfma_f32_16x16x32_bf16 v[60:63], v[162:165], v[178:181], v[60:63]
	v_mfma_f32_16x16x32_bf16 v[56:59], v[170:173], v[178:181], v[56:59]
	v_mfma_f32_16x16x32_bf16 v[44:47], v[162:165], v[186:189], v[44:47]
	v_mfma_f32_16x16x32_bf16 v[40:43], v[170:173], v[186:189], v[40:43]
	v_mfma_f32_16x16x32_bf16 v[28:31], v[162:165], v[194:197], v[28:31]
	v_mfma_f32_16x16x32_bf16 v[24:27], v[170:173], v[194:197], v[24:27]
	v_mfma_f32_16x16x32_bf16 v[12:15], v[162:165], v[202:205], v[12:15]
	v_mfma_f32_16x16x32_bf16 v[8:11], v[170:173], v[202:205], v[8:11]
	s_setprio 0
	s_barrier
	s_add_u32 s34, s34, 0x40080
	s_addc_u32 s35, s35, 0
	s_mov_b32 m0, s51
	v_lshl_add_u64 v[158:159], s[34:35], 0, v[130:131]
	global_load_lds_dwordx4 v[158:159], off
	v_lshl_add_u64 v[158:159], s[34:35], 0, v[134:135]
	s_mov_b32 m0, s52
	s_nop 0
	global_load_lds_dwordx4 v[158:159], off
	s_waitcnt vmcnt(6)
	s_barrier
	s_setprio 1
	v_mfma_f32_16x16x32_bf16 v[52:55], v[206:209], v[174:177], v[52:55]
	v_mfma_f32_16x16x32_bf16 v[48:51], v[214:217], v[174:177], v[48:51]
	v_mfma_f32_16x16x32_bf16 v[36:39], v[206:209], v[182:185], v[36:39]
	v_mfma_f32_16x16x32_bf16 v[32:35], v[214:217], v[182:185], v[32:35]
	v_mfma_f32_16x16x32_bf16 v[20:23], v[206:209], v[190:193], v[20:23]
	v_mfma_f32_16x16x32_bf16 v[16:19], v[214:217], v[190:193], v[16:19]
	v_mfma_f32_16x16x32_bf16 v[4:7], v[206:209], v[198:201], v[4:7]
	v_mfma_f32_16x16x32_bf16 v[0:3], v[214:217], v[198:201], v[0:3]
	v_mfma_f32_16x16x32_bf16 v[52:55], v[210:213], v[178:181], v[52:55]
	v_mfma_f32_16x16x32_bf16 v[48:51], v[218:221], v[178:181], v[48:51]
	v_mfma_f32_16x16x32_bf16 v[36:39], v[210:213], v[186:189], v[36:39]
	v_mfma_f32_16x16x32_bf16 v[32:35], v[218:221], v[186:189], v[32:35]
	v_mfma_f32_16x16x32_bf16 v[20:23], v[210:213], v[194:197], v[20:23]
	v_mfma_f32_16x16x32_bf16 v[16:19], v[218:221], v[194:197], v[16:19]
	v_mfma_f32_16x16x32_bf16 v[4:7], v[210:213], v[202:205], v[4:7]
	v_mfma_f32_16x16x32_bf16 v[0:3], v[218:221], v[202:205], v[0:3]
	s_setprio 0
	s_add_i32 s60, s60, 2
	s_add_u32 s30, s30, 0x100
	s_addc_u32 s31, s31, 0
	s_add_u32 s58, s58, 0x100
	s_addc_u32 s59, s59, 0
	s_cmp_gt_u32 s60, 13
	s_barrier
	s_cbranch_scc0 .LBB0_264
	v_lshl_add_u32 v157, s28, 8, v150
	s_cmp_gt_i32 s4, 3
	s_mov_b64 s[28:29], -1
	s_cbranch_scc0 .LBB0_269
	s_and_saveexec_b64 s[28:29], s[16:17]
	s_cbranch_execz .LBB0_268
	v_lshlrev_b32_e32 v160, 3, v157
	v_or_b32_e32 v136, v160, v142
	v_lshl_add_u64 v[158:159], v[136:137], 2, s[14:15]
	v_add_u32_e32 v136, v160, v145
	global_store_dword v[158:159], v124, off
	global_store_dword v[158:159], v120, off offset:128
	global_store_dword v[158:159], v125, off offset:32
	global_store_dword v[158:159], v121, off offset:160
	global_store_dword v[158:159], v126, off offset:64
	global_store_dword v[158:159], v122, off offset:192
	global_store_dword v[158:159], v127, off offset:96
	global_store_dword v[158:159], v123, off offset:224
	v_lshl_add_u64 v[158:159], v[136:137], 2, s[14:15]
	v_add_u32_e32 v136, v147, v160
	global_store_dword v[158:159], v116, off
	global_store_dword v[158:159], v112, off offset:128
	v_lshl_add_u64 v[158:159], v[136:137], 2, s[14:15]
	v_add_u32_e32 v136, v160, v148
	global_store_dword v[158:159], v117, off
	global_store_dword v[158:159], v113, off offset:128
	v_lshl_add_u64 v[158:159], v[136:137], 2, s[14:15]
	v_add_u32_e32 v136, v149, v160
	global_store_dword v[158:159], v118, off
	global_store_dword v[158:159], v114, off offset:128
	v_lshl_add_u64 v[158:159], v[136:137], 2, s[14:15]
	global_store_dword v[158:159], v119, off
	global_store_dword v[158:159], v115, off offset:128

.LBB0_733:
	ds_read_b128 v[148:151], v144
	ds_read_b128 v[152:155], v144 offset:1024
	ds_read_b128 v[156:159], v144 offset:2048
	ds_read_b128 v[160:163], v144 offset:3072
	s_add_u32 s26, s24, 0xfffc0080
	s_addc_u32 s27, s25, -1
	s_cmp_eq_u32 s62, 12
	s_cselect_b32 s29, s7, s27
	s_cselect_b32 s28, s17, s26
	s_cselect_b32 s27, s15, vcc_hi
	s_cselect_b32 s26, s23, vcc_lo
	s_mov_b32 m0, s31
	v_lshl_add_u64 v[198:199], s[24:25], 0, v[136:137]
	ds_read_b128 v[164:167], v142
	ds_read_b128 v[168:171], v142 offset:1024
	ds_read_b128 v[172:175], v142 offset:2048
	ds_read_b128 v[176:179], v142 offset:3072
	ds_read_b128 v[182:185], v142 offset:4096
	ds_read_b128 v[186:189], v142 offset:5120
	ds_read_b128 v[190:193], v142 offset:6144
	ds_read_b128 v[194:197], v142 offset:7168
	global_load_lds_dwordx4 v[198:199], off
	v_lshl_add_u64 v[198:199], s[24:25], 0, v[138:139]
	s_mov_b32 m0, s94
	s_nop 0
	global_load_lds_dwordx4 v[198:199], off
	s_waitcnt lgkmcnt(8)
	s_barrier
	s_waitcnt lgkmcnt(0)
	s_setprio 1
	s_waitcnt lgkmcnt(0)
	v_mfma_f32_16x16x32_bf16 v[126:129], v[148:151], v[164:167], v[126:129]
	v_mfma_f32_16x16x32_bf16 v[122:125], v[156:159], v[164:167], v[122:125]
	v_mfma_f32_16x16x32_bf16 v[114:117], v[148:151], v[172:175], v[114:117]
	v_mfma_f32_16x16x32_bf16 v[106:109], v[156:159], v[172:175], v[106:109]
	v_mfma_f32_16x16x32_bf16 v[98:101], v[148:151], v[182:185], v[98:101]
	v_mfma_f32_16x16x32_bf16 v[90:93], v[156:159], v[182:185], v[90:93]
	v_mfma_f32_16x16x32_bf16 v[82:85], v[148:151], v[190:193], v[82:85]
	v_mfma_f32_16x16x32_bf16 v[74:77], v[156:159], v[190:193], v[74:77]
	v_mfma_f32_16x16x32_bf16 v[126:129], v[152:155], v[168:171], v[126:129]
	v_mfma_f32_16x16x32_bf16 v[122:125], v[160:163], v[168:171], v[122:125]
	v_mfma_f32_16x16x32_bf16 v[114:117], v[152:155], v[176:179], v[114:117]
	v_mfma_f32_16x16x32_bf16 v[106:109], v[160:163], v[176:179], v[106:109]
	v_mfma_f32_16x16x32_bf16 v[98:101], v[152:155], v[186:189], v[98:101]
	v_mfma_f32_16x16x32_bf16 v[90:93], v[160:163], v[186:189], v[90:93]
	v_mfma_f32_16x16x32_bf16 v[82:85], v[152:155], v[194:197], v[82:85]
	v_mfma_f32_16x16x32_bf16 v[74:77], v[160:163], v[194:197], v[74:77]
	s_setprio 0
	s_barrier
	s_mov_b32 m0, s36
	v_lshl_add_u64 v[214:215], s[26:27], 0, v[0:1]
	ds_read_b128 v[198:201], v145
	ds_read_b128 v[202:205], v145 offset:1024
	ds_read_b128 v[206:209], v145 offset:2048
	ds_read_b128 v[210:213], v145 offset:3072
	global_load_lds_dwordx4 v[214:215], off
	v_lshl_add_u64 v[216:217], s[26:27], 0, v[134:135]
	s_mov_b32 m0, s37
	s_nop 0
	global_load_lds_dwordx4 v[216:217], off
	s_barrier
	s_waitcnt lgkmcnt(0)
	s_setprio 1
	s_waitcnt lgkmcnt(0)
	v_mfma_f32_16x16x32_bf16 v[118:121], v[198:201], v[164:167], v[118:121]
	v_mfma_f32_16x16x32_bf16 v[110:113], v[206:209], v[164:167], v[110:113]
	v_mfma_f32_16x16x32_bf16 v[102:105], v[198:201], v[172:175], v[102:105]
	v_mfma_f32_16x16x32_bf16 v[94:97], v[206:209], v[172:175], v[94:97]
	v_mfma_f32_16x16x32_bf16 v[86:89], v[198:201], v[182:185], v[86:89]
	v_mfma_f32_16x16x32_bf16 v[78:81], v[206:209], v[182:185], v[78:81]
	v_mfma_f32_16x16x32_bf16 v[70:73], v[198:201], v[190:193], v[70:73]
	v_mfma_f32_16x16x32_bf16 v[66:69], v[206:209], v[190:193], v[66:69]
	v_mfma_f32_16x16x32_bf16 v[118:121], v[202:205], v[168:171], v[118:121]
	v_mfma_f32_16x16x32_bf16 v[110:113], v[210:213], v[168:171], v[110:113]
	v_mfma_f32_16x16x32_bf16 v[102:105], v[202:205], v[176:179], v[102:105]
	v_mfma_f32_16x16x32_bf16 v[94:97], v[210:213], v[176:179], v[94:97]
	v_mfma_f32_16x16x32_bf16 v[86:89], v[202:205], v[186:189], v[86:89]
	v_mfma_f32_16x16x32_bf16 v[78:81], v[210:213], v[186:189], v[78:81]
	v_mfma_f32_16x16x32_bf16 v[70:73], v[202:205], v[194:197], v[70:73]
	v_mfma_f32_16x16x32_bf16 v[66:69], v[210:213], v[194:197], v[66:69]
	s_setprio 0
	s_mov_b32 m0, s89
	v_lshl_add_u64 v[222:223], s[28:29], 0, v[130:131]
	s_barrier
	ds_read_b128 v[164:167], v142 offset:16384
	ds_read_b128 v[168:171], v142 offset:17408
	ds_read_b128 v[172:175], v142 offset:18432
	ds_read_b128 v[176:179], v142 offset:19456
	ds_read_b128 v[182:185], v142 offset:20480
	ds_read_b128 v[186:189], v142 offset:21504
	ds_read_b128 v[190:193], v142 offset:22528
	ds_read_b128 v[194:197], v142 offset:23552
	global_load_lds_dwordx4 v[222:223], off
	v_lshl_add_u64 v[224:225], s[28:29], 0, v[132:133]
	s_mov_b32 m0, s38
	s_nop 0
	global_load_lds_dwordx4 v[224:225], off
	s_barrier
	s_waitcnt lgkmcnt(0)
	s_setprio 1
	s_waitcnt lgkmcnt(0)
	v_mfma_f32_16x16x32_bf16 v[62:65], v[148:151], v[164:167], v[62:65]
	v_mfma_f32_16x16x32_bf16 v[58:61], v[156:159], v[164:167], v[58:61]
	v_mfma_f32_16x16x32_bf16 v[50:53], v[148:151], v[172:175], v[50:53]
	v_mfma_f32_16x16x32_bf16 v[42:45], v[156:159], v[172:175], v[42:45]
	v_mfma_f32_16x16x32_bf16 v[34:37], v[148:151], v[182:185], v[34:37]
	v_mfma_f32_16x16x32_bf16 v[26:29], v[156:159], v[182:185], v[26:29]
	v_mfma_f32_16x16x32_bf16 v[18:21], v[148:151], v[190:193], v[18:21]
	v_mfma_f32_16x16x32_bf16 v[10:13], v[156:159], v[190:193], v[10:13]
	v_mfma_f32_16x16x32_bf16 v[62:65], v[152:155], v[168:171], v[62:65]
	v_mfma_f32_16x16x32_bf16 v[58:61], v[160:163], v[168:171], v[58:61]
	v_mfma_f32_16x16x32_bf16 v[50:53], v[152:155], v[176:179], v[50:53]
	v_mfma_f32_16x16x32_bf16 v[42:45], v[160:163], v[176:179], v[42:45]
	v_mfma_f32_16x16x32_bf16 v[34:37], v[152:155], v[186:189], v[34:37]
	v_mfma_f32_16x16x32_bf16 v[26:29], v[160:163], v[186:189], v[26:29]
	v_mfma_f32_16x16x32_bf16 v[18:21], v[152:155], v[194:197], v[18:21]
	v_mfma_f32_16x16x32_bf16 v[10:13], v[160:163], v[194:197], v[10:13]
	s_setprio 0
	s_barrier
	s_add_u32 s76, s26, 0x40000
	s_addc_u32 s77, s27, 0
	s_mov_b32 m0, s39
	v_lshl_add_u64 v[148:149], s[76:77], 0, v[0:1]
	global_load_lds_dwordx4 v[148:149], off
	v_lshl_add_u64 v[148:149], s[76:77], 0, v[134:135]
	s_mov_b32 m0, s60
	s_nop 0
	global_load_lds_dwordx4 v[148:149], off
	s_waitcnt vmcnt(6)
	s_barrier
	s_setprio 1
	v_mfma_f32_16x16x32_bf16 v[54:57], v[198:201], v[164:167], v[54:57]
	v_mfma_f32_16x16x32_bf16 v[46:49], v[206:209], v[164:167], v[46:49]
	v_mfma_f32_16x16x32_bf16 v[38:41], v[198:201], v[172:175], v[38:41]
	v_mfma_f32_16x16x32_bf16 v[30:33], v[206:209], v[172:175], v[30:33]
	v_mfma_f32_16x16x32_bf16 v[22:25], v[198:201], v[182:185], v[22:25]
	v_mfma_f32_16x16x32_bf16 v[14:17], v[206:209], v[182:185], v[14:17]
	v_mfma_f32_16x16x32_bf16 v[6:9], v[198:201], v[190:193], v[6:9]
	v_mfma_f32_16x16x32_bf16 v[2:5], v[206:209], v[190:193], v[2:5]
	v_mfma_f32_16x16x32_bf16 v[54:57], v[202:205], v[168:171], v[54:57]
	v_mfma_f32_16x16x32_bf16 v[46:49], v[210:213], v[168:171], v[46:49]
	v_mfma_f32_16x16x32_bf16 v[38:41], v[202:205], v[176:179], v[38:41]
	v_mfma_f32_16x16x32_bf16 v[30:33], v[210:213], v[176:179], v[30:33]
	v_mfma_f32_16x16x32_bf16 v[22:25], v[202:205], v[186:189], v[22:25]
	v_mfma_f32_16x16x32_bf16 v[14:17], v[210:213], v[186:189], v[14:17]
	v_mfma_f32_16x16x32_bf16 v[6:9], v[202:205], v[194:197], v[6:9]
	v_mfma_f32_16x16x32_bf16 v[2:5], v[210:213], v[194:197], v[2:5]
	s_setprio 0
	s_barrier
	ds_read_b128 v[148:151], v146
	ds_read_b128 v[152:155], v146 offset:1024
	ds_read_b128 v[156:159], v146 offset:2048
	ds_read_b128 v[160:163], v146 offset:3072
	s_add_u32 s28, s28, 0x40000
	s_addc_u32 s29, s29, 0
	s_mov_b32 m0, s68
	v_lshl_add_u64 v[198:199], s[28:29], 0, v[130:131]
	ds_read_b128 v[164:167], v142 offset:32768
	ds_read_b128 v[168:171], v142 offset:33792
	ds_read_b128 v[172:175], v142 offset:34816
	ds_read_b128 v[176:179], v142 offset:35840
	ds_read_b128 v[182:185], v142 offset:36864
	ds_read_b128 v[186:189], v142 offset:37888
	ds_read_b128 v[190:193], v142 offset:38912
	ds_read_b128 v[194:197], v142 offset:39936
	global_load_lds_dwordx4 v[198:199], off
	v_lshl_add_u64 v[198:199], s[28:29], 0, v[132:133]
	s_mov_b32 m0, s69
	s_nop 0
	global_load_lds_dwordx4 v[198:199], off
	s_waitcnt lgkmcnt(8)
	s_barrier
	s_waitcnt lgkmcnt(0)
	s_setprio 1
	s_waitcnt lgkmcnt(0)
	v_mfma_f32_16x16x32_bf16 v[126:129], v[148:151], v[164:167], v[126:129]
	v_mfma_f32_16x16x32_bf16 v[122:125], v[156:159], v[164:167], v[122:125]
	v_mfma_f32_16x16x32_bf16 v[114:117], v[148:151], v[172:175], v[114:117]
	v_mfma_f32_16x16x32_bf16 v[106:109], v[156:159], v[172:175], v[106:109]
	v_mfma_f32_16x16x32_bf16 v[98:101], v[148:151], v[182:185], v[98:101]
	v_mfma_f32_16x16x32_bf16 v[90:93], v[156:159], v[182:185], v[90:93]
	v_mfma_f32_16x16x32_bf16 v[82:85], v[148:151], v[190:193], v[82:85]
	v_mfma_f32_16x16x32_bf16 v[74:77], v[156:159], v[190:193], v[74:77]
	v_mfma_f32_16x16x32_bf16 v[126:129], v[152:155], v[168:171], v[126:129]
	v_mfma_f32_16x16x32_bf16 v[122:125], v[160:163], v[168:171], v[122:125]
	v_mfma_f32_16x16x32_bf16 v[114:117], v[152:155], v[176:179], v[114:117]
	v_mfma_f32_16x16x32_bf16 v[106:109], v[160:163], v[176:179], v[106:109]
	v_mfma_f32_16x16x32_bf16 v[98:101], v[152:155], v[186:189], v[98:101]
	v_mfma_f32_16x16x32_bf16 v[90:93], v[160:163], v[186:189], v[90:93]
	v_mfma_f32_16x16x32_bf16 v[82:85], v[152:155], v[194:197], v[82:85]
	v_mfma_f32_16x16x32_bf16 v[74:77], v[160:163], v[194:197], v[74:77]
	s_setprio 0
	s_barrier
	s_mov_b32 m0, s75
	v_lshl_add_u64 v[214:215], v[214:215], 0, s[84:85]
	ds_read_b128 v[198:201], v147
	ds_read_b128 v[202:205], v147 offset:1024
	ds_read_b128 v[206:209], v147 offset:2048
	ds_read_b128 v[210:213], v147 offset:3072
	global_load_lds_dwordx4 v[214:215], off
	v_lshl_add_u64 v[214:215], v[216:217], 0, s[84:85]
	s_mov_b32 m0, s82
	s_nop 0
	global_load_lds_dwordx4 v[214:215], off
	s_barrier
	s_waitcnt lgkmcnt(0)
	s_setprio 1
	s_waitcnt lgkmcnt(0)
	v_mfma_f32_16x16x32_bf16 v[118:121], v[198:201], v[164:167], v[118:121]
	v_mfma_f32_16x16x32_bf16 v[110:113], v[206:209], v[164:167], v[110:113]
	v_mfma_f32_16x16x32_bf16 v[102:105], v[198:201], v[172:175], v[102:105]
	v_mfma_f32_16x16x32_bf16 v[94:97], v[206:209], v[172:175], v[94:97]
	v_mfma_f32_16x16x32_bf16 v[86:89], v[198:201], v[182:185], v[86:89]
	v_mfma_f32_16x16x32_bf16 v[78:81], v[206:209], v[182:185], v[78:81]
	v_mfma_f32_16x16x32_bf16 v[70:73], v[198:201], v[190:193], v[70:73]
	v_mfma_f32_16x16x32_bf16 v[66:69], v[206:209], v[190:193], v[66:69]
	v_mfma_f32_16x16x32_bf16 v[118:121], v[202:205], v[168:171], v[118:121]
	v_mfma_f32_16x16x32_bf16 v[110:113], v[210:213], v[168:171], v[110:113]
	v_mfma_f32_16x16x32_bf16 v[102:105], v[202:205], v[176:179], v[102:105]
	v_mfma_f32_16x16x32_bf16 v[94:97], v[210:213], v[176:179], v[94:97]
	v_mfma_f32_16x16x32_bf16 v[86:89], v[202:205], v[186:189], v[86:89]
	v_mfma_f32_16x16x32_bf16 v[78:81], v[210:213], v[186:189], v[78:81]
	v_mfma_f32_16x16x32_bf16 v[70:73], v[202:205], v[194:197], v[70:73]
	v_mfma_f32_16x16x32_bf16 v[66:69], v[210:213], v[194:197], v[66:69]
	s_setprio 0
	s_mov_b32 m0, s92
	v_lshl_add_u64 v[214:215], v[222:223], 0, s[84:85]
	s_barrier
	ds_read_b128 v[164:167], v142 offset:49152
	ds_read_b128 v[168:171], v142 offset:50176
	ds_read_b128 v[172:175], v142 offset:51200
	ds_read_b128 v[176:179], v142 offset:52224
	ds_read_b128 v[182:185], v142 offset:53248
	ds_read_b128 v[186:189], v142 offset:54272
	ds_read_b128 v[190:193], v142 offset:55296
	ds_read_b128 v[194:197], v142 offset:56320
	global_load_lds_dwordx4 v[214:215], off
	v_lshl_add_u64 v[214:215], v[224:225], 0, s[84:85]
	s_mov_b32 m0, s93
	s_nop 0
	global_load_lds_dwordx4 v[214:215], off
	s_barrier
	s_waitcnt lgkmcnt(0)
	s_setprio 1
	s_waitcnt lgkmcnt(0)
	v_mfma_f32_16x16x32_bf16 v[62:65], v[148:151], v[164:167], v[62:65]
	v_mfma_f32_16x16x32_bf16 v[58:61], v[156:159], v[164:167], v[58:61]
	v_mfma_f32_16x16x32_bf16 v[50:53], v[148:151], v[172:175], v[50:53]
	v_mfma_f32_16x16x32_bf16 v[42:45], v[156:159], v[172:175], v[42:45]
	v_mfma_f32_16x16x32_bf16 v[34:37], v[148:151], v[182:185], v[34:37]
	v_mfma_f32_16x16x32_bf16 v[26:29], v[156:159], v[182:185], v[26:29]
	v_mfma_f32_16x16x32_bf16 v[18:21], v[148:151], v[190:193], v[18:21]
	v_mfma_f32_16x16x32_bf16 v[10:13], v[156:159], v[190:193], v[10:13]
	v_mfma_f32_16x16x32_bf16 v[62:65], v[152:155], v[168:171], v[62:65]
	v_mfma_f32_16x16x32_bf16 v[58:61], v[160:163], v[168:171], v[58:61]
	v_mfma_f32_16x16x32_bf16 v[50:53], v[152:155], v[176:179], v[50:53]
	v_mfma_f32_16x16x32_bf16 v[42:45], v[160:163], v[176:179], v[42:45]
	v_mfma_f32_16x16x32_bf16 v[34:37], v[152:155], v[186:189], v[34:37]
	v_mfma_f32_16x16x32_bf16 v[26:29], v[160:163], v[186:189], v[26:29]
	v_mfma_f32_16x16x32_bf16 v[18:21], v[152:155], v[194:197], v[18:21]
	v_mfma_f32_16x16x32_bf16 v[10:13], v[160:163], v[194:197], v[10:13]
	s_setprio 0
	s_barrier
	s_add_u32 s26, s26, 0x40080
	s_addc_u32 s27, s27, 0
	s_mov_b32 m0, s96
	v_lshl_add_u64 v[148:149], s[26:27], 0, v[0:1]
	global_load_lds_dwordx4 v[148:149], off
	v_lshl_add_u64 v[148:149], s[26:27], 0, v[134:135]
	s_mov_b32 m0, s97
	s_nop 0
	global_load_lds_dwordx4 v[148:149], off
	s_waitcnt vmcnt(6)
	s_barrier
	s_setprio 1
	v_mfma_f32_16x16x32_bf16 v[54:57], v[198:201], v[164:167], v[54:57]
	v_mfma_f32_16x16x32_bf16 v[46:49], v[206:209], v[164:167], v[46:49]
	v_mfma_f32_16x16x32_bf16 v[38:41], v[198:201], v[172:175], v[38:41]
	v_mfma_f32_16x16x32_bf16 v[30:33], v[206:209], v[172:175], v[30:33]
	v_mfma_f32_16x16x32_bf16 v[22:25], v[198:201], v[182:185], v[22:25]
	v_mfma_f32_16x16x32_bf16 v[14:17], v[206:209], v[182:185], v[14:17]
	v_mfma_f32_16x16x32_bf16 v[6:9], v[198:201], v[190:193], v[6:9]
	v_mfma_f32_16x16x32_bf16 v[2:5], v[206:209], v[190:193], v[2:5]
	v_mfma_f32_16x16x32_bf16 v[54:57], v[202:205], v[168:171], v[54:57]
	v_mfma_f32_16x16x32_bf16 v[46:49], v[210:213], v[168:171], v[46:49]
	v_mfma_f32_16x16x32_bf16 v[38:41], v[202:205], v[176:179], v[38:41]
	v_mfma_f32_16x16x32_bf16 v[30:33], v[210:213], v[176:179], v[30:33]
	v_mfma_f32_16x16x32_bf16 v[22:25], v[202:205], v[186:189], v[22:25]
	v_mfma_f32_16x16x32_bf16 v[14:17], v[210:213], v[186:189], v[14:17]
	v_mfma_f32_16x16x32_bf16 v[6:9], v[202:205], v[194:197], v[6:9]
	v_mfma_f32_16x16x32_bf16 v[2:5], v[210:213], v[194:197], v[2:5]
	s_setprio 0
	s_add_i32 s62, s62, 2
	s_add_u32 s24, s24, 0x100
	s_addc_u32 s25, s25, 0
	s_add_u32 vcc_lo, vcc_lo, 0x100
	s_addc_u32 vcc_hi, vcc_hi, 0
	s_cmp_gt_u32 s62, 13
	s_barrier
	s_cbranch_scc0 .LBB0_733
	v_lshl_add_u32 v149, s6, 8, v143
	v_add_u32_e32 v140, -8, v149
	v_lshl_add_u32 v148, s22, 8, v141
	v_cmp_gt_u32_e32 vcc, s71, v140
	s_and_saveexec_b64 s[6:7], vcc
	s_cbranch_execz .LBB0_736
	v_cvt_pk_bf16_f32 v126, v126, v127
	v_cvt_pk_bf16_f32 v127, v128, v129
	v_cvt_pk_bf16_f32 v128, v122, v123
	v_cvt_pk_bf16_f32 v129, v124, v125
	v_mad_u64_u32 v[122:123], s[22:23], v148, s71, v[140:141]
	v_mov_b32_e32 v123, v1
	v_lshl_add_u64 v[122:123], v[122:123], 1, s[10:11]
	global_store_dwordx4 v[122:123], v[126:129], off

.LBB0_781:
	v_add_u32_e32 v140, 0x10000, v143
	ds_read_b128 v[146:149], v140
	ds_read_b128 v[150:153], v140 offset:1024
	ds_read_b128 v[154:157], v140 offset:2048
	ds_read_b128 v[158:161], v140 offset:3072
	s_add_u32 s26, s24, 0xfffc0080
	s_addc_u32 s27, s25, -1
	s_cmp_eq_u32 vcc_lo, 12
	s_cselect_b32 s29, s7, s27
	s_cselect_b32 s28, s17, s26
	s_cselect_b32 s27, s15, s94
	s_cselect_b32 s26, s23, s89
	v_lshl_add_u64 v[178:179], s[24:25], 0, v[136:137]
	s_add_i32 m0, s30, 0xc000
	ds_read_b128 v[162:165], v142
	ds_read_b128 v[166:169], v142 offset:1024
	ds_read_b128 v[170:173], v142 offset:2048
	ds_read_b128 v[174:177], v142 offset:3072
	ds_read_b128 v[182:185], v142 offset:4096
	ds_read_b128 v[186:189], v142 offset:5120
	ds_read_b128 v[190:193], v142 offset:6144
	ds_read_b128 v[194:197], v142 offset:7168
	global_load_lds_dwordx4 v[178:179], off
	v_lshl_add_u64 v[178:179], s[24:25], 0, v[138:139]
	s_add_i32 m0, s30, 0xe000
	s_nop 0
	global_load_lds_dwordx4 v[178:179], off
	s_waitcnt lgkmcnt(8)
	s_barrier
	s_waitcnt lgkmcnt(0)
	s_setprio 1
	s_waitcnt lgkmcnt(0)
	v_mfma_f32_16x16x32_bf16 v[126:129], v[146:149], v[162:165], v[126:129]
	v_mfma_f32_16x16x32_bf16 v[122:125], v[154:157], v[162:165], v[122:125]
	v_mfma_f32_16x16x32_bf16 v[114:117], v[146:149], v[170:173], v[114:117]
	v_mfma_f32_16x16x32_bf16 v[106:109], v[154:157], v[170:173], v[106:109]
	v_mfma_f32_16x16x32_bf16 v[98:101], v[146:149], v[182:185], v[98:101]
	v_mfma_f32_16x16x32_bf16 v[90:93], v[154:157], v[182:185], v[90:93]
	v_mfma_f32_16x16x32_bf16 v[82:85], v[146:149], v[190:193], v[82:85]
	v_mfma_f32_16x16x32_bf16 v[74:77], v[154:157], v[190:193], v[74:77]
	v_mfma_f32_16x16x32_bf16 v[126:129], v[150:153], v[166:169], v[126:129]
	v_mfma_f32_16x16x32_bf16 v[122:125], v[158:161], v[166:169], v[122:125]
	v_mfma_f32_16x16x32_bf16 v[114:117], v[150:153], v[174:177], v[114:117]
	v_mfma_f32_16x16x32_bf16 v[106:109], v[158:161], v[174:177], v[106:109]
	v_mfma_f32_16x16x32_bf16 v[98:101], v[150:153], v[186:189], v[98:101]
	v_mfma_f32_16x16x32_bf16 v[90:93], v[158:161], v[186:189], v[90:93]
	v_mfma_f32_16x16x32_bf16 v[82:85], v[150:153], v[194:197], v[82:85]
	v_mfma_f32_16x16x32_bf16 v[74:77], v[158:161], v[194:197], v[74:77]
	s_setprio 0
	s_barrier
	s_mov_b32 m0, s35
	v_add_u32_e32 v140, 0x14000, v143
	v_lshl_add_u64 v[178:179], s[26:27], 0, v[0:1]
	ds_read_b128 v[198:201], v140
	ds_read_b128 v[202:205], v140 offset:1024
	ds_read_b128 v[206:209], v140 offset:2048
	ds_read_b128 v[210:213], v140 offset:3072
	global_load_lds_dwordx4 v[178:179], off
	v_lshl_add_u64 v[214:215], s[26:27], 0, v[134:135]
	s_mov_b32 m0, s36
	s_nop 0
	global_load_lds_dwordx4 v[214:215], off
	s_barrier
	s_waitcnt lgkmcnt(0)
	s_setprio 1
	s_waitcnt lgkmcnt(0)
	v_mfma_f32_16x16x32_bf16 v[118:121], v[198:201], v[162:165], v[118:121]
	v_mfma_f32_16x16x32_bf16 v[110:113], v[206:209], v[162:165], v[110:113]
	v_mfma_f32_16x16x32_bf16 v[102:105], v[198:201], v[170:173], v[102:105]
	v_mfma_f32_16x16x32_bf16 v[94:97], v[206:209], v[170:173], v[94:97]
	v_mfma_f32_16x16x32_bf16 v[86:89], v[198:201], v[182:185], v[86:89]
	v_mfma_f32_16x16x32_bf16 v[78:81], v[206:209], v[182:185], v[78:81]
	v_mfma_f32_16x16x32_bf16 v[70:73], v[198:201], v[190:193], v[70:73]
	v_mfma_f32_16x16x32_bf16 v[66:69], v[206:209], v[190:193], v[66:69]
	v_mfma_f32_16x16x32_bf16 v[118:121], v[202:205], v[166:169], v[118:121]
	v_mfma_f32_16x16x32_bf16 v[110:113], v[210:213], v[166:169], v[110:113]
	v_mfma_f32_16x16x32_bf16 v[102:105], v[202:205], v[174:177], v[102:105]
	v_mfma_f32_16x16x32_bf16 v[94:97], v[210:213], v[174:177], v[94:97]
	v_mfma_f32_16x16x32_bf16 v[86:89], v[202:205], v[186:189], v[86:89]
	v_mfma_f32_16x16x32_bf16 v[78:81], v[210:213], v[186:189], v[78:81]
	v_mfma_f32_16x16x32_bf16 v[70:73], v[202:205], v[194:197], v[70:73]
	v_mfma_f32_16x16x32_bf16 v[66:69], v[210:213], v[194:197], v[66:69]
	s_setprio 0
	s_mov_b32 m0, s30
	v_lshl_add_u64 v[216:217], s[28:29], 0, v[130:131]
	s_barrier
	ds_read_b128 v[162:165], v142 offset:16384
	ds_read_b128 v[166:169], v142 offset:17408
	ds_read_b128 v[170:173], v142 offset:18432
	ds_read_b128 v[174:177], v142 offset:19456
	ds_read_b128 v[182:185], v142 offset:20480
	ds_read_b128 v[186:189], v142 offset:21504
	ds_read_b128 v[190:193], v142 offset:22528
	ds_read_b128 v[194:197], v142 offset:23552
	global_load_lds_dwordx4 v[216:217], off
	v_lshl_add_u64 v[222:223], s[28:29], 0, v[132:133]
	s_mov_b32 m0, s37
	s_nop 0
	global_load_lds_dwordx4 v[222:223], off
	s_barrier
	s_waitcnt lgkmcnt(0)
	s_setprio 1
	s_waitcnt lgkmcnt(0)
	v_mfma_f32_16x16x32_bf16 v[62:65], v[146:149], v[162:165], v[62:65]
	v_mfma_f32_16x16x32_bf16 v[58:61], v[154:157], v[162:165], v[58:61]
	v_mfma_f32_16x16x32_bf16 v[50:53], v[146:149], v[170:173], v[50:53]
	v_mfma_f32_16x16x32_bf16 v[42:45], v[154:157], v[170:173], v[42:45]
	v_mfma_f32_16x16x32_bf16 v[34:37], v[146:149], v[182:185], v[34:37]
	v_mfma_f32_16x16x32_bf16 v[26:29], v[154:157], v[182:185], v[26:29]
	v_mfma_f32_16x16x32_bf16 v[18:21], v[146:149], v[190:193], v[18:21]
	v_mfma_f32_16x16x32_bf16 v[10:13], v[154:157], v[190:193], v[10:13]
	v_mfma_f32_16x16x32_bf16 v[62:65], v[150:153], v[166:169], v[62:65]
	v_mfma_f32_16x16x32_bf16 v[58:61], v[158:161], v[166:169], v[58:61]
	v_mfma_f32_16x16x32_bf16 v[50:53], v[150:153], v[174:177], v[50:53]
	v_mfma_f32_16x16x32_bf16 v[42:45], v[158:161], v[174:177], v[42:45]
	v_mfma_f32_16x16x32_bf16 v[34:37], v[150:153], v[186:189], v[34:37]
	v_mfma_f32_16x16x32_bf16 v[26:29], v[158:161], v[186:189], v[26:29]
	v_mfma_f32_16x16x32_bf16 v[18:21], v[150:153], v[194:197], v[18:21]
	v_mfma_f32_16x16x32_bf16 v[10:13], v[158:161], v[194:197], v[10:13]
	s_setprio 0
	s_barrier
	s_add_u32 s76, s26, 0x40000
	s_addc_u32 s77, s27, 0
	s_mov_b32 m0, s38
	v_lshl_add_u64 v[146:147], s[76:77], 0, v[0:1]
	global_load_lds_dwordx4 v[146:147], off
	v_lshl_add_u64 v[146:147], s[76:77], 0, v[134:135]
	s_mov_b32 m0, s39
	s_nop 0
	global_load_lds_dwordx4 v[146:147], off
	s_waitcnt vmcnt(6)
	s_barrier
	s_setprio 1
	v_mfma_f32_16x16x32_bf16 v[54:57], v[198:201], v[162:165], v[54:57]
	v_mfma_f32_16x16x32_bf16 v[46:49], v[206:209], v[162:165], v[46:49]
	v_mfma_f32_16x16x32_bf16 v[38:41], v[198:201], v[170:173], v[38:41]
	v_mfma_f32_16x16x32_bf16 v[30:33], v[206:209], v[170:173], v[30:33]
	v_mfma_f32_16x16x32_bf16 v[22:25], v[198:201], v[182:185], v[22:25]
	v_mfma_f32_16x16x32_bf16 v[14:17], v[206:209], v[182:185], v[14:17]
	v_mfma_f32_16x16x32_bf16 v[6:9], v[198:201], v[190:193], v[6:9]
	v_mfma_f32_16x16x32_bf16 v[2:5], v[206:209], v[190:193], v[2:5]
	v_mfma_f32_16x16x32_bf16 v[54:57], v[202:205], v[166:169], v[54:57]
	v_mfma_f32_16x16x32_bf16 v[46:49], v[210:213], v[166:169], v[46:49]
	v_mfma_f32_16x16x32_bf16 v[38:41], v[202:205], v[174:177], v[38:41]
	v_mfma_f32_16x16x32_bf16 v[30:33], v[210:213], v[174:177], v[30:33]
	v_mfma_f32_16x16x32_bf16 v[22:25], v[202:205], v[186:189], v[22:25]
	v_mfma_f32_16x16x32_bf16 v[14:17], v[210:213], v[186:189], v[14:17]
	v_mfma_f32_16x16x32_bf16 v[6:9], v[202:205], v[194:197], v[6:9]
	v_mfma_f32_16x16x32_bf16 v[2:5], v[210:213], v[194:197], v[2:5]
	s_setprio 0
	v_add_u32_e32 v140, 0x18000, v143
	s_barrier
	ds_read_b128 v[146:149], v140
	ds_read_b128 v[150:153], v140 offset:1024
	ds_read_b128 v[154:157], v140 offset:2048
	ds_read_b128 v[158:161], v140 offset:3072
	s_add_u32 s28, s28, 0x40000
	s_addc_u32 s29, s29, 0
	s_mov_b32 m0, s60
	v_lshl_add_u64 v[198:199], s[28:29], 0, v[130:131]
	ds_read_b128 v[162:165], v142 offset:32768
	ds_read_b128 v[166:169], v142 offset:33792
	ds_read_b128 v[170:173], v142 offset:34816
	ds_read_b128 v[174:177], v142 offset:35840
	ds_read_b128 v[182:185], v142 offset:36864
	ds_read_b128 v[186:189], v142 offset:37888
	ds_read_b128 v[190:193], v142 offset:38912
	ds_read_b128 v[194:197], v142 offset:39936
	global_load_lds_dwordx4 v[198:199], off
	v_lshl_add_u64 v[198:199], s[28:29], 0, v[132:133]
	s_mov_b32 m0, s68
	s_nop 0
	global_load_lds_dwordx4 v[198:199], off
	s_waitcnt lgkmcnt(8)
	s_barrier
	s_waitcnt lgkmcnt(0)
	s_setprio 1
	s_waitcnt lgkmcnt(0)
	v_mfma_f32_16x16x32_bf16 v[126:129], v[146:149], v[162:165], v[126:129]
	v_mfma_f32_16x16x32_bf16 v[122:125], v[154:157], v[162:165], v[122:125]
	v_mfma_f32_16x16x32_bf16 v[114:117], v[146:149], v[170:173], v[114:117]
	v_mfma_f32_16x16x32_bf16 v[106:109], v[154:157], v[170:173], v[106:109]
	v_mfma_f32_16x16x32_bf16 v[98:101], v[146:149], v[182:185], v[98:101]
	v_mfma_f32_16x16x32_bf16 v[90:93], v[154:157], v[182:185], v[90:93]
	v_mfma_f32_16x16x32_bf16 v[82:85], v[146:149], v[190:193], v[82:85]
	v_mfma_f32_16x16x32_bf16 v[74:77], v[154:157], v[190:193], v[74:77]
	v_mfma_f32_16x16x32_bf16 v[126:129], v[150:153], v[166:169], v[126:129]
	v_mfma_f32_16x16x32_bf16 v[122:125], v[158:161], v[166:169], v[122:125]
	v_mfma_f32_16x16x32_bf16 v[114:117], v[150:153], v[174:177], v[114:117]
	v_mfma_f32_16x16x32_bf16 v[106:109], v[158:161], v[174:177], v[106:109]
	v_mfma_f32_16x16x32_bf16 v[98:101], v[150:153], v[186:189], v[98:101]
	v_mfma_f32_16x16x32_bf16 v[90:93], v[158:161], v[186:189], v[90:93]
	v_mfma_f32_16x16x32_bf16 v[82:85], v[150:153], v[194:197], v[82:85]
	v_mfma_f32_16x16x32_bf16 v[74:77], v[158:161], v[194:197], v[74:77]
	s_setprio 0
	s_barrier
	s_mov_b32 m0, s75
	v_add_u32_e32 v140, 0x1c000, v143
	v_lshl_add_u64 v[178:179], v[178:179], 0, s[84:85]
	ds_read_b128 v[198:201], v140
	ds_read_b128 v[202:205], v140 offset:1024
	ds_read_b128 v[206:209], v140 offset:2048
	ds_read_b128 v[210:213], v140 offset:3072
	global_load_lds_dwordx4 v[178:179], off
	v_lshl_add_u64 v[178:179], v[214:215], 0, s[84:85]
	s_mov_b32 m0, s82
	s_nop 0
	global_load_lds_dwordx4 v[178:179], off
	s_barrier
	s_waitcnt lgkmcnt(0)
	s_setprio 1
	s_waitcnt lgkmcnt(0)
	v_mfma_f32_16x16x32_bf16 v[118:121], v[198:201], v[162:165], v[118:121]
	v_mfma_f32_16x16x32_bf16 v[110:113], v[206:209], v[162:165], v[110:113]
	v_mfma_f32_16x16x32_bf16 v[102:105], v[198:201], v[170:173], v[102:105]
	v_mfma_f32_16x16x32_bf16 v[94:97], v[206:209], v[170:173], v[94:97]
	v_mfma_f32_16x16x32_bf16 v[86:89], v[198:201], v[182:185], v[86:89]
	v_mfma_f32_16x16x32_bf16 v[78:81], v[206:209], v[182:185], v[78:81]
	v_mfma_f32_16x16x32_bf16 v[70:73], v[198:201], v[190:193], v[70:73]
	v_mfma_f32_16x16x32_bf16 v[66:69], v[206:209], v[190:193], v[66:69]
	v_mfma_f32_16x16x32_bf16 v[118:121], v[202:205], v[166:169], v[118:121]
	v_mfma_f32_16x16x32_bf16 v[110:113], v[210:213], v[166:169], v[110:113]
	v_mfma_f32_16x16x32_bf16 v[102:105], v[202:205], v[174:177], v[102:105]
	v_mfma_f32_16x16x32_bf16 v[94:97], v[210:213], v[174:177], v[94:97]
	v_mfma_f32_16x16x32_bf16 v[86:89], v[202:205], v[186:189], v[86:89]
	v_mfma_f32_16x16x32_bf16 v[78:81], v[210:213], v[186:189], v[78:81]
	v_mfma_f32_16x16x32_bf16 v[70:73], v[202:205], v[194:197], v[70:73]
	v_mfma_f32_16x16x32_bf16 v[66:69], v[210:213], v[194:197], v[66:69]
	s_setprio 0
	s_mov_b32 m0, s92
	v_lshl_add_u64 v[178:179], v[216:217], 0, s[84:85]
	s_barrier
	ds_read_b128 v[162:165], v142 offset:49152
	ds_read_b128 v[166:169], v142 offset:50176
	ds_read_b128 v[170:173], v142 offset:51200
	ds_read_b128 v[174:177], v142 offset:52224
	ds_read_b128 v[182:185], v142 offset:53248
	ds_read_b128 v[186:189], v142 offset:54272
	ds_read_b128 v[190:193], v142 offset:55296
	ds_read_b128 v[194:197], v142 offset:56320
	global_load_lds_dwordx4 v[178:179], off
	v_lshl_add_u64 v[178:179], v[222:223], 0, s[84:85]
	s_mov_b32 m0, s93
	s_nop 0
	global_load_lds_dwordx4 v[178:179], off
	s_barrier
	s_waitcnt lgkmcnt(0)
	s_setprio 1
	s_waitcnt lgkmcnt(0)
	v_mfma_f32_16x16x32_bf16 v[62:65], v[146:149], v[162:165], v[62:65]
	v_mfma_f32_16x16x32_bf16 v[58:61], v[154:157], v[162:165], v[58:61]
	v_mfma_f32_16x16x32_bf16 v[50:53], v[146:149], v[170:173], v[50:53]
	v_mfma_f32_16x16x32_bf16 v[42:45], v[154:157], v[170:173], v[42:45]
	v_mfma_f32_16x16x32_bf16 v[34:37], v[146:149], v[182:185], v[34:37]
	v_mfma_f32_16x16x32_bf16 v[26:29], v[154:157], v[182:185], v[26:29]
	v_mfma_f32_16x16x32_bf16 v[18:21], v[146:149], v[190:193], v[18:21]
	v_mfma_f32_16x16x32_bf16 v[10:13], v[154:157], v[190:193], v[10:13]
	v_mfma_f32_16x16x32_bf16 v[62:65], v[150:153], v[166:169], v[62:65]
	v_mfma_f32_16x16x32_bf16 v[58:61], v[158:161], v[166:169], v[58:61]
	v_mfma_f32_16x16x32_bf16 v[50:53], v[150:153], v[174:177], v[50:53]
	v_mfma_f32_16x16x32_bf16 v[42:45], v[158:161], v[174:177], v[42:45]
	v_mfma_f32_16x16x32_bf16 v[34:37], v[150:153], v[186:189], v[34:37]
	v_mfma_f32_16x16x32_bf16 v[26:29], v[158:161], v[186:189], v[26:29]
	v_mfma_f32_16x16x32_bf16 v[18:21], v[150:153], v[194:197], v[18:21]
	v_mfma_f32_16x16x32_bf16 v[10:13], v[158:161], v[194:197], v[10:13]
	s_setprio 0
	s_barrier
	s_add_u32 s26, s26, 0x40080
	s_addc_u32 s27, s27, 0
	s_mov_b32 m0, s96
	v_lshl_add_u64 v[146:147], s[26:27], 0, v[0:1]
	global_load_lds_dwordx4 v[146:147], off
	v_lshl_add_u64 v[146:147], s[26:27], 0, v[134:135]
	s_mov_b32 m0, s97
	s_nop 0
	global_load_lds_dwordx4 v[146:147], off
	s_waitcnt vmcnt(6)
	s_barrier
	s_setprio 1
	v_mfma_f32_16x16x32_bf16 v[54:57], v[198:201], v[162:165], v[54:57]
	v_mfma_f32_16x16x32_bf16 v[46:49], v[206:209], v[162:165], v[46:49]
	v_mfma_f32_16x16x32_bf16 v[38:41], v[198:201], v[170:173], v[38:41]
	v_mfma_f32_16x16x32_bf16 v[30:33], v[206:209], v[170:173], v[30:33]
	v_mfma_f32_16x16x32_bf16 v[22:25], v[198:201], v[182:185], v[22:25]
	v_mfma_f32_16x16x32_bf16 v[14:17], v[206:209], v[182:185], v[14:17]
	v_mfma_f32_16x16x32_bf16 v[6:9], v[198:201], v[190:193], v[6:9]
	v_mfma_f32_16x16x32_bf16 v[2:5], v[206:209], v[190:193], v[2:5]
	v_mfma_f32_16x16x32_bf16 v[54:57], v[202:205], v[166:169], v[54:57]
	v_mfma_f32_16x16x32_bf16 v[46:49], v[210:213], v[166:169], v[46:49]
	v_mfma_f32_16x16x32_bf16 v[38:41], v[202:205], v[174:177], v[38:41]
	v_mfma_f32_16x16x32_bf16 v[30:33], v[210:213], v[174:177], v[30:33]
	v_mfma_f32_16x16x32_bf16 v[22:25], v[202:205], v[186:189], v[22:25]
	v_mfma_f32_16x16x32_bf16 v[14:17], v[210:213], v[186:189], v[14:17]
	v_mfma_f32_16x16x32_bf16 v[6:9], v[202:205], v[194:197], v[6:9]
	v_mfma_f32_16x16x32_bf16 v[2:5], v[210:213], v[194:197], v[2:5]
	s_setprio 0
	s_add_i32 vcc_lo, vcc_lo, 2
	s_add_u32 s24, s24, 0x100
	s_addc_u32 s25, s25, 0
	s_add_u32 s89, s89, 0x100
	s_addc_u32 s94, s94, 0
	s_cmp_gt_u32 vcc_lo, 13
	s_barrier
	s_cbranch_scc0 .LBB0_781
	s_cmp_lt_i32 s22, s69
	s_cselect_b64 s[24:25], -1, 0
	s_and_b64 s[24:25], s[24:25], exec
	s_cselect_b32 s7, 0, s69
	v_lshl_add_u32 v146, s6, 8, v144
	s_cselect_b32 s25, s9, s11
	s_cselect_b32 s24, s8, s10
	s_sub_i32 s7, s22, s7
	v_add_u32_e32 v140, -8, v146
	v_lshl_add_u32 v145, s7, 8, v141
	v_cmp_gt_u32_e32 vcc, s71, v140
	s_and_saveexec_b64 s[6:7], vcc
	s_cbranch_execz .LBB0_784
	v_cvt_pk_bf16_f32 v126, v126, v127
	v_cvt_pk_bf16_f32 v127, v128, v129
	v_cvt_pk_bf16_f32 v128, v122, v123
	v_cvt_pk_bf16_f32 v129, v124, v125
	v_mad_u64_u32 v[122:123], s[22:23], v145, s71, v[140:141]
	v_mov_b32_e32 v123, v1
	v_lshl_add_u64 v[122:123], v[122:123], 1, s[24:25]
	global_store_dwordx4 v[122:123], v[126:129], off

.LBB0_926:
	v_add_u32_e32 v140, 0x10000, v143
	ds_read_b128 v[146:149], v140
	ds_read_b128 v[150:153], v140 offset:1024
	ds_read_b128 v[154:157], v140 offset:2048
	ds_read_b128 v[158:161], v140 offset:3072
	s_add_u32 s6, s20, 0x100
	s_addc_u32 s7, s21, 0
	s_cmp_eq_u32 s96, 2
	s_cselect_b32 s25, s17, s7
	s_cselect_b32 s24, s16, s6
	s_cselect_b32 s23, s19, s94
	s_cselect_b32 s22, s18, s93
	v_lshl_add_u64 v[178:179], s[20:21], 0, v[136:137]
	s_add_i32 m0, s27, 0xc000
	ds_read_b128 v[162:165], v142
	ds_read_b128 v[166:169], v142 offset:1024
	ds_read_b128 v[170:173], v142 offset:2048
	ds_read_b128 v[174:177], v142 offset:3072
	ds_read_b128 v[182:185], v142 offset:4096
	ds_read_b128 v[186:189], v142 offset:5120
	ds_read_b128 v[190:193], v142 offset:6144
	ds_read_b128 v[194:197], v142 offset:7168
	global_load_lds_dwordx4 v[178:179], off
	v_lshl_add_u64 v[178:179], s[20:21], 0, v[138:139]
	s_add_i32 m0, s27, 0xe000
	s_nop 0
	global_load_lds_dwordx4 v[178:179], off
	s_waitcnt lgkmcnt(8)
	s_barrier
	s_waitcnt lgkmcnt(0)
	s_setprio 1
	s_waitcnt lgkmcnt(0)
	v_mfma_f32_16x16x32_bf16 v[126:129], v[146:149], v[162:165], v[126:129]
	v_mfma_f32_16x16x32_bf16 v[122:125], v[154:157], v[162:165], v[122:125]
	v_mfma_f32_16x16x32_bf16 v[114:117], v[146:149], v[170:173], v[114:117]
	v_mfma_f32_16x16x32_bf16 v[106:109], v[154:157], v[170:173], v[106:109]
	v_mfma_f32_16x16x32_bf16 v[98:101], v[146:149], v[182:185], v[98:101]
	v_mfma_f32_16x16x32_bf16 v[90:93], v[154:157], v[182:185], v[90:93]
	v_mfma_f32_16x16x32_bf16 v[82:85], v[146:149], v[190:193], v[82:85]
	v_mfma_f32_16x16x32_bf16 v[74:77], v[154:157], v[190:193], v[74:77]
	v_mfma_f32_16x16x32_bf16 v[126:129], v[150:153], v[166:169], v[126:129]
	v_mfma_f32_16x16x32_bf16 v[122:125], v[158:161], v[166:169], v[122:125]
	v_mfma_f32_16x16x32_bf16 v[114:117], v[150:153], v[174:177], v[114:117]
	v_mfma_f32_16x16x32_bf16 v[106:109], v[158:161], v[174:177], v[106:109]
	v_mfma_f32_16x16x32_bf16 v[98:101], v[150:153], v[186:189], v[98:101]
	v_mfma_f32_16x16x32_bf16 v[90:93], v[158:161], v[186:189], v[90:93]
	v_mfma_f32_16x16x32_bf16 v[82:85], v[150:153], v[194:197], v[82:85]
	v_mfma_f32_16x16x32_bf16 v[74:77], v[158:161], v[194:197], v[74:77]
	s_setprio 0
	s_barrier
	s_mov_b32 m0, s28
	v_add_u32_e32 v140, 0x14000, v143
	v_lshl_add_u64 v[178:179], s[22:23], 0, v[0:1]
	ds_read_b128 v[198:201], v140
	ds_read_b128 v[202:205], v140 offset:1024
	ds_read_b128 v[206:209], v140 offset:2048
	ds_read_b128 v[210:213], v140 offset:3072
	global_load_lds_dwordx4 v[178:179], off
	v_lshl_add_u64 v[214:215], s[22:23], 0, v[134:135]
	s_mov_b32 m0, s29
	s_nop 0
	global_load_lds_dwordx4 v[214:215], off
	s_barrier
	s_waitcnt lgkmcnt(0)
	s_setprio 1
	s_waitcnt lgkmcnt(0)
	v_mfma_f32_16x16x32_bf16 v[118:121], v[198:201], v[162:165], v[118:121]
	v_mfma_f32_16x16x32_bf16 v[110:113], v[206:209], v[162:165], v[110:113]
	v_mfma_f32_16x16x32_bf16 v[102:105], v[198:201], v[170:173], v[102:105]
	v_mfma_f32_16x16x32_bf16 v[94:97], v[206:209], v[170:173], v[94:97]
	v_mfma_f32_16x16x32_bf16 v[86:89], v[198:201], v[182:185], v[86:89]
	v_mfma_f32_16x16x32_bf16 v[78:81], v[206:209], v[182:185], v[78:81]
	v_mfma_f32_16x16x32_bf16 v[70:73], v[198:201], v[190:193], v[70:73]
	v_mfma_f32_16x16x32_bf16 v[66:69], v[206:209], v[190:193], v[66:69]
	v_mfma_f32_16x16x32_bf16 v[118:121], v[202:205], v[166:169], v[118:121]
	v_mfma_f32_16x16x32_bf16 v[110:113], v[210:213], v[166:169], v[110:113]
	v_mfma_f32_16x16x32_bf16 v[102:105], v[202:205], v[174:177], v[102:105]
	v_mfma_f32_16x16x32_bf16 v[94:97], v[210:213], v[174:177], v[94:97]
	v_mfma_f32_16x16x32_bf16 v[86:89], v[202:205], v[186:189], v[86:89]
	v_mfma_f32_16x16x32_bf16 v[78:81], v[210:213], v[186:189], v[78:81]
	v_mfma_f32_16x16x32_bf16 v[70:73], v[202:205], v[194:197], v[70:73]
	v_mfma_f32_16x16x32_bf16 v[66:69], v[210:213], v[194:197], v[66:69]
	s_setprio 0
	s_mov_b32 m0, s27
	v_lshl_add_u64 v[216:217], s[24:25], 0, v[130:131]
	s_barrier
	ds_read_b128 v[162:165], v142 offset:16384
	ds_read_b128 v[166:169], v142 offset:17408
	ds_read_b128 v[170:173], v142 offset:18432
	ds_read_b128 v[174:177], v142 offset:19456
	ds_read_b128 v[182:185], v142 offset:20480
	ds_read_b128 v[186:189], v142 offset:21504
	ds_read_b128 v[190:193], v142 offset:22528
	ds_read_b128 v[194:197], v142 offset:23552
	global_load_lds_dwordx4 v[216:217], off
	v_lshl_add_u64 v[222:223], s[24:25], 0, v[132:133]
	s_mov_b32 m0, s30
	s_nop 0
	global_load_lds_dwordx4 v[222:223], off
	s_barrier
	s_waitcnt lgkmcnt(0)
	s_setprio 1
	s_waitcnt lgkmcnt(0)
	v_mfma_f32_16x16x32_bf16 v[62:65], v[146:149], v[162:165], v[62:65]
	v_mfma_f32_16x16x32_bf16 v[58:61], v[154:157], v[162:165], v[58:61]
	v_mfma_f32_16x16x32_bf16 v[50:53], v[146:149], v[170:173], v[50:53]
	v_mfma_f32_16x16x32_bf16 v[42:45], v[154:157], v[170:173], v[42:45]
	v_mfma_f32_16x16x32_bf16 v[34:37], v[146:149], v[182:185], v[34:37]
	v_mfma_f32_16x16x32_bf16 v[26:29], v[154:157], v[182:185], v[26:29]
	v_mfma_f32_16x16x32_bf16 v[18:21], v[146:149], v[190:193], v[18:21]
	v_mfma_f32_16x16x32_bf16 v[10:13], v[154:157], v[190:193], v[10:13]
	v_mfma_f32_16x16x32_bf16 v[62:65], v[150:153], v[166:169], v[62:65]
	v_mfma_f32_16x16x32_bf16 v[58:61], v[158:161], v[166:169], v[58:61]
	v_mfma_f32_16x16x32_bf16 v[50:53], v[150:153], v[174:177], v[50:53]
	v_mfma_f32_16x16x32_bf16 v[42:45], v[158:161], v[174:177], v[42:45]
	v_mfma_f32_16x16x32_bf16 v[34:37], v[150:153], v[186:189], v[34:37]
	v_mfma_f32_16x16x32_bf16 v[26:29], v[158:161], v[186:189], v[26:29]
	v_mfma_f32_16x16x32_bf16 v[18:21], v[150:153], v[194:197], v[18:21]
	v_mfma_f32_16x16x32_bf16 v[10:13], v[158:161], v[194:197], v[10:13]
	s_setprio 0
	s_barrier
	s_add_u32 s20, s22, 0x18000
	s_addc_u32 s21, s23, 0
	s_mov_b32 m0, s31
	v_lshl_add_u64 v[146:147], s[20:21], 0, v[0:1]
	global_load_lds_dwordx4 v[146:147], off
	v_lshl_add_u64 v[146:147], s[20:21], 0, v[134:135]
	s_mov_b32 m0, s34
	s_nop 0
	global_load_lds_dwordx4 v[146:147], off
	s_waitcnt vmcnt(6)
	s_barrier
	s_setprio 1
	v_mfma_f32_16x16x32_bf16 v[54:57], v[198:201], v[162:165], v[54:57]
	v_mfma_f32_16x16x32_bf16 v[46:49], v[206:209], v[162:165], v[46:49]
	v_mfma_f32_16x16x32_bf16 v[38:41], v[198:201], v[170:173], v[38:41]
	v_mfma_f32_16x16x32_bf16 v[30:33], v[206:209], v[170:173], v[30:33]
	v_mfma_f32_16x16x32_bf16 v[22:25], v[198:201], v[182:185], v[22:25]
	v_mfma_f32_16x16x32_bf16 v[14:17], v[206:209], v[182:185], v[14:17]
	v_mfma_f32_16x16x32_bf16 v[6:9], v[198:201], v[190:193], v[6:9]
	v_mfma_f32_16x16x32_bf16 v[2:5], v[206:209], v[190:193], v[2:5]
	v_mfma_f32_16x16x32_bf16 v[54:57], v[202:205], v[166:169], v[54:57]
	v_mfma_f32_16x16x32_bf16 v[46:49], v[210:213], v[166:169], v[46:49]
	v_mfma_f32_16x16x32_bf16 v[38:41], v[202:205], v[174:177], v[38:41]
	v_mfma_f32_16x16x32_bf16 v[30:33], v[210:213], v[174:177], v[30:33]
	v_mfma_f32_16x16x32_bf16 v[22:25], v[202:205], v[186:189], v[22:25]
	v_mfma_f32_16x16x32_bf16 v[14:17], v[210:213], v[186:189], v[14:17]
	v_mfma_f32_16x16x32_bf16 v[6:9], v[202:205], v[194:197], v[6:9]
	v_mfma_f32_16x16x32_bf16 v[2:5], v[210:213], v[194:197], v[2:5]
	s_setprio 0
	v_add_u32_e32 v140, 0x18000, v143
	s_barrier
	ds_read_b128 v[146:149], v140
	ds_read_b128 v[150:153], v140 offset:1024
	ds_read_b128 v[154:157], v140 offset:2048
	ds_read_b128 v[158:161], v140 offset:3072
	s_add_u32 s20, s24, 0x18000
	s_addc_u32 s21, s25, 0
	s_mov_b32 m0, s35
	v_lshl_add_u64 v[198:199], s[20:21], 0, v[130:131]
	ds_read_b128 v[162:165], v142 offset:32768
	ds_read_b128 v[166:169], v142 offset:33792
	ds_read_b128 v[170:173], v142 offset:34816
	ds_read_b128 v[174:177], v142 offset:35840
	ds_read_b128 v[182:185], v142 offset:36864
	ds_read_b128 v[186:189], v142 offset:37888
	ds_read_b128 v[190:193], v142 offset:38912
	ds_read_b128 v[194:197], v142 offset:39936
	global_load_lds_dwordx4 v[198:199], off
	v_lshl_add_u64 v[198:199], s[20:21], 0, v[132:133]
	s_mov_b32 m0, s36
	s_nop 0
	global_load_lds_dwordx4 v[198:199], off
	s_waitcnt lgkmcnt(8)
	s_barrier
	s_waitcnt lgkmcnt(0)
	s_setprio 1
	s_waitcnt lgkmcnt(0)
	v_mfma_f32_16x16x32_bf16 v[126:129], v[146:149], v[162:165], v[126:129]
	v_mfma_f32_16x16x32_bf16 v[122:125], v[154:157], v[162:165], v[122:125]
	v_mfma_f32_16x16x32_bf16 v[114:117], v[146:149], v[170:173], v[114:117]
	v_mfma_f32_16x16x32_bf16 v[106:109], v[154:157], v[170:173], v[106:109]
	v_mfma_f32_16x16x32_bf16 v[98:101], v[146:149], v[182:185], v[98:101]
	v_mfma_f32_16x16x32_bf16 v[90:93], v[154:157], v[182:185], v[90:93]
	v_mfma_f32_16x16x32_bf16 v[82:85], v[146:149], v[190:193], v[82:85]
	v_mfma_f32_16x16x32_bf16 v[74:77], v[154:157], v[190:193], v[74:77]
	v_mfma_f32_16x16x32_bf16 v[126:129], v[150:153], v[166:169], v[126:129]
	v_mfma_f32_16x16x32_bf16 v[122:125], v[158:161], v[166:169], v[122:125]
	v_mfma_f32_16x16x32_bf16 v[114:117], v[150:153], v[174:177], v[114:117]
	v_mfma_f32_16x16x32_bf16 v[106:109], v[158:161], v[174:177], v[106:109]
	v_mfma_f32_16x16x32_bf16 v[98:101], v[150:153], v[186:189], v[98:101]
	v_mfma_f32_16x16x32_bf16 v[90:93], v[158:161], v[186:189], v[90:93]
	v_mfma_f32_16x16x32_bf16 v[82:85], v[150:153], v[194:197], v[82:85]
	v_mfma_f32_16x16x32_bf16 v[74:77], v[158:161], v[194:197], v[74:77]
	s_setprio 0
	s_barrier
	s_mov_b32 m0, s37
	v_add_u32_e32 v140, 0x1c000, v143
	v_lshl_add_u64 v[178:179], v[178:179], 0, s[84:85]
	ds_read_b128 v[198:201], v140
	ds_read_b128 v[202:205], v140 offset:1024
	ds_read_b128 v[206:209], v140 offset:2048
	ds_read_b128 v[210:213], v140 offset:3072
	global_load_lds_dwordx4 v[178:179], off
	v_lshl_add_u64 v[178:179], v[214:215], 0, s[84:85]
	s_mov_b32 m0, s38
	s_nop 0
	global_load_lds_dwordx4 v[178:179], off
	s_barrier
	s_waitcnt lgkmcnt(0)
	s_setprio 1
	s_waitcnt lgkmcnt(0)
	v_mfma_f32_16x16x32_bf16 v[118:121], v[198:201], v[162:165], v[118:121]
	v_mfma_f32_16x16x32_bf16 v[110:113], v[206:209], v[162:165], v[110:113]
	v_mfma_f32_16x16x32_bf16 v[102:105], v[198:201], v[170:173], v[102:105]
	v_mfma_f32_16x16x32_bf16 v[94:97], v[206:209], v[170:173], v[94:97]
	v_mfma_f32_16x16x32_bf16 v[86:89], v[198:201], v[182:185], v[86:89]
	v_mfma_f32_16x16x32_bf16 v[78:81], v[206:209], v[182:185], v[78:81]
	v_mfma_f32_16x16x32_bf16 v[70:73], v[198:201], v[190:193], v[70:73]
	v_mfma_f32_16x16x32_bf16 v[66:69], v[206:209], v[190:193], v[66:69]
	v_mfma_f32_16x16x32_bf16 v[118:121], v[202:205], v[166:169], v[118:121]
	v_mfma_f32_16x16x32_bf16 v[110:113], v[210:213], v[166:169], v[110:113]
	v_mfma_f32_16x16x32_bf16 v[102:105], v[202:205], v[174:177], v[102:105]
	v_mfma_f32_16x16x32_bf16 v[94:97], v[210:213], v[174:177], v[94:97]
	v_mfma_f32_16x16x32_bf16 v[86:89], v[202:205], v[186:189], v[86:89]
	v_mfma_f32_16x16x32_bf16 v[78:81], v[210:213], v[186:189], v[78:81]
	v_mfma_f32_16x16x32_bf16 v[70:73], v[202:205], v[194:197], v[70:73]
	v_mfma_f32_16x16x32_bf16 v[66:69], v[210:213], v[194:197], v[66:69]
	s_setprio 0
	s_mov_b32 m0, s39
	v_lshl_add_u64 v[178:179], v[216:217], 0, s[84:85]
	s_barrier
	ds_read_b128 v[162:165], v142 offset:49152
	ds_read_b128 v[166:169], v142 offset:50176
	ds_read_b128 v[170:173], v142 offset:51200
	ds_read_b128 v[174:177], v142 offset:52224
	ds_read_b128 v[182:185], v142 offset:53248
	ds_read_b128 v[186:189], v142 offset:54272
	ds_read_b128 v[190:193], v142 offset:55296
	ds_read_b128 v[194:197], v142 offset:56320
	global_load_lds_dwordx4 v[178:179], off
	v_lshl_add_u64 v[178:179], v[222:223], 0, s[84:85]
	s_mov_b32 m0, s60
	s_nop 0
	global_load_lds_dwordx4 v[178:179], off
	s_barrier
	s_waitcnt lgkmcnt(0)
	s_setprio 1
	s_waitcnt lgkmcnt(0)
	v_mfma_f32_16x16x32_bf16 v[62:65], v[146:149], v[162:165], v[62:65]
	v_mfma_f32_16x16x32_bf16 v[58:61], v[154:157], v[162:165], v[58:61]
	v_mfma_f32_16x16x32_bf16 v[50:53], v[146:149], v[170:173], v[50:53]
	v_mfma_f32_16x16x32_bf16 v[42:45], v[154:157], v[170:173], v[42:45]
	v_mfma_f32_16x16x32_bf16 v[34:37], v[146:149], v[182:185], v[34:37]
	v_mfma_f32_16x16x32_bf16 v[26:29], v[154:157], v[182:185], v[26:29]
	v_mfma_f32_16x16x32_bf16 v[18:21], v[146:149], v[190:193], v[18:21]
	v_mfma_f32_16x16x32_bf16 v[10:13], v[154:157], v[190:193], v[10:13]
	v_mfma_f32_16x16x32_bf16 v[62:65], v[150:153], v[166:169], v[62:65]
	v_mfma_f32_16x16x32_bf16 v[58:61], v[158:161], v[166:169], v[58:61]
	v_mfma_f32_16x16x32_bf16 v[50:53], v[150:153], v[174:177], v[50:53]
	v_mfma_f32_16x16x32_bf16 v[42:45], v[158:161], v[174:177], v[42:45]
	v_mfma_f32_16x16x32_bf16 v[34:37], v[150:153], v[186:189], v[34:37]
	v_mfma_f32_16x16x32_bf16 v[26:29], v[158:161], v[186:189], v[26:29]
	v_mfma_f32_16x16x32_bf16 v[18:21], v[150:153], v[194:197], v[18:21]
	v_mfma_f32_16x16x32_bf16 v[10:13], v[158:161], v[194:197], v[10:13]
	s_setprio 0
	s_barrier
	s_add_u32 s20, s22, 0x18080
	s_addc_u32 s21, s23, 0
	s_mov_b32 m0, s68
	v_lshl_add_u64 v[146:147], s[20:21], 0, v[0:1]
	global_load_lds_dwordx4 v[146:147], off
	v_lshl_add_u64 v[146:147], s[20:21], 0, v[134:135]
	s_mov_b32 m0, s69
	s_nop 0
	global_load_lds_dwordx4 v[146:147], off
	s_waitcnt vmcnt(6)
	s_barrier
	s_setprio 1
	v_mfma_f32_16x16x32_bf16 v[54:57], v[198:201], v[162:165], v[54:57]
	v_mfma_f32_16x16x32_bf16 v[46:49], v[206:209], v[162:165], v[46:49]
	v_mfma_f32_16x16x32_bf16 v[38:41], v[198:201], v[170:173], v[38:41]
	v_mfma_f32_16x16x32_bf16 v[30:33], v[206:209], v[170:173], v[30:33]
	v_mfma_f32_16x16x32_bf16 v[22:25], v[198:201], v[182:185], v[22:25]
	v_mfma_f32_16x16x32_bf16 v[14:17], v[206:209], v[182:185], v[14:17]
	v_mfma_f32_16x16x32_bf16 v[6:9], v[198:201], v[190:193], v[6:9]
	v_mfma_f32_16x16x32_bf16 v[2:5], v[206:209], v[190:193], v[2:5]
	v_mfma_f32_16x16x32_bf16 v[54:57], v[202:205], v[166:169], v[54:57]
	v_mfma_f32_16x16x32_bf16 v[46:49], v[210:213], v[166:169], v[46:49]
	v_mfma_f32_16x16x32_bf16 v[38:41], v[202:205], v[174:177], v[38:41]
	v_mfma_f32_16x16x32_bf16 v[30:33], v[210:213], v[174:177], v[30:33]
	v_mfma_f32_16x16x32_bf16 v[22:25], v[202:205], v[186:189], v[22:25]
	v_mfma_f32_16x16x32_bf16 v[14:17], v[210:213], v[186:189], v[14:17]
	v_mfma_f32_16x16x32_bf16 v[6:9], v[202:205], v[194:197], v[6:9]
	v_mfma_f32_16x16x32_bf16 v[2:5], v[210:213], v[194:197], v[2:5]
	s_setprio 0
	s_add_i32 s96, s96, 2
	s_add_u32 s93, s93, 0x100
	s_addc_u32 s94, s94, 0
	s_cmp_gt_u32 s96, 3
	s_mov_b64 s[20:21], s[6:7]
	s_barrier
	s_cbranch_scc0 .LBB0_926
	v_lshl_add_u32 v140, s90, 8, v144
	v_lshl_add_u32 v145, s92, 8, v141
	v_cmp_gt_u32_e32 vcc, s63, v140
	s_and_saveexec_b64 s[6:7], vcc
	s_cbranch_execz .LBB0_929
	v_cvt_pk_bf16_f32 v126, v126, v127
	v_cvt_pk_bf16_f32 v127, v128, v129
	v_cvt_pk_bf16_f32 v128, v122, v123
	v_cvt_pk_bf16_f32 v129, v124, v125
	v_mad_u64_u32 v[122:123], s[20:21], v145, s63, v[140:141]
	v_mov_b32_e32 v123, v1
	v_lshl_add_u64 v[122:123], v[122:123], 1, s[10:11]
	global_store_dwordx4 v[122:123], v[126:129], off

.LBB0_1052:
	v_add_u32_e32 v140, 0x10000, v143
	ds_read_b128 v[146:149], v140
	ds_read_b128 v[150:153], v140 offset:1024
	ds_read_b128 v[154:157], v140 offset:2048
	ds_read_b128 v[158:161], v140 offset:3072
	s_add_u32 s6, s20, 0x100
	s_addc_u32 s7, s21, 0
	s_cmp_eq_u32 s94, 2
	s_cselect_b32 s25, s17, s7
	s_cselect_b32 s24, s16, s6
	s_cselect_b32 s23, s19, s93
	s_cselect_b32 s22, s18, s92
	v_lshl_add_u64 v[178:179], s[20:21], 0, v[136:137]
	s_add_i32 m0, s26, 0xc000
	ds_read_b128 v[162:165], v142
	ds_read_b128 v[166:169], v142 offset:1024
	ds_read_b128 v[170:173], v142 offset:2048
	ds_read_b128 v[174:177], v142 offset:3072
	ds_read_b128 v[182:185], v142 offset:4096
	ds_read_b128 v[186:189], v142 offset:5120
	ds_read_b128 v[190:193], v142 offset:6144
	ds_read_b128 v[194:197], v142 offset:7168
	global_load_lds_dwordx4 v[178:179], off
	v_lshl_add_u64 v[178:179], s[20:21], 0, v[138:139]
	s_add_i32 m0, s26, 0xe000
	s_nop 0
	global_load_lds_dwordx4 v[178:179], off
	s_waitcnt lgkmcnt(8)
	s_barrier
	s_waitcnt lgkmcnt(0)
	s_setprio 1
	s_waitcnt lgkmcnt(0)
	v_mfma_f32_16x16x32_bf16 v[126:129], v[146:149], v[162:165], v[126:129]
	v_mfma_f32_16x16x32_bf16 v[122:125], v[154:157], v[162:165], v[122:125]
	v_mfma_f32_16x16x32_bf16 v[114:117], v[146:149], v[170:173], v[114:117]
	v_mfma_f32_16x16x32_bf16 v[106:109], v[154:157], v[170:173], v[106:109]
	v_mfma_f32_16x16x32_bf16 v[98:101], v[146:149], v[182:185], v[98:101]
	v_mfma_f32_16x16x32_bf16 v[90:93], v[154:157], v[182:185], v[90:93]
	v_mfma_f32_16x16x32_bf16 v[82:85], v[146:149], v[190:193], v[82:85]
	v_mfma_f32_16x16x32_bf16 v[74:77], v[154:157], v[190:193], v[74:77]
	v_mfma_f32_16x16x32_bf16 v[126:129], v[150:153], v[166:169], v[126:129]
	v_mfma_f32_16x16x32_bf16 v[122:125], v[158:161], v[166:169], v[122:125]
	v_mfma_f32_16x16x32_bf16 v[114:117], v[150:153], v[174:177], v[114:117]
	v_mfma_f32_16x16x32_bf16 v[106:109], v[158:161], v[174:177], v[106:109]
	v_mfma_f32_16x16x32_bf16 v[98:101], v[150:153], v[186:189], v[98:101]
	v_mfma_f32_16x16x32_bf16 v[90:93], v[158:161], v[186:189], v[90:93]
	v_mfma_f32_16x16x32_bf16 v[82:85], v[150:153], v[194:197], v[82:85]
	v_mfma_f32_16x16x32_bf16 v[74:77], v[158:161], v[194:197], v[74:77]
	s_setprio 0
	s_barrier
	s_mov_b32 m0, s27
	v_add_u32_e32 v140, 0x14000, v143
	v_lshl_add_u64 v[178:179], s[22:23], 0, v[0:1]
	ds_read_b128 v[198:201], v140
	ds_read_b128 v[202:205], v140 offset:1024
	ds_read_b128 v[206:209], v140 offset:2048
	ds_read_b128 v[210:213], v140 offset:3072
	global_load_lds_dwordx4 v[178:179], off
	v_lshl_add_u64 v[214:215], s[22:23], 0, v[134:135]
	s_mov_b32 m0, s28
	s_nop 0
	global_load_lds_dwordx4 v[214:215], off
	s_barrier
	s_waitcnt lgkmcnt(0)
	s_setprio 1
	s_waitcnt lgkmcnt(0)
	v_mfma_f32_16x16x32_bf16 v[118:121], v[198:201], v[162:165], v[118:121]
	v_mfma_f32_16x16x32_bf16 v[110:113], v[206:209], v[162:165], v[110:113]
	v_mfma_f32_16x16x32_bf16 v[102:105], v[198:201], v[170:173], v[102:105]
	v_mfma_f32_16x16x32_bf16 v[94:97], v[206:209], v[170:173], v[94:97]
	v_mfma_f32_16x16x32_bf16 v[86:89], v[198:201], v[182:185], v[86:89]
	v_mfma_f32_16x16x32_bf16 v[78:81], v[206:209], v[182:185], v[78:81]
	v_mfma_f32_16x16x32_bf16 v[70:73], v[198:201], v[190:193], v[70:73]
	v_mfma_f32_16x16x32_bf16 v[66:69], v[206:209], v[190:193], v[66:69]
	v_mfma_f32_16x16x32_bf16 v[118:121], v[202:205], v[166:169], v[118:121]
	v_mfma_f32_16x16x32_bf16 v[110:113], v[210:213], v[166:169], v[110:113]
	v_mfma_f32_16x16x32_bf16 v[102:105], v[202:205], v[174:177], v[102:105]
	v_mfma_f32_16x16x32_bf16 v[94:97], v[210:213], v[174:177], v[94:97]
	v_mfma_f32_16x16x32_bf16 v[86:89], v[202:205], v[186:189], v[86:89]
	v_mfma_f32_16x16x32_bf16 v[78:81], v[210:213], v[186:189], v[78:81]
	v_mfma_f32_16x16x32_bf16 v[70:73], v[202:205], v[194:197], v[70:73]
	v_mfma_f32_16x16x32_bf16 v[66:69], v[210:213], v[194:197], v[66:69]
	s_setprio 0
	s_mov_b32 m0, s26
	v_lshl_add_u64 v[216:217], s[24:25], 0, v[130:131]
	s_barrier
	ds_read_b128 v[162:165], v142 offset:16384
	ds_read_b128 v[166:169], v142 offset:17408
	ds_read_b128 v[170:173], v142 offset:18432
	ds_read_b128 v[174:177], v142 offset:19456
	ds_read_b128 v[182:185], v142 offset:20480
	ds_read_b128 v[186:189], v142 offset:21504
	ds_read_b128 v[190:193], v142 offset:22528
	ds_read_b128 v[194:197], v142 offset:23552
	global_load_lds_dwordx4 v[216:217], off
	v_lshl_add_u64 v[222:223], s[24:25], 0, v[132:133]
	s_mov_b32 m0, s29
	s_nop 0
	global_load_lds_dwordx4 v[222:223], off
	s_barrier
	s_waitcnt lgkmcnt(0)
	s_setprio 1
	s_waitcnt lgkmcnt(0)
	v_mfma_f32_16x16x32_bf16 v[62:65], v[146:149], v[162:165], v[62:65]
	v_mfma_f32_16x16x32_bf16 v[58:61], v[154:157], v[162:165], v[58:61]
	v_mfma_f32_16x16x32_bf16 v[50:53], v[146:149], v[170:173], v[50:53]
	v_mfma_f32_16x16x32_bf16 v[42:45], v[154:157], v[170:173], v[42:45]
	v_mfma_f32_16x16x32_bf16 v[34:37], v[146:149], v[182:185], v[34:37]
	v_mfma_f32_16x16x32_bf16 v[26:29], v[154:157], v[182:185], v[26:29]
	v_mfma_f32_16x16x32_bf16 v[18:21], v[146:149], v[190:193], v[18:21]
	v_mfma_f32_16x16x32_bf16 v[10:13], v[154:157], v[190:193], v[10:13]
	v_mfma_f32_16x16x32_bf16 v[62:65], v[150:153], v[166:169], v[62:65]
	v_mfma_f32_16x16x32_bf16 v[58:61], v[158:161], v[166:169], v[58:61]
	v_mfma_f32_16x16x32_bf16 v[50:53], v[150:153], v[174:177], v[50:53]
	v_mfma_f32_16x16x32_bf16 v[42:45], v[158:161], v[174:177], v[42:45]
	v_mfma_f32_16x16x32_bf16 v[34:37], v[150:153], v[186:189], v[34:37]
	v_mfma_f32_16x16x32_bf16 v[26:29], v[158:161], v[186:189], v[26:29]
	v_mfma_f32_16x16x32_bf16 v[18:21], v[150:153], v[194:197], v[18:21]
	v_mfma_f32_16x16x32_bf16 v[10:13], v[158:161], v[194:197], v[10:13]
	s_setprio 0
	s_barrier
	s_add_u32 s20, s22, 0x18000
	s_addc_u32 s21, s23, 0
	s_mov_b32 m0, s30
	v_lshl_add_u64 v[146:147], s[20:21], 0, v[0:1]
	global_load_lds_dwordx4 v[146:147], off
	v_lshl_add_u64 v[146:147], s[20:21], 0, v[134:135]
	s_mov_b32 m0, s31
	s_nop 0
	global_load_lds_dwordx4 v[146:147], off
	s_waitcnt vmcnt(6)
	s_barrier
	s_setprio 1
	v_mfma_f32_16x16x32_bf16 v[54:57], v[198:201], v[162:165], v[54:57]
	v_mfma_f32_16x16x32_bf16 v[46:49], v[206:209], v[162:165], v[46:49]
	v_mfma_f32_16x16x32_bf16 v[38:41], v[198:201], v[170:173], v[38:41]
	v_mfma_f32_16x16x32_bf16 v[30:33], v[206:209], v[170:173], v[30:33]
	v_mfma_f32_16x16x32_bf16 v[22:25], v[198:201], v[182:185], v[22:25]
	v_mfma_f32_16x16x32_bf16 v[14:17], v[206:209], v[182:185], v[14:17]
	v_mfma_f32_16x16x32_bf16 v[6:9], v[198:201], v[190:193], v[6:9]
	v_mfma_f32_16x16x32_bf16 v[2:5], v[206:209], v[190:193], v[2:5]
	v_mfma_f32_16x16x32_bf16 v[54:57], v[202:205], v[166:169], v[54:57]
	v_mfma_f32_16x16x32_bf16 v[46:49], v[210:213], v[166:169], v[46:49]
	v_mfma_f32_16x16x32_bf16 v[38:41], v[202:205], v[174:177], v[38:41]
	v_mfma_f32_16x16x32_bf16 v[30:33], v[210:213], v[174:177], v[30:33]
	v_mfma_f32_16x16x32_bf16 v[22:25], v[202:205], v[186:189], v[22:25]
	v_mfma_f32_16x16x32_bf16 v[14:17], v[210:213], v[186:189], v[14:17]
	v_mfma_f32_16x16x32_bf16 v[6:9], v[202:205], v[194:197], v[6:9]
	v_mfma_f32_16x16x32_bf16 v[2:5], v[210:213], v[194:197], v[2:5]
	s_setprio 0
	v_add_u32_e32 v140, 0x18000, v143
	s_barrier
	ds_read_b128 v[146:149], v140
	ds_read_b128 v[150:153], v140 offset:1024
	ds_read_b128 v[154:157], v140 offset:2048
	ds_read_b128 v[158:161], v140 offset:3072
	s_add_u32 s20, s24, 0x18000
	s_addc_u32 s21, s25, 0
	s_mov_b32 m0, s34
	v_lshl_add_u64 v[198:199], s[20:21], 0, v[130:131]
	ds_read_b128 v[162:165], v142 offset:32768
	ds_read_b128 v[166:169], v142 offset:33792
	ds_read_b128 v[170:173], v142 offset:34816
	ds_read_b128 v[174:177], v142 offset:35840
	ds_read_b128 v[182:185], v142 offset:36864
	ds_read_b128 v[186:189], v142 offset:37888
	ds_read_b128 v[190:193], v142 offset:38912
	ds_read_b128 v[194:197], v142 offset:39936
	global_load_lds_dwordx4 v[198:199], off
	v_lshl_add_u64 v[198:199], s[20:21], 0, v[132:133]
	s_mov_b32 m0, s35
	s_nop 0
	global_load_lds_dwordx4 v[198:199], off
	s_waitcnt lgkmcnt(8)
	s_barrier
	s_waitcnt lgkmcnt(0)
	s_setprio 1
	s_waitcnt lgkmcnt(0)
	v_mfma_f32_16x16x32_bf16 v[126:129], v[146:149], v[162:165], v[126:129]
	v_mfma_f32_16x16x32_bf16 v[122:125], v[154:157], v[162:165], v[122:125]
	v_mfma_f32_16x16x32_bf16 v[114:117], v[146:149], v[170:173], v[114:117]
	v_mfma_f32_16x16x32_bf16 v[106:109], v[154:157], v[170:173], v[106:109]
	v_mfma_f32_16x16x32_bf16 v[98:101], v[146:149], v[182:185], v[98:101]
	v_mfma_f32_16x16x32_bf16 v[90:93], v[154:157], v[182:185], v[90:93]
	v_mfma_f32_16x16x32_bf16 v[82:85], v[146:149], v[190:193], v[82:85]
	v_mfma_f32_16x16x32_bf16 v[74:77], v[154:157], v[190:193], v[74:77]
	v_mfma_f32_16x16x32_bf16 v[126:129], v[150:153], v[166:169], v[126:129]
	v_mfma_f32_16x16x32_bf16 v[122:125], v[158:161], v[166:169], v[122:125]
	v_mfma_f32_16x16x32_bf16 v[114:117], v[150:153], v[174:177], v[114:117]
	v_mfma_f32_16x16x32_bf16 v[106:109], v[158:161], v[174:177], v[106:109]
	v_mfma_f32_16x16x32_bf16 v[98:101], v[150:153], v[186:189], v[98:101]
	v_mfma_f32_16x16x32_bf16 v[90:93], v[158:161], v[186:189], v[90:93]
	v_mfma_f32_16x16x32_bf16 v[82:85], v[150:153], v[194:197], v[82:85]
	v_mfma_f32_16x16x32_bf16 v[74:77], v[158:161], v[194:197], v[74:77]
	s_setprio 0
	s_barrier
	s_mov_b32 m0, s36
	v_add_u32_e32 v140, 0x1c000, v143
	v_lshl_add_u64 v[178:179], v[178:179], 0, s[84:85]
	ds_read_b128 v[198:201], v140
	ds_read_b128 v[202:205], v140 offset:1024
	ds_read_b128 v[206:209], v140 offset:2048
	ds_read_b128 v[210:213], v140 offset:3072
	global_load_lds_dwordx4 v[178:179], off
	v_lshl_add_u64 v[178:179], v[214:215], 0, s[84:85]
	s_mov_b32 m0, s37
	s_nop 0
	global_load_lds_dwordx4 v[178:179], off
	s_barrier
	s_waitcnt lgkmcnt(0)
	s_setprio 1
	s_waitcnt lgkmcnt(0)
	v_mfma_f32_16x16x32_bf16 v[118:121], v[198:201], v[162:165], v[118:121]
	v_mfma_f32_16x16x32_bf16 v[110:113], v[206:209], v[162:165], v[110:113]
	v_mfma_f32_16x16x32_bf16 v[102:105], v[198:201], v[170:173], v[102:105]
	v_mfma_f32_16x16x32_bf16 v[94:97], v[206:209], v[170:173], v[94:97]
	v_mfma_f32_16x16x32_bf16 v[86:89], v[198:201], v[182:185], v[86:89]
	v_mfma_f32_16x16x32_bf16 v[78:81], v[206:209], v[182:185], v[78:81]
	v_mfma_f32_16x16x32_bf16 v[70:73], v[198:201], v[190:193], v[70:73]
	v_mfma_f32_16x16x32_bf16 v[66:69], v[206:209], v[190:193], v[66:69]
	v_mfma_f32_16x16x32_bf16 v[118:121], v[202:205], v[166:169], v[118:121]
	v_mfma_f32_16x16x32_bf16 v[110:113], v[210:213], v[166:169], v[110:113]
	v_mfma_f32_16x16x32_bf16 v[102:105], v[202:205], v[174:177], v[102:105]
	v_mfma_f32_16x16x32_bf16 v[94:97], v[210:213], v[174:177], v[94:97]
	v_mfma_f32_16x16x32_bf16 v[86:89], v[202:205], v[186:189], v[86:89]
	v_mfma_f32_16x16x32_bf16 v[78:81], v[210:213], v[186:189], v[78:81]
	v_mfma_f32_16x16x32_bf16 v[70:73], v[202:205], v[194:197], v[70:73]
	v_mfma_f32_16x16x32_bf16 v[66:69], v[210:213], v[194:197], v[66:69]
	s_setprio 0
	s_mov_b32 m0, s38
	v_lshl_add_u64 v[178:179], v[216:217], 0, s[84:85]
	s_barrier
	ds_read_b128 v[162:165], v142 offset:49152
	ds_read_b128 v[166:169], v142 offset:50176
	ds_read_b128 v[170:173], v142 offset:51200
	ds_read_b128 v[174:177], v142 offset:52224
	ds_read_b128 v[182:185], v142 offset:53248
	ds_read_b128 v[186:189], v142 offset:54272
	ds_read_b128 v[190:193], v142 offset:55296
	ds_read_b128 v[194:197], v142 offset:56320
	global_load_lds_dwordx4 v[178:179], off
	v_lshl_add_u64 v[178:179], v[222:223], 0, s[84:85]
	s_mov_b32 m0, s39
	s_nop 0
	global_load_lds_dwordx4 v[178:179], off
	s_barrier
	s_waitcnt lgkmcnt(0)
	s_setprio 1
	s_waitcnt lgkmcnt(0)
	v_mfma_f32_16x16x32_bf16 v[62:65], v[146:149], v[162:165], v[62:65]
	v_mfma_f32_16x16x32_bf16 v[58:61], v[154:157], v[162:165], v[58:61]
	v_mfma_f32_16x16x32_bf16 v[50:53], v[146:149], v[170:173], v[50:53]
	v_mfma_f32_16x16x32_bf16 v[42:45], v[154:157], v[170:173], v[42:45]
	v_mfma_f32_16x16x32_bf16 v[34:37], v[146:149], v[182:185], v[34:37]
	v_mfma_f32_16x16x32_bf16 v[26:29], v[154:157], v[182:185], v[26:29]
	v_mfma_f32_16x16x32_bf16 v[18:21], v[146:149], v[190:193], v[18:21]
	v_mfma_f32_16x16x32_bf16 v[10:13], v[154:157], v[190:193], v[10:13]
	v_mfma_f32_16x16x32_bf16 v[62:65], v[150:153], v[166:169], v[62:65]
	v_mfma_f32_16x16x32_bf16 v[58:61], v[158:161], v[166:169], v[58:61]
	v_mfma_f32_16x16x32_bf16 v[50:53], v[150:153], v[174:177], v[50:53]
	v_mfma_f32_16x16x32_bf16 v[42:45], v[158:161], v[174:177], v[42:45]
	v_mfma_f32_16x16x32_bf16 v[34:37], v[150:153], v[186:189], v[34:37]
	v_mfma_f32_16x16x32_bf16 v[26:29], v[158:161], v[186:189], v[26:29]
	v_mfma_f32_16x16x32_bf16 v[18:21], v[150:153], v[194:197], v[18:21]
	v_mfma_f32_16x16x32_bf16 v[10:13], v[158:161], v[194:197], v[10:13]
	s_setprio 0
	s_barrier
	s_add_u32 s20, s22, 0x18080
	s_addc_u32 s21, s23, 0
	s_mov_b32 m0, s60
	v_lshl_add_u64 v[146:147], s[20:21], 0, v[0:1]
	global_load_lds_dwordx4 v[146:147], off
	v_lshl_add_u64 v[146:147], s[20:21], 0, v[134:135]
	s_mov_b32 m0, s68
	s_nop 0
	global_load_lds_dwordx4 v[146:147], off
	s_waitcnt vmcnt(6)
	s_barrier
	s_setprio 1
	v_mfma_f32_16x16x32_bf16 v[54:57], v[198:201], v[162:165], v[54:57]
	v_mfma_f32_16x16x32_bf16 v[46:49], v[206:209], v[162:165], v[46:49]
	v_mfma_f32_16x16x32_bf16 v[38:41], v[198:201], v[170:173], v[38:41]
	v_mfma_f32_16x16x32_bf16 v[30:33], v[206:209], v[170:173], v[30:33]
	v_mfma_f32_16x16x32_bf16 v[22:25], v[198:201], v[182:185], v[22:25]
	v_mfma_f32_16x16x32_bf16 v[14:17], v[206:209], v[182:185], v[14:17]
	v_mfma_f32_16x16x32_bf16 v[6:9], v[198:201], v[190:193], v[6:9]
	v_mfma_f32_16x16x32_bf16 v[2:5], v[206:209], v[190:193], v[2:5]
	v_mfma_f32_16x16x32_bf16 v[54:57], v[202:205], v[166:169], v[54:57]
	v_mfma_f32_16x16x32_bf16 v[46:49], v[210:213], v[166:169], v[46:49]
	v_mfma_f32_16x16x32_bf16 v[38:41], v[202:205], v[174:177], v[38:41]
	v_mfma_f32_16x16x32_bf16 v[30:33], v[210:213], v[174:177], v[30:33]
	v_mfma_f32_16x16x32_bf16 v[22:25], v[202:205], v[186:189], v[22:25]
	v_mfma_f32_16x16x32_bf16 v[14:17], v[210:213], v[186:189], v[14:17]
	v_mfma_f32_16x16x32_bf16 v[6:9], v[202:205], v[194:197], v[6:9]
	v_mfma_f32_16x16x32_bf16 v[2:5], v[210:213], v[194:197], v[2:5]
	s_setprio 0
	s_add_i32 s94, s94, 2
	s_add_u32 s92, s92, 0x100
	s_addc_u32 s93, s93, 0
	s_cmp_gt_u32 s94, 3
	s_mov_b64 s[20:21], s[6:7]
	s_barrier
	s_cbranch_scc0 .LBB0_1052
	v_lshl_add_u32 v140, s89, 8, v144
	v_lshl_add_u32 v145, s90, 8, v141
	v_cmp_gt_u32_e32 vcc, s63, v140
	s_and_saveexec_b64 s[6:7], vcc
	s_cbranch_execz .LBB0_1055
	v_cvt_pk_bf16_f32 v126, v126, v127
	v_cvt_pk_bf16_f32 v127, v128, v129
	v_cvt_pk_bf16_f32 v128, v122, v123
	v_cvt_pk_bf16_f32 v129, v124, v125
	v_mad_u64_u32 v[122:123], s[20:21], v145, s63, v[140:141]
	v_mov_b32_e32 v123, v1
	v_lshl_add_u64 v[122:123], v[122:123], 1, s[10:11]
	global_store_dwordx4 v[122:123], v[126:129], off

.LBB0_1268:
	s_and_saveexec_b64 s[14:15], s[16:17]
	s_cbranch_execz .LBB0_1209
	s_mul_i32 s2, s18, 0x78
	s_mul_hi_i32 s3, s18, 0x78
	s_add_u32 s2, s0, s2
	s_addc_u32 s3, s1, s3
	s_load_dwordx2 s[4:5], s[2:3], 0x1e8
	s_nop 0
	s_load_dwordx2 s[2:3], s[2:3], 0x220
	v_mov_b32_e32 v12, v64
	v_mov_b32_e32 v13, v66
	s_waitcnt lgkmcnt(0)
	v_mov_b64_e32 v[2:3], s[4:5]
	v_mad_u64_u32 v[2:3], s[4:5], v182, s68, v[2:3]
	v_mov_b32_e32 v0, v3
	v_mad_u64_u32 v[4:5], s[4:5], v183, s68, v[0:1]
	v_mov_b32_e32 v3, v4
	s_lshl_b64 s[4:5], s[82:83], 1
	v_lshl_add_u64 v[4:5], v[2:3], 0, s[4:5]
	s_nop 0
	v_rcp_f32_e32 v2, v187
	s_nop 0
	v_lshlrev_b64 v[6:7], 11, v[182:183]
	v_lshlrev_b32_e32 v0, 3, v221
	v_lshl_add_u64 v[6:7], s[2:3], 0, v[6:7]
	v_lshl_add_u64 v[8:9], v[4:5], 0, v[0:1]
	s_mov_b64 s[2:3], 0x1580
	v_lshl_add_u64 v[4:5], v[8:9], 0, s[2:3]
	v_add_co_u32_e32 v8, vcc, s89, v8
	v_lshl_add_u64 v[6:7], v[6:7], 0, s[4:5]
	s_nop 0
	v_addc_co_u32_e32 v9, vcc, 0, v9, vcc
	global_load_dwordx2 v[8:9], v[8:9], off offset:1408
	global_load_dwordx2 v[80:81], v[4:5], off offset:16
	global_load_dwordx2 v[82:83], v[4:5], off offset:32
	global_load_dwordx2 v[84:85], v[4:5], off offset:48
	global_load_dwordx2 v[86:87], v[4:5], off offset:64
	global_load_dwordx2 v[88:89], v[4:5], off offset:80
	global_load_dwordx2 v[90:91], v[4:5], off offset:96
	global_load_dwordx2 v[92:93], v[4:5], off offset:112
	global_load_dwordx2 v[94:95], v[4:5], off offset:128
	global_load_dwordx2 v[96:97], v[4:5], off offset:144
	global_load_dwordx2 v[98:99], v[4:5], off offset:160
	global_load_dwordx2 v[100:101], v[4:5], off offset:176
	global_load_dwordx2 v[102:103], v[4:5], off offset:192
	global_load_dwordx2 v[104:105], v[4:5], off offset:208
	global_load_dwordx2 v[106:107], v[4:5], off offset:224
	global_load_dwordx2 v[108:109], v[4:5], off offset:240
	v_lshl_add_u64 v[6:7], v[6:7], 0, v[0:1]
	s_waitcnt vmcnt(15)
	v_and_b32_e32 v15, 0xffff0000, v8
	v_lshlrev_b32_e32 v3, 16, v9
	v_lshlrev_b32_e32 v11, 16, v8
	v_and_b32_e32 v14, 0xffff0000, v9
	v_mul_f32_e32 v9, 0xbfb8aa3b, v15
	v_mul_f32_e32 v8, 0xbfb8aa3b, v11
	v_exp_f32_e32 v10, v9
	v_mul_f32_e32 v9, 0xbfb8aa3b, v3
	v_exp_f32_e32 v8, v8
	v_exp_f32_e32 v9, v9
	v_pk_mul_f32 v[12:13], v[12:13], v[2:3] op_sel_hi:[1,0]
	v_pk_add_f32 v[8:9], v[8:9], 1.0 op_sel_hi:[1,0]
	s_nop 0
	s_nop 0
	v_rcp_f32_e32 v64, v9
	s_nop 0
	v_mul_f32_e32 v9, v3, v64
	s_nop 0
	v_rcp_f32_e32 v3, v8
	s_nop 0
	v_mul_f32_e32 v8, v11, v3
	v_mov_b32_e32 v66, v65
	v_pk_mul_f32 v[8:9], v[12:13], v[8:9]
	v_pk_mul_f32 v[12:13], v[66:67], v[2:3] op_sel_hi:[1,0]
	v_mul_f32_e32 v3, 0xbfb8aa3b, v14
	v_exp_f32_e32 v11, v3
	s_nop 0
	v_pk_add_f32 v[10:11], v[10:11], 1.0 op_sel_hi:[1,0]
	s_nop 0
	s_nop 0
	v_rcp_f32_e32 v3, v11
	s_nop 0
	v_mul_f32_e32 v11, v14, v3
	s_nop 0
	v_rcp_f32_e32 v3, v10
	s_nop 0
	v_mul_f32_e32 v10, v15, v3
	v_pk_mul_f32 v[10:11], v[12:13], v[10:11]
	v_cvt_pk_bf16_f32 v3, v8, v9
	v_cvt_pk_bf16_f32 v8, v10, v11
	v_and_b32_e32 v9, 0xffff0000, v8
	v_lshlrev_b32_e32 v8, 16, v8
	v_or_b32_sdwa v9, v9, v3 dst_sel:DWORD dst_unused:UNUSED_PAD src0_sel:DWORD src1_sel:WORD_1
	v_or_b32_sdwa v8, v8, v3 dst_sel:DWORD dst_unused:UNUSED_PAD src0_sel:DWORD src1_sel:WORD_0
	global_store_dwordx2 v[6:7], v[8:9], off
	v_mov_b32_e32 v12, v68
	v_mov_b32_e32 v13, v70
	v_mov_b32_e32 v70, v69
	s_waitcnt vmcnt(15)
	v_and_b32_e32 v15, 0xffff0000, v80
	v_lshlrev_b32_e32 v0, 16, v81
	v_lshlrev_b32_e32 v3, 16, v80
	v_and_b32_e32 v14, 0xffff0000, v81
	v_mul_f32_e32 v9, 0xbfb8aa3b, v15
	v_mul_f32_e32 v8, 0xbfb8aa3b, v3
	v_exp_f32_e32 v10, v9
	v_mul_f32_e32 v9, 0xbfb8aa3b, v0
	v_exp_f32_e32 v8, v8
	v_exp_f32_e32 v9, v9
	v_pk_mul_f32 v[12:13], v[12:13], v[2:3] op_sel_hi:[1,0]
	v_pk_add_f32 v[8:9], v[8:9], 1.0 op_sel_hi:[1,0]
	s_nop 0
	s_nop 0
	v_rcp_f32_e32 v11, v9
	s_nop 0
	v_mul_f32_e32 v9, v0, v11
	s_nop 0
	v_rcp_f32_e32 v0, v8
	s_nop 0
	v_mul_f32_e32 v8, v3, v0
	v_mul_f32_e32 v0, 0xbfb8aa3b, v14
	v_exp_f32_e32 v11, v0
	v_pk_mul_f32 v[8:9], v[12:13], v[8:9]
	v_pk_mul_f32 v[12:13], v[70:71], v[2:3] op_sel_hi:[1,0]
	v_pk_add_f32 v[10:11], v[10:11], 1.0 op_sel_hi:[1,0]
	s_nop 0
	s_nop 0
	v_rcp_f32_e32 v0, v11
	s_nop 0
	v_mul_f32_e32 v11, v14, v0
	s_nop 0
	v_rcp_f32_e32 v0, v10
	s_nop 0
	v_mul_f32_e32 v10, v15, v0
	v_pk_mul_f32 v[10:11], v[12:13], v[10:11]
	v_cvt_pk_bf16_f32 v0, v8, v9
	v_cvt_pk_bf16_f32 v3, v10, v11
	v_and_b32_e32 v8, 0xffff0000, v3
	v_lshlrev_b32_e32 v3, 16, v3
	v_or_b32_sdwa v9, v8, v0 dst_sel:DWORD dst_unused:UNUSED_PAD src0_sel:DWORD src1_sel:WORD_1
	v_or_b32_sdwa v8, v3, v0 dst_sel:DWORD dst_unused:UNUSED_PAD src0_sel:DWORD src1_sel:WORD_0
	global_store_dwordx2 v[6:7], v[8:9], off offset:16
	v_mov_b32_e32 v12, v72
	v_mov_b32_e32 v13, v74
	v_mov_b32_e32 v74, v73
	s_waitcnt vmcnt(15)
	v_and_b32_e32 v15, 0xffff0000, v82
	v_lshlrev_b32_e32 v0, 16, v83
	v_lshlrev_b32_e32 v3, 16, v82
	v_and_b32_e32 v14, 0xffff0000, v83
	v_mul_f32_e32 v9, 0xbfb8aa3b, v15
	v_mul_f32_e32 v8, 0xbfb8aa3b, v3
	v_exp_f32_e32 v10, v9
	v_mul_f32_e32 v9, 0xbfb8aa3b, v0
	v_exp_f32_e32 v8, v8
	v_exp_f32_e32 v9, v9
	v_pk_mul_f32 v[12:13], v[12:13], v[2:3] op_sel_hi:[1,0]
	v_pk_add_f32 v[8:9], v[8:9], 1.0 op_sel_hi:[1,0]
	s_nop 0
	s_nop 0
	v_rcp_f32_e32 v11, v9
	s_nop 0
	v_mul_f32_e32 v9, v0, v11
	s_nop 0
	v_rcp_f32_e32 v0, v8
	s_nop 0
	v_mul_f32_e32 v8, v3, v0
	v_mul_f32_e32 v0, 0xbfb8aa3b, v14
	v_exp_f32_e32 v11, v0
	v_pk_mul_f32 v[8:9], v[12:13], v[8:9]
	v_pk_mul_f32 v[12:13], v[74:75], v[2:3] op_sel_hi:[1,0]
	v_pk_add_f32 v[10:11], v[10:11], 1.0 op_sel_hi:[1,0]
	s_nop 0
	s_nop 0
	v_rcp_f32_e32 v0, v11
	s_nop 0
	v_mul_f32_e32 v11, v14, v0
	s_nop 0
	v_rcp_f32_e32 v0, v10
	s_nop 0
	v_mul_f32_e32 v10, v15, v0
	v_pk_mul_f32 v[10:11], v[12:13], v[10:11]
	v_cvt_pk_bf16_f32 v0, v8, v9
	v_cvt_pk_bf16_f32 v3, v10, v11
	v_and_b32_e32 v8, 0xffff0000, v3
	v_lshlrev_b32_e32 v3, 16, v3
	v_or_b32_sdwa v9, v8, v0 dst_sel:DWORD dst_unused:UNUSED_PAD src0_sel:DWORD src1_sel:WORD_1
	v_or_b32_sdwa v8, v3, v0 dst_sel:DWORD dst_unused:UNUSED_PAD src0_sel:DWORD src1_sel:WORD_0
	global_store_dwordx2 v[6:7], v[8:9], off offset:32
	v_mov_b32_e32 v12, v76
	v_mov_b32_e32 v13, v78
	v_mov_b32_e32 v78, v77
	s_waitcnt vmcnt(15)
	v_and_b32_e32 v15, 0xffff0000, v84
	v_lshlrev_b32_e32 v0, 16, v85
	v_lshlrev_b32_e32 v3, 16, v84
	v_and_b32_e32 v14, 0xffff0000, v85
	v_mul_f32_e32 v9, 0xbfb8aa3b, v15
	v_mul_f32_e32 v8, 0xbfb8aa3b, v3
	v_exp_f32_e32 v10, v9
	v_mul_f32_e32 v9, 0xbfb8aa3b, v0
	v_exp_f32_e32 v8, v8
	v_exp_f32_e32 v9, v9
	v_pk_mul_f32 v[12:13], v[12:13], v[2:3] op_sel_hi:[1,0]
	v_pk_add_f32 v[8:9], v[8:9], 1.0 op_sel_hi:[1,0]
	s_nop 0
	s_nop 0
	v_rcp_f32_e32 v11, v9
	s_nop 0
	v_mul_f32_e32 v9, v0, v11
	s_nop 0
	v_rcp_f32_e32 v0, v8
	s_nop 0
	v_mul_f32_e32 v8, v3, v0
	v_mul_f32_e32 v0, 0xbfb8aa3b, v14
	v_exp_f32_e32 v11, v0
	v_pk_mul_f32 v[8:9], v[12:13], v[8:9]
	v_pk_mul_f32 v[12:13], v[78:79], v[2:3] op_sel_hi:[1,0]
	v_pk_add_f32 v[10:11], v[10:11], 1.0 op_sel_hi:[1,0]
	s_nop 0
	s_nop 0
	v_rcp_f32_e32 v0, v11
	s_nop 0
	v_mul_f32_e32 v11, v14, v0
	s_nop 0
	v_rcp_f32_e32 v0, v10
	s_nop 0
	v_mul_f32_e32 v10, v15, v0
	v_pk_mul_f32 v[10:11], v[12:13], v[10:11]
	v_cvt_pk_bf16_f32 v0, v8, v9
	v_cvt_pk_bf16_f32 v3, v10, v11
	v_and_b32_e32 v8, 0xffff0000, v3
	v_lshlrev_b32_e32 v3, 16, v3
	v_or_b32_sdwa v9, v8, v0 dst_sel:DWORD dst_unused:UNUSED_PAD src0_sel:DWORD src1_sel:WORD_1
	v_or_b32_sdwa v8, v3, v0 dst_sel:DWORD dst_unused:UNUSED_PAD src0_sel:DWORD src1_sel:WORD_0
	global_store_dwordx2 v[6:7], v[8:9], off offset:48
	v_mov_b32_e32 v12, v48
	v_mov_b32_e32 v13, v50
	s_waitcnt vmcnt(15)
	v_and_b32_e32 v15, 0xffff0000, v86
	v_lshlrev_b32_e32 v0, 16, v87
	v_lshlrev_b32_e32 v3, 16, v86
	v_and_b32_e32 v14, 0xffff0000, v87
	v_mul_f32_e32 v9, 0xbfb8aa3b, v15
	v_mul_f32_e32 v8, 0xbfb8aa3b, v3
	v_exp_f32_e32 v10, v9
	v_mul_f32_e32 v9, 0xbfb8aa3b, v0
	v_exp_f32_e32 v8, v8
	v_exp_f32_e32 v9, v9
	v_pk_mul_f32 v[12:13], v[12:13], v[2:3] op_sel_hi:[1,0]
	v_pk_add_f32 v[8:9], v[8:9], 1.0 op_sel_hi:[1,0]
	s_nop 0
	s_nop 0
	v_rcp_f32_e32 v11, v9
	s_nop 0
	v_mul_f32_e32 v9, v0, v11
	s_nop 0
	v_rcp_f32_e32 v0, v8
	s_nop 0
	v_mul_f32_e32 v8, v3, v0
	v_mul_f32_e32 v0, 0xbfb8aa3b, v14
	v_exp_f32_e32 v11, v0
	v_mov_b32_e32 v50, v49
	v_pk_mul_f32 v[8:9], v[12:13], v[8:9]
	v_pk_mul_f32 v[12:13], v[50:51], v[2:3] op_sel_hi:[1,0]
	v_pk_add_f32 v[10:11], v[10:11], 1.0 op_sel_hi:[1,0]
	s_nop 0
	s_nop 0
	v_rcp_f32_e32 v0, v11
	s_nop 0
	v_mul_f32_e32 v11, v14, v0
	s_nop 0
	v_rcp_f32_e32 v0, v10
	s_nop 0
	v_mul_f32_e32 v10, v15, v0
	v_pk_mul_f32 v[10:11], v[12:13], v[10:11]
	v_cvt_pk_bf16_f32 v0, v8, v9
	v_cvt_pk_bf16_f32 v3, v10, v11
	v_and_b32_e32 v8, 0xffff0000, v3
	v_lshlrev_b32_e32 v3, 16, v3
	v_or_b32_sdwa v9, v8, v0 dst_sel:DWORD dst_unused:UNUSED_PAD src0_sel:DWORD src1_sel:WORD_1
	v_or_b32_sdwa v8, v3, v0 dst_sel:DWORD dst_unused:UNUSED_PAD src0_sel:DWORD src1_sel:WORD_0
	global_store_dwordx2 v[6:7], v[8:9], off offset:64
	v_mov_b32_e32 v12, v52
	v_mov_b32_e32 v13, v54
	v_mov_b32_e32 v54, v53
	s_waitcnt vmcnt(15)
	v_and_b32_e32 v15, 0xffff0000, v88
	v_lshlrev_b32_e32 v0, 16, v89
	v_lshlrev_b32_e32 v3, 16, v88
	v_and_b32_e32 v14, 0xffff0000, v89
	v_mul_f32_e32 v9, 0xbfb8aa3b, v15
	v_mul_f32_e32 v8, 0xbfb8aa3b, v3
	v_exp_f32_e32 v10, v9
	v_mul_f32_e32 v9, 0xbfb8aa3b, v0
	v_exp_f32_e32 v8, v8
	v_exp_f32_e32 v9, v9
	v_pk_mul_f32 v[12:13], v[12:13], v[2:3] op_sel_hi:[1,0]
	v_pk_add_f32 v[8:9], v[8:9], 1.0 op_sel_hi:[1,0]
	s_nop 0
	s_nop 0
	v_rcp_f32_e32 v11, v9
	s_nop 0
	v_mul_f32_e32 v9, v0, v11
	s_nop 0
	v_rcp_f32_e32 v0, v8
	s_nop 0
	v_mul_f32_e32 v8, v3, v0
	v_mul_f32_e32 v0, 0xbfb8aa3b, v14
	v_exp_f32_e32 v11, v0
	v_pk_mul_f32 v[8:9], v[12:13], v[8:9]
	v_pk_mul_f32 v[12:13], v[54:55], v[2:3] op_sel_hi:[1,0]
	v_pk_add_f32 v[10:11], v[10:11], 1.0 op_sel_hi:[1,0]
	s_nop 0
	s_nop 0
	v_rcp_f32_e32 v0, v11
	s_nop 0
	v_mul_f32_e32 v11, v14, v0
	s_nop 0
	v_rcp_f32_e32 v0, v10
	s_nop 0
	v_mul_f32_e32 v10, v15, v0
	v_pk_mul_f32 v[10:11], v[12:13], v[10:11]
	v_cvt_pk_bf16_f32 v0, v8, v9
	v_cvt_pk_bf16_f32 v3, v10, v11
	v_and_b32_e32 v8, 0xffff0000, v3
	v_lshlrev_b32_e32 v3, 16, v3
	v_or_b32_sdwa v9, v8, v0 dst_sel:DWORD dst_unused:UNUSED_PAD src0_sel:DWORD src1_sel:WORD_1
	v_or_b32_sdwa v8, v3, v0 dst_sel:DWORD dst_unused:UNUSED_PAD src0_sel:DWORD src1_sel:WORD_0
	global_store_dwordx2 v[6:7], v[8:9], off offset:80
	v_mov_b32_e32 v12, v56
	v_mov_b32_e32 v13, v58
	v_mov_b32_e32 v58, v57
	s_waitcnt vmcnt(15)
	v_and_b32_e32 v15, 0xffff0000, v90
	v_lshlrev_b32_e32 v0, 16, v91
	v_lshlrev_b32_e32 v3, 16, v90
	v_and_b32_e32 v14, 0xffff0000, v91
	v_mul_f32_e32 v9, 0xbfb8aa3b, v15
	v_mul_f32_e32 v8, 0xbfb8aa3b, v3
	v_exp_f32_e32 v10, v9
	v_mul_f32_e32 v9, 0xbfb8aa3b, v0
	v_exp_f32_e32 v8, v8
	v_exp_f32_e32 v9, v9
	v_pk_mul_f32 v[12:13], v[12:13], v[2:3] op_sel_hi:[1,0]
	v_pk_add_f32 v[8:9], v[8:9], 1.0 op_sel_hi:[1,0]
	s_nop 0
	s_nop 0
	v_rcp_f32_e32 v11, v9
	s_nop 0
	v_mul_f32_e32 v9, v0, v11
	s_nop 0
	v_rcp_f32_e32 v0, v8
	s_nop 0
	v_mul_f32_e32 v8, v3, v0
	v_mul_f32_e32 v0, 0xbfb8aa3b, v14
	v_exp_f32_e32 v11, v0
	v_pk_mul_f32 v[8:9], v[12:13], v[8:9]
	v_pk_mul_f32 v[12:13], v[58:59], v[2:3] op_sel_hi:[1,0]
	v_pk_add_f32 v[10:11], v[10:11], 1.0 op_sel_hi:[1,0]
	s_nop 0
	s_nop 0
	v_rcp_f32_e32 v0, v11
	s_nop 0
	v_mul_f32_e32 v11, v14, v0
	s_nop 0
	v_rcp_f32_e32 v0, v10
	s_nop 0
	v_mul_f32_e32 v10, v15, v0
	v_pk_mul_f32 v[10:11], v[12:13], v[10:11]
	v_cvt_pk_bf16_f32 v0, v8, v9
	v_cvt_pk_bf16_f32 v3, v10, v11
	v_and_b32_e32 v8, 0xffff0000, v3
	v_lshlrev_b32_e32 v3, 16, v3
	v_or_b32_sdwa v9, v8, v0 dst_sel:DWORD dst_unused:UNUSED_PAD src0_sel:DWORD src1_sel:WORD_1
	v_or_b32_sdwa v8, v3, v0 dst_sel:DWORD dst_unused:UNUSED_PAD src0_sel:DWORD src1_sel:WORD_0
	global_store_dwordx2 v[6:7], v[8:9], off offset:96
	v_mov_b32_e32 v12, v60
	v_mov_b32_e32 v13, v62
	v_mov_b32_e32 v62, v61
	s_waitcnt vmcnt(15)
	v_and_b32_e32 v15, 0xffff0000, v92
	v_lshlrev_b32_e32 v0, 16, v93
	v_lshlrev_b32_e32 v3, 16, v92
	v_and_b32_e32 v14, 0xffff0000, v93
	v_mul_f32_e32 v9, 0xbfb8aa3b, v15
	v_mul_f32_e32 v8, 0xbfb8aa3b, v3
	v_exp_f32_e32 v10, v9
	v_mul_f32_e32 v9, 0xbfb8aa3b, v0
	v_exp_f32_e32 v8, v8
	v_exp_f32_e32 v9, v9
	v_pk_mul_f32 v[12:13], v[12:13], v[2:3] op_sel_hi:[1,0]
	v_pk_add_f32 v[8:9], v[8:9], 1.0 op_sel_hi:[1,0]
	s_nop 0
	s_nop 0
	v_rcp_f32_e32 v11, v9
	s_nop 0
	v_mul_f32_e32 v9, v0, v11
	s_nop 0
	v_rcp_f32_e32 v0, v8
	s_nop 0
	v_mul_f32_e32 v8, v3, v0
	v_mul_f32_e32 v0, 0xbfb8aa3b, v14
	v_exp_f32_e32 v11, v0
	v_pk_mul_f32 v[8:9], v[12:13], v[8:9]
	v_pk_mul_f32 v[12:13], v[62:63], v[2:3] op_sel_hi:[1,0]
	v_pk_add_f32 v[10:11], v[10:11], 1.0 op_sel_hi:[1,0]
	s_nop 0
	s_nop 0
	v_rcp_f32_e32 v0, v11
	s_nop 0
	v_mul_f32_e32 v11, v14, v0
	s_nop 0
	v_rcp_f32_e32 v0, v10
	s_nop 0
	v_mul_f32_e32 v10, v15, v0
	v_pk_mul_f32 v[10:11], v[12:13], v[10:11]
	v_cvt_pk_bf16_f32 v0, v8, v9
	v_cvt_pk_bf16_f32 v3, v10, v11
	v_and_b32_e32 v8, 0xffff0000, v3
	v_lshlrev_b32_e32 v3, 16, v3
	v_or_b32_sdwa v9, v8, v0 dst_sel:DWORD dst_unused:UNUSED_PAD src0_sel:DWORD src1_sel:WORD_1
	v_or_b32_sdwa v8, v3, v0 dst_sel:DWORD dst_unused:UNUSED_PAD src0_sel:DWORD src1_sel:WORD_0
	global_store_dwordx2 v[6:7], v[8:9], off offset:112
	v_mov_b32_e32 v12, v32
	v_mov_b32_e32 v13, v34
	s_waitcnt vmcnt(15)
	v_and_b32_e32 v15, 0xffff0000, v94
	v_lshlrev_b32_e32 v0, 16, v95
	v_lshlrev_b32_e32 v3, 16, v94
	v_and_b32_e32 v14, 0xffff0000, v95
	v_mul_f32_e32 v9, 0xbfb8aa3b, v15
	v_mul_f32_e32 v8, 0xbfb8aa3b, v3
	v_exp_f32_e32 v10, v9
	v_mul_f32_e32 v9, 0xbfb8aa3b, v0
	v_exp_f32_e32 v8, v8
	v_exp_f32_e32 v9, v9
	v_pk_mul_f32 v[12:13], v[12:13], v[2:3] op_sel_hi:[1,0]
	v_pk_add_f32 v[8:9], v[8:9], 1.0 op_sel_hi:[1,0]
	s_nop 0
	s_nop 0
	v_rcp_f32_e32 v11, v9
	s_nop 0
	v_mul_f32_e32 v9, v0, v11
	s_nop 0
	v_rcp_f32_e32 v0, v8
	s_nop 0
	v_mul_f32_e32 v8, v3, v0
	v_mul_f32_e32 v0, 0xbfb8aa3b, v14
	v_exp_f32_e32 v11, v0
	v_mov_b32_e32 v34, v33
	v_pk_mul_f32 v[8:9], v[12:13], v[8:9]
	v_pk_mul_f32 v[12:13], v[34:35], v[2:3] op_sel_hi:[1,0]
	v_pk_add_f32 v[10:11], v[10:11], 1.0 op_sel_hi:[1,0]
	s_nop 0
	s_nop 0
	v_rcp_f32_e32 v0, v11
	s_nop 0
	v_mul_f32_e32 v11, v14, v0
	s_nop 0
	v_rcp_f32_e32 v0, v10
	s_nop 0
	v_mul_f32_e32 v10, v15, v0
	v_pk_mul_f32 v[10:11], v[12:13], v[10:11]
	v_cvt_pk_bf16_f32 v0, v8, v9
	v_cvt_pk_bf16_f32 v3, v10, v11
	v_and_b32_e32 v8, 0xffff0000, v3
	v_lshlrev_b32_e32 v3, 16, v3
	v_or_b32_sdwa v9, v8, v0 dst_sel:DWORD dst_unused:UNUSED_PAD src0_sel:DWORD src1_sel:WORD_1
	v_or_b32_sdwa v8, v3, v0 dst_sel:DWORD dst_unused:UNUSED_PAD src0_sel:DWORD src1_sel:WORD_0
	global_store_dwordx2 v[6:7], v[8:9], off offset:128
	v_mov_b32_e32 v12, v36
	v_mov_b32_e32 v13, v38
	v_mov_b32_e32 v38, v37
	s_waitcnt vmcnt(15)
	v_and_b32_e32 v15, 0xffff0000, v96
	v_lshlrev_b32_e32 v0, 16, v97
	v_lshlrev_b32_e32 v3, 16, v96
	v_and_b32_e32 v14, 0xffff0000, v97
	v_mul_f32_e32 v9, 0xbfb8aa3b, v15
	v_mul_f32_e32 v8, 0xbfb8aa3b, v3
	v_exp_f32_e32 v10, v9
	v_mul_f32_e32 v9, 0xbfb8aa3b, v0
	v_exp_f32_e32 v8, v8
	v_exp_f32_e32 v9, v9
	v_pk_mul_f32 v[12:13], v[12:13], v[2:3] op_sel_hi:[1,0]
	v_pk_add_f32 v[8:9], v[8:9], 1.0 op_sel_hi:[1,0]
	s_nop 0
	s_nop 0
	v_rcp_f32_e32 v11, v9
	s_nop 0
	v_mul_f32_e32 v9, v0, v11
	s_nop 0
	v_rcp_f32_e32 v0, v8
	s_nop 0
	v_mul_f32_e32 v8, v3, v0
	v_mul_f32_e32 v0, 0xbfb8aa3b, v14
	v_exp_f32_e32 v11, v0
	v_pk_mul_f32 v[8:9], v[12:13], v[8:9]
	v_pk_mul_f32 v[12:13], v[38:39], v[2:3] op_sel_hi:[1,0]
	v_pk_add_f32 v[10:11], v[10:11], 1.0 op_sel_hi:[1,0]
	s_nop 0
	s_nop 0
	v_rcp_f32_e32 v0, v11
	s_nop 0
	v_mul_f32_e32 v11, v14, v0
	s_nop 0
	v_rcp_f32_e32 v0, v10
	s_nop 0
	v_mul_f32_e32 v10, v15, v0
	v_pk_mul_f32 v[10:11], v[12:13], v[10:11]
	v_cvt_pk_bf16_f32 v0, v8, v9
	v_cvt_pk_bf16_f32 v3, v10, v11
	v_and_b32_e32 v8, 0xffff0000, v3
	v_lshlrev_b32_e32 v3, 16, v3
	v_or_b32_sdwa v9, v8, v0 dst_sel:DWORD dst_unused:UNUSED_PAD src0_sel:DWORD src1_sel:WORD_1
	v_or_b32_sdwa v8, v3, v0 dst_sel:DWORD dst_unused:UNUSED_PAD src0_sel:DWORD src1_sel:WORD_0
	global_store_dwordx2 v[6:7], v[8:9], off offset:144
	v_mov_b32_e32 v12, v40
	v_mov_b32_e32 v13, v42
	v_mov_b32_e32 v42, v41
	s_waitcnt vmcnt(15)
	v_and_b32_e32 v15, 0xffff0000, v98
	v_lshlrev_b32_e32 v0, 16, v99
	v_lshlrev_b32_e32 v3, 16, v98
	v_and_b32_e32 v14, 0xffff0000, v99
	v_mul_f32_e32 v9, 0xbfb8aa3b, v15
	v_mul_f32_e32 v8, 0xbfb8aa3b, v3
	v_exp_f32_e32 v10, v9
	v_mul_f32_e32 v9, 0xbfb8aa3b, v0
	v_exp_f32_e32 v8, v8
	v_exp_f32_e32 v9, v9
	v_pk_mul_f32 v[12:13], v[12:13], v[2:3] op_sel_hi:[1,0]
	v_pk_add_f32 v[8:9], v[8:9], 1.0 op_sel_hi:[1,0]
	s_nop 0
	s_nop 0
	v_rcp_f32_e32 v11, v9
	s_nop 0
	v_mul_f32_e32 v9, v0, v11
	s_nop 0
	v_rcp_f32_e32 v0, v8
	s_nop 0
	v_mul_f32_e32 v8, v3, v0
	v_mul_f32_e32 v0, 0xbfb8aa3b, v14
	v_exp_f32_e32 v11, v0
	v_pk_mul_f32 v[8:9], v[12:13], v[8:9]
	v_pk_mul_f32 v[12:13], v[42:43], v[2:3] op_sel_hi:[1,0]
	v_pk_add_f32 v[10:11], v[10:11], 1.0 op_sel_hi:[1,0]
	s_nop 0
	s_nop 0
	v_rcp_f32_e32 v0, v11
	s_nop 0
	v_mul_f32_e32 v11, v14, v0
	s_nop 0
	v_rcp_f32_e32 v0, v10
	s_nop 0
	v_mul_f32_e32 v10, v15, v0
	v_pk_mul_f32 v[10:11], v[12:13], v[10:11]
	v_cvt_pk_bf16_f32 v0, v8, v9
	v_cvt_pk_bf16_f32 v3, v10, v11
	v_and_b32_e32 v8, 0xffff0000, v3
	v_lshlrev_b32_e32 v3, 16, v3
	v_or_b32_sdwa v9, v8, v0 dst_sel:DWORD dst_unused:UNUSED_PAD src0_sel:DWORD src1_sel:WORD_1
	v_or_b32_sdwa v8, v3, v0 dst_sel:DWORD dst_unused:UNUSED_PAD src0_sel:DWORD src1_sel:WORD_0
	global_store_dwordx2 v[6:7], v[8:9], off offset:160
	v_mov_b32_e32 v12, v44
	v_mov_b32_e32 v13, v46
	v_mov_b32_e32 v46, v45
	s_waitcnt vmcnt(15)
	v_and_b32_e32 v15, 0xffff0000, v100
	v_lshlrev_b32_e32 v0, 16, v101
	v_lshlrev_b32_e32 v3, 16, v100
	v_and_b32_e32 v14, 0xffff0000, v101
	v_mul_f32_e32 v9, 0xbfb8aa3b, v15
	v_mul_f32_e32 v8, 0xbfb8aa3b, v3
	v_exp_f32_e32 v10, v9
	v_mul_f32_e32 v9, 0xbfb8aa3b, v0
	v_exp_f32_e32 v8, v8
	v_exp_f32_e32 v9, v9
	v_pk_mul_f32 v[12:13], v[12:13], v[2:3] op_sel_hi:[1,0]
	v_pk_add_f32 v[8:9], v[8:9], 1.0 op_sel_hi:[1,0]
	s_nop 0
	s_nop 0
	v_rcp_f32_e32 v11, v9
	s_nop 0
	v_mul_f32_e32 v9, v0, v11
	s_nop 0
	v_rcp_f32_e32 v0, v8
	s_nop 0
	v_mul_f32_e32 v8, v3, v0
	v_mul_f32_e32 v0, 0xbfb8aa3b, v14
	v_exp_f32_e32 v11, v0
	v_pk_mul_f32 v[8:9], v[12:13], v[8:9]
	v_pk_mul_f32 v[12:13], v[46:47], v[2:3] op_sel_hi:[1,0]
	v_pk_add_f32 v[10:11], v[10:11], 1.0 op_sel_hi:[1,0]
	s_nop 0
	s_nop 0
	v_rcp_f32_e32 v0, v11
	s_nop 0
	v_mul_f32_e32 v11, v14, v0
	s_nop 0
	v_rcp_f32_e32 v0, v10
	s_nop 0
	v_mul_f32_e32 v10, v15, v0
	v_pk_mul_f32 v[10:11], v[12:13], v[10:11]
	v_cvt_pk_bf16_f32 v0, v8, v9
	v_cvt_pk_bf16_f32 v3, v10, v11
	v_and_b32_e32 v8, 0xffff0000, v3
	v_lshlrev_b32_e32 v3, 16, v3
	v_or_b32_sdwa v9, v8, v0 dst_sel:DWORD dst_unused:UNUSED_PAD src0_sel:DWORD src1_sel:WORD_1
	v_or_b32_sdwa v8, v3, v0 dst_sel:DWORD dst_unused:UNUSED_PAD src0_sel:DWORD src1_sel:WORD_0
	global_store_dwordx2 v[6:7], v[8:9], off offset:176
	v_mov_b32_e32 v12, v16
	v_mov_b32_e32 v13, v18
	s_waitcnt vmcnt(15)
	v_and_b32_e32 v15, 0xffff0000, v102
	v_lshlrev_b32_e32 v0, 16, v103
	v_lshlrev_b32_e32 v3, 16, v102
	v_and_b32_e32 v14, 0xffff0000, v103
	v_mul_f32_e32 v9, 0xbfb8aa3b, v15
	v_mul_f32_e32 v8, 0xbfb8aa3b, v3
	v_exp_f32_e32 v10, v9
	v_mul_f32_e32 v9, 0xbfb8aa3b, v0
	v_exp_f32_e32 v8, v8
	v_exp_f32_e32 v9, v9
	v_pk_mul_f32 v[12:13], v[12:13], v[2:3] op_sel_hi:[1,0]
	v_pk_add_f32 v[8:9], v[8:9], 1.0 op_sel_hi:[1,0]
	s_nop 0
	s_nop 0
	v_rcp_f32_e32 v11, v9
	s_nop 0
	v_mul_f32_e32 v9, v0, v11
	s_nop 0
	v_rcp_f32_e32 v0, v8
	s_nop 0
	v_mul_f32_e32 v8, v3, v0
	v_mul_f32_e32 v0, 0xbfb8aa3b, v14
	v_exp_f32_e32 v11, v0
	v_mov_b32_e32 v18, v17
	v_pk_mul_f32 v[8:9], v[12:13], v[8:9]
	v_pk_mul_f32 v[12:13], v[18:19], v[2:3] op_sel_hi:[1,0]
	v_pk_add_f32 v[10:11], v[10:11], 1.0 op_sel_hi:[1,0]
	s_nop 0
	s_nop 0
	v_rcp_f32_e32 v0, v11
	s_nop 0
	v_mul_f32_e32 v11, v14, v0
	s_nop 0
	v_rcp_f32_e32 v0, v10
	s_nop 0
	v_mul_f32_e32 v10, v15, v0
	v_pk_mul_f32 v[10:11], v[12:13], v[10:11]
	v_cvt_pk_bf16_f32 v0, v8, v9
	v_cvt_pk_bf16_f32 v3, v10, v11
	v_and_b32_e32 v8, 0xffff0000, v3
	v_lshlrev_b32_e32 v3, 16, v3
	v_or_b32_sdwa v9, v8, v0 dst_sel:DWORD dst_unused:UNUSED_PAD src0_sel:DWORD src1_sel:WORD_1
	v_or_b32_sdwa v8, v3, v0 dst_sel:DWORD dst_unused:UNUSED_PAD src0_sel:DWORD src1_sel:WORD_0
	global_store_dwordx2 v[6:7], v[8:9], off offset:192
	v_mov_b32_e32 v12, v20
	v_mov_b32_e32 v13, v22
	v_mov_b32_e32 v22, v21
	s_waitcnt vmcnt(15)
	v_and_b32_e32 v15, 0xffff0000, v104
	v_lshlrev_b32_e32 v0, 16, v105
	v_lshlrev_b32_e32 v3, 16, v104
	v_and_b32_e32 v14, 0xffff0000, v105
	v_mul_f32_e32 v9, 0xbfb8aa3b, v15
	v_mul_f32_e32 v8, 0xbfb8aa3b, v3
	v_exp_f32_e32 v10, v9
	v_mul_f32_e32 v9, 0xbfb8aa3b, v0
	v_exp_f32_e32 v8, v8
	v_exp_f32_e32 v9, v9
	v_pk_mul_f32 v[12:13], v[12:13], v[2:3] op_sel_hi:[1,0]
	v_pk_add_f32 v[8:9], v[8:9], 1.0 op_sel_hi:[1,0]
	s_nop 0
	s_nop 0
	v_rcp_f32_e32 v11, v9
	s_nop 0
	v_mul_f32_e32 v9, v0, v11
	s_nop 0
	v_rcp_f32_e32 v0, v8
	s_nop 0
	v_mul_f32_e32 v8, v3, v0
	v_mul_f32_e32 v0, 0xbfb8aa3b, v14
	v_exp_f32_e32 v11, v0
	v_pk_mul_f32 v[8:9], v[12:13], v[8:9]
	v_pk_mul_f32 v[12:13], v[22:23], v[2:3] op_sel_hi:[1,0]
	v_pk_add_f32 v[10:11], v[10:11], 1.0 op_sel_hi:[1,0]
	s_nop 0
	s_nop 0
	v_rcp_f32_e32 v0, v11
	s_nop 0
	v_mul_f32_e32 v11, v14, v0
	s_nop 0
	v_rcp_f32_e32 v0, v10
	s_nop 0
	v_mul_f32_e32 v10, v15, v0
	v_pk_mul_f32 v[10:11], v[12:13], v[10:11]
	v_cvt_pk_bf16_f32 v0, v8, v9
	v_cvt_pk_bf16_f32 v3, v10, v11
	v_and_b32_e32 v8, 0xffff0000, v3
	v_lshlrev_b32_e32 v3, 16, v3
	v_or_b32_sdwa v9, v8, v0 dst_sel:DWORD dst_unused:UNUSED_PAD src0_sel:DWORD src1_sel:WORD_1
	v_or_b32_sdwa v8, v3, v0 dst_sel:DWORD dst_unused:UNUSED_PAD src0_sel:DWORD src1_sel:WORD_0
	global_store_dwordx2 v[6:7], v[8:9], off offset:208
	v_mov_b32_e32 v12, v24
	v_mov_b32_e32 v13, v26
	v_mov_b32_e32 v26, v25
	s_waitcnt vmcnt(15)
	v_and_b32_e32 v15, 0xffff0000, v106
	v_lshlrev_b32_e32 v0, 16, v107
	v_lshlrev_b32_e32 v3, 16, v106
	v_and_b32_e32 v14, 0xffff0000, v107
	v_mul_f32_e32 v9, 0xbfb8aa3b, v15
	v_mul_f32_e32 v8, 0xbfb8aa3b, v3
	v_exp_f32_e32 v10, v9
	v_mul_f32_e32 v9, 0xbfb8aa3b, v0
	v_exp_f32_e32 v8, v8
	v_exp_f32_e32 v9, v9
	v_pk_mul_f32 v[12:13], v[12:13], v[2:3] op_sel_hi:[1,0]
	v_pk_add_f32 v[8:9], v[8:9], 1.0 op_sel_hi:[1,0]
	s_nop 0
	s_nop 0
	v_rcp_f32_e32 v11, v9
	s_nop 0
	v_mul_f32_e32 v9, v0, v11
	s_nop 0
	v_rcp_f32_e32 v0, v8
	s_nop 0
	v_mul_f32_e32 v8, v3, v0
	v_mul_f32_e32 v0, 0xbfb8aa3b, v14
	v_exp_f32_e32 v11, v0
	v_pk_mul_f32 v[8:9], v[12:13], v[8:9]
	v_pk_mul_f32 v[12:13], v[26:27], v[2:3] op_sel_hi:[1,0]
	v_pk_add_f32 v[10:11], v[10:11], 1.0 op_sel_hi:[1,0]
	s_nop 0
	s_nop 0
	v_rcp_f32_e32 v0, v11
	s_nop 0
	v_mul_f32_e32 v11, v14, v0
	s_nop 0
	v_rcp_f32_e32 v0, v10
	s_nop 0
	v_mul_f32_e32 v10, v15, v0
	v_pk_mul_f32 v[10:11], v[12:13], v[10:11]
	v_cvt_pk_bf16_f32 v0, v8, v9
	v_cvt_pk_bf16_f32 v3, v10, v11
	v_and_b32_e32 v8, 0xffff0000, v3
	v_lshlrev_b32_e32 v3, 16, v3
	v_or_b32_sdwa v9, v8, v0 dst_sel:DWORD dst_unused:UNUSED_PAD src0_sel:DWORD src1_sel:WORD_1
	v_or_b32_sdwa v8, v3, v0 dst_sel:DWORD dst_unused:UNUSED_PAD src0_sel:DWORD src1_sel:WORD_0
	global_store_dwordx2 v[6:7], v[8:9], off offset:224
	v_mov_b32_e32 v10, v28
	v_mov_b32_e32 v11, v30
	v_mov_b32_e32 v30, v29
	s_waitcnt vmcnt(15)
	v_and_b32_e32 v13, 0xffff0000, v108
	v_lshlrev_b32_e32 v0, 16, v109
	v_lshlrev_b32_e32 v3, 16, v108
	v_and_b32_e32 v12, 0xffff0000, v109
	v_mul_f32_e32 v5, 0xbfb8aa3b, v13
	v_mul_f32_e32 v4, 0xbfb8aa3b, v3
	v_exp_f32_e32 v8, v5
	v_mul_f32_e32 v5, 0xbfb8aa3b, v0
	v_exp_f32_e32 v4, v4
	v_exp_f32_e32 v5, v5
	v_pk_mul_f32 v[10:11], v[10:11], v[2:3] op_sel_hi:[1,0]
	v_pk_add_f32 v[4:5], v[4:5], 1.0 op_sel_hi:[1,0]
	s_nop 0
	s_nop 0
	v_rcp_f32_e32 v9, v5
	s_nop 0
	v_mul_f32_e32 v5, v0, v9
	s_nop 0
	v_rcp_f32_e32 v0, v4
	s_nop 0
	v_mul_f32_e32 v4, v3, v0
	v_mul_f32_e32 v0, 0xbfb8aa3b, v12
	v_exp_f32_e32 v9, v0
	v_pk_mul_f32 v[4:5], v[10:11], v[4:5]
	v_pk_mul_f32 v[2:3], v[30:31], v[2:3] op_sel_hi:[1,0]
	v_pk_add_f32 v[8:9], v[8:9], 1.0 op_sel_hi:[1,0]
	s_nop 0
	s_nop 0
	v_rcp_f32_e32 v0, v9
	s_nop 0
	v_mul_f32_e32 v9, v12, v0
	s_nop 0
	v_rcp_f32_e32 v0, v8
	s_nop 0
	v_mul_f32_e32 v8, v13, v0
	v_pk_mul_f32 v[2:3], v[2:3], v[8:9]
	v_cvt_pk_bf16_f32 v0, v4, v5
	v_cvt_pk_bf16_f32 v2, v2, v3
	v_and_b32_e32 v3, 0xffff0000, v2
	v_lshlrev_b32_e32 v2, 16, v2
	v_or_b32_sdwa v3, v3, v0 dst_sel:DWORD dst_unused:UNUSED_PAD src0_sel:DWORD src1_sel:WORD_1
	v_or_b32_sdwa v2, v2, v0 dst_sel:DWORD dst_unused:UNUSED_PAD src0_sel:DWORD src1_sel:WORD_0
	global_store_dwordx2 v[6:7], v[2:3], off offset:240
	s_branch .LBB0_1209

.LBB0_1334:
	v_add_u32_e32 v0, 0x10000, v148
	ds_read_b128 v[142:145], v0
	ds_read_b128 v[150:153], v0 offset:1024
	ds_read_b128 v[154:157], v0 offset:2048
	ds_read_b128 v[158:161], v0 offset:3072
	s_add_u32 s26, s24, 0xfffc0080
	s_addc_u32 s27, s25, -1
	s_cmp_eq_u32 vcc_lo, 12
	s_cselect_b32 s29, s2, s27
	s_cselect_b32 s28, s15, s26
	s_cselect_b32 s27, s13, s94
	s_cselect_b32 s26, s89, s90
	v_lshl_add_u64 v[178:179], s[24:25], 0, v[138:139]
	s_add_i32 m0, s36, 0xc000
	ds_read_b128 v[162:165], v147
	ds_read_b128 v[166:169], v147 offset:1024
	ds_read_b128 v[170:173], v147 offset:2048
	ds_read_b128 v[174:177], v147 offset:3072
	ds_read_b128 v[182:185], v147 offset:4096
	ds_read_b128 v[186:189], v147 offset:5120
	ds_read_b128 v[190:193], v147 offset:6144
	ds_read_b128 v[194:197], v147 offset:7168
	global_load_lds_dwordx4 v[178:179], off
	v_lshl_add_u64 v[178:179], s[24:25], 0, v[140:141]
	s_add_i32 m0, s36, 0xe000
	s_nop 0
	global_load_lds_dwordx4 v[178:179], off
	s_waitcnt lgkmcnt(8)
	s_barrier
	s_waitcnt lgkmcnt(0)
	s_setprio 1
	s_waitcnt lgkmcnt(0)
	v_mfma_f32_16x16x32_bf16 v[126:129], v[142:145], v[162:165], v[126:129]
	v_mfma_f32_16x16x32_bf16 v[122:125], v[154:157], v[162:165], v[122:125]
	v_mfma_f32_16x16x32_bf16 v[110:113], v[142:145], v[170:173], v[110:113]
	v_mfma_f32_16x16x32_bf16 v[106:109], v[154:157], v[170:173], v[106:109]
	v_mfma_f32_16x16x32_bf16 v[94:97], v[142:145], v[182:185], v[94:97]
	v_mfma_f32_16x16x32_bf16 v[90:93], v[154:157], v[182:185], v[90:93]
	v_mfma_f32_16x16x32_bf16 v[78:81], v[142:145], v[190:193], v[78:81]
	v_mfma_f32_16x16x32_bf16 v[74:77], v[154:157], v[190:193], v[74:77]
	v_mfma_f32_16x16x32_bf16 v[126:129], v[150:153], v[166:169], v[126:129]
	v_mfma_f32_16x16x32_bf16 v[122:125], v[158:161], v[166:169], v[122:125]
	v_mfma_f32_16x16x32_bf16 v[110:113], v[150:153], v[174:177], v[110:113]
	v_mfma_f32_16x16x32_bf16 v[106:109], v[158:161], v[174:177], v[106:109]
	v_mfma_f32_16x16x32_bf16 v[94:97], v[150:153], v[186:189], v[94:97]
	v_mfma_f32_16x16x32_bf16 v[90:93], v[158:161], v[186:189], v[90:93]
	v_mfma_f32_16x16x32_bf16 v[78:81], v[150:153], v[194:197], v[78:81]
	v_mfma_f32_16x16x32_bf16 v[74:77], v[158:161], v[194:197], v[74:77]
	s_setprio 0
	s_barrier
	s_mov_b32 m0, s21
	v_add_u32_e32 v0, 0x14000, v148
	v_lshl_add_u64 v[178:179], s[26:27], 0, v[134:135]
	ds_read_b128 v[198:201], v0
	ds_read_b128 v[202:205], v0 offset:1024
	ds_read_b128 v[206:209], v0 offset:2048
	ds_read_b128 v[210:213], v0 offset:3072
	global_load_lds_dwordx4 v[178:179], off
	v_lshl_add_u64 v[214:215], s[26:27], 0, v[130:131]
	s_mov_b32 m0, s23
	s_nop 0
	global_load_lds_dwordx4 v[214:215], off
	s_barrier
	s_waitcnt lgkmcnt(0)
	s_setprio 1
	s_waitcnt lgkmcnt(0)
	v_mfma_f32_16x16x32_bf16 v[118:121], v[198:201], v[162:165], v[118:121]
	v_mfma_f32_16x16x32_bf16 v[114:117], v[206:209], v[162:165], v[114:117]
	v_mfma_f32_16x16x32_bf16 v[102:105], v[198:201], v[170:173], v[102:105]
	v_mfma_f32_16x16x32_bf16 v[98:101], v[206:209], v[170:173], v[98:101]
	v_mfma_f32_16x16x32_bf16 v[86:89], v[198:201], v[182:185], v[86:89]
	v_mfma_f32_16x16x32_bf16 v[82:85], v[206:209], v[182:185], v[82:85]
	v_mfma_f32_16x16x32_bf16 v[70:73], v[198:201], v[190:193], v[70:73]
	v_mfma_f32_16x16x32_bf16 v[66:69], v[206:209], v[190:193], v[66:69]
	v_mfma_f32_16x16x32_bf16 v[118:121], v[202:205], v[166:169], v[118:121]
	v_mfma_f32_16x16x32_bf16 v[114:117], v[210:213], v[166:169], v[114:117]
	v_mfma_f32_16x16x32_bf16 v[102:105], v[202:205], v[174:177], v[102:105]
	v_mfma_f32_16x16x32_bf16 v[98:101], v[210:213], v[174:177], v[98:101]
	v_mfma_f32_16x16x32_bf16 v[86:89], v[202:205], v[186:189], v[86:89]
	v_mfma_f32_16x16x32_bf16 v[82:85], v[210:213], v[186:189], v[82:85]
	v_mfma_f32_16x16x32_bf16 v[70:73], v[202:205], v[194:197], v[70:73]
	v_mfma_f32_16x16x32_bf16 v[66:69], v[210:213], v[194:197], v[66:69]
	s_setprio 0
	s_mov_b32 m0, s36
	v_lshl_add_u64 v[216:217], s[28:29], 0, v[136:137]
	s_barrier
	ds_read_b128 v[162:165], v147 offset:16384
	ds_read_b128 v[166:169], v147 offset:17408
	ds_read_b128 v[170:173], v147 offset:18432
	ds_read_b128 v[174:177], v147 offset:19456
	ds_read_b128 v[182:185], v147 offset:20480
	ds_read_b128 v[186:189], v147 offset:21504
	ds_read_b128 v[190:193], v147 offset:22528
	ds_read_b128 v[194:197], v147 offset:23552
	global_load_lds_dwordx4 v[216:217], off
	v_lshl_add_u64 v[222:223], s[28:29], 0, v[132:133]
	s_mov_b32 m0, s37
	s_nop 0
	global_load_lds_dwordx4 v[222:223], off
	s_barrier
	s_waitcnt lgkmcnt(0)
	s_setprio 1
	s_waitcnt lgkmcnt(0)
	v_mfma_f32_16x16x32_bf16 v[62:65], v[142:145], v[162:165], v[62:65]
	v_mfma_f32_16x16x32_bf16 v[58:61], v[154:157], v[162:165], v[58:61]
	v_mfma_f32_16x16x32_bf16 v[46:49], v[142:145], v[170:173], v[46:49]
	v_mfma_f32_16x16x32_bf16 v[42:45], v[154:157], v[170:173], v[42:45]
	v_mfma_f32_16x16x32_bf16 v[30:33], v[142:145], v[182:185], v[30:33]
	v_mfma_f32_16x16x32_bf16 v[26:29], v[154:157], v[182:185], v[26:29]
	v_mfma_f32_16x16x32_bf16 v[14:17], v[142:145], v[190:193], v[14:17]
	v_mfma_f32_16x16x32_bf16 v[10:13], v[154:157], v[190:193], v[10:13]
	v_mfma_f32_16x16x32_bf16 v[62:65], v[150:153], v[166:169], v[62:65]
	v_mfma_f32_16x16x32_bf16 v[58:61], v[158:161], v[166:169], v[58:61]
	v_mfma_f32_16x16x32_bf16 v[46:49], v[150:153], v[174:177], v[46:49]
	v_mfma_f32_16x16x32_bf16 v[42:45], v[158:161], v[174:177], v[42:45]
	v_mfma_f32_16x16x32_bf16 v[30:33], v[150:153], v[186:189], v[30:33]
	v_mfma_f32_16x16x32_bf16 v[26:29], v[158:161], v[186:189], v[26:29]
	v_mfma_f32_16x16x32_bf16 v[14:17], v[150:153], v[194:197], v[14:17]
	v_mfma_f32_16x16x32_bf16 v[10:13], v[158:161], v[194:197], v[10:13]
	s_setprio 0
	s_barrier
	s_add_u32 s76, s26, 0x40000
	s_addc_u32 s77, s27, 0
	s_mov_b32 m0, s38
	v_lshl_add_u64 v[142:143], s[76:77], 0, v[134:135]
	global_load_lds_dwordx4 v[142:143], off
	v_lshl_add_u64 v[142:143], s[76:77], 0, v[130:131]
	s_mov_b32 m0, s39
	s_nop 0
	global_load_lds_dwordx4 v[142:143], off
	s_waitcnt vmcnt(6)
	s_barrier
	s_setprio 1
	v_mfma_f32_16x16x32_bf16 v[54:57], v[198:201], v[162:165], v[54:57]
	v_mfma_f32_16x16x32_bf16 v[50:53], v[206:209], v[162:165], v[50:53]
	v_mfma_f32_16x16x32_bf16 v[38:41], v[198:201], v[170:173], v[38:41]
	v_mfma_f32_16x16x32_bf16 v[34:37], v[206:209], v[170:173], v[34:37]
	v_mfma_f32_16x16x32_bf16 v[22:25], v[198:201], v[182:185], v[22:25]
	v_mfma_f32_16x16x32_bf16 v[18:21], v[206:209], v[182:185], v[18:21]
	v_mfma_f32_16x16x32_bf16 v[6:9], v[198:201], v[190:193], v[6:9]
	v_mfma_f32_16x16x32_bf16 v[2:5], v[206:209], v[190:193], v[2:5]
	v_mfma_f32_16x16x32_bf16 v[54:57], v[202:205], v[166:169], v[54:57]
	v_mfma_f32_16x16x32_bf16 v[50:53], v[210:213], v[166:169], v[50:53]
	v_mfma_f32_16x16x32_bf16 v[38:41], v[202:205], v[174:177], v[38:41]
	v_mfma_f32_16x16x32_bf16 v[34:37], v[210:213], v[174:177], v[34:37]
	v_mfma_f32_16x16x32_bf16 v[22:25], v[202:205], v[186:189], v[22:25]
	v_mfma_f32_16x16x32_bf16 v[18:21], v[210:213], v[186:189], v[18:21]
	v_mfma_f32_16x16x32_bf16 v[6:9], v[202:205], v[194:197], v[6:9]
	v_mfma_f32_16x16x32_bf16 v[2:5], v[210:213], v[194:197], v[2:5]
	s_setprio 0
	v_add_u32_e32 v0, 0x18000, v148
	s_barrier
	ds_read_b128 v[142:145], v0
	ds_read_b128 v[150:153], v0 offset:1024
	ds_read_b128 v[154:157], v0 offset:2048
	ds_read_b128 v[158:161], v0 offset:3072
	s_add_u32 s28, s28, 0x40000
	s_addc_u32 s29, s29, 0
	s_mov_b32 m0, s60
	v_lshl_add_u64 v[198:199], s[28:29], 0, v[136:137]
	ds_read_b128 v[162:165], v147 offset:32768
	ds_read_b128 v[166:169], v147 offset:33792
	ds_read_b128 v[170:173], v147 offset:34816
	ds_read_b128 v[174:177], v147 offset:35840
	ds_read_b128 v[182:185], v147 offset:36864
	ds_read_b128 v[186:189], v147 offset:37888
	ds_read_b128 v[190:193], v147 offset:38912
	ds_read_b128 v[194:197], v147 offset:39936
	global_load_lds_dwordx4 v[198:199], off
	v_lshl_add_u64 v[198:199], s[28:29], 0, v[132:133]
	s_mov_b32 m0, s68
	s_nop 0
	global_load_lds_dwordx4 v[198:199], off
	s_waitcnt lgkmcnt(8)
	s_barrier
	s_waitcnt lgkmcnt(0)
	s_setprio 1
	s_waitcnt lgkmcnt(0)
	v_mfma_f32_16x16x32_bf16 v[126:129], v[142:145], v[162:165], v[126:129]
	v_mfma_f32_16x16x32_bf16 v[122:125], v[154:157], v[162:165], v[122:125]
	v_mfma_f32_16x16x32_bf16 v[110:113], v[142:145], v[170:173], v[110:113]
	v_mfma_f32_16x16x32_bf16 v[106:109], v[154:157], v[170:173], v[106:109]
	v_mfma_f32_16x16x32_bf16 v[94:97], v[142:145], v[182:185], v[94:97]
	v_mfma_f32_16x16x32_bf16 v[90:93], v[154:157], v[182:185], v[90:93]
	v_mfma_f32_16x16x32_bf16 v[78:81], v[142:145], v[190:193], v[78:81]
	v_mfma_f32_16x16x32_bf16 v[74:77], v[154:157], v[190:193], v[74:77]
	v_mfma_f32_16x16x32_bf16 v[126:129], v[150:153], v[166:169], v[126:129]
	v_mfma_f32_16x16x32_bf16 v[122:125], v[158:161], v[166:169], v[122:125]
	v_mfma_f32_16x16x32_bf16 v[110:113], v[150:153], v[174:177], v[110:113]
	v_mfma_f32_16x16x32_bf16 v[106:109], v[158:161], v[174:177], v[106:109]
	v_mfma_f32_16x16x32_bf16 v[94:97], v[150:153], v[186:189], v[94:97]
	v_mfma_f32_16x16x32_bf16 v[90:93], v[158:161], v[186:189], v[90:93]
	v_mfma_f32_16x16x32_bf16 v[78:81], v[150:153], v[194:197], v[78:81]
	v_mfma_f32_16x16x32_bf16 v[74:77], v[158:161], v[194:197], v[74:77]
	s_setprio 0
	s_barrier
	s_mov_b32 m0, s69
	v_add_u32_e32 v0, 0x1c000, v148
	v_lshl_add_u64 v[178:179], v[178:179], 0, s[84:85]
	ds_read_b128 v[198:201], v0
	ds_read_b128 v[202:205], v0 offset:1024
	ds_read_b128 v[206:209], v0 offset:2048
	ds_read_b128 v[210:213], v0 offset:3072
	global_load_lds_dwordx4 v[178:179], off
	v_lshl_add_u64 v[178:179], v[214:215], 0, s[84:85]
	s_mov_b32 m0, s75
	s_nop 0
	global_load_lds_dwordx4 v[178:179], off
	s_barrier
	s_waitcnt lgkmcnt(0)
	s_setprio 1
	s_waitcnt lgkmcnt(0)
	v_mfma_f32_16x16x32_bf16 v[118:121], v[198:201], v[162:165], v[118:121]
	v_mfma_f32_16x16x32_bf16 v[114:117], v[206:209], v[162:165], v[114:117]
	v_mfma_f32_16x16x32_bf16 v[102:105], v[198:201], v[170:173], v[102:105]
	v_mfma_f32_16x16x32_bf16 v[98:101], v[206:209], v[170:173], v[98:101]
	v_mfma_f32_16x16x32_bf16 v[86:89], v[198:201], v[182:185], v[86:89]
	v_mfma_f32_16x16x32_bf16 v[82:85], v[206:209], v[182:185], v[82:85]
	v_mfma_f32_16x16x32_bf16 v[70:73], v[198:201], v[190:193], v[70:73]
	v_mfma_f32_16x16x32_bf16 v[66:69], v[206:209], v[190:193], v[66:69]
	v_mfma_f32_16x16x32_bf16 v[118:121], v[202:205], v[166:169], v[118:121]
	v_mfma_f32_16x16x32_bf16 v[114:117], v[210:213], v[166:169], v[114:117]
	v_mfma_f32_16x16x32_bf16 v[102:105], v[202:205], v[174:177], v[102:105]
	v_mfma_f32_16x16x32_bf16 v[98:101], v[210:213], v[174:177], v[98:101]
	v_mfma_f32_16x16x32_bf16 v[86:89], v[202:205], v[186:189], v[86:89]
	v_mfma_f32_16x16x32_bf16 v[82:85], v[210:213], v[186:189], v[82:85]
	v_mfma_f32_16x16x32_bf16 v[70:73], v[202:205], v[194:197], v[70:73]
	v_mfma_f32_16x16x32_bf16 v[66:69], v[210:213], v[194:197], v[66:69]
	s_setprio 0
	s_mov_b32 m0, s82
	v_lshl_add_u64 v[178:179], v[216:217], 0, s[84:85]
	s_barrier
	ds_read_b128 v[162:165], v147 offset:49152
	ds_read_b128 v[166:169], v147 offset:50176
	ds_read_b128 v[170:173], v147 offset:51200
	ds_read_b128 v[174:177], v147 offset:52224
	ds_read_b128 v[182:185], v147 offset:53248
	ds_read_b128 v[186:189], v147 offset:54272
	ds_read_b128 v[190:193], v147 offset:55296
	ds_read_b128 v[194:197], v147 offset:56320
	global_load_lds_dwordx4 v[178:179], off
	v_lshl_add_u64 v[178:179], v[222:223], 0, s[84:85]
	s_mov_b32 m0, s92
	s_nop 0
	global_load_lds_dwordx4 v[178:179], off
	s_barrier
	s_waitcnt lgkmcnt(0)
	s_setprio 1
	s_waitcnt lgkmcnt(0)
	v_mfma_f32_16x16x32_bf16 v[62:65], v[142:145], v[162:165], v[62:65]
	v_mfma_f32_16x16x32_bf16 v[58:61], v[154:157], v[162:165], v[58:61]
	v_mfma_f32_16x16x32_bf16 v[46:49], v[142:145], v[170:173], v[46:49]
	v_mfma_f32_16x16x32_bf16 v[42:45], v[154:157], v[170:173], v[42:45]
	v_mfma_f32_16x16x32_bf16 v[30:33], v[142:145], v[182:185], v[30:33]
	v_mfma_f32_16x16x32_bf16 v[26:29], v[154:157], v[182:185], v[26:29]
	v_mfma_f32_16x16x32_bf16 v[14:17], v[142:145], v[190:193], v[14:17]
	v_mfma_f32_16x16x32_bf16 v[10:13], v[154:157], v[190:193], v[10:13]
	v_mfma_f32_16x16x32_bf16 v[62:65], v[150:153], v[166:169], v[62:65]
	v_mfma_f32_16x16x32_bf16 v[58:61], v[158:161], v[166:169], v[58:61]
	v_mfma_f32_16x16x32_bf16 v[46:49], v[150:153], v[174:177], v[46:49]
	v_mfma_f32_16x16x32_bf16 v[42:45], v[158:161], v[174:177], v[42:45]
	v_mfma_f32_16x16x32_bf16 v[30:33], v[150:153], v[186:189], v[30:33]
	v_mfma_f32_16x16x32_bf16 v[26:29], v[158:161], v[186:189], v[26:29]
	v_mfma_f32_16x16x32_bf16 v[14:17], v[150:153], v[194:197], v[14:17]
	v_mfma_f32_16x16x32_bf16 v[10:13], v[158:161], v[194:197], v[10:13]
	s_setprio 0
	s_barrier
	s_add_u32 s26, s26, 0x40080
	s_addc_u32 s27, s27, 0
	s_mov_b32 m0, s93
	v_lshl_add_u64 v[142:143], s[26:27], 0, v[134:135]
	global_load_lds_dwordx4 v[142:143], off
	v_lshl_add_u64 v[142:143], s[26:27], 0, v[130:131]
	s_mov_b32 m0, s96
	s_nop 0
	global_load_lds_dwordx4 v[142:143], off
	s_waitcnt vmcnt(6)
	s_barrier
	s_setprio 1
	v_mfma_f32_16x16x32_bf16 v[54:57], v[198:201], v[162:165], v[54:57]
	v_mfma_f32_16x16x32_bf16 v[50:53], v[206:209], v[162:165], v[50:53]
	v_mfma_f32_16x16x32_bf16 v[38:41], v[198:201], v[170:173], v[38:41]
	v_mfma_f32_16x16x32_bf16 v[34:37], v[206:209], v[170:173], v[34:37]
	v_mfma_f32_16x16x32_bf16 v[22:25], v[198:201], v[182:185], v[22:25]
	v_mfma_f32_16x16x32_bf16 v[18:21], v[206:209], v[182:185], v[18:21]
	v_mfma_f32_16x16x32_bf16 v[6:9], v[198:201], v[190:193], v[6:9]
	v_mfma_f32_16x16x32_bf16 v[2:5], v[206:209], v[190:193], v[2:5]
	v_mfma_f32_16x16x32_bf16 v[54:57], v[202:205], v[166:169], v[54:57]
	v_mfma_f32_16x16x32_bf16 v[50:53], v[210:213], v[166:169], v[50:53]
	v_mfma_f32_16x16x32_bf16 v[38:41], v[202:205], v[174:177], v[38:41]
	v_mfma_f32_16x16x32_bf16 v[34:37], v[210:213], v[174:177], v[34:37]
	v_mfma_f32_16x16x32_bf16 v[22:25], v[202:205], v[186:189], v[22:25]
	v_mfma_f32_16x16x32_bf16 v[18:21], v[210:213], v[186:189], v[18:21]
	v_mfma_f32_16x16x32_bf16 v[6:9], v[202:205], v[194:197], v[6:9]
	v_mfma_f32_16x16x32_bf16 v[2:5], v[210:213], v[194:197], v[2:5]
	s_setprio 0
	s_add_i32 vcc_lo, vcc_lo, 2
	s_add_u32 s24, s24, 0x100
	s_addc_u32 s25, s25, 0
	s_add_u32 s90, s90, 0x100
	s_addc_u32 s94, s94, 0
	s_cmp_gt_u32 vcc_lo, 13
	s_barrier
	s_cbranch_scc0 .LBB0_1334
	v_lshl_add_u32 v152, s22, 8, v146
	v_lshl_add_u32 v150, s20, 8, v149
	v_mul_lo_u32 v151, v152, s71
	v_add_u32_e32 v0, v151, v150
	v_lshl_add_u64 v[142:143], v[0:1], 1, s[8:9]
	global_load_dwordx4 v[142:145], v[142:143], off
	v_mov_b32_e32 v178, v0
	v_mov_b32_e32 v161, 0
	v_add_u32_e32 v160, 0x80, v178
	v_lshl_add_u64 v[162:163], v[160:161], 1, s[8:9]
	global_load_dwordx4 v[162:165], v[162:163], off
	v_add_u32_e32 v160, 0x16c00, v178
	v_lshl_add_u64 v[166:167], v[160:161], 1, s[8:9]
	global_load_dwordx4 v[166:169], v[166:167], off
	v_add_u32_e32 v160, 0x16c80, v178
	v_lshl_add_u64 v[170:171], v[160:161], 1, s[8:9]
	global_load_dwordx4 v[170:173], v[170:171], off
	v_add_u32_e32 v160, 0x2d800, v178
	v_lshl_add_u64 v[174:175], v[160:161], 1, s[8:9]
	global_load_dwordx4 v[174:177], v[174:175], off
	v_add_u32_e32 v160, 0x2d880, v178
	v_lshl_add_u64 v[182:183], v[160:161], 1, s[8:9]
	global_load_dwordx4 v[182:185], v[182:183], off
	v_add_u32_e32 v160, 0x44400, v178
	v_lshl_add_u64 v[186:187], v[160:161], 1, s[8:9]
	global_load_dwordx4 v[186:189], v[186:187], off
	v_add_u32_e32 v160, 0x44480, v178
	v_lshl_add_u64 v[190:191], v[160:161], 1, s[8:9]
	global_load_dwordx4 v[190:193], v[190:191], off
	v_add_u32_e32 v160, 0xb6000, v178
	v_lshl_add_u64 v[194:195], v[160:161], 1, s[8:9]
	global_load_dwordx4 v[194:197], v[194:195], off
	v_add_u32_e32 v160, 0xb6080, v178
	v_lshl_add_u64 v[198:199], v[160:161], 1, s[8:9]
	global_load_dwordx4 v[198:201], v[198:199], off
	v_add_u32_e32 v160, 0xccc00, v178
	v_lshl_add_u64 v[202:203], v[160:161], 1, s[8:9]
	global_load_dwordx4 v[202:205], v[202:203], off
	v_add_u32_e32 v160, 0xccc80, v178
	v_lshl_add_u64 v[206:207], v[160:161], 1, s[8:9]
	global_load_dwordx4 v[206:209], v[206:207], off
	v_add_u32_e32 v160, 0xe3800, v178
	v_lshl_add_u64 v[210:211], v[160:161], 1, s[8:9]
	global_load_dwordx4 v[210:213], v[210:211], off
	s_mov_b32 s20, s12
	s_mov_b32 s22, s14
	s_mov_b64 s[26:27], s[18:19]
	s_waitcnt vmcnt(12)
	v_lshlrev_b32_e32 v153, 16, v142
	v_lshlrev_b32_e32 v155, 16, v143
	v_lshlrev_b32_e32 v156, 16, v144
	v_and_b32_e32 v157, 0xffff0000, v144
	v_lshlrev_b32_e32 v158, 16, v145
	v_and_b32_e32 v159, 0xffff0000, v145
	v_mul_f32_e32 v144, 0xbfb8aa3b, v153
	v_mul_f32_e32 v145, 0xbfb8aa3b, v155
	v_exp_f32_e32 v154, v144
	v_exp_f32_e32 v155, v145
	v_mul_f32_e32 v145, 0xbfb8aa3b, v158
	v_and_b32_e32 v142, 0xffff0000, v142
	v_and_b32_e32 v143, 0xffff0000, v143
	v_pk_add_f32 v[154:155], v[154:155], 1.0 op_sel_hi:[1,0]
	v_mul_f32_e32 v142, 0xbfb8aa3b, v142
	v_mul_f32_e32 v143, 0xbfb8aa3b, v143
	v_mul_f32_e32 v144, 0xbfb8aa3b, v156
	v_exp_f32_e32 v156, v142
	v_mul_f32_e32 v142, 0xbfb8aa3b, v157
	v_exp_f32_e32 v157, v143
	v_mul_f32_e32 v143, 0xbfb8aa3b, v159
	v_rcp_f32_e32 v155, v155
	s_nop 0
	v_pk_add_f32 v[156:157], v[156:157], 1.0 op_sel_hi:[1,0]
	v_exp_f32_e32 v144, v144
	v_exp_f32_e32 v145, v145
	v_mov_b32_e32 v158, v126
	v_mov_b32_e32 v159, v128
	v_rcp_f32_e32 v154, v154
	s_nop 0
	v_pk_mul_f32 v[154:155], v[158:159], v[154:155]
	v_exp_f32_e32 v142, v142
	v_rcp_f32_e32 v157, v157
	s_nop 0
	v_exp_f32_e32 v143, v143
	v_rcp_f32_e32 v156, v156
	s_nop 0
	v_mov_b32_e32 v128, v127
	v_pk_mul_f32 v[126:127], v[128:129], v[156:157]
	v_cvt_pk_bf16_f32 v128, v154, v155
	v_cvt_pk_bf16_f32 v126, v126, v127
	v_and_b32_e32 v127, 0xffff0000, v126
	v_lshlrev_b32_e32 v126, 16, v126
	v_or_b32_sdwa v127, v127, v128 dst_sel:DWORD dst_unused:UNUSED_PAD src0_sel:DWORD src1_sel:WORD_1
	v_or_b32_sdwa v126, v126, v128 dst_sel:DWORD dst_unused:UNUSED_PAD src0_sel:DWORD src1_sel:WORD_0
	v_pk_add_f32 v[128:129], v[144:145], 1.0 op_sel_hi:[1,0]
	v_pk_add_f32 v[142:143], v[142:143], 1.0 op_sel_hi:[1,0]
	s_nop 0
	v_rcp_f32_e32 v129, v129
	s_nop 0
	s_nop 0
	v_rcp_f32_e32 v128, v128
	s_nop 0
	v_mov_b32_e32 v144, v122
	v_mov_b32_e32 v145, v124
	v_pk_mul_f32 v[128:129], v[144:145], v[128:129]
	v_rcp_f32_e32 v143, v143
	s_nop 0
	s_nop 0
	v_rcp_f32_e32 v142, v142
	s_nop 0
	v_mov_b32_e32 v124, v123
	v_pk_mul_f32 v[122:123], v[124:125], v[142:143]
	v_cvt_pk_bf16_f32 v124, v128, v129
	v_cvt_pk_bf16_f32 v122, v122, v123
	v_and_b32_e32 v123, 0xffff0000, v122
	v_lshlrev_b32_e32 v122, 16, v122
	v_or_b32_sdwa v129, v123, v124 dst_sel:DWORD dst_unused:UNUSED_PAD src0_sel:DWORD src1_sel:WORD_1
	v_or_b32_sdwa v128, v122, v124 dst_sel:DWORD dst_unused:UNUSED_PAD src0_sel:DWORD src1_sel:WORD_0
	v_mul_lo_u32 v124, v152, s61
	v_add_u32_e32 v0, v0, v124
	v_add_u32_e32 v125, 0x80, v150
	v_lshl_add_u64 v[122:123], v[0:1], 1, s[6:7]
	v_add_u32_e32 v0, v151, v125
	global_store_dwordx4 v[122:123], v[126:129], off
	v_add_u32_e32 v0, v0, v124
	s_waitcnt vmcnt(12)
	v_lshlrev_b32_e32 v122, 16, v162
	v_lshlrev_b32_e32 v143, 16, v163
	v_and_b32_e32 v144, 0xffff0000, v163
	v_lshlrev_b32_e32 v127, 16, v164
	v_mul_f32_e32 v122, 0xbfb8aa3b, v122
	v_and_b32_e32 v123, 0xffff0000, v162
	v_exp_f32_e32 v126, v122
	v_mul_f32_e32 v122, 0xbfb8aa3b, v127
	v_and_b32_e32 v145, 0xffff0000, v164
	v_exp_f32_e32 v128, v122
	v_mul_f32_e32 v122, 0xbfb8aa3b, v123
	v_mul_f32_e32 v123, 0xbfb8aa3b, v143
	v_exp_f32_e32 v127, v123
	v_lshlrev_b32_e32 v153, 16, v165
	v_mul_f32_e32 v123, 0xbfb8aa3b, v153
	v_and_b32_e32 v154, 0xffff0000, v165
	v_pk_add_f32 v[126:127], v[126:127], 1.0 op_sel_hi:[1,0]
	v_exp_f32_e32 v129, v123
	v_mul_f32_e32 v123, 0xbfb8aa3b, v144
	v_exp_f32_e32 v142, v122
	v_mul_f32_e32 v122, 0xbfb8aa3b, v145
	v_exp_f32_e32 v143, v123
	v_mul_f32_e32 v123, 0xbfb8aa3b, v154
	v_exp_f32_e32 v122, v122
	v_rcp_f32_e32 v127, v127
	s_nop 0
	v_pk_add_f32 v[142:143], v[142:143], 1.0 op_sel_hi:[1,0]
	v_exp_f32_e32 v123, v123
	v_rcp_f32_e32 v126, v126
	s_nop 0
	v_mov_b32_e32 v144, v118
	v_mov_b32_e32 v145, v120
	v_pk_mul_f32 v[126:127], v[144:145], v[126:127]
	v_pk_add_f32 v[122:123], v[122:123], 1.0 op_sel_hi:[1,0]
	v_rcp_f32_e32 v143, v143
	s_nop 0
	s_nop 0
	v_rcp_f32_e32 v142, v142
	s_nop 0
	v_mov_b32_e32 v120, v119
	v_pk_mul_f32 v[118:119], v[120:121], v[142:143]
	v_cvt_pk_bf16_f32 v120, v126, v127
	v_cvt_pk_bf16_f32 v118, v118, v119
	v_and_b32_e32 v119, 0xffff0000, v118
	v_lshlrev_b32_e32 v118, 16, v118
	v_or_b32_sdwa v119, v119, v120 dst_sel:DWORD dst_unused:UNUSED_PAD src0_sel:DWORD src1_sel:WORD_1
	v_or_b32_sdwa v118, v118, v120 dst_sel:DWORD dst_unused:UNUSED_PAD src0_sel:DWORD src1_sel:WORD_0
	v_pk_add_f32 v[120:121], v[128:129], 1.0 op_sel_hi:[1,0]
	s_nop 0
	s_nop 0
	v_rcp_f32_e32 v121, v121
	s_nop 0
	s_nop 0
	v_rcp_f32_e32 v120, v120
	s_nop 0
	v_mov_b32_e32 v126, v114
	v_mov_b32_e32 v127, v116
	v_pk_mul_f32 v[120:121], v[126:127], v[120:121]
	v_rcp_f32_e32 v123, v123
	s_nop 0
	s_nop 0
	v_rcp_f32_e32 v122, v122
	s_nop 0
	v_mov_b32_e32 v116, v115
	v_pk_mul_f32 v[114:115], v[116:117], v[122:123]
	v_cvt_pk_bf16_f32 v116, v120, v121
	v_cvt_pk_bf16_f32 v114, v114, v115
	v_and_b32_e32 v115, 0xffff0000, v114
	v_lshlrev_b32_e32 v114, 16, v114
	v_add_u32_e32 v127, 0x16c00, v151
	v_or_b32_sdwa v121, v115, v116 dst_sel:DWORD dst_unused:UNUSED_PAD src0_sel:DWORD src1_sel:WORD_1
	v_or_b32_sdwa v120, v114, v116 dst_sel:DWORD dst_unused:UNUSED_PAD src0_sel:DWORD src1_sel:WORD_0
	v_lshl_add_u64 v[114:115], v[0:1], 1, s[6:7]
	v_add_u32_e32 v0, v127, v150
	v_add_u32_e32 v160, 0xe3880, v178
	v_lshl_add_u64 v[162:163], v[160:161], 1, s[8:9]
	global_load_dwordx4 v[162:165], v[162:163], off
	global_store_dwordx4 v[114:115], v[118:121], off
	v_or_b32_e32 v126, 16, v152
	s_waitcnt vmcnt(13)
	v_lshlrev_b32_e32 v121, 16, v167
	v_and_b32_e32 v122, 0xffff0000, v167
	v_lshlrev_b32_e32 v115, 16, v168
	v_and_b32_e32 v119, 0xffff0000, v166
	v_mul_f32_e32 v115, 0xbfb8aa3b, v115
	v_lshlrev_b32_e32 v118, 16, v166
	v_and_b32_e32 v120, 0xffff0000, v168
	v_exp_f32_e32 v116, v115
	v_mul_f32_e32 v115, 0xbfb8aa3b, v119
	v_mul_f32_e32 v114, 0xbfb8aa3b, v118
	v_exp_f32_e32 v118, v115
	v_mul_f32_e32 v115, 0xbfb8aa3b, v120
	v_exp_f32_e32 v120, v115
	v_mul_f32_e32 v115, 0xbfb8aa3b, v121
	v_exp_f32_e32 v114, v114
	v_exp_f32_e32 v115, v115
	v_lshlrev_b32_e32 v123, 16, v169
	v_mul_f32_e32 v119, 0xbfb8aa3b, v122
	v_and_b32_e32 v128, 0xffff0000, v169
	v_pk_add_f32 v[114:115], v[114:115], 1.0 op_sel_hi:[1,0]
	v_mul_f32_e32 v117, 0xbfb8aa3b, v123
	v_mul_f32_e32 v121, 0xbfb8aa3b, v128
	v_exp_f32_e32 v119, v119
	v_exp_f32_e32 v117, v117
	v_rcp_f32_e32 v115, v115
	s_nop 0
	v_pk_add_f32 v[118:119], v[118:119], 1.0 op_sel_hi:[1,0]
	v_exp_f32_e32 v121, v121
	v_rcp_f32_e32 v114, v114
	s_nop 0
	v_mov_b32_e32 v122, v110
	v_mov_b32_e32 v123, v112
	v_pk_mul_f32 v[114:115], v[122:123], v[114:115]
	v_rcp_f32_e32 v119, v119
	s_nop 0
	s_nop 0
	v_rcp_f32_e32 v118, v118
	s_nop 0
	v_mov_b32_e32 v112, v111
	v_pk_mul_f32 v[110:111], v[112:113], v[118:119]
	v_cvt_pk_bf16_f32 v112, v114, v115
	v_cvt_pk_bf16_f32 v110, v110, v111
	v_and_b32_e32 v111, 0xffff0000, v110
	v_lshlrev_b32_e32 v110, 16, v110
	v_or_b32_sdwa v111, v111, v112 dst_sel:DWORD dst_unused:UNUSED_PAD src0_sel:DWORD src1_sel:WORD_1
	v_or_b32_sdwa v110, v110, v112 dst_sel:DWORD dst_unused:UNUSED_PAD src0_sel:DWORD src1_sel:WORD_0
	v_pk_add_f32 v[112:113], v[116:117], 1.0 op_sel_hi:[1,0]
	s_nop 0
	s_nop 0
	v_rcp_f32_e32 v113, v113
	s_nop 0
	s_nop 0
	v_rcp_f32_e32 v112, v112
	s_nop 0
	v_mov_b32_e32 v114, v106
	v_mov_b32_e32 v115, v108
	v_pk_mul_f32 v[112:113], v[114:115], v[112:113]
	v_pk_add_f32 v[114:115], v[120:121], 1.0 op_sel_hi:[1,0]
	s_nop 0
	s_nop 0
	v_rcp_f32_e32 v115, v115
	s_nop 0
	s_nop 0
	v_rcp_f32_e32 v114, v114
	s_nop 0
	v_mov_b32_e32 v108, v107
	v_pk_mul_f32 v[106:107], v[108:109], v[114:115]
	v_mul_lo_u32 v116, v126, s61
	v_cvt_pk_bf16_f32 v106, v106, v107
	v_cvt_pk_bf16_f32 v108, v112, v113
	v_and_b32_e32 v107, 0xffff0000, v106
	v_lshlrev_b32_e32 v106, 16, v106
	v_add_u32_e32 v0, v0, v116
	v_or_b32_sdwa v113, v107, v108 dst_sel:DWORD dst_unused:UNUSED_PAD src0_sel:DWORD src1_sel:WORD_1
	v_or_b32_sdwa v112, v106, v108 dst_sel:DWORD dst_unused:UNUSED_PAD src0_sel:DWORD src1_sel:WORD_0
	v_lshl_add_u64 v[106:107], v[0:1], 1, s[6:7]
	v_add_u32_e32 v0, v127, v125
	v_add_u32_e32 v160, 0xfa400, v178
	v_lshl_add_u64 v[166:167], v[160:161], 1, s[8:9]
	global_load_dwordx4 v[166:169], v[166:167], off
	global_store_dwordx4 v[106:107], v[110:113], off
	v_add_u32_e32 v0, v0, v116
	s_waitcnt vmcnt(14)
	v_lshlrev_b32_e32 v113, 16, v171
	v_and_b32_e32 v114, 0xffff0000, v171
	v_lshlrev_b32_e32 v107, 16, v172
	v_and_b32_e32 v111, 0xffff0000, v170
	v_mul_f32_e32 v107, 0xbfb8aa3b, v107
	v_lshlrev_b32_e32 v110, 16, v170
	v_and_b32_e32 v112, 0xffff0000, v172
	v_exp_f32_e32 v108, v107
	v_mul_f32_e32 v107, 0xbfb8aa3b, v111
	v_mul_f32_e32 v106, 0xbfb8aa3b, v110
	v_exp_f32_e32 v110, v107
	v_mul_f32_e32 v107, 0xbfb8aa3b, v112
	v_exp_f32_e32 v112, v107
	v_mul_f32_e32 v107, 0xbfb8aa3b, v113
	v_exp_f32_e32 v106, v106
	v_exp_f32_e32 v107, v107
	v_lshlrev_b32_e32 v115, 16, v173
	v_mul_f32_e32 v111, 0xbfb8aa3b, v114
	v_and_b32_e32 v117, 0xffff0000, v173
	v_pk_add_f32 v[106:107], v[106:107], 1.0 op_sel_hi:[1,0]
	v_mul_f32_e32 v109, 0xbfb8aa3b, v115
	v_mul_f32_e32 v113, 0xbfb8aa3b, v117
	v_exp_f32_e32 v111, v111
	v_exp_f32_e32 v109, v109
	v_rcp_f32_e32 v107, v107
	s_nop 0
	v_pk_add_f32 v[110:111], v[110:111], 1.0 op_sel_hi:[1,0]
	v_exp_f32_e32 v113, v113
	v_rcp_f32_e32 v106, v106
	s_nop 0
	v_mov_b32_e32 v114, v102
	v_mov_b32_e32 v115, v104
	v_pk_mul_f32 v[106:107], v[114:115], v[106:107]
	v_rcp_f32_e32 v111, v111
	s_nop 0
	s_nop 0
	v_rcp_f32_e32 v110, v110
	s_nop 0
	v_mov_b32_e32 v104, v103
	v_pk_mul_f32 v[102:103], v[104:105], v[110:111]
	v_cvt_pk_bf16_f32 v104, v106, v107
	v_cvt_pk_bf16_f32 v102, v102, v103
	v_and_b32_e32 v103, 0xffff0000, v102
	v_lshlrev_b32_e32 v102, 16, v102
	v_or_b32_sdwa v103, v103, v104 dst_sel:DWORD dst_unused:UNUSED_PAD src0_sel:DWORD src1_sel:WORD_1
	v_or_b32_sdwa v102, v102, v104 dst_sel:DWORD dst_unused:UNUSED_PAD src0_sel:DWORD src1_sel:WORD_0
	v_pk_add_f32 v[104:105], v[108:109], 1.0 op_sel_hi:[1,0]
	s_nop 0
	s_nop 0
	v_rcp_f32_e32 v105, v105
	s_nop 0
	s_nop 0
	v_rcp_f32_e32 v104, v104
	s_nop 0
	v_mov_b32_e32 v106, v98
	v_mov_b32_e32 v107, v100
	v_pk_mul_f32 v[104:105], v[106:107], v[104:105]
	v_pk_add_f32 v[106:107], v[112:113], 1.0 op_sel_hi:[1,0]
	s_nop 0
	s_nop 0
	v_rcp_f32_e32 v107, v107
	s_nop 0
	s_nop 0
	v_rcp_f32_e32 v106, v106
	s_nop 0
	v_mov_b32_e32 v100, v99
	v_pk_mul_f32 v[98:99], v[100:101], v[106:107]
	v_cvt_pk_bf16_f32 v100, v104, v105
	v_cvt_pk_bf16_f32 v98, v98, v99
	v_and_b32_e32 v99, 0xffff0000, v98
	v_lshlrev_b32_e32 v98, 16, v98
	v_add_u32_e32 v109, 0x2d800, v151
	v_or_b32_sdwa v105, v99, v100 dst_sel:DWORD dst_unused:UNUSED_PAD src0_sel:DWORD src1_sel:WORD_1
	v_or_b32_sdwa v104, v98, v100 dst_sel:DWORD dst_unused:UNUSED_PAD src0_sel:DWORD src1_sel:WORD_0
	v_lshl_add_u64 v[98:99], v[0:1], 1, s[6:7]
	v_add_u32_e32 v0, v109, v150
	v_add_u32_e32 v160, 0xfa480, v178
	v_lshl_add_u64 v[170:171], v[160:161], 1, s[8:9]
	global_load_dwordx4 v[170:173], v[170:171], off
	global_store_dwordx4 v[98:99], v[102:105], off
	v_or_b32_e32 v108, 32, v152
	s_waitcnt vmcnt(15)
	v_lshlrev_b32_e32 v105, 16, v175
	v_and_b32_e32 v106, 0xffff0000, v175
	v_lshlrev_b32_e32 v99, 16, v176
	v_and_b32_e32 v103, 0xffff0000, v174
	v_mul_f32_e32 v99, 0xbfb8aa3b, v99
	v_lshlrev_b32_e32 v102, 16, v174
	v_and_b32_e32 v104, 0xffff0000, v176
	v_exp_f32_e32 v100, v99
	v_mul_f32_e32 v99, 0xbfb8aa3b, v103
	v_mul_f32_e32 v98, 0xbfb8aa3b, v102
	v_exp_f32_e32 v102, v99
	v_mul_f32_e32 v99, 0xbfb8aa3b, v104
	v_exp_f32_e32 v104, v99
	v_mul_f32_e32 v99, 0xbfb8aa3b, v105
	v_exp_f32_e32 v98, v98
	v_exp_f32_e32 v99, v99
	v_lshlrev_b32_e32 v107, 16, v177
	v_mul_f32_e32 v103, 0xbfb8aa3b, v106
	v_and_b32_e32 v110, 0xffff0000, v177
	v_pk_add_f32 v[98:99], v[98:99], 1.0 op_sel_hi:[1,0]
	v_mul_f32_e32 v101, 0xbfb8aa3b, v107
	v_mul_f32_e32 v105, 0xbfb8aa3b, v110
	v_exp_f32_e32 v103, v103
	v_exp_f32_e32 v101, v101
	v_rcp_f32_e32 v99, v99
	s_nop 0
	v_pk_add_f32 v[102:103], v[102:103], 1.0 op_sel_hi:[1,0]
	v_exp_f32_e32 v105, v105
	v_rcp_f32_e32 v98, v98
	s_nop 0
	v_mov_b32_e32 v106, v94
	v_mov_b32_e32 v107, v96
	v_pk_mul_f32 v[98:99], v[106:107], v[98:99]
	v_rcp_f32_e32 v103, v103
	s_nop 0
	s_nop 0
	v_rcp_f32_e32 v102, v102
	s_nop 0
	v_mov_b32_e32 v96, v95
	v_pk_mul_f32 v[94:95], v[96:97], v[102:103]
	v_cvt_pk_bf16_f32 v96, v98, v99
	v_cvt_pk_bf16_f32 v94, v94, v95
	v_and_b32_e32 v95, 0xffff0000, v94
	v_lshlrev_b32_e32 v94, 16, v94
	v_or_b32_sdwa v95, v95, v96 dst_sel:DWORD dst_unused:UNUSED_PAD src0_sel:DWORD src1_sel:WORD_1
	v_or_b32_sdwa v94, v94, v96 dst_sel:DWORD dst_unused:UNUSED_PAD src0_sel:DWORD src1_sel:WORD_0
	v_pk_add_f32 v[96:97], v[100:101], 1.0 op_sel_hi:[1,0]
	s_nop 0
	s_nop 0
	v_rcp_f32_e32 v97, v97
	s_nop 0
	s_nop 0
	v_rcp_f32_e32 v96, v96
	s_nop 0
	v_mov_b32_e32 v98, v90
	v_mov_b32_e32 v99, v92
	v_pk_mul_f32 v[96:97], v[98:99], v[96:97]
	v_pk_add_f32 v[98:99], v[104:105], 1.0 op_sel_hi:[1,0]
	s_nop 0
	s_nop 0
	v_rcp_f32_e32 v99, v99
	s_nop 0
	s_nop 0
	v_rcp_f32_e32 v98, v98
	s_nop 0
	v_mov_b32_e32 v92, v91
	v_pk_mul_f32 v[90:91], v[92:93], v[98:99]
	v_mul_lo_u32 v100, v108, s61
	v_cvt_pk_bf16_f32 v90, v90, v91
	v_cvt_pk_bf16_f32 v92, v96, v97
	v_and_b32_e32 v91, 0xffff0000, v90
	v_lshlrev_b32_e32 v90, 16, v90
	v_add_u32_e32 v0, v0, v100
	v_or_b32_sdwa v97, v91, v92 dst_sel:DWORD dst_unused:UNUSED_PAD src0_sel:DWORD src1_sel:WORD_1
	v_or_b32_sdwa v96, v90, v92 dst_sel:DWORD dst_unused:UNUSED_PAD src0_sel:DWORD src1_sel:WORD_0
	v_lshl_add_u64 v[90:91], v[0:1], 1, s[6:7]
	v_add_u32_e32 v0, v109, v125
	global_store_dwordx4 v[90:91], v[94:97], off
	v_add_u32_e32 v0, v0, v100
	s_waitcnt vmcnt(15)
	v_lshlrev_b32_e32 v97, 16, v183
	v_and_b32_e32 v98, 0xffff0000, v183
	v_lshlrev_b32_e32 v91, 16, v184
	v_and_b32_e32 v95, 0xffff0000, v182
	v_mul_f32_e32 v91, 0xbfb8aa3b, v91
	v_lshlrev_b32_e32 v94, 16, v182
	v_and_b32_e32 v96, 0xffff0000, v184
	v_exp_f32_e32 v92, v91
	v_mul_f32_e32 v91, 0xbfb8aa3b, v95
	v_mul_f32_e32 v90, 0xbfb8aa3b, v94
	v_exp_f32_e32 v94, v91
	v_mul_f32_e32 v91, 0xbfb8aa3b, v96
	v_exp_f32_e32 v96, v91
	v_mul_f32_e32 v91, 0xbfb8aa3b, v97
	v_exp_f32_e32 v90, v90
	v_exp_f32_e32 v91, v91
	v_lshlrev_b32_e32 v99, 16, v185
	v_mul_f32_e32 v95, 0xbfb8aa3b, v98
	v_and_b32_e32 v101, 0xffff0000, v185
	v_pk_add_f32 v[90:91], v[90:91], 1.0 op_sel_hi:[1,0]
	v_mul_f32_e32 v93, 0xbfb8aa3b, v99
	v_mul_f32_e32 v97, 0xbfb8aa3b, v101
	v_exp_f32_e32 v95, v95
	v_exp_f32_e32 v93, v93
	v_rcp_f32_e32 v91, v91
	s_nop 0
	v_pk_add_f32 v[94:95], v[94:95], 1.0 op_sel_hi:[1,0]
	v_exp_f32_e32 v97, v97
	v_rcp_f32_e32 v90, v90
	s_nop 0
	v_mov_b32_e32 v98, v86
	v_mov_b32_e32 v99, v88
	v_pk_mul_f32 v[90:91], v[98:99], v[90:91]
	v_rcp_f32_e32 v95, v95
	s_nop 0
	s_nop 0
	v_rcp_f32_e32 v94, v94
	s_nop 0
	v_mov_b32_e32 v88, v87
	v_pk_mul_f32 v[86:87], v[88:89], v[94:95]
	v_cvt_pk_bf16_f32 v88, v90, v91
	v_cvt_pk_bf16_f32 v86, v86, v87
	v_and_b32_e32 v87, 0xffff0000, v86
	v_lshlrev_b32_e32 v86, 16, v86
	v_or_b32_sdwa v87, v87, v88 dst_sel:DWORD dst_unused:UNUSED_PAD src0_sel:DWORD src1_sel:WORD_1
	v_or_b32_sdwa v86, v86, v88 dst_sel:DWORD dst_unused:UNUSED_PAD src0_sel:DWORD src1_sel:WORD_0
	v_pk_add_f32 v[88:89], v[92:93], 1.0 op_sel_hi:[1,0]
	s_nop 0
	s_nop 0
	v_rcp_f32_e32 v89, v89
	s_nop 0
	s_nop 0
	v_rcp_f32_e32 v88, v88
	s_nop 0
	v_mov_b32_e32 v90, v82
	v_mov_b32_e32 v91, v84
	v_pk_mul_f32 v[88:89], v[90:91], v[88:89]
	v_pk_add_f32 v[90:91], v[96:97], 1.0 op_sel_hi:[1,0]
	s_nop 0
	s_nop 0
	v_rcp_f32_e32 v91, v91
	s_nop 0
	s_nop 0
	v_rcp_f32_e32 v90, v90
	s_nop 0
	v_mov_b32_e32 v84, v83
	v_pk_mul_f32 v[82:83], v[84:85], v[90:91]
	v_cvt_pk_bf16_f32 v84, v88, v89
	v_cvt_pk_bf16_f32 v82, v82, v83
	v_and_b32_e32 v83, 0xffff0000, v82
	v_lshlrev_b32_e32 v82, 16, v82
	v_add_u32_e32 v93, 0x44400, v151
	v_or_b32_sdwa v89, v83, v84 dst_sel:DWORD dst_unused:UNUSED_PAD src0_sel:DWORD src1_sel:WORD_1
	v_or_b32_sdwa v88, v82, v84 dst_sel:DWORD dst_unused:UNUSED_PAD src0_sel:DWORD src1_sel:WORD_0
	v_lshl_add_u64 v[82:83], v[0:1], 1, s[6:7]
	v_add_u32_e32 v0, v93, v150
	global_store_dwordx4 v[82:83], v[86:89], off
	v_or_b32_e32 v92, 48, v152
	s_waitcnt vmcnt(15)
	v_lshlrev_b32_e32 v89, 16, v187
	v_and_b32_e32 v90, 0xffff0000, v187
	v_lshlrev_b32_e32 v83, 16, v188
	v_and_b32_e32 v87, 0xffff0000, v186
	v_mul_f32_e32 v83, 0xbfb8aa3b, v83
	v_lshlrev_b32_e32 v86, 16, v186
	v_and_b32_e32 v88, 0xffff0000, v188
	v_exp_f32_e32 v84, v83
	v_mul_f32_e32 v83, 0xbfb8aa3b, v87
	v_mul_f32_e32 v82, 0xbfb8aa3b, v86
	v_exp_f32_e32 v86, v83
	v_mul_f32_e32 v83, 0xbfb8aa3b, v88
	v_exp_f32_e32 v88, v83
	v_mul_f32_e32 v83, 0xbfb8aa3b, v89
	v_exp_f32_e32 v82, v82
	v_exp_f32_e32 v83, v83
	v_lshlrev_b32_e32 v91, 16, v189
	v_mul_f32_e32 v87, 0xbfb8aa3b, v90
	v_and_b32_e32 v94, 0xffff0000, v189
	v_pk_add_f32 v[82:83], v[82:83], 1.0 op_sel_hi:[1,0]
	v_mul_f32_e32 v85, 0xbfb8aa3b, v91
	v_mul_f32_e32 v89, 0xbfb8aa3b, v94
	v_exp_f32_e32 v87, v87
	v_exp_f32_e32 v85, v85
	v_rcp_f32_e32 v83, v83
	s_nop 0
	v_pk_add_f32 v[86:87], v[86:87], 1.0 op_sel_hi:[1,0]
	v_exp_f32_e32 v89, v89
	v_rcp_f32_e32 v82, v82
	s_nop 0
	v_mov_b32_e32 v90, v78
	v_mov_b32_e32 v91, v80
	v_pk_mul_f32 v[82:83], v[90:91], v[82:83]
	v_rcp_f32_e32 v87, v87
	s_nop 0
	s_nop 0
	v_rcp_f32_e32 v86, v86
	s_nop 0
	v_mov_b32_e32 v80, v79
	v_pk_mul_f32 v[78:79], v[80:81], v[86:87]
	v_cvt_pk_bf16_f32 v80, v82, v83
	v_cvt_pk_bf16_f32 v78, v78, v79
	v_and_b32_e32 v79, 0xffff0000, v78
	v_lshlrev_b32_e32 v78, 16, v78
	v_or_b32_sdwa v79, v79, v80 dst_sel:DWORD dst_unused:UNUSED_PAD src0_sel:DWORD src1_sel:WORD_1
	v_or_b32_sdwa v78, v78, v80 dst_sel:DWORD dst_unused:UNUSED_PAD src0_sel:DWORD src1_sel:WORD_0
	v_pk_add_f32 v[80:81], v[84:85], 1.0 op_sel_hi:[1,0]
	s_nop 0
	s_nop 0
	v_rcp_f32_e32 v81, v81
	s_nop 0
	s_nop 0
	v_rcp_f32_e32 v80, v80
	s_nop 0
	v_mov_b32_e32 v82, v74
	v_mov_b32_e32 v83, v76
	v_pk_mul_f32 v[80:81], v[82:83], v[80:81]
	v_pk_add_f32 v[82:83], v[88:89], 1.0 op_sel_hi:[1,0]
	s_nop 0
	s_nop 0
	v_rcp_f32_e32 v83, v83
	s_nop 0
	s_nop 0
	v_rcp_f32_e32 v82, v82
	s_nop 0
	v_mov_b32_e32 v76, v75
	v_pk_mul_f32 v[74:75], v[76:77], v[82:83]
	v_mul_lo_u32 v84, v92, s61
	v_cvt_pk_bf16_f32 v74, v74, v75
	v_cvt_pk_bf16_f32 v76, v80, v81
	v_and_b32_e32 v75, 0xffff0000, v74
	v_lshlrev_b32_e32 v74, 16, v74
	v_add_u32_e32 v0, v0, v84
	v_or_b32_sdwa v81, v75, v76 dst_sel:DWORD dst_unused:UNUSED_PAD src0_sel:DWORD src1_sel:WORD_1
	v_or_b32_sdwa v80, v74, v76 dst_sel:DWORD dst_unused:UNUSED_PAD src0_sel:DWORD src1_sel:WORD_0
	v_lshl_add_u64 v[74:75], v[0:1], 1, s[6:7]
	v_add_u32_e32 v0, v93, v125
	global_store_dwordx4 v[74:75], v[78:81], off
	v_add_u32_e32 v0, v0, v84
	s_waitcnt vmcnt(15)
	v_lshlrev_b32_e32 v81, 16, v191
	v_and_b32_e32 v82, 0xffff0000, v191
	v_lshlrev_b32_e32 v75, 16, v192
	v_and_b32_e32 v79, 0xffff0000, v190
	v_mul_f32_e32 v75, 0xbfb8aa3b, v75
	v_lshlrev_b32_e32 v78, 16, v190
	v_and_b32_e32 v80, 0xffff0000, v192
	v_exp_f32_e32 v76, v75
	v_mul_f32_e32 v75, 0xbfb8aa3b, v79
	v_mul_f32_e32 v74, 0xbfb8aa3b, v78
	v_exp_f32_e32 v78, v75
	v_mul_f32_e32 v75, 0xbfb8aa3b, v80
	v_exp_f32_e32 v80, v75
	v_mul_f32_e32 v75, 0xbfb8aa3b, v81
	v_exp_f32_e32 v74, v74
	v_exp_f32_e32 v75, v75
	v_lshlrev_b32_e32 v83, 16, v193
	v_mul_f32_e32 v79, 0xbfb8aa3b, v82
	v_and_b32_e32 v85, 0xffff0000, v193
	v_pk_add_f32 v[74:75], v[74:75], 1.0 op_sel_hi:[1,0]
	v_mul_f32_e32 v77, 0xbfb8aa3b, v83
	v_mul_f32_e32 v81, 0xbfb8aa3b, v85
	v_exp_f32_e32 v79, v79
	v_exp_f32_e32 v77, v77
	v_rcp_f32_e32 v75, v75
	s_nop 0
	v_pk_add_f32 v[78:79], v[78:79], 1.0 op_sel_hi:[1,0]
	v_exp_f32_e32 v81, v81
	v_rcp_f32_e32 v74, v74
	s_nop 0
	v_mov_b32_e32 v82, v70
	v_mov_b32_e32 v83, v72
	v_pk_mul_f32 v[74:75], v[82:83], v[74:75]
	v_rcp_f32_e32 v79, v79
	s_nop 0
	s_nop 0
	v_rcp_f32_e32 v78, v78
	s_nop 0
	v_mov_b32_e32 v72, v71
	v_pk_mul_f32 v[70:71], v[72:73], v[78:79]
	v_cvt_pk_bf16_f32 v72, v74, v75
	v_cvt_pk_bf16_f32 v70, v70, v71
	v_and_b32_e32 v71, 0xffff0000, v70
	v_lshlrev_b32_e32 v70, 16, v70
	v_or_b32_sdwa v71, v71, v72 dst_sel:DWORD dst_unused:UNUSED_PAD src0_sel:DWORD src1_sel:WORD_1
	v_or_b32_sdwa v70, v70, v72 dst_sel:DWORD dst_unused:UNUSED_PAD src0_sel:DWORD src1_sel:WORD_0
	v_pk_add_f32 v[72:73], v[76:77], 1.0 op_sel_hi:[1,0]
	s_nop 0
	s_nop 0
	v_rcp_f32_e32 v73, v73
	s_nop 0
	s_nop 0
	v_rcp_f32_e32 v72, v72
	s_nop 0
	v_mov_b32_e32 v74, v66
	v_mov_b32_e32 v75, v68
	v_pk_mul_f32 v[72:73], v[74:75], v[72:73]
	v_pk_add_f32 v[74:75], v[80:81], 1.0 op_sel_hi:[1,0]
	s_nop 0
	s_nop 0
	v_rcp_f32_e32 v75, v75
	s_nop 0
	s_nop 0
	v_rcp_f32_e32 v74, v74
	s_nop 0
	v_mov_b32_e32 v68, v67
	v_pk_mul_f32 v[66:67], v[68:69], v[74:75]
	v_cvt_pk_bf16_f32 v68, v72, v73
	v_cvt_pk_bf16_f32 v66, v66, v67
	v_and_b32_e32 v67, 0xffff0000, v66
	v_lshlrev_b32_e32 v66, 16, v66
	v_add_u32_e32 v76, 0xb6000, v151
	v_or_b32_sdwa v73, v67, v68 dst_sel:DWORD dst_unused:UNUSED_PAD src0_sel:DWORD src1_sel:WORD_1
	v_or_b32_sdwa v72, v66, v68 dst_sel:DWORD dst_unused:UNUSED_PAD src0_sel:DWORD src1_sel:WORD_0
	v_lshl_add_u64 v[66:67], v[0:1], 1, s[6:7]
	v_add_u32_e32 v0, v76, v150
	global_store_dwordx4 v[66:67], v[70:73], off
	s_nop 1
	s_waitcnt vmcnt(15)
	v_lshlrev_b32_e32 v73, 16, v195
	v_and_b32_e32 v74, 0xffff0000, v195
	v_lshlrev_b32_e32 v67, 16, v196
	v_and_b32_e32 v71, 0xffff0000, v194
	v_mul_f32_e32 v67, 0xbfb8aa3b, v67
	v_lshlrev_b32_e32 v70, 16, v194
	v_and_b32_e32 v72, 0xffff0000, v196
	v_exp_f32_e32 v68, v67
	v_mul_f32_e32 v67, 0xbfb8aa3b, v71
	v_mul_f32_e32 v66, 0xbfb8aa3b, v70
	v_exp_f32_e32 v70, v67
	v_mul_f32_e32 v67, 0xbfb8aa3b, v72
	v_exp_f32_e32 v72, v67
	v_mul_f32_e32 v67, 0xbfb8aa3b, v73
	v_exp_f32_e32 v66, v66
	v_exp_f32_e32 v67, v67
	v_lshlrev_b32_e32 v75, 16, v197
	v_mul_f32_e32 v71, 0xbfb8aa3b, v74
	v_and_b32_e32 v77, 0xffff0000, v197
	v_pk_add_f32 v[66:67], v[66:67], 1.0 op_sel_hi:[1,0]
	v_mul_f32_e32 v69, 0xbfb8aa3b, v75
	v_mul_f32_e32 v73, 0xbfb8aa3b, v77
	v_exp_f32_e32 v71, v71
	v_exp_f32_e32 v69, v69
	v_rcp_f32_e32 v67, v67
	s_nop 0
	v_pk_add_f32 v[70:71], v[70:71], 1.0 op_sel_hi:[1,0]
	v_exp_f32_e32 v73, v73
	v_rcp_f32_e32 v66, v66
	s_nop 0
	v_mov_b32_e32 v74, v62
	v_mov_b32_e32 v75, v64
	v_pk_mul_f32 v[66:67], v[74:75], v[66:67]
	v_rcp_f32_e32 v71, v71
	s_nop 0
	s_nop 0
	v_rcp_f32_e32 v70, v70
	s_nop 0
	v_mov_b32_e32 v64, v63
	v_pk_mul_f32 v[62:63], v[64:65], v[70:71]
	v_cvt_pk_bf16_f32 v64, v66, v67
	v_cvt_pk_bf16_f32 v62, v62, v63
	v_and_b32_e32 v63, 0xffff0000, v62
	v_lshlrev_b32_e32 v62, 16, v62
	v_or_b32_sdwa v63, v63, v64 dst_sel:DWORD dst_unused:UNUSED_PAD src0_sel:DWORD src1_sel:WORD_1
	v_or_b32_sdwa v62, v62, v64 dst_sel:DWORD dst_unused:UNUSED_PAD src0_sel:DWORD src1_sel:WORD_0
	v_pk_add_f32 v[64:65], v[68:69], 1.0 op_sel_hi:[1,0]
	s_nop 0
	s_nop 0
	v_rcp_f32_e32 v65, v65
	s_nop 0
	s_nop 0
	v_rcp_f32_e32 v64, v64
	s_nop 0
	v_mov_b32_e32 v66, v58
	v_mov_b32_e32 v67, v60
	v_pk_mul_f32 v[64:65], v[66:67], v[64:65]
	v_pk_add_f32 v[66:67], v[72:73], 1.0 op_sel_hi:[1,0]
	s_nop 0
	s_nop 0
	v_rcp_f32_e32 v67, v67
	s_nop 0
	s_nop 0
	v_rcp_f32_e32 v66, v66
	s_nop 0
	v_mov_b32_e32 v60, v59
	v_pk_mul_f32 v[58:59], v[60:61], v[66:67]
	v_add_u32_e32 v68, 0xfff6a000, v124
	v_cvt_pk_bf16_f32 v58, v58, v59
	v_cvt_pk_bf16_f32 v60, v64, v65
	v_and_b32_e32 v59, 0xffff0000, v58
	v_lshlrev_b32_e32 v58, 16, v58
	v_add_u32_e32 v0, v0, v68
	v_or_b32_sdwa v65, v59, v60 dst_sel:DWORD dst_unused:UNUSED_PAD src0_sel:DWORD src1_sel:WORD_1
	v_or_b32_sdwa v64, v58, v60 dst_sel:DWORD dst_unused:UNUSED_PAD src0_sel:DWORD src1_sel:WORD_0
	v_lshl_add_u64 v[58:59], v[0:1], 1, s[6:7]
	v_add_u32_e32 v0, v76, v125
	global_store_dwordx4 v[58:59], v[62:65], off
	v_add_u32_e32 v0, v0, v68
	s_waitcnt vmcnt(15)
	v_lshlrev_b32_e32 v65, 16, v199
	v_and_b32_e32 v66, 0xffff0000, v199
	v_lshlrev_b32_e32 v59, 16, v200
	v_and_b32_e32 v63, 0xffff0000, v198
	v_mul_f32_e32 v59, 0xbfb8aa3b, v59
	v_lshlrev_b32_e32 v62, 16, v198
	v_and_b32_e32 v64, 0xffff0000, v200
	v_exp_f32_e32 v60, v59
	v_mul_f32_e32 v59, 0xbfb8aa3b, v63
	v_mul_f32_e32 v58, 0xbfb8aa3b, v62
	v_exp_f32_e32 v62, v59
	v_mul_f32_e32 v59, 0xbfb8aa3b, v64
	v_exp_f32_e32 v64, v59
	v_mul_f32_e32 v59, 0xbfb8aa3b, v65
	v_exp_f32_e32 v58, v58
	v_exp_f32_e32 v59, v59
	v_lshlrev_b32_e32 v67, 16, v201
	v_mul_f32_e32 v63, 0xbfb8aa3b, v66
	v_and_b32_e32 v69, 0xffff0000, v201
	v_pk_add_f32 v[58:59], v[58:59], 1.0 op_sel_hi:[1,0]
	v_mul_f32_e32 v61, 0xbfb8aa3b, v67
	v_mul_f32_e32 v65, 0xbfb8aa3b, v69
	v_exp_f32_e32 v63, v63
	v_exp_f32_e32 v61, v61
	v_rcp_f32_e32 v59, v59
	s_nop 0
	v_pk_add_f32 v[62:63], v[62:63], 1.0 op_sel_hi:[1,0]
	v_exp_f32_e32 v65, v65
	v_rcp_f32_e32 v58, v58
	s_nop 0
	v_mov_b32_e32 v66, v54
	v_mov_b32_e32 v67, v56
	v_pk_mul_f32 v[58:59], v[66:67], v[58:59]
	v_rcp_f32_e32 v63, v63
	s_nop 0
	s_nop 0
	v_rcp_f32_e32 v62, v62
	s_nop 0
	v_mov_b32_e32 v56, v55
	v_pk_mul_f32 v[54:55], v[56:57], v[62:63]
	v_cvt_pk_bf16_f32 v56, v58, v59
	v_cvt_pk_bf16_f32 v54, v54, v55
	v_and_b32_e32 v55, 0xffff0000, v54
	v_lshlrev_b32_e32 v54, 16, v54
	v_or_b32_sdwa v55, v55, v56 dst_sel:DWORD dst_unused:UNUSED_PAD src0_sel:DWORD src1_sel:WORD_1
	v_or_b32_sdwa v54, v54, v56 dst_sel:DWORD dst_unused:UNUSED_PAD src0_sel:DWORD src1_sel:WORD_0
	v_pk_add_f32 v[56:57], v[60:61], 1.0 op_sel_hi:[1,0]
	s_nop 0
	s_nop 0
	v_rcp_f32_e32 v57, v57
	s_nop 0
	s_nop 0
	v_rcp_f32_e32 v56, v56
	s_nop 0
	v_mov_b32_e32 v58, v50
	v_mov_b32_e32 v59, v52
	v_pk_mul_f32 v[56:57], v[58:59], v[56:57]
	v_pk_add_f32 v[58:59], v[64:65], 1.0 op_sel_hi:[1,0]
	s_nop 0
	s_nop 0
	v_rcp_f32_e32 v59, v59
	s_nop 0
	s_nop 0
	v_rcp_f32_e32 v58, v58
	s_nop 0
	v_mov_b32_e32 v52, v51
	v_pk_mul_f32 v[50:51], v[52:53], v[58:59]
	v_cvt_pk_bf16_f32 v52, v56, v57
	v_cvt_pk_bf16_f32 v50, v50, v51
	v_and_b32_e32 v51, 0xffff0000, v50
	v_lshlrev_b32_e32 v50, 16, v50
	v_add_u32_e32 v60, 0xccc00, v151
	v_or_b32_sdwa v57, v51, v52 dst_sel:DWORD dst_unused:UNUSED_PAD src0_sel:DWORD src1_sel:WORD_1
	v_or_b32_sdwa v56, v50, v52 dst_sel:DWORD dst_unused:UNUSED_PAD src0_sel:DWORD src1_sel:WORD_0
	v_lshl_add_u64 v[50:51], v[0:1], 1, s[6:7]
	v_add_u32_e32 v0, v60, v150
	global_store_dwordx4 v[50:51], v[54:57], off
	s_nop 1
	s_waitcnt vmcnt(15)
	v_lshlrev_b32_e32 v57, 16, v203
	v_and_b32_e32 v58, 0xffff0000, v203
	v_lshlrev_b32_e32 v51, 16, v204
	v_and_b32_e32 v55, 0xffff0000, v202
	v_mul_f32_e32 v51, 0xbfb8aa3b, v51
	v_lshlrev_b32_e32 v54, 16, v202
	v_and_b32_e32 v56, 0xffff0000, v204
	v_exp_f32_e32 v52, v51
	v_mul_f32_e32 v51, 0xbfb8aa3b, v55
	v_mul_f32_e32 v50, 0xbfb8aa3b, v54
	v_exp_f32_e32 v54, v51
	v_mul_f32_e32 v51, 0xbfb8aa3b, v56
	v_exp_f32_e32 v56, v51
	v_mul_f32_e32 v51, 0xbfb8aa3b, v57
	v_exp_f32_e32 v50, v50
	v_exp_f32_e32 v51, v51
	v_lshlrev_b32_e32 v59, 16, v205
	v_mul_f32_e32 v55, 0xbfb8aa3b, v58
	v_and_b32_e32 v61, 0xffff0000, v205
	v_pk_add_f32 v[50:51], v[50:51], 1.0 op_sel_hi:[1,0]
	v_mul_f32_e32 v53, 0xbfb8aa3b, v59
	v_mul_f32_e32 v57, 0xbfb8aa3b, v61
	v_exp_f32_e32 v55, v55
	v_exp_f32_e32 v53, v53
	v_rcp_f32_e32 v51, v51
	s_nop 0
	v_pk_add_f32 v[54:55], v[54:55], 1.0 op_sel_hi:[1,0]
	v_exp_f32_e32 v57, v57
	v_rcp_f32_e32 v50, v50
	s_nop 0
	v_mov_b32_e32 v58, v46
	v_mov_b32_e32 v59, v48
	v_pk_mul_f32 v[50:51], v[58:59], v[50:51]
	v_rcp_f32_e32 v55, v55
	s_nop 0
	s_nop 0
	v_rcp_f32_e32 v54, v54
	s_nop 0
	v_mov_b32_e32 v48, v47
	v_pk_mul_f32 v[46:47], v[48:49], v[54:55]
	v_cvt_pk_bf16_f32 v48, v50, v51
	v_cvt_pk_bf16_f32 v46, v46, v47
	v_and_b32_e32 v47, 0xffff0000, v46
	v_lshlrev_b32_e32 v46, 16, v46
	v_or_b32_sdwa v47, v47, v48 dst_sel:DWORD dst_unused:UNUSED_PAD src0_sel:DWORD src1_sel:WORD_1
	v_or_b32_sdwa v46, v46, v48 dst_sel:DWORD dst_unused:UNUSED_PAD src0_sel:DWORD src1_sel:WORD_0
	v_pk_add_f32 v[48:49], v[52:53], 1.0 op_sel_hi:[1,0]
	s_nop 0
	s_nop 0
	v_rcp_f32_e32 v49, v49
	s_nop 0
	s_nop 0
	v_rcp_f32_e32 v48, v48
	s_nop 0
	v_mov_b32_e32 v50, v42
	v_mov_b32_e32 v51, v44
	v_pk_mul_f32 v[48:49], v[50:51], v[48:49]
	v_pk_add_f32 v[50:51], v[56:57], 1.0 op_sel_hi:[1,0]
	s_nop 0
	s_nop 0
	v_rcp_f32_e32 v51, v51
	s_nop 0
	s_nop 0
	v_rcp_f32_e32 v50, v50
	s_nop 0
	v_mov_b32_e32 v44, v43
	v_pk_mul_f32 v[42:43], v[44:45], v[50:51]
	v_add_u32_e32 v52, 0xfff57400, v124
	v_cvt_pk_bf16_f32 v42, v42, v43
	v_cvt_pk_bf16_f32 v44, v48, v49
	v_and_b32_e32 v43, 0xffff0000, v42
	v_lshlrev_b32_e32 v42, 16, v42
	v_add_u32_e32 v0, v0, v52
	v_or_b32_sdwa v49, v43, v44 dst_sel:DWORD dst_unused:UNUSED_PAD src0_sel:DWORD src1_sel:WORD_1
	v_or_b32_sdwa v48, v42, v44 dst_sel:DWORD dst_unused:UNUSED_PAD src0_sel:DWORD src1_sel:WORD_0
	v_lshl_add_u64 v[42:43], v[0:1], 1, s[6:7]
	v_add_u32_e32 v0, v60, v125
	global_store_dwordx4 v[42:43], v[46:49], off
	v_add_u32_e32 v0, v0, v52
	s_waitcnt vmcnt(15)
	v_lshlrev_b32_e32 v49, 16, v207
	v_and_b32_e32 v50, 0xffff0000, v207
	v_lshlrev_b32_e32 v43, 16, v208
	v_and_b32_e32 v47, 0xffff0000, v206
	v_mul_f32_e32 v43, 0xbfb8aa3b, v43
	v_lshlrev_b32_e32 v46, 16, v206
	v_and_b32_e32 v48, 0xffff0000, v208
	v_exp_f32_e32 v44, v43
	v_mul_f32_e32 v43, 0xbfb8aa3b, v47
	v_mul_f32_e32 v42, 0xbfb8aa3b, v46
	v_exp_f32_e32 v46, v43
	v_mul_f32_e32 v43, 0xbfb8aa3b, v48
	v_exp_f32_e32 v48, v43
	v_mul_f32_e32 v43, 0xbfb8aa3b, v49
	v_exp_f32_e32 v42, v42
	v_exp_f32_e32 v43, v43
	v_lshlrev_b32_e32 v51, 16, v209
	v_mul_f32_e32 v47, 0xbfb8aa3b, v50
	v_and_b32_e32 v53, 0xffff0000, v209
	v_pk_add_f32 v[42:43], v[42:43], 1.0 op_sel_hi:[1,0]
	v_mul_f32_e32 v45, 0xbfb8aa3b, v51
	v_mul_f32_e32 v49, 0xbfb8aa3b, v53
	v_exp_f32_e32 v47, v47
	v_exp_f32_e32 v45, v45
	v_rcp_f32_e32 v43, v43
	s_nop 0
	v_pk_add_f32 v[46:47], v[46:47], 1.0 op_sel_hi:[1,0]
	v_exp_f32_e32 v49, v49
	v_rcp_f32_e32 v42, v42
	s_nop 0
	v_mov_b32_e32 v50, v38
	v_mov_b32_e32 v51, v40
	v_pk_mul_f32 v[42:43], v[50:51], v[42:43]
	v_rcp_f32_e32 v47, v47
	s_nop 0
	s_nop 0
	v_rcp_f32_e32 v46, v46
	s_nop 0
	v_mov_b32_e32 v40, v39
	v_pk_mul_f32 v[38:39], v[40:41], v[46:47]
	v_cvt_pk_bf16_f32 v40, v42, v43
	v_cvt_pk_bf16_f32 v38, v38, v39
	v_and_b32_e32 v39, 0xffff0000, v38
	v_lshlrev_b32_e32 v38, 16, v38
	v_or_b32_sdwa v39, v39, v40 dst_sel:DWORD dst_unused:UNUSED_PAD src0_sel:DWORD src1_sel:WORD_1
	v_or_b32_sdwa v38, v38, v40 dst_sel:DWORD dst_unused:UNUSED_PAD src0_sel:DWORD src1_sel:WORD_0
	v_pk_add_f32 v[40:41], v[44:45], 1.0 op_sel_hi:[1,0]
	s_nop 0
	s_nop 0
	v_rcp_f32_e32 v41, v41
	s_nop 0
	s_nop 0
	v_rcp_f32_e32 v40, v40
	s_nop 0
	v_mov_b32_e32 v42, v34
	v_mov_b32_e32 v43, v36
	v_pk_mul_f32 v[40:41], v[42:43], v[40:41]
	v_pk_add_f32 v[42:43], v[48:49], 1.0 op_sel_hi:[1,0]
	s_nop 0
	s_nop 0
	v_rcp_f32_e32 v43, v43
	s_nop 0
	s_nop 0
	v_rcp_f32_e32 v42, v42
	s_nop 0
	v_mov_b32_e32 v36, v35
	v_pk_mul_f32 v[34:35], v[36:37], v[42:43]
	v_cvt_pk_bf16_f32 v36, v40, v41
	v_cvt_pk_bf16_f32 v34, v34, v35
	v_and_b32_e32 v35, 0xffff0000, v34
	v_lshlrev_b32_e32 v34, 16, v34
	v_add_u32_e32 v44, 0xe3800, v151
	v_or_b32_sdwa v41, v35, v36 dst_sel:DWORD dst_unused:UNUSED_PAD src0_sel:DWORD src1_sel:WORD_1
	v_or_b32_sdwa v40, v34, v36 dst_sel:DWORD dst_unused:UNUSED_PAD src0_sel:DWORD src1_sel:WORD_0
	v_lshl_add_u64 v[34:35], v[0:1], 1, s[6:7]
	v_add_u32_e32 v0, v44, v150
	global_store_dwordx4 v[34:35], v[38:41], off
	s_nop 1
	s_waitcnt vmcnt(15)
	v_lshlrev_b32_e32 v41, 16, v211
	v_and_b32_e32 v42, 0xffff0000, v211
	v_lshlrev_b32_e32 v35, 16, v212
	v_and_b32_e32 v39, 0xffff0000, v210
	v_mul_f32_e32 v35, 0xbfb8aa3b, v35
	v_lshlrev_b32_e32 v38, 16, v210
	v_and_b32_e32 v40, 0xffff0000, v212
	v_exp_f32_e32 v36, v35
	v_mul_f32_e32 v35, 0xbfb8aa3b, v39
	v_mul_f32_e32 v34, 0xbfb8aa3b, v38
	v_exp_f32_e32 v38, v35
	v_mul_f32_e32 v35, 0xbfb8aa3b, v40
	v_exp_f32_e32 v40, v35
	v_mul_f32_e32 v35, 0xbfb8aa3b, v41
	v_exp_f32_e32 v34, v34
	v_exp_f32_e32 v35, v35
	v_lshlrev_b32_e32 v43, 16, v213
	v_mul_f32_e32 v39, 0xbfb8aa3b, v42
	v_and_b32_e32 v45, 0xffff0000, v213
	v_pk_add_f32 v[34:35], v[34:35], 1.0 op_sel_hi:[1,0]
	v_mul_f32_e32 v37, 0xbfb8aa3b, v43
	v_mul_f32_e32 v41, 0xbfb8aa3b, v45
	v_exp_f32_e32 v39, v39
	v_exp_f32_e32 v37, v37
	v_rcp_f32_e32 v35, v35
	s_nop 0
	v_pk_add_f32 v[38:39], v[38:39], 1.0 op_sel_hi:[1,0]
	v_exp_f32_e32 v41, v41
	v_rcp_f32_e32 v34, v34
	s_nop 0
	v_mov_b32_e32 v42, v30
	v_mov_b32_e32 v43, v32
	v_pk_mul_f32 v[34:35], v[42:43], v[34:35]
	v_rcp_f32_e32 v39, v39
	s_nop 0
	s_nop 0
	v_rcp_f32_e32 v38, v38
	s_nop 0
	v_mov_b32_e32 v32, v31
	v_pk_mul_f32 v[30:31], v[32:33], v[38:39]
	v_cvt_pk_bf16_f32 v32, v34, v35
	v_cvt_pk_bf16_f32 v30, v30, v31
	v_and_b32_e32 v31, 0xffff0000, v30
	v_lshlrev_b32_e32 v30, 16, v30
	v_or_b32_sdwa v31, v31, v32 dst_sel:DWORD dst_unused:UNUSED_PAD src0_sel:DWORD src1_sel:WORD_1
	v_or_b32_sdwa v30, v30, v32 dst_sel:DWORD dst_unused:UNUSED_PAD src0_sel:DWORD src1_sel:WORD_0
	v_pk_add_f32 v[32:33], v[36:37], 1.0 op_sel_hi:[1,0]
	s_nop 0
	s_nop 0
	v_rcp_f32_e32 v33, v33
	s_nop 0
	s_nop 0
	v_rcp_f32_e32 v32, v32
	s_nop 0
	v_mov_b32_e32 v34, v26
	v_mov_b32_e32 v35, v28
	v_pk_mul_f32 v[32:33], v[34:35], v[32:33]
	v_pk_add_f32 v[34:35], v[40:41], 1.0 op_sel_hi:[1,0]
	s_nop 0
	s_nop 0
	v_rcp_f32_e32 v35, v35
	s_nop 0
	s_nop 0
	v_rcp_f32_e32 v34, v34
	s_nop 0
	v_mov_b32_e32 v28, v27
	v_pk_mul_f32 v[26:27], v[28:29], v[34:35]
	v_add_u32_e32 v36, 0xfff44800, v124
	v_cvt_pk_bf16_f32 v26, v26, v27
	v_cvt_pk_bf16_f32 v28, v32, v33
	v_and_b32_e32 v27, 0xffff0000, v26
	v_lshlrev_b32_e32 v26, 16, v26
	v_add_u32_e32 v0, v0, v36
	v_or_b32_sdwa v33, v27, v28 dst_sel:DWORD dst_unused:UNUSED_PAD src0_sel:DWORD src1_sel:WORD_1
	v_or_b32_sdwa v32, v26, v28 dst_sel:DWORD dst_unused:UNUSED_PAD src0_sel:DWORD src1_sel:WORD_0
	v_lshl_add_u64 v[26:27], v[0:1], 1, s[6:7]
	v_add_u32_e32 v0, v44, v125
	global_store_dwordx4 v[26:27], v[30:33], off
	v_add_u32_e32 v0, v0, v36
	s_waitcnt vmcnt(14)
	v_lshlrev_b32_e32 v33, 16, v163
	v_and_b32_e32 v34, 0xffff0000, v163
	v_lshlrev_b32_e32 v27, 16, v164
	v_and_b32_e32 v31, 0xffff0000, v162
	v_mul_f32_e32 v27, 0xbfb8aa3b, v27
	v_lshlrev_b32_e32 v30, 16, v162
	v_and_b32_e32 v32, 0xffff0000, v164
	v_exp_f32_e32 v28, v27
	v_mul_f32_e32 v27, 0xbfb8aa3b, v31
	v_mul_f32_e32 v26, 0xbfb8aa3b, v30
	v_exp_f32_e32 v30, v27
	v_mul_f32_e32 v27, 0xbfb8aa3b, v32
	v_exp_f32_e32 v32, v27
	v_mul_f32_e32 v27, 0xbfb8aa3b, v33
	v_exp_f32_e32 v26, v26
	v_exp_f32_e32 v27, v27
	v_lshlrev_b32_e32 v35, 16, v165
	v_mul_f32_e32 v31, 0xbfb8aa3b, v34
	v_and_b32_e32 v37, 0xffff0000, v165
	v_pk_add_f32 v[26:27], v[26:27], 1.0 op_sel_hi:[1,0]
	v_mul_f32_e32 v29, 0xbfb8aa3b, v35
	v_mul_f32_e32 v33, 0xbfb8aa3b, v37
	v_exp_f32_e32 v31, v31
	v_exp_f32_e32 v29, v29
	v_rcp_f32_e32 v27, v27
	s_nop 0
	v_pk_add_f32 v[30:31], v[30:31], 1.0 op_sel_hi:[1,0]
	v_exp_f32_e32 v33, v33
	v_rcp_f32_e32 v26, v26
	s_nop 0
	v_mov_b32_e32 v34, v22
	v_mov_b32_e32 v35, v24
	v_pk_mul_f32 v[26:27], v[34:35], v[26:27]
	v_rcp_f32_e32 v31, v31
	s_nop 0
	s_nop 0
	v_rcp_f32_e32 v30, v30
	s_nop 0
	v_mov_b32_e32 v24, v23
	v_pk_mul_f32 v[22:23], v[24:25], v[30:31]
	v_cvt_pk_bf16_f32 v24, v26, v27
	v_cvt_pk_bf16_f32 v22, v22, v23
	v_and_b32_e32 v23, 0xffff0000, v22
	v_lshlrev_b32_e32 v22, 16, v22
	v_or_b32_sdwa v23, v23, v24 dst_sel:DWORD dst_unused:UNUSED_PAD src0_sel:DWORD src1_sel:WORD_1
	v_or_b32_sdwa v22, v22, v24 dst_sel:DWORD dst_unused:UNUSED_PAD src0_sel:DWORD src1_sel:WORD_0
	v_pk_add_f32 v[24:25], v[28:29], 1.0 op_sel_hi:[1,0]
	s_nop 0
	s_nop 0
	v_rcp_f32_e32 v25, v25
	s_nop 0
	s_nop 0
	v_rcp_f32_e32 v24, v24
	s_nop 0
	v_mov_b32_e32 v26, v18
	v_mov_b32_e32 v27, v20
	v_pk_mul_f32 v[24:25], v[26:27], v[24:25]
	v_pk_add_f32 v[26:27], v[32:33], 1.0 op_sel_hi:[1,0]
	s_nop 0
	s_nop 0
	v_rcp_f32_e32 v27, v27
	s_nop 0
	s_nop 0
	v_rcp_f32_e32 v26, v26
	s_nop 0
	v_mov_b32_e32 v20, v19
	v_pk_mul_f32 v[18:19], v[20:21], v[26:27]
	v_cvt_pk_bf16_f32 v20, v24, v25
	v_cvt_pk_bf16_f32 v18, v18, v19
	v_and_b32_e32 v19, 0xffff0000, v18
	v_lshlrev_b32_e32 v18, 16, v18
	v_add_u32_e32 v28, 0xfa400, v151
	v_or_b32_sdwa v25, v19, v20 dst_sel:DWORD dst_unused:UNUSED_PAD src0_sel:DWORD src1_sel:WORD_1
	v_or_b32_sdwa v24, v18, v20 dst_sel:DWORD dst_unused:UNUSED_PAD src0_sel:DWORD src1_sel:WORD_0
	v_lshl_add_u64 v[18:19], v[0:1], 1, s[6:7]
	v_add_u32_e32 v0, v28, v150
	global_store_dwordx4 v[18:19], v[22:25], off
	s_nop 1
	s_waitcnt vmcnt(13)
	v_lshlrev_b32_e32 v25, 16, v167
	v_and_b32_e32 v26, 0xffff0000, v167
	v_lshlrev_b32_e32 v19, 16, v168
	v_and_b32_e32 v23, 0xffff0000, v166
	v_mul_f32_e32 v19, 0xbfb8aa3b, v19
	v_lshlrev_b32_e32 v22, 16, v166
	v_and_b32_e32 v24, 0xffff0000, v168
	v_exp_f32_e32 v20, v19
	v_mul_f32_e32 v19, 0xbfb8aa3b, v23
	v_mul_f32_e32 v18, 0xbfb8aa3b, v22
	v_exp_f32_e32 v22, v19
	v_mul_f32_e32 v19, 0xbfb8aa3b, v24
	v_exp_f32_e32 v24, v19
	v_mul_f32_e32 v19, 0xbfb8aa3b, v25
	v_exp_f32_e32 v18, v18
	v_exp_f32_e32 v19, v19
	v_lshlrev_b32_e32 v27, 16, v169
	v_mul_f32_e32 v23, 0xbfb8aa3b, v26
	v_and_b32_e32 v29, 0xffff0000, v169
	v_pk_add_f32 v[18:19], v[18:19], 1.0 op_sel_hi:[1,0]
	v_mul_f32_e32 v21, 0xbfb8aa3b, v27
	v_mul_f32_e32 v25, 0xbfb8aa3b, v29
	v_exp_f32_e32 v23, v23
	v_exp_f32_e32 v21, v21
	v_rcp_f32_e32 v19, v19
	s_nop 0
	v_pk_add_f32 v[22:23], v[22:23], 1.0 op_sel_hi:[1,0]
	v_exp_f32_e32 v25, v25
	v_rcp_f32_e32 v18, v18
	s_nop 0
	v_mov_b32_e32 v26, v14
	v_mov_b32_e32 v27, v16
	v_pk_mul_f32 v[18:19], v[26:27], v[18:19]
	v_rcp_f32_e32 v23, v23
	s_nop 0
	s_nop 0
	v_rcp_f32_e32 v22, v22
	s_nop 0
	v_mov_b32_e32 v16, v15
	v_pk_mul_f32 v[14:15], v[16:17], v[22:23]
	v_cvt_pk_bf16_f32 v16, v18, v19
	v_cvt_pk_bf16_f32 v14, v14, v15
	v_and_b32_e32 v15, 0xffff0000, v14
	v_lshlrev_b32_e32 v14, 16, v14
	v_or_b32_sdwa v15, v15, v16 dst_sel:DWORD dst_unused:UNUSED_PAD src0_sel:DWORD src1_sel:WORD_1
	v_or_b32_sdwa v14, v14, v16 dst_sel:DWORD dst_unused:UNUSED_PAD src0_sel:DWORD src1_sel:WORD_0
	v_pk_add_f32 v[16:17], v[20:21], 1.0 op_sel_hi:[1,0]
	s_nop 0
	s_nop 0
	v_rcp_f32_e32 v17, v17
	s_nop 0
	s_nop 0
	v_rcp_f32_e32 v16, v16
	s_nop 0
	v_mov_b32_e32 v18, v10
	v_mov_b32_e32 v19, v12
	v_pk_mul_f32 v[16:17], v[18:19], v[16:17]
	v_pk_add_f32 v[18:19], v[24:25], 1.0 op_sel_hi:[1,0]
	s_nop 0
	s_nop 0
	v_rcp_f32_e32 v19, v19
	s_nop 0
	s_nop 0
	v_rcp_f32_e32 v18, v18
	s_nop 0
	v_mov_b32_e32 v12, v11
	v_pk_mul_f32 v[10:11], v[12:13], v[18:19]
	v_add_u32_e32 v20, 0xfff31c00, v124
	v_cvt_pk_bf16_f32 v10, v10, v11
	v_cvt_pk_bf16_f32 v12, v16, v17
	v_and_b32_e32 v11, 0xffff0000, v10
	v_lshlrev_b32_e32 v10, 16, v10
	v_add_u32_e32 v0, v0, v20
	v_or_b32_sdwa v17, v11, v12 dst_sel:DWORD dst_unused:UNUSED_PAD src0_sel:DWORD src1_sel:WORD_1
	v_or_b32_sdwa v16, v10, v12 dst_sel:DWORD dst_unused:UNUSED_PAD src0_sel:DWORD src1_sel:WORD_0
	v_lshl_add_u64 v[10:11], v[0:1], 1, s[6:7]
	v_add_u32_e32 v0, v28, v125
	global_store_dwordx4 v[10:11], v[14:17], off
	v_add_u32_e32 v0, v0, v20
	s_waitcnt vmcnt(12)
	v_lshlrev_b32_e32 v17, 16, v171
	v_and_b32_e32 v18, 0xffff0000, v171
	v_lshlrev_b32_e32 v11, 16, v172
	v_and_b32_e32 v15, 0xffff0000, v170
	v_mul_f32_e32 v11, 0xbfb8aa3b, v11
	v_lshlrev_b32_e32 v14, 16, v170
	v_and_b32_e32 v16, 0xffff0000, v172
	v_exp_f32_e32 v12, v11
	v_mul_f32_e32 v11, 0xbfb8aa3b, v15
	v_mul_f32_e32 v10, 0xbfb8aa3b, v14
	v_exp_f32_e32 v14, v11
	v_mul_f32_e32 v11, 0xbfb8aa3b, v16
	v_exp_f32_e32 v16, v11
	v_mul_f32_e32 v11, 0xbfb8aa3b, v17
	v_exp_f32_e32 v10, v10
	v_exp_f32_e32 v11, v11
	v_lshlrev_b32_e32 v19, 16, v173
	v_mul_f32_e32 v15, 0xbfb8aa3b, v18
	v_and_b32_e32 v21, 0xffff0000, v173
	v_pk_add_f32 v[10:11], v[10:11], 1.0 op_sel_hi:[1,0]
	v_mul_f32_e32 v13, 0xbfb8aa3b, v19
	v_mul_f32_e32 v17, 0xbfb8aa3b, v21
	v_exp_f32_e32 v15, v15
	v_exp_f32_e32 v13, v13
	v_rcp_f32_e32 v11, v11
	s_nop 0
	v_pk_add_f32 v[14:15], v[14:15], 1.0 op_sel_hi:[1,0]
	v_exp_f32_e32 v17, v17
	v_rcp_f32_e32 v10, v10
	s_nop 0
	v_mov_b32_e32 v18, v6
	v_mov_b32_e32 v19, v8
	v_pk_mul_f32 v[10:11], v[18:19], v[10:11]
	v_rcp_f32_e32 v15, v15
	s_nop 0
	s_nop 0
	v_rcp_f32_e32 v14, v14
	s_nop 0
	v_mov_b32_e32 v8, v7
	v_pk_mul_f32 v[6:7], v[8:9], v[14:15]
	v_cvt_pk_bf16_f32 v8, v10, v11
	v_cvt_pk_bf16_f32 v6, v6, v7
	v_and_b32_e32 v7, 0xffff0000, v6
	v_lshlrev_b32_e32 v6, 16, v6
	v_or_b32_sdwa v7, v7, v8 dst_sel:DWORD dst_unused:UNUSED_PAD src0_sel:DWORD src1_sel:WORD_1
	v_or_b32_sdwa v6, v6, v8 dst_sel:DWORD dst_unused:UNUSED_PAD src0_sel:DWORD src1_sel:WORD_0
	v_pk_add_f32 v[8:9], v[12:13], 1.0 op_sel_hi:[1,0]
	s_nop 0
	s_nop 0
	v_rcp_f32_e32 v9, v9
	s_nop 0
	s_nop 0
	v_rcp_f32_e32 v8, v8
	s_nop 0
	v_mov_b32_e32 v10, v2
	v_mov_b32_e32 v11, v4
	v_pk_mul_f32 v[8:9], v[10:11], v[8:9]
	v_pk_add_f32 v[10:11], v[16:17], 1.0 op_sel_hi:[1,0]
	s_nop 0
	s_nop 0
	v_rcp_f32_e32 v11, v11
	s_nop 0
	s_mov_b64 s[24:25], s[16:17]
	v_rcp_f32_e32 v10, v10
	s_nop 0
	v_mov_b32_e32 v4, v3
	v_pk_mul_f32 v[2:3], v[4:5], v[10:11]
	v_cvt_pk_bf16_f32 v4, v8, v9
	v_cvt_pk_bf16_f32 v2, v2, v3
	v_and_b32_e32 v3, 0xffff0000, v2
	v_lshlrev_b32_e32 v2, 16, v2
	v_or_b32_sdwa v9, v3, v4 dst_sel:DWORD dst_unused:UNUSED_PAD src0_sel:DWORD src1_sel:WORD_1
	v_or_b32_sdwa v8, v2, v4 dst_sel:DWORD dst_unused:UNUSED_PAD src0_sel:DWORD src1_sel:WORD_0
	v_lshl_add_u64 v[2:3], v[0:1], 1, s[6:7]
	s_and_b64 vcc, exec, s[10:11]
	global_store_dwordx4 v[2:3], v[6:9], off
	s_cbranch_vccz .LBB0_1331
	s_waitcnt vmcnt(0)
	v_readlane_b32 s76, v255, 8
	s_mov_b32 s92, 0x3b2aaaab
	s_cmp_gt_u32 s5, 3
	v_readlane_b32 s77, v255, 9
	s_mul_i32 s60, s33, 0x1800
	s_mul_hi_i32 s62, s64, 0x300
	s_mul_i32 s75, s33, 0x16c00
	s_mov_b32 s93, 0x3c800000
	s_mov_b32 s82, s70
	s_cbranch_scc1 .LBB0_1338
	s_barrier

.LBB0_1347:
	v_add_u32_e32 v0, 0x10000, v148
	ds_read_b128 v[142:145], v0
	ds_read_b128 v[150:153], v0 offset:1024
	ds_read_b128 v[154:157], v0 offset:2048
	ds_read_b128 v[158:161], v0 offset:3072
	s_add_u32 s26, s24, 0xfffc0080
	s_addc_u32 s27, s25, -1
	s_cmp_eq_u32 s97, 12
	s_cselect_b32 s29, s2, s27
	s_cselect_b32 s28, s15, s26
	s_cselect_b32 s27, s13, s94
	s_cselect_b32 s26, s89, s90
	v_lshl_add_u64 v[178:179], s[24:25], 0, v[138:139]
	s_add_i32 m0, s35, 0xc000
	ds_read_b128 v[162:165], v147
	ds_read_b128 v[166:169], v147 offset:1024
	ds_read_b128 v[170:173], v147 offset:2048
	ds_read_b128 v[174:177], v147 offset:3072
	ds_read_b128 v[182:185], v147 offset:4096
	ds_read_b128 v[186:189], v147 offset:5120
	ds_read_b128 v[190:193], v147 offset:6144
	ds_read_b128 v[194:197], v147 offset:7168
	global_load_lds_dwordx4 v[178:179], off
	v_lshl_add_u64 v[178:179], s[24:25], 0, v[140:141]
	s_add_i32 m0, s35, 0xe000
	s_nop 0
	global_load_lds_dwordx4 v[178:179], off
	s_waitcnt lgkmcnt(8)
	s_barrier
	s_waitcnt lgkmcnt(0)
	s_setprio 1
	s_waitcnt lgkmcnt(0)
	v_mfma_f32_16x16x32_bf16 v[126:129], v[142:145], v[162:165], v[126:129]
	v_mfma_f32_16x16x32_bf16 v[122:125], v[154:157], v[162:165], v[122:125]
	v_mfma_f32_16x16x32_bf16 v[110:113], v[142:145], v[170:173], v[110:113]
	v_mfma_f32_16x16x32_bf16 v[106:109], v[154:157], v[170:173], v[106:109]
	v_mfma_f32_16x16x32_bf16 v[94:97], v[142:145], v[182:185], v[94:97]
	v_mfma_f32_16x16x32_bf16 v[90:93], v[154:157], v[182:185], v[90:93]
	v_mfma_f32_16x16x32_bf16 v[78:81], v[142:145], v[190:193], v[78:81]
	v_mfma_f32_16x16x32_bf16 v[74:77], v[154:157], v[190:193], v[74:77]
	v_mfma_f32_16x16x32_bf16 v[126:129], v[150:153], v[166:169], v[126:129]
	v_mfma_f32_16x16x32_bf16 v[122:125], v[158:161], v[166:169], v[122:125]
	v_mfma_f32_16x16x32_bf16 v[110:113], v[150:153], v[174:177], v[110:113]
	v_mfma_f32_16x16x32_bf16 v[106:109], v[158:161], v[174:177], v[106:109]
	v_mfma_f32_16x16x32_bf16 v[94:97], v[150:153], v[186:189], v[94:97]
	v_mfma_f32_16x16x32_bf16 v[90:93], v[158:161], v[186:189], v[90:93]
	v_mfma_f32_16x16x32_bf16 v[78:81], v[150:153], v[194:197], v[78:81]
	v_mfma_f32_16x16x32_bf16 v[74:77], v[158:161], v[194:197], v[74:77]
	s_setprio 0
	s_barrier
	s_mov_b32 m0, s21
	v_add_u32_e32 v0, 0x14000, v148
	v_lshl_add_u64 v[178:179], s[26:27], 0, v[134:135]
	ds_read_b128 v[198:201], v0
	ds_read_b128 v[202:205], v0 offset:1024
	ds_read_b128 v[206:209], v0 offset:2048
	ds_read_b128 v[210:213], v0 offset:3072
	global_load_lds_dwordx4 v[178:179], off
	v_lshl_add_u64 v[214:215], s[26:27], 0, v[130:131]
	s_mov_b32 m0, s23
	s_nop 0
	global_load_lds_dwordx4 v[214:215], off
	s_barrier
	s_waitcnt lgkmcnt(0)
	s_setprio 1
	s_waitcnt lgkmcnt(0)
	v_mfma_f32_16x16x32_bf16 v[118:121], v[198:201], v[162:165], v[118:121]
	v_mfma_f32_16x16x32_bf16 v[114:117], v[206:209], v[162:165], v[114:117]
	v_mfma_f32_16x16x32_bf16 v[102:105], v[198:201], v[170:173], v[102:105]
	v_mfma_f32_16x16x32_bf16 v[98:101], v[206:209], v[170:173], v[98:101]
	v_mfma_f32_16x16x32_bf16 v[86:89], v[198:201], v[182:185], v[86:89]
	v_mfma_f32_16x16x32_bf16 v[82:85], v[206:209], v[182:185], v[82:85]
	v_mfma_f32_16x16x32_bf16 v[70:73], v[198:201], v[190:193], v[70:73]
	v_mfma_f32_16x16x32_bf16 v[66:69], v[206:209], v[190:193], v[66:69]
	v_mfma_f32_16x16x32_bf16 v[118:121], v[202:205], v[166:169], v[118:121]
	v_mfma_f32_16x16x32_bf16 v[114:117], v[210:213], v[166:169], v[114:117]
	v_mfma_f32_16x16x32_bf16 v[102:105], v[202:205], v[174:177], v[102:105]
	v_mfma_f32_16x16x32_bf16 v[98:101], v[210:213], v[174:177], v[98:101]
	v_mfma_f32_16x16x32_bf16 v[86:89], v[202:205], v[186:189], v[86:89]
	v_mfma_f32_16x16x32_bf16 v[82:85], v[210:213], v[186:189], v[82:85]
	v_mfma_f32_16x16x32_bf16 v[70:73], v[202:205], v[194:197], v[70:73]
	v_mfma_f32_16x16x32_bf16 v[66:69], v[210:213], v[194:197], v[66:69]
	s_setprio 0
	s_mov_b32 m0, s35
	v_lshl_add_u64 v[216:217], s[28:29], 0, v[136:137]
	s_barrier
	ds_read_b128 v[162:165], v147 offset:16384
	ds_read_b128 v[166:169], v147 offset:17408
	ds_read_b128 v[170:173], v147 offset:18432
	ds_read_b128 v[174:177], v147 offset:19456
	ds_read_b128 v[182:185], v147 offset:20480
	ds_read_b128 v[186:189], v147 offset:21504
	ds_read_b128 v[190:193], v147 offset:22528
	ds_read_b128 v[194:197], v147 offset:23552
	global_load_lds_dwordx4 v[216:217], off
	v_lshl_add_u64 v[222:223], s[28:29], 0, v[132:133]
	s_mov_b32 m0, s36
	s_nop 0
	global_load_lds_dwordx4 v[222:223], off
	s_barrier
	s_waitcnt lgkmcnt(0)
	s_setprio 1
	s_waitcnt lgkmcnt(0)
	v_mfma_f32_16x16x32_bf16 v[62:65], v[142:145], v[162:165], v[62:65]
	v_mfma_f32_16x16x32_bf16 v[58:61], v[154:157], v[162:165], v[58:61]
	v_mfma_f32_16x16x32_bf16 v[46:49], v[142:145], v[170:173], v[46:49]
	v_mfma_f32_16x16x32_bf16 v[42:45], v[154:157], v[170:173], v[42:45]
	v_mfma_f32_16x16x32_bf16 v[30:33], v[142:145], v[182:185], v[30:33]
	v_mfma_f32_16x16x32_bf16 v[26:29], v[154:157], v[182:185], v[26:29]
	v_mfma_f32_16x16x32_bf16 v[14:17], v[142:145], v[190:193], v[14:17]
	v_mfma_f32_16x16x32_bf16 v[10:13], v[154:157], v[190:193], v[10:13]
	v_mfma_f32_16x16x32_bf16 v[62:65], v[150:153], v[166:169], v[62:65]
	v_mfma_f32_16x16x32_bf16 v[58:61], v[158:161], v[166:169], v[58:61]
	v_mfma_f32_16x16x32_bf16 v[46:49], v[150:153], v[174:177], v[46:49]
	v_mfma_f32_16x16x32_bf16 v[42:45], v[158:161], v[174:177], v[42:45]
	v_mfma_f32_16x16x32_bf16 v[30:33], v[150:153], v[186:189], v[30:33]
	v_mfma_f32_16x16x32_bf16 v[26:29], v[158:161], v[186:189], v[26:29]
	v_mfma_f32_16x16x32_bf16 v[14:17], v[150:153], v[194:197], v[14:17]
	v_mfma_f32_16x16x32_bf16 v[10:13], v[158:161], v[194:197], v[10:13]
	s_setprio 0
	s_barrier
	s_add_u32 s76, s26, 0x40000
	s_addc_u32 s77, s27, 0
	s_mov_b32 m0, s37
	v_lshl_add_u64 v[142:143], s[76:77], 0, v[134:135]
	global_load_lds_dwordx4 v[142:143], off
	v_lshl_add_u64 v[142:143], s[76:77], 0, v[130:131]
	s_mov_b32 m0, s38
	s_nop 0
	global_load_lds_dwordx4 v[142:143], off
	s_waitcnt vmcnt(6)
	s_barrier
	s_setprio 1
	v_mfma_f32_16x16x32_bf16 v[54:57], v[198:201], v[162:165], v[54:57]
	v_mfma_f32_16x16x32_bf16 v[50:53], v[206:209], v[162:165], v[50:53]
	v_mfma_f32_16x16x32_bf16 v[38:41], v[198:201], v[170:173], v[38:41]
	v_mfma_f32_16x16x32_bf16 v[34:37], v[206:209], v[170:173], v[34:37]
	v_mfma_f32_16x16x32_bf16 v[22:25], v[198:201], v[182:185], v[22:25]
	v_mfma_f32_16x16x32_bf16 v[18:21], v[206:209], v[182:185], v[18:21]
	v_mfma_f32_16x16x32_bf16 v[6:9], v[198:201], v[190:193], v[6:9]
	v_mfma_f32_16x16x32_bf16 v[2:5], v[206:209], v[190:193], v[2:5]
	v_mfma_f32_16x16x32_bf16 v[54:57], v[202:205], v[166:169], v[54:57]
	v_mfma_f32_16x16x32_bf16 v[50:53], v[210:213], v[166:169], v[50:53]
	v_mfma_f32_16x16x32_bf16 v[38:41], v[202:205], v[174:177], v[38:41]
	v_mfma_f32_16x16x32_bf16 v[34:37], v[210:213], v[174:177], v[34:37]
	v_mfma_f32_16x16x32_bf16 v[22:25], v[202:205], v[186:189], v[22:25]
	v_mfma_f32_16x16x32_bf16 v[18:21], v[210:213], v[186:189], v[18:21]
	v_mfma_f32_16x16x32_bf16 v[6:9], v[202:205], v[194:197], v[6:9]
	v_mfma_f32_16x16x32_bf16 v[2:5], v[210:213], v[194:197], v[2:5]
	s_setprio 0
	v_add_u32_e32 v0, 0x18000, v148
	s_barrier
	ds_read_b128 v[142:145], v0
	ds_read_b128 v[150:153], v0 offset:1024
	ds_read_b128 v[154:157], v0 offset:2048
	ds_read_b128 v[158:161], v0 offset:3072
	s_add_u32 s28, s28, 0x40000
	s_addc_u32 s29, s29, 0
	s_mov_b32 m0, s39
	v_lshl_add_u64 v[198:199], s[28:29], 0, v[136:137]
	ds_read_b128 v[162:165], v147 offset:32768
	ds_read_b128 v[166:169], v147 offset:33792
	ds_read_b128 v[170:173], v147 offset:34816
	ds_read_b128 v[174:177], v147 offset:35840
	ds_read_b128 v[182:185], v147 offset:36864
	ds_read_b128 v[186:189], v147 offset:37888
	ds_read_b128 v[190:193], v147 offset:38912
	ds_read_b128 v[194:197], v147 offset:39936
	global_load_lds_dwordx4 v[198:199], off
	v_lshl_add_u64 v[198:199], s[28:29], 0, v[132:133]
	s_mov_b32 m0, s60
	s_nop 0
	global_load_lds_dwordx4 v[198:199], off
	s_waitcnt lgkmcnt(8)
	s_barrier
	s_waitcnt lgkmcnt(0)
	s_setprio 1
	s_waitcnt lgkmcnt(0)
	v_mfma_f32_16x16x32_bf16 v[126:129], v[142:145], v[162:165], v[126:129]
	v_mfma_f32_16x16x32_bf16 v[122:125], v[154:157], v[162:165], v[122:125]
	v_mfma_f32_16x16x32_bf16 v[110:113], v[142:145], v[170:173], v[110:113]
	v_mfma_f32_16x16x32_bf16 v[106:109], v[154:157], v[170:173], v[106:109]
	v_mfma_f32_16x16x32_bf16 v[94:97], v[142:145], v[182:185], v[94:97]
	v_mfma_f32_16x16x32_bf16 v[90:93], v[154:157], v[182:185], v[90:93]
	v_mfma_f32_16x16x32_bf16 v[78:81], v[142:145], v[190:193], v[78:81]
	v_mfma_f32_16x16x32_bf16 v[74:77], v[154:157], v[190:193], v[74:77]
	v_mfma_f32_16x16x32_bf16 v[126:129], v[150:153], v[166:169], v[126:129]
	v_mfma_f32_16x16x32_bf16 v[122:125], v[158:161], v[166:169], v[122:125]
	v_mfma_f32_16x16x32_bf16 v[110:113], v[150:153], v[174:177], v[110:113]
	v_mfma_f32_16x16x32_bf16 v[106:109], v[158:161], v[174:177], v[106:109]
	v_mfma_f32_16x16x32_bf16 v[94:97], v[150:153], v[186:189], v[94:97]
	v_mfma_f32_16x16x32_bf16 v[90:93], v[158:161], v[186:189], v[90:93]
	v_mfma_f32_16x16x32_bf16 v[78:81], v[150:153], v[194:197], v[78:81]
	v_mfma_f32_16x16x32_bf16 v[74:77], v[158:161], v[194:197], v[74:77]
	s_setprio 0
	s_barrier
	s_mov_b32 m0, s68
	v_add_u32_e32 v0, 0x1c000, v148
	v_lshl_add_u64 v[178:179], v[178:179], 0, s[84:85]
	ds_read_b128 v[198:201], v0
	ds_read_b128 v[202:205], v0 offset:1024
	ds_read_b128 v[206:209], v0 offset:2048
	ds_read_b128 v[210:213], v0 offset:3072
	global_load_lds_dwordx4 v[178:179], off
	v_lshl_add_u64 v[178:179], v[214:215], 0, s[84:85]
	s_mov_b32 m0, s69
	s_nop 0
	global_load_lds_dwordx4 v[178:179], off
	s_barrier
	s_waitcnt lgkmcnt(0)
	s_setprio 1
	s_waitcnt lgkmcnt(0)
	v_mfma_f32_16x16x32_bf16 v[118:121], v[198:201], v[162:165], v[118:121]
	v_mfma_f32_16x16x32_bf16 v[114:117], v[206:209], v[162:165], v[114:117]
	v_mfma_f32_16x16x32_bf16 v[102:105], v[198:201], v[170:173], v[102:105]
	v_mfma_f32_16x16x32_bf16 v[98:101], v[206:209], v[170:173], v[98:101]
	v_mfma_f32_16x16x32_bf16 v[86:89], v[198:201], v[182:185], v[86:89]
	v_mfma_f32_16x16x32_bf16 v[82:85], v[206:209], v[182:185], v[82:85]
	v_mfma_f32_16x16x32_bf16 v[70:73], v[198:201], v[190:193], v[70:73]
	v_mfma_f32_16x16x32_bf16 v[66:69], v[206:209], v[190:193], v[66:69]
	v_mfma_f32_16x16x32_bf16 v[118:121], v[202:205], v[166:169], v[118:121]
	v_mfma_f32_16x16x32_bf16 v[114:117], v[210:213], v[166:169], v[114:117]
	v_mfma_f32_16x16x32_bf16 v[102:105], v[202:205], v[174:177], v[102:105]
	v_mfma_f32_16x16x32_bf16 v[98:101], v[210:213], v[174:177], v[98:101]
	v_mfma_f32_16x16x32_bf16 v[86:89], v[202:205], v[186:189], v[86:89]
	v_mfma_f32_16x16x32_bf16 v[82:85], v[210:213], v[186:189], v[82:85]
	v_mfma_f32_16x16x32_bf16 v[70:73], v[202:205], v[194:197], v[70:73]
	v_mfma_f32_16x16x32_bf16 v[66:69], v[210:213], v[194:197], v[66:69]
	s_setprio 0
	s_mov_b32 m0, s75
	v_lshl_add_u64 v[178:179], v[216:217], 0, s[84:85]
	s_barrier
	ds_read_b128 v[162:165], v147 offset:49152
	ds_read_b128 v[166:169], v147 offset:50176
	ds_read_b128 v[170:173], v147 offset:51200
	ds_read_b128 v[174:177], v147 offset:52224
	ds_read_b128 v[182:185], v147 offset:53248
	ds_read_b128 v[186:189], v147 offset:54272
	ds_read_b128 v[190:193], v147 offset:55296
	ds_read_b128 v[194:197], v147 offset:56320
	global_load_lds_dwordx4 v[178:179], off
	v_lshl_add_u64 v[178:179], v[222:223], 0, s[84:85]
	s_mov_b32 m0, s82
	s_nop 0
	global_load_lds_dwordx4 v[178:179], off
	s_barrier
	s_waitcnt lgkmcnt(0)
	s_setprio 1
	s_waitcnt lgkmcnt(0)
	v_mfma_f32_16x16x32_bf16 v[62:65], v[142:145], v[162:165], v[62:65]
	v_mfma_f32_16x16x32_bf16 v[58:61], v[154:157], v[162:165], v[58:61]
	v_mfma_f32_16x16x32_bf16 v[46:49], v[142:145], v[170:173], v[46:49]
	v_mfma_f32_16x16x32_bf16 v[42:45], v[154:157], v[170:173], v[42:45]
	v_mfma_f32_16x16x32_bf16 v[30:33], v[142:145], v[182:185], v[30:33]
	v_mfma_f32_16x16x32_bf16 v[26:29], v[154:157], v[182:185], v[26:29]
	v_mfma_f32_16x16x32_bf16 v[14:17], v[142:145], v[190:193], v[14:17]
	v_mfma_f32_16x16x32_bf16 v[10:13], v[154:157], v[190:193], v[10:13]
	v_mfma_f32_16x16x32_bf16 v[62:65], v[150:153], v[166:169], v[62:65]
	v_mfma_f32_16x16x32_bf16 v[58:61], v[158:161], v[166:169], v[58:61]
	v_mfma_f32_16x16x32_bf16 v[46:49], v[150:153], v[174:177], v[46:49]
	v_mfma_f32_16x16x32_bf16 v[42:45], v[158:161], v[174:177], v[42:45]
	v_mfma_f32_16x16x32_bf16 v[30:33], v[150:153], v[186:189], v[30:33]
	v_mfma_f32_16x16x32_bf16 v[26:29], v[158:161], v[186:189], v[26:29]
	v_mfma_f32_16x16x32_bf16 v[14:17], v[150:153], v[194:197], v[14:17]
	v_mfma_f32_16x16x32_bf16 v[10:13], v[158:161], v[194:197], v[10:13]
	s_setprio 0
	s_barrier
	s_add_u32 s26, s26, 0x40080
	s_addc_u32 s27, s27, 0
	s_mov_b32 m0, s92
	v_lshl_add_u64 v[142:143], s[26:27], 0, v[134:135]
	global_load_lds_dwordx4 v[142:143], off
	v_lshl_add_u64 v[142:143], s[26:27], 0, v[130:131]
	s_mov_b32 m0, s93
	s_nop 0
	global_load_lds_dwordx4 v[142:143], off
	s_waitcnt vmcnt(6)
	s_barrier
	s_setprio 1
	v_mfma_f32_16x16x32_bf16 v[54:57], v[198:201], v[162:165], v[54:57]
	v_mfma_f32_16x16x32_bf16 v[50:53], v[206:209], v[162:165], v[50:53]
	v_mfma_f32_16x16x32_bf16 v[38:41], v[198:201], v[170:173], v[38:41]
	v_mfma_f32_16x16x32_bf16 v[34:37], v[206:209], v[170:173], v[34:37]
	v_mfma_f32_16x16x32_bf16 v[22:25], v[198:201], v[182:185], v[22:25]
	v_mfma_f32_16x16x32_bf16 v[18:21], v[206:209], v[182:185], v[18:21]
	v_mfma_f32_16x16x32_bf16 v[6:9], v[198:201], v[190:193], v[6:9]
	v_mfma_f32_16x16x32_bf16 v[2:5], v[206:209], v[190:193], v[2:5]
	v_mfma_f32_16x16x32_bf16 v[54:57], v[202:205], v[166:169], v[54:57]
	v_mfma_f32_16x16x32_bf16 v[50:53], v[210:213], v[166:169], v[50:53]
	v_mfma_f32_16x16x32_bf16 v[38:41], v[202:205], v[174:177], v[38:41]
	v_mfma_f32_16x16x32_bf16 v[34:37], v[210:213], v[174:177], v[34:37]
	v_mfma_f32_16x16x32_bf16 v[22:25], v[202:205], v[186:189], v[22:25]
	v_mfma_f32_16x16x32_bf16 v[18:21], v[210:213], v[186:189], v[18:21]
	v_mfma_f32_16x16x32_bf16 v[6:9], v[202:205], v[194:197], v[6:9]
	v_mfma_f32_16x16x32_bf16 v[2:5], v[210:213], v[194:197], v[2:5]
	s_setprio 0
	s_add_i32 s97, s97, 2
	s_add_u32 s24, s24, 0x100
	s_addc_u32 s25, s25, 0
	s_add_u32 s90, s90, 0x100
	s_addc_u32 s94, s94, 0
	s_cmp_gt_u32 s97, 13
	s_barrier
	s_cbranch_scc0 .LBB0_1347
	v_lshl_add_u32 v152, s22, 8, v146
	v_lshl_add_u32 v150, s20, 8, v149
	v_mul_lo_u32 v151, v152, s71
	v_add_u32_e32 v0, v151, v150
	v_lshl_add_u64 v[142:143], v[0:1], 1, s[8:9]
	global_load_dwordx4 v[142:145], v[142:143], off
	v_mov_b32_e32 v178, v0
	v_mov_b32_e32 v161, 0
	v_add_u32_e32 v160, 0x80, v178
	v_lshl_add_u64 v[162:163], v[160:161], 1, s[8:9]
	global_load_dwordx4 v[162:165], v[162:163], off
	v_add_u32_e32 v160, 0x16c00, v178
	v_lshl_add_u64 v[166:167], v[160:161], 1, s[8:9]
	global_load_dwordx4 v[166:169], v[166:167], off
	v_add_u32_e32 v160, 0x16c80, v178
	v_lshl_add_u64 v[170:171], v[160:161], 1, s[8:9]
	global_load_dwordx4 v[170:173], v[170:171], off
	v_add_u32_e32 v160, 0x2d800, v178
	v_lshl_add_u64 v[174:175], v[160:161], 1, s[8:9]
	global_load_dwordx4 v[174:177], v[174:175], off
	v_add_u32_e32 v160, 0x2d880, v178
	v_lshl_add_u64 v[182:183], v[160:161], 1, s[8:9]
	global_load_dwordx4 v[182:185], v[182:183], off
	v_add_u32_e32 v160, 0x44400, v178
	v_lshl_add_u64 v[186:187], v[160:161], 1, s[8:9]
	global_load_dwordx4 v[186:189], v[186:187], off
	v_add_u32_e32 v160, 0x44480, v178
	v_lshl_add_u64 v[190:191], v[160:161], 1, s[8:9]
	global_load_dwordx4 v[190:193], v[190:191], off
	v_add_u32_e32 v160, 0xb6000, v178
	v_lshl_add_u64 v[194:195], v[160:161], 1, s[8:9]
	global_load_dwordx4 v[194:197], v[194:195], off
	v_add_u32_e32 v160, 0xb6080, v178
	v_lshl_add_u64 v[198:199], v[160:161], 1, s[8:9]
	global_load_dwordx4 v[198:201], v[198:199], off
	v_add_u32_e32 v160, 0xccc00, v178
	v_lshl_add_u64 v[202:203], v[160:161], 1, s[8:9]
	global_load_dwordx4 v[202:205], v[202:203], off
	v_add_u32_e32 v160, 0xccc80, v178
	v_lshl_add_u64 v[206:207], v[160:161], 1, s[8:9]
	global_load_dwordx4 v[206:209], v[206:207], off
	v_add_u32_e32 v160, 0xe3800, v178
	v_lshl_add_u64 v[210:211], v[160:161], 1, s[8:9]
	global_load_dwordx4 v[210:213], v[210:211], off
	s_mov_b32 s20, s12
	s_mov_b32 s22, s14
	s_mov_b64 s[26:27], s[18:19]
	s_waitcnt vmcnt(12)
	v_lshlrev_b32_e32 v153, 16, v142
	v_lshlrev_b32_e32 v155, 16, v143
	v_lshlrev_b32_e32 v156, 16, v144
	v_and_b32_e32 v157, 0xffff0000, v144
	v_lshlrev_b32_e32 v158, 16, v145
	v_and_b32_e32 v159, 0xffff0000, v145
	v_mul_f32_e32 v144, 0xbfb8aa3b, v153
	v_mul_f32_e32 v145, 0xbfb8aa3b, v155
	v_exp_f32_e32 v154, v144
	v_exp_f32_e32 v155, v145
	v_mul_f32_e32 v145, 0xbfb8aa3b, v158
	v_and_b32_e32 v142, 0xffff0000, v142
	v_and_b32_e32 v143, 0xffff0000, v143
	v_pk_add_f32 v[154:155], v[154:155], 1.0 op_sel_hi:[1,0]
	v_mul_f32_e32 v142, 0xbfb8aa3b, v142
	v_mul_f32_e32 v143, 0xbfb8aa3b, v143
	v_mul_f32_e32 v144, 0xbfb8aa3b, v156
	v_exp_f32_e32 v156, v142
	v_mul_f32_e32 v142, 0xbfb8aa3b, v157
	v_exp_f32_e32 v157, v143
	v_mul_f32_e32 v143, 0xbfb8aa3b, v159
	v_rcp_f32_e32 v155, v155
	s_nop 0
	v_pk_add_f32 v[156:157], v[156:157], 1.0 op_sel_hi:[1,0]
	v_exp_f32_e32 v144, v144
	v_exp_f32_e32 v145, v145
	v_mov_b32_e32 v158, v126
	v_mov_b32_e32 v159, v128
	v_rcp_f32_e32 v154, v154
	s_nop 0
	v_pk_mul_f32 v[154:155], v[158:159], v[154:155]
	v_exp_f32_e32 v142, v142
	v_rcp_f32_e32 v157, v157
	s_nop 0
	v_exp_f32_e32 v143, v143
	v_rcp_f32_e32 v156, v156
	s_nop 0
	v_mov_b32_e32 v128, v127
	v_pk_mul_f32 v[126:127], v[128:129], v[156:157]
	v_cvt_pk_bf16_f32 v128, v154, v155
	v_cvt_pk_bf16_f32 v126, v126, v127
	v_and_b32_e32 v127, 0xffff0000, v126
	v_lshlrev_b32_e32 v126, 16, v126
	v_or_b32_sdwa v127, v127, v128 dst_sel:DWORD dst_unused:UNUSED_PAD src0_sel:DWORD src1_sel:WORD_1
	v_or_b32_sdwa v126, v126, v128 dst_sel:DWORD dst_unused:UNUSED_PAD src0_sel:DWORD src1_sel:WORD_0
	v_pk_add_f32 v[128:129], v[144:145], 1.0 op_sel_hi:[1,0]
	v_pk_add_f32 v[142:143], v[142:143], 1.0 op_sel_hi:[1,0]
	s_nop 0
	v_rcp_f32_e32 v129, v129
	s_nop 0
	s_nop 0
	v_rcp_f32_e32 v128, v128
	s_nop 0
	v_mov_b32_e32 v144, v122
	v_mov_b32_e32 v145, v124
	v_pk_mul_f32 v[128:129], v[144:145], v[128:129]
	v_rcp_f32_e32 v143, v143
	s_nop 0
	s_nop 0
	v_rcp_f32_e32 v142, v142
	s_nop 0
	v_mov_b32_e32 v124, v123
	v_pk_mul_f32 v[122:123], v[124:125], v[142:143]
	v_cvt_pk_bf16_f32 v124, v128, v129
	v_cvt_pk_bf16_f32 v122, v122, v123
	v_and_b32_e32 v123, 0xffff0000, v122
	v_lshlrev_b32_e32 v122, 16, v122
	v_or_b32_sdwa v129, v123, v124 dst_sel:DWORD dst_unused:UNUSED_PAD src0_sel:DWORD src1_sel:WORD_1
	v_or_b32_sdwa v128, v122, v124 dst_sel:DWORD dst_unused:UNUSED_PAD src0_sel:DWORD src1_sel:WORD_0
	v_mul_lo_u32 v124, v152, s61
	v_add_u32_e32 v0, v0, v124
	v_add_u32_e32 v125, 0x80, v150
	v_lshl_add_u64 v[122:123], v[0:1], 1, s[6:7]
	v_add_u32_e32 v0, v151, v125
	global_store_dwordx4 v[122:123], v[126:129], off
	v_add_u32_e32 v0, v0, v124
	s_waitcnt vmcnt(12)
	v_lshlrev_b32_e32 v122, 16, v162
	v_lshlrev_b32_e32 v143, 16, v163
	v_and_b32_e32 v144, 0xffff0000, v163
	v_lshlrev_b32_e32 v127, 16, v164
	v_mul_f32_e32 v122, 0xbfb8aa3b, v122
	v_and_b32_e32 v123, 0xffff0000, v162
	v_exp_f32_e32 v126, v122
	v_mul_f32_e32 v122, 0xbfb8aa3b, v127
	v_and_b32_e32 v145, 0xffff0000, v164
	v_exp_f32_e32 v128, v122
	v_mul_f32_e32 v122, 0xbfb8aa3b, v123
	v_mul_f32_e32 v123, 0xbfb8aa3b, v143
	v_exp_f32_e32 v127, v123
	v_lshlrev_b32_e32 v153, 16, v165
	v_mul_f32_e32 v123, 0xbfb8aa3b, v153
	v_and_b32_e32 v154, 0xffff0000, v165
	v_pk_add_f32 v[126:127], v[126:127], 1.0 op_sel_hi:[1,0]
	v_exp_f32_e32 v129, v123
	v_mul_f32_e32 v123, 0xbfb8aa3b, v144
	v_exp_f32_e32 v142, v122
	v_mul_f32_e32 v122, 0xbfb8aa3b, v145
	v_exp_f32_e32 v143, v123
	v_mul_f32_e32 v123, 0xbfb8aa3b, v154
	v_exp_f32_e32 v122, v122
	v_rcp_f32_e32 v127, v127
	s_nop 0
	v_pk_add_f32 v[142:143], v[142:143], 1.0 op_sel_hi:[1,0]
	v_exp_f32_e32 v123, v123
	v_rcp_f32_e32 v126, v126
	s_nop 0
	v_mov_b32_e32 v144, v118
	v_mov_b32_e32 v145, v120
	v_pk_mul_f32 v[126:127], v[144:145], v[126:127]
	v_pk_add_f32 v[122:123], v[122:123], 1.0 op_sel_hi:[1,0]
	v_rcp_f32_e32 v143, v143
	s_nop 0
	s_nop 0
	v_rcp_f32_e32 v142, v142
	s_nop 0
	v_mov_b32_e32 v120, v119
	v_pk_mul_f32 v[118:119], v[120:121], v[142:143]
	v_cvt_pk_bf16_f32 v120, v126, v127
	v_cvt_pk_bf16_f32 v118, v118, v119
	v_and_b32_e32 v119, 0xffff0000, v118
	v_lshlrev_b32_e32 v118, 16, v118
	v_or_b32_sdwa v119, v119, v120 dst_sel:DWORD dst_unused:UNUSED_PAD src0_sel:DWORD src1_sel:WORD_1
	v_or_b32_sdwa v118, v118, v120 dst_sel:DWORD dst_unused:UNUSED_PAD src0_sel:DWORD src1_sel:WORD_0
	v_pk_add_f32 v[120:121], v[128:129], 1.0 op_sel_hi:[1,0]
	s_nop 0
	s_nop 0
	v_rcp_f32_e32 v121, v121
	s_nop 0
	s_nop 0
	v_rcp_f32_e32 v120, v120
	s_nop 0
	v_mov_b32_e32 v126, v114
	v_mov_b32_e32 v127, v116
	v_pk_mul_f32 v[120:121], v[126:127], v[120:121]
	v_rcp_f32_e32 v123, v123
	s_nop 0
	s_nop 0
	v_rcp_f32_e32 v122, v122
	s_nop 0
	v_mov_b32_e32 v116, v115
	v_pk_mul_f32 v[114:115], v[116:117], v[122:123]
	v_cvt_pk_bf16_f32 v116, v120, v121
	v_cvt_pk_bf16_f32 v114, v114, v115
	v_and_b32_e32 v115, 0xffff0000, v114
	v_lshlrev_b32_e32 v114, 16, v114
	v_add_u32_e32 v127, 0x16c00, v151
	v_or_b32_sdwa v121, v115, v116 dst_sel:DWORD dst_unused:UNUSED_PAD src0_sel:DWORD src1_sel:WORD_1
	v_or_b32_sdwa v120, v114, v116 dst_sel:DWORD dst_unused:UNUSED_PAD src0_sel:DWORD src1_sel:WORD_0
	v_lshl_add_u64 v[114:115], v[0:1], 1, s[6:7]
	v_add_u32_e32 v0, v127, v150
	v_add_u32_e32 v160, 0xe3880, v178
	v_lshl_add_u64 v[162:163], v[160:161], 1, s[8:9]
	global_load_dwordx4 v[162:165], v[162:163], off
	global_store_dwordx4 v[114:115], v[118:121], off
	v_or_b32_e32 v126, 16, v152
	s_waitcnt vmcnt(13)
	v_lshlrev_b32_e32 v121, 16, v167
	v_and_b32_e32 v122, 0xffff0000, v167
	v_lshlrev_b32_e32 v115, 16, v168
	v_and_b32_e32 v119, 0xffff0000, v166
	v_mul_f32_e32 v115, 0xbfb8aa3b, v115
	v_lshlrev_b32_e32 v118, 16, v166
	v_and_b32_e32 v120, 0xffff0000, v168
	v_exp_f32_e32 v116, v115
	v_mul_f32_e32 v115, 0xbfb8aa3b, v119
	v_mul_f32_e32 v114, 0xbfb8aa3b, v118
	v_exp_f32_e32 v118, v115
	v_mul_f32_e32 v115, 0xbfb8aa3b, v120
	v_exp_f32_e32 v120, v115
	v_mul_f32_e32 v115, 0xbfb8aa3b, v121
	v_exp_f32_e32 v114, v114
	v_exp_f32_e32 v115, v115
	v_lshlrev_b32_e32 v123, 16, v169
	v_mul_f32_e32 v119, 0xbfb8aa3b, v122
	v_and_b32_e32 v128, 0xffff0000, v169
	v_pk_add_f32 v[114:115], v[114:115], 1.0 op_sel_hi:[1,0]
	v_mul_f32_e32 v117, 0xbfb8aa3b, v123
	v_mul_f32_e32 v121, 0xbfb8aa3b, v128
	v_exp_f32_e32 v119, v119
	v_exp_f32_e32 v117, v117
	v_rcp_f32_e32 v115, v115
	s_nop 0
	v_pk_add_f32 v[118:119], v[118:119], 1.0 op_sel_hi:[1,0]
	v_exp_f32_e32 v121, v121
	v_rcp_f32_e32 v114, v114
	s_nop 0
	v_mov_b32_e32 v122, v110
	v_mov_b32_e32 v123, v112
	v_pk_mul_f32 v[114:115], v[122:123], v[114:115]
	v_rcp_f32_e32 v119, v119
	s_nop 0
	s_nop 0
	v_rcp_f32_e32 v118, v118
	s_nop 0
	v_mov_b32_e32 v112, v111
	v_pk_mul_f32 v[110:111], v[112:113], v[118:119]
	v_cvt_pk_bf16_f32 v112, v114, v115
	v_cvt_pk_bf16_f32 v110, v110, v111
	v_and_b32_e32 v111, 0xffff0000, v110
	v_lshlrev_b32_e32 v110, 16, v110
	v_or_b32_sdwa v111, v111, v112 dst_sel:DWORD dst_unused:UNUSED_PAD src0_sel:DWORD src1_sel:WORD_1
	v_or_b32_sdwa v110, v110, v112 dst_sel:DWORD dst_unused:UNUSED_PAD src0_sel:DWORD src1_sel:WORD_0
	v_pk_add_f32 v[112:113], v[116:117], 1.0 op_sel_hi:[1,0]
	s_nop 0
	s_nop 0
	v_rcp_f32_e32 v113, v113
	s_nop 0
	s_nop 0
	v_rcp_f32_e32 v112, v112
	s_nop 0
	v_mov_b32_e32 v114, v106
	v_mov_b32_e32 v115, v108
	v_pk_mul_f32 v[112:113], v[114:115], v[112:113]
	v_pk_add_f32 v[114:115], v[120:121], 1.0 op_sel_hi:[1,0]
	s_nop 0
	s_nop 0
	v_rcp_f32_e32 v115, v115
	s_nop 0
	s_nop 0
	v_rcp_f32_e32 v114, v114
	s_nop 0
	v_mov_b32_e32 v108, v107
	v_pk_mul_f32 v[106:107], v[108:109], v[114:115]
	v_mul_lo_u32 v116, v126, s61
	v_cvt_pk_bf16_f32 v106, v106, v107
	v_cvt_pk_bf16_f32 v108, v112, v113
	v_and_b32_e32 v107, 0xffff0000, v106
	v_lshlrev_b32_e32 v106, 16, v106
	v_add_u32_e32 v0, v0, v116
	v_or_b32_sdwa v113, v107, v108 dst_sel:DWORD dst_unused:UNUSED_PAD src0_sel:DWORD src1_sel:WORD_1
	v_or_b32_sdwa v112, v106, v108 dst_sel:DWORD dst_unused:UNUSED_PAD src0_sel:DWORD src1_sel:WORD_0
	v_lshl_add_u64 v[106:107], v[0:1], 1, s[6:7]
	v_add_u32_e32 v0, v127, v125
	v_add_u32_e32 v160, 0xfa400, v178
	v_lshl_add_u64 v[166:167], v[160:161], 1, s[8:9]
	global_load_dwordx4 v[166:169], v[166:167], off
	global_store_dwordx4 v[106:107], v[110:113], off
	v_add_u32_e32 v0, v0, v116
	s_waitcnt vmcnt(14)
	v_lshlrev_b32_e32 v113, 16, v171
	v_and_b32_e32 v114, 0xffff0000, v171
	v_lshlrev_b32_e32 v107, 16, v172
	v_and_b32_e32 v111, 0xffff0000, v170
	v_mul_f32_e32 v107, 0xbfb8aa3b, v107
	v_lshlrev_b32_e32 v110, 16, v170
	v_and_b32_e32 v112, 0xffff0000, v172
	v_exp_f32_e32 v108, v107
	v_mul_f32_e32 v107, 0xbfb8aa3b, v111
	v_mul_f32_e32 v106, 0xbfb8aa3b, v110
	v_exp_f32_e32 v110, v107
	v_mul_f32_e32 v107, 0xbfb8aa3b, v112
	v_exp_f32_e32 v112, v107
	v_mul_f32_e32 v107, 0xbfb8aa3b, v113
	v_exp_f32_e32 v106, v106
	v_exp_f32_e32 v107, v107
	v_lshlrev_b32_e32 v115, 16, v173
	v_mul_f32_e32 v111, 0xbfb8aa3b, v114
	v_and_b32_e32 v117, 0xffff0000, v173
	v_pk_add_f32 v[106:107], v[106:107], 1.0 op_sel_hi:[1,0]
	v_mul_f32_e32 v109, 0xbfb8aa3b, v115
	v_mul_f32_e32 v113, 0xbfb8aa3b, v117
	v_exp_f32_e32 v111, v111
	v_exp_f32_e32 v109, v109
	v_rcp_f32_e32 v107, v107
	s_nop 0
	v_pk_add_f32 v[110:111], v[110:111], 1.0 op_sel_hi:[1,0]
	v_exp_f32_e32 v113, v113
	v_rcp_f32_e32 v106, v106
	s_nop 0
	v_mov_b32_e32 v114, v102
	v_mov_b32_e32 v115, v104
	v_pk_mul_f32 v[106:107], v[114:115], v[106:107]
	v_rcp_f32_e32 v111, v111
	s_nop 0
	s_nop 0
	v_rcp_f32_e32 v110, v110
	s_nop 0
	v_mov_b32_e32 v104, v103
	v_pk_mul_f32 v[102:103], v[104:105], v[110:111]
	v_cvt_pk_bf16_f32 v104, v106, v107
	v_cvt_pk_bf16_f32 v102, v102, v103
	v_and_b32_e32 v103, 0xffff0000, v102
	v_lshlrev_b32_e32 v102, 16, v102
	v_or_b32_sdwa v103, v103, v104 dst_sel:DWORD dst_unused:UNUSED_PAD src0_sel:DWORD src1_sel:WORD_1
	v_or_b32_sdwa v102, v102, v104 dst_sel:DWORD dst_unused:UNUSED_PAD src0_sel:DWORD src1_sel:WORD_0
	v_pk_add_f32 v[104:105], v[108:109], 1.0 op_sel_hi:[1,0]
	s_nop 0
	s_nop 0
	v_rcp_f32_e32 v105, v105
	s_nop 0
	s_nop 0
	v_rcp_f32_e32 v104, v104
	s_nop 0
	v_mov_b32_e32 v106, v98
	v_mov_b32_e32 v107, v100
	v_pk_mul_f32 v[104:105], v[106:107], v[104:105]
	v_pk_add_f32 v[106:107], v[112:113], 1.0 op_sel_hi:[1,0]
	s_nop 0
	s_nop 0
	v_rcp_f32_e32 v107, v107
	s_nop 0
	s_nop 0
	v_rcp_f32_e32 v106, v106
	s_nop 0
	v_mov_b32_e32 v100, v99
	v_pk_mul_f32 v[98:99], v[100:101], v[106:107]
	v_cvt_pk_bf16_f32 v100, v104, v105
	v_cvt_pk_bf16_f32 v98, v98, v99
	v_and_b32_e32 v99, 0xffff0000, v98
	v_lshlrev_b32_e32 v98, 16, v98
	v_add_u32_e32 v109, 0x2d800, v151
	v_or_b32_sdwa v105, v99, v100 dst_sel:DWORD dst_unused:UNUSED_PAD src0_sel:DWORD src1_sel:WORD_1
	v_or_b32_sdwa v104, v98, v100 dst_sel:DWORD dst_unused:UNUSED_PAD src0_sel:DWORD src1_sel:WORD_0
	v_lshl_add_u64 v[98:99], v[0:1], 1, s[6:7]
	v_add_u32_e32 v0, v109, v150
	v_add_u32_e32 v160, 0xfa480, v178
	v_lshl_add_u64 v[170:171], v[160:161], 1, s[8:9]
	global_load_dwordx4 v[170:173], v[170:171], off
	global_store_dwordx4 v[98:99], v[102:105], off
	v_or_b32_e32 v108, 32, v152
	s_waitcnt vmcnt(15)
	v_lshlrev_b32_e32 v105, 16, v175
	v_and_b32_e32 v106, 0xffff0000, v175
	v_lshlrev_b32_e32 v99, 16, v176
	v_and_b32_e32 v103, 0xffff0000, v174
	v_mul_f32_e32 v99, 0xbfb8aa3b, v99
	v_lshlrev_b32_e32 v102, 16, v174
	v_and_b32_e32 v104, 0xffff0000, v176
	v_exp_f32_e32 v100, v99
	v_mul_f32_e32 v99, 0xbfb8aa3b, v103
	v_mul_f32_e32 v98, 0xbfb8aa3b, v102
	v_exp_f32_e32 v102, v99
	v_mul_f32_e32 v99, 0xbfb8aa3b, v104
	v_exp_f32_e32 v104, v99
	v_mul_f32_e32 v99, 0xbfb8aa3b, v105
	v_exp_f32_e32 v98, v98
	v_exp_f32_e32 v99, v99
	v_lshlrev_b32_e32 v107, 16, v177
	v_mul_f32_e32 v103, 0xbfb8aa3b, v106
	v_and_b32_e32 v110, 0xffff0000, v177
	v_pk_add_f32 v[98:99], v[98:99], 1.0 op_sel_hi:[1,0]
	v_mul_f32_e32 v101, 0xbfb8aa3b, v107
	v_mul_f32_e32 v105, 0xbfb8aa3b, v110
	v_exp_f32_e32 v103, v103
	v_exp_f32_e32 v101, v101
	v_rcp_f32_e32 v99, v99
	s_nop 0
	v_pk_add_f32 v[102:103], v[102:103], 1.0 op_sel_hi:[1,0]
	v_exp_f32_e32 v105, v105
	v_rcp_f32_e32 v98, v98
	s_nop 0
	v_mov_b32_e32 v106, v94
	v_mov_b32_e32 v107, v96
	v_pk_mul_f32 v[98:99], v[106:107], v[98:99]
	v_rcp_f32_e32 v103, v103
	s_nop 0
	s_nop 0
	v_rcp_f32_e32 v102, v102
	s_nop 0
	v_mov_b32_e32 v96, v95
	v_pk_mul_f32 v[94:95], v[96:97], v[102:103]
	v_cvt_pk_bf16_f32 v96, v98, v99
	v_cvt_pk_bf16_f32 v94, v94, v95
	v_and_b32_e32 v95, 0xffff0000, v94
	v_lshlrev_b32_e32 v94, 16, v94
	v_or_b32_sdwa v95, v95, v96 dst_sel:DWORD dst_unused:UNUSED_PAD src0_sel:DWORD src1_sel:WORD_1
	v_or_b32_sdwa v94, v94, v96 dst_sel:DWORD dst_unused:UNUSED_PAD src0_sel:DWORD src1_sel:WORD_0
	v_pk_add_f32 v[96:97], v[100:101], 1.0 op_sel_hi:[1,0]
	s_nop 0
	s_nop 0
	v_rcp_f32_e32 v97, v97
	s_nop 0
	s_nop 0
	v_rcp_f32_e32 v96, v96
	s_nop 0
	v_mov_b32_e32 v98, v90
	v_mov_b32_e32 v99, v92
	v_pk_mul_f32 v[96:97], v[98:99], v[96:97]
	v_pk_add_f32 v[98:99], v[104:105], 1.0 op_sel_hi:[1,0]
	s_nop 0
	s_nop 0
	v_rcp_f32_e32 v99, v99
	s_nop 0
	s_nop 0
	v_rcp_f32_e32 v98, v98
	s_nop 0
	v_mov_b32_e32 v92, v91
	v_pk_mul_f32 v[90:91], v[92:93], v[98:99]
	v_mul_lo_u32 v100, v108, s61
	v_cvt_pk_bf16_f32 v90, v90, v91
	v_cvt_pk_bf16_f32 v92, v96, v97
	v_and_b32_e32 v91, 0xffff0000, v90
	v_lshlrev_b32_e32 v90, 16, v90
	v_add_u32_e32 v0, v0, v100
	v_or_b32_sdwa v97, v91, v92 dst_sel:DWORD dst_unused:UNUSED_PAD src0_sel:DWORD src1_sel:WORD_1
	v_or_b32_sdwa v96, v90, v92 dst_sel:DWORD dst_unused:UNUSED_PAD src0_sel:DWORD src1_sel:WORD_0
	v_lshl_add_u64 v[90:91], v[0:1], 1, s[6:7]
	v_add_u32_e32 v0, v109, v125
	global_store_dwordx4 v[90:91], v[94:97], off
	v_add_u32_e32 v0, v0, v100
	s_waitcnt vmcnt(15)
	v_lshlrev_b32_e32 v97, 16, v183
	v_and_b32_e32 v98, 0xffff0000, v183
	v_lshlrev_b32_e32 v91, 16, v184
	v_and_b32_e32 v95, 0xffff0000, v182
	v_mul_f32_e32 v91, 0xbfb8aa3b, v91
	v_lshlrev_b32_e32 v94, 16, v182
	v_and_b32_e32 v96, 0xffff0000, v184
	v_exp_f32_e32 v92, v91
	v_mul_f32_e32 v91, 0xbfb8aa3b, v95
	v_mul_f32_e32 v90, 0xbfb8aa3b, v94
	v_exp_f32_e32 v94, v91
	v_mul_f32_e32 v91, 0xbfb8aa3b, v96
	v_exp_f32_e32 v96, v91
	v_mul_f32_e32 v91, 0xbfb8aa3b, v97
	v_exp_f32_e32 v90, v90
	v_exp_f32_e32 v91, v91
	v_lshlrev_b32_e32 v99, 16, v185
	v_mul_f32_e32 v95, 0xbfb8aa3b, v98
	v_and_b32_e32 v101, 0xffff0000, v185
	v_pk_add_f32 v[90:91], v[90:91], 1.0 op_sel_hi:[1,0]
	v_mul_f32_e32 v93, 0xbfb8aa3b, v99
	v_mul_f32_e32 v97, 0xbfb8aa3b, v101
	v_exp_f32_e32 v95, v95
	v_exp_f32_e32 v93, v93
	v_rcp_f32_e32 v91, v91
	s_nop 0
	v_pk_add_f32 v[94:95], v[94:95], 1.0 op_sel_hi:[1,0]
	v_exp_f32_e32 v97, v97
	v_rcp_f32_e32 v90, v90
	s_nop 0
	v_mov_b32_e32 v98, v86
	v_mov_b32_e32 v99, v88
	v_pk_mul_f32 v[90:91], v[98:99], v[90:91]
	v_rcp_f32_e32 v95, v95
	s_nop 0
	s_nop 0
	v_rcp_f32_e32 v94, v94
	s_nop 0
	v_mov_b32_e32 v88, v87
	v_pk_mul_f32 v[86:87], v[88:89], v[94:95]
	v_cvt_pk_bf16_f32 v88, v90, v91
	v_cvt_pk_bf16_f32 v86, v86, v87
	v_and_b32_e32 v87, 0xffff0000, v86
	v_lshlrev_b32_e32 v86, 16, v86
	v_or_b32_sdwa v87, v87, v88 dst_sel:DWORD dst_unused:UNUSED_PAD src0_sel:DWORD src1_sel:WORD_1
	v_or_b32_sdwa v86, v86, v88 dst_sel:DWORD dst_unused:UNUSED_PAD src0_sel:DWORD src1_sel:WORD_0
	v_pk_add_f32 v[88:89], v[92:93], 1.0 op_sel_hi:[1,0]
	s_nop 0
	s_nop 0
	v_rcp_f32_e32 v89, v89
	s_nop 0
	s_nop 0
	v_rcp_f32_e32 v88, v88
	s_nop 0
	v_mov_b32_e32 v90, v82
	v_mov_b32_e32 v91, v84
	v_pk_mul_f32 v[88:89], v[90:91], v[88:89]
	v_pk_add_f32 v[90:91], v[96:97], 1.0 op_sel_hi:[1,0]
	s_nop 0
	s_nop 0
	v_rcp_f32_e32 v91, v91
	s_nop 0
	s_nop 0
	v_rcp_f32_e32 v90, v90
	s_nop 0
	v_mov_b32_e32 v84, v83
	v_pk_mul_f32 v[82:83], v[84:85], v[90:91]
	v_cvt_pk_bf16_f32 v84, v88, v89
	v_cvt_pk_bf16_f32 v82, v82, v83
	v_and_b32_e32 v83, 0xffff0000, v82
	v_lshlrev_b32_e32 v82, 16, v82
	v_add_u32_e32 v93, 0x44400, v151
	v_or_b32_sdwa v89, v83, v84 dst_sel:DWORD dst_unused:UNUSED_PAD src0_sel:DWORD src1_sel:WORD_1
	v_or_b32_sdwa v88, v82, v84 dst_sel:DWORD dst_unused:UNUSED_PAD src0_sel:DWORD src1_sel:WORD_0
	v_lshl_add_u64 v[82:83], v[0:1], 1, s[6:7]
	v_add_u32_e32 v0, v93, v150
	global_store_dwordx4 v[82:83], v[86:89], off
	v_or_b32_e32 v92, 48, v152
	s_waitcnt vmcnt(15)
	v_lshlrev_b32_e32 v89, 16, v187
	v_and_b32_e32 v90, 0xffff0000, v187
	v_lshlrev_b32_e32 v83, 16, v188
	v_and_b32_e32 v87, 0xffff0000, v186
	v_mul_f32_e32 v83, 0xbfb8aa3b, v83
	v_lshlrev_b32_e32 v86, 16, v186
	v_and_b32_e32 v88, 0xffff0000, v188
	v_exp_f32_e32 v84, v83
	v_mul_f32_e32 v83, 0xbfb8aa3b, v87
	v_mul_f32_e32 v82, 0xbfb8aa3b, v86
	v_exp_f32_e32 v86, v83
	v_mul_f32_e32 v83, 0xbfb8aa3b, v88
	v_exp_f32_e32 v88, v83
	v_mul_f32_e32 v83, 0xbfb8aa3b, v89
	v_exp_f32_e32 v82, v82
	v_exp_f32_e32 v83, v83
	v_lshlrev_b32_e32 v91, 16, v189
	v_mul_f32_e32 v87, 0xbfb8aa3b, v90
	v_and_b32_e32 v94, 0xffff0000, v189
	v_pk_add_f32 v[82:83], v[82:83], 1.0 op_sel_hi:[1,0]
	v_mul_f32_e32 v85, 0xbfb8aa3b, v91
	v_mul_f32_e32 v89, 0xbfb8aa3b, v94
	v_exp_f32_e32 v87, v87
	v_exp_f32_e32 v85, v85
	v_rcp_f32_e32 v83, v83
	s_nop 0
	v_pk_add_f32 v[86:87], v[86:87], 1.0 op_sel_hi:[1,0]
	v_exp_f32_e32 v89, v89
	v_rcp_f32_e32 v82, v82
	s_nop 0
	v_mov_b32_e32 v90, v78
	v_mov_b32_e32 v91, v80
	v_pk_mul_f32 v[82:83], v[90:91], v[82:83]
	v_rcp_f32_e32 v87, v87
	s_nop 0
	s_nop 0
	v_rcp_f32_e32 v86, v86
	s_nop 0
	v_mov_b32_e32 v80, v79
	v_pk_mul_f32 v[78:79], v[80:81], v[86:87]
	v_cvt_pk_bf16_f32 v80, v82, v83
	v_cvt_pk_bf16_f32 v78, v78, v79
	v_and_b32_e32 v79, 0xffff0000, v78
	v_lshlrev_b32_e32 v78, 16, v78
	v_or_b32_sdwa v79, v79, v80 dst_sel:DWORD dst_unused:UNUSED_PAD src0_sel:DWORD src1_sel:WORD_1
	v_or_b32_sdwa v78, v78, v80 dst_sel:DWORD dst_unused:UNUSED_PAD src0_sel:DWORD src1_sel:WORD_0
	v_pk_add_f32 v[80:81], v[84:85], 1.0 op_sel_hi:[1,0]
	s_nop 0
	s_nop 0
	v_rcp_f32_e32 v81, v81
	s_nop 0
	s_nop 0
	v_rcp_f32_e32 v80, v80
	s_nop 0
	v_mov_b32_e32 v82, v74
	v_mov_b32_e32 v83, v76
	v_pk_mul_f32 v[80:81], v[82:83], v[80:81]
	v_pk_add_f32 v[82:83], v[88:89], 1.0 op_sel_hi:[1,0]
	s_nop 0
	s_nop 0
	v_rcp_f32_e32 v83, v83
	s_nop 0
	s_nop 0
	v_rcp_f32_e32 v82, v82
	s_nop 0
	v_mov_b32_e32 v76, v75
	v_pk_mul_f32 v[74:75], v[76:77], v[82:83]
	v_mul_lo_u32 v84, v92, s61
	v_cvt_pk_bf16_f32 v74, v74, v75
	v_cvt_pk_bf16_f32 v76, v80, v81
	v_and_b32_e32 v75, 0xffff0000, v74
	v_lshlrev_b32_e32 v74, 16, v74
	v_add_u32_e32 v0, v0, v84
	v_or_b32_sdwa v81, v75, v76 dst_sel:DWORD dst_unused:UNUSED_PAD src0_sel:DWORD src1_sel:WORD_1
	v_or_b32_sdwa v80, v74, v76 dst_sel:DWORD dst_unused:UNUSED_PAD src0_sel:DWORD src1_sel:WORD_0
	v_lshl_add_u64 v[74:75], v[0:1], 1, s[6:7]
	v_add_u32_e32 v0, v93, v125
	global_store_dwordx4 v[74:75], v[78:81], off
	v_add_u32_e32 v0, v0, v84
	s_waitcnt vmcnt(15)
	v_lshlrev_b32_e32 v81, 16, v191
	v_and_b32_e32 v82, 0xffff0000, v191
	v_lshlrev_b32_e32 v75, 16, v192
	v_and_b32_e32 v79, 0xffff0000, v190
	v_mul_f32_e32 v75, 0xbfb8aa3b, v75
	v_lshlrev_b32_e32 v78, 16, v190
	v_and_b32_e32 v80, 0xffff0000, v192
	v_exp_f32_e32 v76, v75
	v_mul_f32_e32 v75, 0xbfb8aa3b, v79
	v_mul_f32_e32 v74, 0xbfb8aa3b, v78
	v_exp_f32_e32 v78, v75
	v_mul_f32_e32 v75, 0xbfb8aa3b, v80
	v_exp_f32_e32 v80, v75
	v_mul_f32_e32 v75, 0xbfb8aa3b, v81
	v_exp_f32_e32 v74, v74
	v_exp_f32_e32 v75, v75
	v_lshlrev_b32_e32 v83, 16, v193
	v_mul_f32_e32 v79, 0xbfb8aa3b, v82
	v_and_b32_e32 v85, 0xffff0000, v193
	v_pk_add_f32 v[74:75], v[74:75], 1.0 op_sel_hi:[1,0]
	v_mul_f32_e32 v77, 0xbfb8aa3b, v83
	v_mul_f32_e32 v81, 0xbfb8aa3b, v85
	v_exp_f32_e32 v79, v79
	v_exp_f32_e32 v77, v77
	v_rcp_f32_e32 v75, v75
	s_nop 0
	v_pk_add_f32 v[78:79], v[78:79], 1.0 op_sel_hi:[1,0]
	v_exp_f32_e32 v81, v81
	v_rcp_f32_e32 v74, v74
	s_nop 0
	v_mov_b32_e32 v82, v70
	v_mov_b32_e32 v83, v72
	v_pk_mul_f32 v[74:75], v[82:83], v[74:75]
	v_rcp_f32_e32 v79, v79
	s_nop 0
	s_nop 0
	v_rcp_f32_e32 v78, v78
	s_nop 0
	v_mov_b32_e32 v72, v71
	v_pk_mul_f32 v[70:71], v[72:73], v[78:79]
	v_cvt_pk_bf16_f32 v72, v74, v75
	v_cvt_pk_bf16_f32 v70, v70, v71
	v_and_b32_e32 v71, 0xffff0000, v70
	v_lshlrev_b32_e32 v70, 16, v70
	v_or_b32_sdwa v71, v71, v72 dst_sel:DWORD dst_unused:UNUSED_PAD src0_sel:DWORD src1_sel:WORD_1
	v_or_b32_sdwa v70, v70, v72 dst_sel:DWORD dst_unused:UNUSED_PAD src0_sel:DWORD src1_sel:WORD_0
	v_pk_add_f32 v[72:73], v[76:77], 1.0 op_sel_hi:[1,0]
	s_nop 0
	s_nop 0
	v_rcp_f32_e32 v73, v73
	s_nop 0
	s_nop 0
	v_rcp_f32_e32 v72, v72
	s_nop 0
	v_mov_b32_e32 v74, v66
	v_mov_b32_e32 v75, v68
	v_pk_mul_f32 v[72:73], v[74:75], v[72:73]
	v_pk_add_f32 v[74:75], v[80:81], 1.0 op_sel_hi:[1,0]
	s_nop 0
	s_nop 0
	v_rcp_f32_e32 v75, v75
	s_nop 0
	s_nop 0
	v_rcp_f32_e32 v74, v74
	s_nop 0
	v_mov_b32_e32 v68, v67
	v_pk_mul_f32 v[66:67], v[68:69], v[74:75]
	v_cvt_pk_bf16_f32 v68, v72, v73
	v_cvt_pk_bf16_f32 v66, v66, v67
	v_and_b32_e32 v67, 0xffff0000, v66
	v_lshlrev_b32_e32 v66, 16, v66
	v_add_u32_e32 v76, 0xb6000, v151
	v_or_b32_sdwa v73, v67, v68 dst_sel:DWORD dst_unused:UNUSED_PAD src0_sel:DWORD src1_sel:WORD_1
	v_or_b32_sdwa v72, v66, v68 dst_sel:DWORD dst_unused:UNUSED_PAD src0_sel:DWORD src1_sel:WORD_0
	v_lshl_add_u64 v[66:67], v[0:1], 1, s[6:7]
	v_add_u32_e32 v0, v76, v150
	global_store_dwordx4 v[66:67], v[70:73], off
	s_nop 1
	s_waitcnt vmcnt(15)
	v_lshlrev_b32_e32 v73, 16, v195
	v_and_b32_e32 v74, 0xffff0000, v195
	v_lshlrev_b32_e32 v67, 16, v196
	v_and_b32_e32 v71, 0xffff0000, v194
	v_mul_f32_e32 v67, 0xbfb8aa3b, v67
	v_lshlrev_b32_e32 v70, 16, v194
	v_and_b32_e32 v72, 0xffff0000, v196
	v_exp_f32_e32 v68, v67
	v_mul_f32_e32 v67, 0xbfb8aa3b, v71
	v_mul_f32_e32 v66, 0xbfb8aa3b, v70
	v_exp_f32_e32 v70, v67
	v_mul_f32_e32 v67, 0xbfb8aa3b, v72
	v_exp_f32_e32 v72, v67
	v_mul_f32_e32 v67, 0xbfb8aa3b, v73
	v_exp_f32_e32 v66, v66
	v_exp_f32_e32 v67, v67
	v_lshlrev_b32_e32 v75, 16, v197
	v_mul_f32_e32 v71, 0xbfb8aa3b, v74
	v_and_b32_e32 v77, 0xffff0000, v197
	v_pk_add_f32 v[66:67], v[66:67], 1.0 op_sel_hi:[1,0]
	v_mul_f32_e32 v69, 0xbfb8aa3b, v75
	v_mul_f32_e32 v73, 0xbfb8aa3b, v77
	v_exp_f32_e32 v71, v71
	v_exp_f32_e32 v69, v69
	v_rcp_f32_e32 v67, v67
	s_nop 0
	v_pk_add_f32 v[70:71], v[70:71], 1.0 op_sel_hi:[1,0]
	v_exp_f32_e32 v73, v73
	v_rcp_f32_e32 v66, v66
	s_nop 0
	v_mov_b32_e32 v74, v62
	v_mov_b32_e32 v75, v64
	v_pk_mul_f32 v[66:67], v[74:75], v[66:67]
	v_rcp_f32_e32 v71, v71
	s_nop 0
	s_nop 0
	v_rcp_f32_e32 v70, v70
	s_nop 0
	v_mov_b32_e32 v64, v63
	v_pk_mul_f32 v[62:63], v[64:65], v[70:71]
	v_cvt_pk_bf16_f32 v64, v66, v67
	v_cvt_pk_bf16_f32 v62, v62, v63
	v_and_b32_e32 v63, 0xffff0000, v62
	v_lshlrev_b32_e32 v62, 16, v62
	v_or_b32_sdwa v63, v63, v64 dst_sel:DWORD dst_unused:UNUSED_PAD src0_sel:DWORD src1_sel:WORD_1
	v_or_b32_sdwa v62, v62, v64 dst_sel:DWORD dst_unused:UNUSED_PAD src0_sel:DWORD src1_sel:WORD_0
	v_pk_add_f32 v[64:65], v[68:69], 1.0 op_sel_hi:[1,0]
	s_nop 0
	s_nop 0
	v_rcp_f32_e32 v65, v65
	s_nop 0
	s_nop 0
	v_rcp_f32_e32 v64, v64
	s_nop 0
	v_mov_b32_e32 v66, v58
	v_mov_b32_e32 v67, v60
	v_pk_mul_f32 v[64:65], v[66:67], v[64:65]
	v_pk_add_f32 v[66:67], v[72:73], 1.0 op_sel_hi:[1,0]
	s_nop 0
	s_nop 0
	v_rcp_f32_e32 v67, v67
	s_nop 0
	s_nop 0
	v_rcp_f32_e32 v66, v66
	s_nop 0
	v_mov_b32_e32 v60, v59
	v_pk_mul_f32 v[58:59], v[60:61], v[66:67]
	v_add_u32_e32 v68, 0xfff6a000, v124
	v_cvt_pk_bf16_f32 v58, v58, v59
	v_cvt_pk_bf16_f32 v60, v64, v65
	v_and_b32_e32 v59, 0xffff0000, v58
	v_lshlrev_b32_e32 v58, 16, v58
	v_add_u32_e32 v0, v0, v68
	v_or_b32_sdwa v65, v59, v60 dst_sel:DWORD dst_unused:UNUSED_PAD src0_sel:DWORD src1_sel:WORD_1
	v_or_b32_sdwa v64, v58, v60 dst_sel:DWORD dst_unused:UNUSED_PAD src0_sel:DWORD src1_sel:WORD_0
	v_lshl_add_u64 v[58:59], v[0:1], 1, s[6:7]
	v_add_u32_e32 v0, v76, v125
	global_store_dwordx4 v[58:59], v[62:65], off
	v_add_u32_e32 v0, v0, v68
	s_waitcnt vmcnt(15)
	v_lshlrev_b32_e32 v65, 16, v199
	v_and_b32_e32 v66, 0xffff0000, v199
	v_lshlrev_b32_e32 v59, 16, v200
	v_and_b32_e32 v63, 0xffff0000, v198
	v_mul_f32_e32 v59, 0xbfb8aa3b, v59
	v_lshlrev_b32_e32 v62, 16, v198
	v_and_b32_e32 v64, 0xffff0000, v200
	v_exp_f32_e32 v60, v59
	v_mul_f32_e32 v59, 0xbfb8aa3b, v63
	v_mul_f32_e32 v58, 0xbfb8aa3b, v62
	v_exp_f32_e32 v62, v59
	v_mul_f32_e32 v59, 0xbfb8aa3b, v64
	v_exp_f32_e32 v64, v59
	v_mul_f32_e32 v59, 0xbfb8aa3b, v65
	v_exp_f32_e32 v58, v58
	v_exp_f32_e32 v59, v59
	v_lshlrev_b32_e32 v67, 16, v201
	v_mul_f32_e32 v63, 0xbfb8aa3b, v66
	v_and_b32_e32 v69, 0xffff0000, v201
	v_pk_add_f32 v[58:59], v[58:59], 1.0 op_sel_hi:[1,0]
	v_mul_f32_e32 v61, 0xbfb8aa3b, v67
	v_mul_f32_e32 v65, 0xbfb8aa3b, v69
	v_exp_f32_e32 v63, v63
	v_exp_f32_e32 v61, v61
	v_rcp_f32_e32 v59, v59
	s_nop 0
	v_pk_add_f32 v[62:63], v[62:63], 1.0 op_sel_hi:[1,0]
	v_exp_f32_e32 v65, v65
	v_rcp_f32_e32 v58, v58
	s_nop 0
	v_mov_b32_e32 v66, v54
	v_mov_b32_e32 v67, v56
	v_pk_mul_f32 v[58:59], v[66:67], v[58:59]
	v_rcp_f32_e32 v63, v63
	s_nop 0
	s_nop 0
	v_rcp_f32_e32 v62, v62
	s_nop 0
	v_mov_b32_e32 v56, v55
	v_pk_mul_f32 v[54:55], v[56:57], v[62:63]
	v_cvt_pk_bf16_f32 v56, v58, v59
	v_cvt_pk_bf16_f32 v54, v54, v55
	v_and_b32_e32 v55, 0xffff0000, v54
	v_lshlrev_b32_e32 v54, 16, v54
	v_or_b32_sdwa v55, v55, v56 dst_sel:DWORD dst_unused:UNUSED_PAD src0_sel:DWORD src1_sel:WORD_1
	v_or_b32_sdwa v54, v54, v56 dst_sel:DWORD dst_unused:UNUSED_PAD src0_sel:DWORD src1_sel:WORD_0
	v_pk_add_f32 v[56:57], v[60:61], 1.0 op_sel_hi:[1,0]
	s_nop 0
	s_nop 0
	v_rcp_f32_e32 v57, v57
	s_nop 0
	s_nop 0
	v_rcp_f32_e32 v56, v56
	s_nop 0
	v_mov_b32_e32 v58, v50
	v_mov_b32_e32 v59, v52
	v_pk_mul_f32 v[56:57], v[58:59], v[56:57]
	v_pk_add_f32 v[58:59], v[64:65], 1.0 op_sel_hi:[1,0]
	s_nop 0
	s_nop 0
	v_rcp_f32_e32 v59, v59
	s_nop 0
	s_nop 0
	v_rcp_f32_e32 v58, v58
	s_nop 0
	v_mov_b32_e32 v52, v51
	v_pk_mul_f32 v[50:51], v[52:53], v[58:59]
	v_cvt_pk_bf16_f32 v52, v56, v57
	v_cvt_pk_bf16_f32 v50, v50, v51
	v_and_b32_e32 v51, 0xffff0000, v50
	v_lshlrev_b32_e32 v50, 16, v50
	v_add_u32_e32 v60, 0xccc00, v151
	v_or_b32_sdwa v57, v51, v52 dst_sel:DWORD dst_unused:UNUSED_PAD src0_sel:DWORD src1_sel:WORD_1
	v_or_b32_sdwa v56, v50, v52 dst_sel:DWORD dst_unused:UNUSED_PAD src0_sel:DWORD src1_sel:WORD_0
	v_lshl_add_u64 v[50:51], v[0:1], 1, s[6:7]
	v_add_u32_e32 v0, v60, v150
	global_store_dwordx4 v[50:51], v[54:57], off
	s_nop 1
	s_waitcnt vmcnt(15)
	v_lshlrev_b32_e32 v57, 16, v203
	v_and_b32_e32 v58, 0xffff0000, v203
	v_lshlrev_b32_e32 v51, 16, v204
	v_and_b32_e32 v55, 0xffff0000, v202
	v_mul_f32_e32 v51, 0xbfb8aa3b, v51
	v_lshlrev_b32_e32 v54, 16, v202
	v_and_b32_e32 v56, 0xffff0000, v204
	v_exp_f32_e32 v52, v51
	v_mul_f32_e32 v51, 0xbfb8aa3b, v55
	v_mul_f32_e32 v50, 0xbfb8aa3b, v54
	v_exp_f32_e32 v54, v51
	v_mul_f32_e32 v51, 0xbfb8aa3b, v56
	v_exp_f32_e32 v56, v51
	v_mul_f32_e32 v51, 0xbfb8aa3b, v57
	v_exp_f32_e32 v50, v50
	v_exp_f32_e32 v51, v51
	v_lshlrev_b32_e32 v59, 16, v205
	v_mul_f32_e32 v55, 0xbfb8aa3b, v58
	v_and_b32_e32 v61, 0xffff0000, v205
	v_pk_add_f32 v[50:51], v[50:51], 1.0 op_sel_hi:[1,0]
	v_mul_f32_e32 v53, 0xbfb8aa3b, v59
	v_mul_f32_e32 v57, 0xbfb8aa3b, v61
	v_exp_f32_e32 v55, v55
	v_exp_f32_e32 v53, v53
	v_rcp_f32_e32 v51, v51
	s_nop 0
	v_pk_add_f32 v[54:55], v[54:55], 1.0 op_sel_hi:[1,0]
	v_exp_f32_e32 v57, v57
	v_rcp_f32_e32 v50, v50
	s_nop 0
	v_mov_b32_e32 v58, v46
	v_mov_b32_e32 v59, v48
	v_pk_mul_f32 v[50:51], v[58:59], v[50:51]
	v_rcp_f32_e32 v55, v55
	s_nop 0
	s_nop 0
	v_rcp_f32_e32 v54, v54
	s_nop 0
	v_mov_b32_e32 v48, v47
	v_pk_mul_f32 v[46:47], v[48:49], v[54:55]
	v_cvt_pk_bf16_f32 v48, v50, v51
	v_cvt_pk_bf16_f32 v46, v46, v47
	v_and_b32_e32 v47, 0xffff0000, v46
	v_lshlrev_b32_e32 v46, 16, v46
	v_or_b32_sdwa v47, v47, v48 dst_sel:DWORD dst_unused:UNUSED_PAD src0_sel:DWORD src1_sel:WORD_1
	v_or_b32_sdwa v46, v46, v48 dst_sel:DWORD dst_unused:UNUSED_PAD src0_sel:DWORD src1_sel:WORD_0
	v_pk_add_f32 v[48:49], v[52:53], 1.0 op_sel_hi:[1,0]
	s_nop 0
	s_nop 0
	v_rcp_f32_e32 v49, v49
	s_nop 0
	s_nop 0
	v_rcp_f32_e32 v48, v48
	s_nop 0
	v_mov_b32_e32 v50, v42
	v_mov_b32_e32 v51, v44
	v_pk_mul_f32 v[48:49], v[50:51], v[48:49]
	v_pk_add_f32 v[50:51], v[56:57], 1.0 op_sel_hi:[1,0]
	s_nop 0
	s_nop 0
	v_rcp_f32_e32 v51, v51
	s_nop 0
	s_nop 0
	v_rcp_f32_e32 v50, v50
	s_nop 0
	v_mov_b32_e32 v44, v43
	v_pk_mul_f32 v[42:43], v[44:45], v[50:51]
	v_add_u32_e32 v52, 0xfff57400, v124
	v_cvt_pk_bf16_f32 v42, v42, v43
	v_cvt_pk_bf16_f32 v44, v48, v49
	v_and_b32_e32 v43, 0xffff0000, v42
	v_lshlrev_b32_e32 v42, 16, v42
	v_add_u32_e32 v0, v0, v52
	v_or_b32_sdwa v49, v43, v44 dst_sel:DWORD dst_unused:UNUSED_PAD src0_sel:DWORD src1_sel:WORD_1
	v_or_b32_sdwa v48, v42, v44 dst_sel:DWORD dst_unused:UNUSED_PAD src0_sel:DWORD src1_sel:WORD_0
	v_lshl_add_u64 v[42:43], v[0:1], 1, s[6:7]
	v_add_u32_e32 v0, v60, v125
	global_store_dwordx4 v[42:43], v[46:49], off
	v_add_u32_e32 v0, v0, v52
	s_waitcnt vmcnt(15)
	v_lshlrev_b32_e32 v49, 16, v207
	v_and_b32_e32 v50, 0xffff0000, v207
	v_lshlrev_b32_e32 v43, 16, v208
	v_and_b32_e32 v47, 0xffff0000, v206
	v_mul_f32_e32 v43, 0xbfb8aa3b, v43
	v_lshlrev_b32_e32 v46, 16, v206
	v_and_b32_e32 v48, 0xffff0000, v208
	v_exp_f32_e32 v44, v43
	v_mul_f32_e32 v43, 0xbfb8aa3b, v47
	v_mul_f32_e32 v42, 0xbfb8aa3b, v46
	v_exp_f32_e32 v46, v43
	v_mul_f32_e32 v43, 0xbfb8aa3b, v48
	v_exp_f32_e32 v48, v43
	v_mul_f32_e32 v43, 0xbfb8aa3b, v49
	v_exp_f32_e32 v42, v42
	v_exp_f32_e32 v43, v43
	v_lshlrev_b32_e32 v51, 16, v209
	v_mul_f32_e32 v47, 0xbfb8aa3b, v50
	v_and_b32_e32 v53, 0xffff0000, v209
	v_pk_add_f32 v[42:43], v[42:43], 1.0 op_sel_hi:[1,0]
	v_mul_f32_e32 v45, 0xbfb8aa3b, v51
	v_mul_f32_e32 v49, 0xbfb8aa3b, v53
	v_exp_f32_e32 v47, v47
	v_exp_f32_e32 v45, v45
	v_rcp_f32_e32 v43, v43
	s_nop 0
	v_pk_add_f32 v[46:47], v[46:47], 1.0 op_sel_hi:[1,0]
	v_exp_f32_e32 v49, v49
	v_rcp_f32_e32 v42, v42
	s_nop 0
	v_mov_b32_e32 v50, v38
	v_mov_b32_e32 v51, v40
	v_pk_mul_f32 v[42:43], v[50:51], v[42:43]
	v_rcp_f32_e32 v47, v47
	s_nop 0
	s_nop 0
	v_rcp_f32_e32 v46, v46
	s_nop 0
	v_mov_b32_e32 v40, v39
	v_pk_mul_f32 v[38:39], v[40:41], v[46:47]
	v_cvt_pk_bf16_f32 v40, v42, v43
	v_cvt_pk_bf16_f32 v38, v38, v39
	v_and_b32_e32 v39, 0xffff0000, v38
	v_lshlrev_b32_e32 v38, 16, v38
	v_or_b32_sdwa v39, v39, v40 dst_sel:DWORD dst_unused:UNUSED_PAD src0_sel:DWORD src1_sel:WORD_1
	v_or_b32_sdwa v38, v38, v40 dst_sel:DWORD dst_unused:UNUSED_PAD src0_sel:DWORD src1_sel:WORD_0
	v_pk_add_f32 v[40:41], v[44:45], 1.0 op_sel_hi:[1,0]
	s_nop 0
	s_nop 0
	v_rcp_f32_e32 v41, v41
	s_nop 0
	s_nop 0
	v_rcp_f32_e32 v40, v40
	s_nop 0
	v_mov_b32_e32 v42, v34
	v_mov_b32_e32 v43, v36
	v_pk_mul_f32 v[40:41], v[42:43], v[40:41]
	v_pk_add_f32 v[42:43], v[48:49], 1.0 op_sel_hi:[1,0]
	s_nop 0
	s_nop 0
	v_rcp_f32_e32 v43, v43
	s_nop 0
	s_nop 0
	v_rcp_f32_e32 v42, v42
	s_nop 0
	v_mov_b32_e32 v36, v35
	v_pk_mul_f32 v[34:35], v[36:37], v[42:43]
	v_cvt_pk_bf16_f32 v36, v40, v41
	v_cvt_pk_bf16_f32 v34, v34, v35
	v_and_b32_e32 v35, 0xffff0000, v34
	v_lshlrev_b32_e32 v34, 16, v34
	v_add_u32_e32 v44, 0xe3800, v151
	v_or_b32_sdwa v41, v35, v36 dst_sel:DWORD dst_unused:UNUSED_PAD src0_sel:DWORD src1_sel:WORD_1
	v_or_b32_sdwa v40, v34, v36 dst_sel:DWORD dst_unused:UNUSED_PAD src0_sel:DWORD src1_sel:WORD_0
	v_lshl_add_u64 v[34:35], v[0:1], 1, s[6:7]
	v_add_u32_e32 v0, v44, v150
	global_store_dwordx4 v[34:35], v[38:41], off
	s_nop 1
	s_waitcnt vmcnt(15)
	v_lshlrev_b32_e32 v41, 16, v211
	v_and_b32_e32 v42, 0xffff0000, v211
	v_lshlrev_b32_e32 v35, 16, v212
	v_and_b32_e32 v39, 0xffff0000, v210
	v_mul_f32_e32 v35, 0xbfb8aa3b, v35
	v_lshlrev_b32_e32 v38, 16, v210
	v_and_b32_e32 v40, 0xffff0000, v212
	v_exp_f32_e32 v36, v35
	v_mul_f32_e32 v35, 0xbfb8aa3b, v39
	v_mul_f32_e32 v34, 0xbfb8aa3b, v38
	v_exp_f32_e32 v38, v35
	v_mul_f32_e32 v35, 0xbfb8aa3b, v40
	v_exp_f32_e32 v40, v35
	v_mul_f32_e32 v35, 0xbfb8aa3b, v41
	v_exp_f32_e32 v34, v34
	v_exp_f32_e32 v35, v35
	v_lshlrev_b32_e32 v43, 16, v213
	v_mul_f32_e32 v39, 0xbfb8aa3b, v42
	v_and_b32_e32 v45, 0xffff0000, v213
	v_pk_add_f32 v[34:35], v[34:35], 1.0 op_sel_hi:[1,0]
	v_mul_f32_e32 v37, 0xbfb8aa3b, v43
	v_mul_f32_e32 v41, 0xbfb8aa3b, v45
	v_exp_f32_e32 v39, v39
	v_exp_f32_e32 v37, v37
	v_rcp_f32_e32 v35, v35
	s_nop 0
	v_pk_add_f32 v[38:39], v[38:39], 1.0 op_sel_hi:[1,0]
	v_exp_f32_e32 v41, v41
	v_rcp_f32_e32 v34, v34
	s_nop 0
	v_mov_b32_e32 v42, v30
	v_mov_b32_e32 v43, v32
	v_pk_mul_f32 v[34:35], v[42:43], v[34:35]
	v_rcp_f32_e32 v39, v39
	s_nop 0
	s_nop 0
	v_rcp_f32_e32 v38, v38
	s_nop 0
	v_mov_b32_e32 v32, v31
	v_pk_mul_f32 v[30:31], v[32:33], v[38:39]
	v_cvt_pk_bf16_f32 v32, v34, v35
	v_cvt_pk_bf16_f32 v30, v30, v31
	v_and_b32_e32 v31, 0xffff0000, v30
	v_lshlrev_b32_e32 v30, 16, v30
	v_or_b32_sdwa v31, v31, v32 dst_sel:DWORD dst_unused:UNUSED_PAD src0_sel:DWORD src1_sel:WORD_1
	v_or_b32_sdwa v30, v30, v32 dst_sel:DWORD dst_unused:UNUSED_PAD src0_sel:DWORD src1_sel:WORD_0
	v_pk_add_f32 v[32:33], v[36:37], 1.0 op_sel_hi:[1,0]
	s_nop 0
	s_nop 0
	v_rcp_f32_e32 v33, v33
	s_nop 0
	s_nop 0
	v_rcp_f32_e32 v32, v32
	s_nop 0
	v_mov_b32_e32 v34, v26
	v_mov_b32_e32 v35, v28
	v_pk_mul_f32 v[32:33], v[34:35], v[32:33]
	v_pk_add_f32 v[34:35], v[40:41], 1.0 op_sel_hi:[1,0]
	s_nop 0
	s_nop 0
	v_rcp_f32_e32 v35, v35
	s_nop 0
	s_nop 0
	v_rcp_f32_e32 v34, v34
	s_nop 0
	v_mov_b32_e32 v28, v27
	v_pk_mul_f32 v[26:27], v[28:29], v[34:35]
	v_add_u32_e32 v36, 0xfff44800, v124
	v_cvt_pk_bf16_f32 v26, v26, v27
	v_cvt_pk_bf16_f32 v28, v32, v33
	v_and_b32_e32 v27, 0xffff0000, v26
	v_lshlrev_b32_e32 v26, 16, v26
	v_add_u32_e32 v0, v0, v36
	v_or_b32_sdwa v33, v27, v28 dst_sel:DWORD dst_unused:UNUSED_PAD src0_sel:DWORD src1_sel:WORD_1
	v_or_b32_sdwa v32, v26, v28 dst_sel:DWORD dst_unused:UNUSED_PAD src0_sel:DWORD src1_sel:WORD_0
	v_lshl_add_u64 v[26:27], v[0:1], 1, s[6:7]
	v_add_u32_e32 v0, v44, v125
	global_store_dwordx4 v[26:27], v[30:33], off
	v_add_u32_e32 v0, v0, v36
	s_waitcnt vmcnt(14)
	v_lshlrev_b32_e32 v33, 16, v163
	v_and_b32_e32 v34, 0xffff0000, v163
	v_lshlrev_b32_e32 v27, 16, v164
	v_and_b32_e32 v31, 0xffff0000, v162
	v_mul_f32_e32 v27, 0xbfb8aa3b, v27
	v_lshlrev_b32_e32 v30, 16, v162
	v_and_b32_e32 v32, 0xffff0000, v164
	v_exp_f32_e32 v28, v27
	v_mul_f32_e32 v27, 0xbfb8aa3b, v31
	v_mul_f32_e32 v26, 0xbfb8aa3b, v30
	v_exp_f32_e32 v30, v27
	v_mul_f32_e32 v27, 0xbfb8aa3b, v32
	v_exp_f32_e32 v32, v27
	v_mul_f32_e32 v27, 0xbfb8aa3b, v33
	v_exp_f32_e32 v26, v26
	v_exp_f32_e32 v27, v27
	v_lshlrev_b32_e32 v35, 16, v165
	v_mul_f32_e32 v31, 0xbfb8aa3b, v34
	v_and_b32_e32 v37, 0xffff0000, v165
	v_pk_add_f32 v[26:27], v[26:27], 1.0 op_sel_hi:[1,0]
	v_mul_f32_e32 v29, 0xbfb8aa3b, v35
	v_mul_f32_e32 v33, 0xbfb8aa3b, v37
	v_exp_f32_e32 v31, v31
	v_exp_f32_e32 v29, v29
	v_rcp_f32_e32 v27, v27
	s_nop 0
	v_pk_add_f32 v[30:31], v[30:31], 1.0 op_sel_hi:[1,0]
	v_exp_f32_e32 v33, v33
	v_rcp_f32_e32 v26, v26
	s_nop 0
	v_mov_b32_e32 v34, v22
	v_mov_b32_e32 v35, v24
	v_pk_mul_f32 v[26:27], v[34:35], v[26:27]
	v_rcp_f32_e32 v31, v31
	s_nop 0
	s_nop 0
	v_rcp_f32_e32 v30, v30
	s_nop 0
	v_mov_b32_e32 v24, v23
	v_pk_mul_f32 v[22:23], v[24:25], v[30:31]
	v_cvt_pk_bf16_f32 v24, v26, v27
	v_cvt_pk_bf16_f32 v22, v22, v23
	v_and_b32_e32 v23, 0xffff0000, v22
	v_lshlrev_b32_e32 v22, 16, v22
	v_or_b32_sdwa v23, v23, v24 dst_sel:DWORD dst_unused:UNUSED_PAD src0_sel:DWORD src1_sel:WORD_1
	v_or_b32_sdwa v22, v22, v24 dst_sel:DWORD dst_unused:UNUSED_PAD src0_sel:DWORD src1_sel:WORD_0
	v_pk_add_f32 v[24:25], v[28:29], 1.0 op_sel_hi:[1,0]
	s_nop 0
	s_nop 0
	v_rcp_f32_e32 v25, v25
	s_nop 0
	s_nop 0
	v_rcp_f32_e32 v24, v24
	s_nop 0
	v_mov_b32_e32 v26, v18
	v_mov_b32_e32 v27, v20
	v_pk_mul_f32 v[24:25], v[26:27], v[24:25]
	v_pk_add_f32 v[26:27], v[32:33], 1.0 op_sel_hi:[1,0]
	s_nop 0
	s_nop 0
	v_rcp_f32_e32 v27, v27
	s_nop 0
	s_nop 0
	v_rcp_f32_e32 v26, v26
	s_nop 0
	v_mov_b32_e32 v20, v19
	v_pk_mul_f32 v[18:19], v[20:21], v[26:27]
	v_cvt_pk_bf16_f32 v20, v24, v25
	v_cvt_pk_bf16_f32 v18, v18, v19
	v_and_b32_e32 v19, 0xffff0000, v18
	v_lshlrev_b32_e32 v18, 16, v18
	v_add_u32_e32 v28, 0xfa400, v151
	v_or_b32_sdwa v25, v19, v20 dst_sel:DWORD dst_unused:UNUSED_PAD src0_sel:DWORD src1_sel:WORD_1
	v_or_b32_sdwa v24, v18, v20 dst_sel:DWORD dst_unused:UNUSED_PAD src0_sel:DWORD src1_sel:WORD_0
	v_lshl_add_u64 v[18:19], v[0:1], 1, s[6:7]
	v_add_u32_e32 v0, v28, v150
	global_store_dwordx4 v[18:19], v[22:25], off
	s_nop 1
	s_waitcnt vmcnt(13)
	v_lshlrev_b32_e32 v25, 16, v167
	v_and_b32_e32 v26, 0xffff0000, v167
	v_lshlrev_b32_e32 v19, 16, v168
	v_and_b32_e32 v23, 0xffff0000, v166
	v_mul_f32_e32 v19, 0xbfb8aa3b, v19
	v_lshlrev_b32_e32 v22, 16, v166
	v_and_b32_e32 v24, 0xffff0000, v168
	v_exp_f32_e32 v20, v19
	v_mul_f32_e32 v19, 0xbfb8aa3b, v23
	v_mul_f32_e32 v18, 0xbfb8aa3b, v22
	v_exp_f32_e32 v22, v19
	v_mul_f32_e32 v19, 0xbfb8aa3b, v24
	v_exp_f32_e32 v24, v19
	v_mul_f32_e32 v19, 0xbfb8aa3b, v25
	v_exp_f32_e32 v18, v18
	v_exp_f32_e32 v19, v19
	v_lshlrev_b32_e32 v27, 16, v169
	v_mul_f32_e32 v23, 0xbfb8aa3b, v26
	v_and_b32_e32 v29, 0xffff0000, v169
	v_pk_add_f32 v[18:19], v[18:19], 1.0 op_sel_hi:[1,0]
	v_mul_f32_e32 v21, 0xbfb8aa3b, v27
	v_mul_f32_e32 v25, 0xbfb8aa3b, v29
	v_exp_f32_e32 v23, v23
	v_exp_f32_e32 v21, v21
	v_rcp_f32_e32 v19, v19
	s_nop 0
	v_pk_add_f32 v[22:23], v[22:23], 1.0 op_sel_hi:[1,0]
	v_exp_f32_e32 v25, v25
	v_rcp_f32_e32 v18, v18
	s_nop 0
	v_mov_b32_e32 v26, v14
	v_mov_b32_e32 v27, v16
	v_pk_mul_f32 v[18:19], v[26:27], v[18:19]
	v_rcp_f32_e32 v23, v23
	s_nop 0
	s_nop 0
	v_rcp_f32_e32 v22, v22
	s_nop 0
	v_mov_b32_e32 v16, v15
	v_pk_mul_f32 v[14:15], v[16:17], v[22:23]
	v_cvt_pk_bf16_f32 v16, v18, v19
	v_cvt_pk_bf16_f32 v14, v14, v15
	v_and_b32_e32 v15, 0xffff0000, v14
	v_lshlrev_b32_e32 v14, 16, v14
	v_or_b32_sdwa v15, v15, v16 dst_sel:DWORD dst_unused:UNUSED_PAD src0_sel:DWORD src1_sel:WORD_1
	v_or_b32_sdwa v14, v14, v16 dst_sel:DWORD dst_unused:UNUSED_PAD src0_sel:DWORD src1_sel:WORD_0
	v_pk_add_f32 v[16:17], v[20:21], 1.0 op_sel_hi:[1,0]
	s_nop 0
	s_nop 0
	v_rcp_f32_e32 v17, v17
	s_nop 0
	s_nop 0
	v_rcp_f32_e32 v16, v16
	s_nop 0
	v_mov_b32_e32 v18, v10
	v_mov_b32_e32 v19, v12
	v_pk_mul_f32 v[16:17], v[18:19], v[16:17]
	v_pk_add_f32 v[18:19], v[24:25], 1.0 op_sel_hi:[1,0]
	s_nop 0
	s_nop 0
	v_rcp_f32_e32 v19, v19
	s_nop 0
	s_nop 0
	v_rcp_f32_e32 v18, v18
	s_nop 0
	v_mov_b32_e32 v12, v11
	v_pk_mul_f32 v[10:11], v[12:13], v[18:19]
	v_add_u32_e32 v20, 0xfff31c00, v124
	v_cvt_pk_bf16_f32 v10, v10, v11
	v_cvt_pk_bf16_f32 v12, v16, v17
	v_and_b32_e32 v11, 0xffff0000, v10
	v_lshlrev_b32_e32 v10, 16, v10
	v_add_u32_e32 v0, v0, v20
	v_or_b32_sdwa v17, v11, v12 dst_sel:DWORD dst_unused:UNUSED_PAD src0_sel:DWORD src1_sel:WORD_1
	v_or_b32_sdwa v16, v10, v12 dst_sel:DWORD dst_unused:UNUSED_PAD src0_sel:DWORD src1_sel:WORD_0
	v_lshl_add_u64 v[10:11], v[0:1], 1, s[6:7]
	v_add_u32_e32 v0, v28, v125
	global_store_dwordx4 v[10:11], v[14:17], off
	v_add_u32_e32 v0, v0, v20
	s_waitcnt vmcnt(12)
	v_lshlrev_b32_e32 v17, 16, v171
	v_and_b32_e32 v18, 0xffff0000, v171
	v_lshlrev_b32_e32 v11, 16, v172
	v_and_b32_e32 v15, 0xffff0000, v170
	v_mul_f32_e32 v11, 0xbfb8aa3b, v11
	v_lshlrev_b32_e32 v14, 16, v170
	v_and_b32_e32 v16, 0xffff0000, v172
	v_exp_f32_e32 v12, v11
	v_mul_f32_e32 v11, 0xbfb8aa3b, v15
	v_mul_f32_e32 v10, 0xbfb8aa3b, v14
	v_exp_f32_e32 v14, v11
	v_mul_f32_e32 v11, 0xbfb8aa3b, v16
	v_exp_f32_e32 v16, v11
	v_mul_f32_e32 v11, 0xbfb8aa3b, v17
	v_exp_f32_e32 v10, v10
	v_exp_f32_e32 v11, v11
	v_lshlrev_b32_e32 v19, 16, v173
	v_mul_f32_e32 v15, 0xbfb8aa3b, v18
	v_and_b32_e32 v21, 0xffff0000, v173
	v_pk_add_f32 v[10:11], v[10:11], 1.0 op_sel_hi:[1,0]
	v_mul_f32_e32 v13, 0xbfb8aa3b, v19
	v_mul_f32_e32 v17, 0xbfb8aa3b, v21
	v_exp_f32_e32 v15, v15
	v_exp_f32_e32 v13, v13
	v_rcp_f32_e32 v11, v11
	s_nop 0
	v_pk_add_f32 v[14:15], v[14:15], 1.0 op_sel_hi:[1,0]
	v_exp_f32_e32 v17, v17
	v_rcp_f32_e32 v10, v10
	s_nop 0
	v_mov_b32_e32 v18, v6
	v_mov_b32_e32 v19, v8
	v_pk_mul_f32 v[10:11], v[18:19], v[10:11]
	v_rcp_f32_e32 v15, v15
	s_nop 0
	s_nop 0
	v_rcp_f32_e32 v14, v14
	s_nop 0
	v_mov_b32_e32 v8, v7
	v_pk_mul_f32 v[6:7], v[8:9], v[14:15]
	v_cvt_pk_bf16_f32 v8, v10, v11
	v_cvt_pk_bf16_f32 v6, v6, v7
	v_and_b32_e32 v7, 0xffff0000, v6
	v_lshlrev_b32_e32 v6, 16, v6
	v_or_b32_sdwa v7, v7, v8 dst_sel:DWORD dst_unused:UNUSED_PAD src0_sel:DWORD src1_sel:WORD_1
	v_or_b32_sdwa v6, v6, v8 dst_sel:DWORD dst_unused:UNUSED_PAD src0_sel:DWORD src1_sel:WORD_0
	v_pk_add_f32 v[8:9], v[12:13], 1.0 op_sel_hi:[1,0]
	s_nop 0
	s_nop 0
	v_rcp_f32_e32 v9, v9
	s_nop 0
	s_nop 0
	v_rcp_f32_e32 v8, v8
	s_nop 0
	v_mov_b32_e32 v10, v2
	v_mov_b32_e32 v11, v4
	v_pk_mul_f32 v[8:9], v[10:11], v[8:9]
	v_pk_add_f32 v[10:11], v[16:17], 1.0 op_sel_hi:[1,0]
	s_nop 0
	s_nop 0
	v_rcp_f32_e32 v11, v11
	s_nop 0
	s_mov_b64 s[24:25], s[16:17]
	v_rcp_f32_e32 v10, v10
	s_nop 0
	v_mov_b32_e32 v4, v3
	v_pk_mul_f32 v[2:3], v[4:5], v[10:11]
	v_cvt_pk_bf16_f32 v4, v8, v9
	v_cvt_pk_bf16_f32 v2, v2, v3
	v_and_b32_e32 v3, 0xffff0000, v2
	v_lshlrev_b32_e32 v2, 16, v2
	v_or_b32_sdwa v9, v3, v4 dst_sel:DWORD dst_unused:UNUSED_PAD src0_sel:DWORD src1_sel:WORD_1
	v_or_b32_sdwa v8, v2, v4 dst_sel:DWORD dst_unused:UNUSED_PAD src0_sel:DWORD src1_sel:WORD_0
	v_lshl_add_u64 v[2:3], v[0:1], 1, s[6:7]
	s_and_b64 vcc, exec, s[10:11]
	global_store_dwordx4 v[2:3], v[6:9], off
	s_cbranch_vccz .LBB0_1344
	s_waitcnt vmcnt(0)
	v_readlane_b32 s76, v255, 8
	s_mov_b32 s92, 0x3b2aaaab
	s_cmp_gt_u32 s4, 3
	v_readlane_b32 s77, v255, 9
	s_mul_i32 s60, s33, 0x1800
	s_mul_hi_i32 s62, s64, 0x300
	s_mul_i32 s75, s33, 0x16c00
	s_mov_b32 s93, 0x3c800000
	s_mov_b32 s82, s70
	s_cbranch_scc1 .LBB0_1351
	s_barrier

.LBB0_1359:
	v_add_u32_e32 v0, 0x10000, v154
	ds_read_b128 v[130:133], v0
	ds_read_b128 v[146:149], v0 offset:1024
	ds_read_b128 v[156:159], v0 offset:2048
	ds_read_b128 v[160:163], v0 offset:3072
	s_add_u32 s28, s26, 0xfffc0080
	s_addc_u32 s29, s27, -1
	s_cmp_eq_u32 vcc_lo, 12
	s_cselect_b32 s31, s2, s29
	s_cselect_b32 s30, s17, s28
	s_cselect_b32 s29, s15, s94
	s_cselect_b32 s28, s89, s90
	v_lshl_add_u64 v[150:151], s[26:27], 0, v[142:143]
	s_add_i32 m0, s39, 0xc000
	ds_read_b128 v[164:167], v153
	ds_read_b128 v[168:171], v153 offset:1024
	ds_read_b128 v[172:175], v153 offset:2048
	ds_read_b128 v[176:179], v153 offset:3072
	ds_read_b128 v[182:185], v153 offset:4096
	ds_read_b128 v[186:189], v153 offset:5120
	ds_read_b128 v[190:193], v153 offset:6144
	ds_read_b128 v[194:197], v153 offset:7168
	global_load_lds_dwordx4 v[150:151], off
	v_lshl_add_u64 v[150:151], s[26:27], 0, v[144:145]
	s_add_i32 m0, s39, 0xe000
	s_nop 0
	global_load_lds_dwordx4 v[150:151], off
	s_waitcnt lgkmcnt(8)
	s_barrier
	s_waitcnt lgkmcnt(0)
	s_setprio 1
	s_waitcnt lgkmcnt(0)
	v_mfma_f32_16x16x32_bf16 v[126:129], v[130:133], v[164:167], v[126:129]
	v_mfma_f32_16x16x32_bf16 v[122:125], v[156:159], v[164:167], v[122:125]
	v_mfma_f32_16x16x32_bf16 v[110:113], v[130:133], v[172:175], v[110:113]
	v_mfma_f32_16x16x32_bf16 v[106:109], v[156:159], v[172:175], v[106:109]
	v_mfma_f32_16x16x32_bf16 v[94:97], v[130:133], v[182:185], v[94:97]
	v_mfma_f32_16x16x32_bf16 v[90:93], v[156:159], v[182:185], v[90:93]
	v_mfma_f32_16x16x32_bf16 v[78:81], v[130:133], v[190:193], v[78:81]
	v_mfma_f32_16x16x32_bf16 v[74:77], v[156:159], v[190:193], v[74:77]
	v_mfma_f32_16x16x32_bf16 v[126:129], v[146:149], v[168:171], v[126:129]
	v_mfma_f32_16x16x32_bf16 v[122:125], v[160:163], v[168:171], v[122:125]
	v_mfma_f32_16x16x32_bf16 v[110:113], v[146:149], v[176:179], v[110:113]
	v_mfma_f32_16x16x32_bf16 v[106:109], v[160:163], v[176:179], v[106:109]
	v_mfma_f32_16x16x32_bf16 v[94:97], v[146:149], v[186:189], v[94:97]
	v_mfma_f32_16x16x32_bf16 v[90:93], v[160:163], v[186:189], v[90:93]
	v_mfma_f32_16x16x32_bf16 v[78:81], v[146:149], v[194:197], v[78:81]
	v_mfma_f32_16x16x32_bf16 v[74:77], v[160:163], v[194:197], v[74:77]
	s_setprio 0
	s_barrier
	s_mov_b32 m0, s23
	v_add_u32_e32 v0, 0x14000, v154
	v_lshl_add_u64 v[150:151], s[28:29], 0, v[138:139]
	ds_read_b128 v[198:201], v0
	ds_read_b128 v[202:205], v0 offset:1024
	ds_read_b128 v[206:209], v0 offset:2048
	ds_read_b128 v[210:213], v0 offset:3072
	global_load_lds_dwordx4 v[150:151], off
	v_lshl_add_u64 v[214:215], s[28:29], 0, v[134:135]
	s_mov_b32 m0, s25
	s_nop 0
	global_load_lds_dwordx4 v[214:215], off
	s_barrier
	s_waitcnt lgkmcnt(0)
	s_setprio 1
	s_waitcnt lgkmcnt(0)
	v_mfma_f32_16x16x32_bf16 v[118:121], v[198:201], v[164:167], v[118:121]
	v_mfma_f32_16x16x32_bf16 v[114:117], v[206:209], v[164:167], v[114:117]
	v_mfma_f32_16x16x32_bf16 v[102:105], v[198:201], v[172:175], v[102:105]
	v_mfma_f32_16x16x32_bf16 v[98:101], v[206:209], v[172:175], v[98:101]
	v_mfma_f32_16x16x32_bf16 v[86:89], v[198:201], v[182:185], v[86:89]
	v_mfma_f32_16x16x32_bf16 v[82:85], v[206:209], v[182:185], v[82:85]
	v_mfma_f32_16x16x32_bf16 v[70:73], v[198:201], v[190:193], v[70:73]
	v_mfma_f32_16x16x32_bf16 v[66:69], v[206:209], v[190:193], v[66:69]
	v_mfma_f32_16x16x32_bf16 v[118:121], v[202:205], v[168:171], v[118:121]
	v_mfma_f32_16x16x32_bf16 v[114:117], v[210:213], v[168:171], v[114:117]
	v_mfma_f32_16x16x32_bf16 v[102:105], v[202:205], v[176:179], v[102:105]
	v_mfma_f32_16x16x32_bf16 v[98:101], v[210:213], v[176:179], v[98:101]
	v_mfma_f32_16x16x32_bf16 v[86:89], v[202:205], v[186:189], v[86:89]
	v_mfma_f32_16x16x32_bf16 v[82:85], v[210:213], v[186:189], v[82:85]
	v_mfma_f32_16x16x32_bf16 v[70:73], v[202:205], v[194:197], v[70:73]
	v_mfma_f32_16x16x32_bf16 v[66:69], v[210:213], v[194:197], v[66:69]
	s_setprio 0
	s_mov_b32 m0, s39
	v_lshl_add_u64 v[216:217], s[30:31], 0, v[140:141]
	s_barrier
	ds_read_b128 v[164:167], v153 offset:16384
	ds_read_b128 v[168:171], v153 offset:17408
	ds_read_b128 v[172:175], v153 offset:18432
	ds_read_b128 v[176:179], v153 offset:19456
	ds_read_b128 v[182:185], v153 offset:20480
	ds_read_b128 v[186:189], v153 offset:21504
	ds_read_b128 v[190:193], v153 offset:22528
	ds_read_b128 v[194:197], v153 offset:23552
	global_load_lds_dwordx4 v[216:217], off
	v_lshl_add_u64 v[222:223], s[30:31], 0, v[136:137]
	s_mov_b32 m0, s82
	s_nop 0
	global_load_lds_dwordx4 v[222:223], off
	s_barrier
	s_waitcnt lgkmcnt(0)
	s_setprio 1
	s_waitcnt lgkmcnt(0)
	v_mfma_f32_16x16x32_bf16 v[62:65], v[130:133], v[164:167], v[62:65]
	v_mfma_f32_16x16x32_bf16 v[58:61], v[156:159], v[164:167], v[58:61]
	v_mfma_f32_16x16x32_bf16 v[46:49], v[130:133], v[172:175], v[46:49]
	v_mfma_f32_16x16x32_bf16 v[42:45], v[156:159], v[172:175], v[42:45]
	v_mfma_f32_16x16x32_bf16 v[30:33], v[130:133], v[182:185], v[30:33]
	v_mfma_f32_16x16x32_bf16 v[26:29], v[156:159], v[182:185], v[26:29]
	v_mfma_f32_16x16x32_bf16 v[14:17], v[130:133], v[190:193], v[14:17]
	v_mfma_f32_16x16x32_bf16 v[10:13], v[156:159], v[190:193], v[10:13]
	v_mfma_f32_16x16x32_bf16 v[62:65], v[146:149], v[168:171], v[62:65]
	v_mfma_f32_16x16x32_bf16 v[58:61], v[160:163], v[168:171], v[58:61]
	v_mfma_f32_16x16x32_bf16 v[46:49], v[146:149], v[176:179], v[46:49]
	v_mfma_f32_16x16x32_bf16 v[42:45], v[160:163], v[176:179], v[42:45]
	v_mfma_f32_16x16x32_bf16 v[30:33], v[146:149], v[186:189], v[30:33]
	v_mfma_f32_16x16x32_bf16 v[26:29], v[160:163], v[186:189], v[26:29]
	v_mfma_f32_16x16x32_bf16 v[14:17], v[146:149], v[194:197], v[14:17]
	v_mfma_f32_16x16x32_bf16 v[10:13], v[160:163], v[194:197], v[10:13]
	s_setprio 0
	s_barrier
	s_add_u32 s76, s28, 0x40000
	s_addc_u32 s77, s29, 0
	s_mov_b32 m0, s96
	v_lshl_add_u64 v[130:131], s[76:77], 0, v[138:139]
	global_load_lds_dwordx4 v[130:131], off
	v_lshl_add_u64 v[130:131], s[76:77], 0, v[134:135]
	s_mov_b32 m0, s97
	s_nop 0
	global_load_lds_dwordx4 v[130:131], off
	s_waitcnt vmcnt(6)
	s_barrier
	s_setprio 1
	v_mfma_f32_16x16x32_bf16 v[54:57], v[198:201], v[164:167], v[54:57]
	v_mfma_f32_16x16x32_bf16 v[50:53], v[206:209], v[164:167], v[50:53]
	v_mfma_f32_16x16x32_bf16 v[38:41], v[198:201], v[172:175], v[38:41]
	v_mfma_f32_16x16x32_bf16 v[34:37], v[206:209], v[172:175], v[34:37]
	v_mfma_f32_16x16x32_bf16 v[22:25], v[198:201], v[182:185], v[22:25]
	v_mfma_f32_16x16x32_bf16 v[18:21], v[206:209], v[182:185], v[18:21]
	v_mfma_f32_16x16x32_bf16 v[6:9], v[198:201], v[190:193], v[6:9]
	v_mfma_f32_16x16x32_bf16 v[2:5], v[206:209], v[190:193], v[2:5]
	v_mfma_f32_16x16x32_bf16 v[54:57], v[202:205], v[168:171], v[54:57]
	v_mfma_f32_16x16x32_bf16 v[50:53], v[210:213], v[168:171], v[50:53]
	v_mfma_f32_16x16x32_bf16 v[38:41], v[202:205], v[176:179], v[38:41]
	v_mfma_f32_16x16x32_bf16 v[34:37], v[210:213], v[176:179], v[34:37]
	v_mfma_f32_16x16x32_bf16 v[22:25], v[202:205], v[186:189], v[22:25]
	v_mfma_f32_16x16x32_bf16 v[18:21], v[210:213], v[186:189], v[18:21]
	v_mfma_f32_16x16x32_bf16 v[6:9], v[202:205], v[194:197], v[6:9]
	v_mfma_f32_16x16x32_bf16 v[2:5], v[210:213], v[194:197], v[2:5]
	s_setprio 0
	v_add_u32_e32 v0, 0x18000, v154
	s_barrier
	ds_read_b128 v[130:133], v0
	ds_read_b128 v[146:149], v0 offset:1024
	ds_read_b128 v[156:159], v0 offset:2048
	ds_read_b128 v[160:163], v0 offset:3072
	s_add_u32 s30, s30, 0x40000
	s_addc_u32 s31, s31, 0
	s_mov_b32 m0, s68
	v_lshl_add_u64 v[198:199], s[30:31], 0, v[140:141]
	ds_read_b128 v[164:167], v153 offset:32768
	ds_read_b128 v[168:171], v153 offset:33792
	ds_read_b128 v[172:175], v153 offset:34816
	ds_read_b128 v[176:179], v153 offset:35840
	ds_read_b128 v[182:185], v153 offset:36864
	ds_read_b128 v[186:189], v153 offset:37888
	ds_read_b128 v[190:193], v153 offset:38912
	ds_read_b128 v[194:197], v153 offset:39936
	global_load_lds_dwordx4 v[198:199], off
	v_lshl_add_u64 v[198:199], s[30:31], 0, v[136:137]
	s_mov_b32 m0, s69
	s_nop 0
	global_load_lds_dwordx4 v[198:199], off
	s_waitcnt lgkmcnt(8)
	s_barrier
	s_waitcnt lgkmcnt(0)
	s_setprio 1
	s_waitcnt lgkmcnt(0)
	v_mfma_f32_16x16x32_bf16 v[126:129], v[130:133], v[164:167], v[126:129]
	v_mfma_f32_16x16x32_bf16 v[122:125], v[156:159], v[164:167], v[122:125]
	v_mfma_f32_16x16x32_bf16 v[110:113], v[130:133], v[172:175], v[110:113]
	v_mfma_f32_16x16x32_bf16 v[106:109], v[156:159], v[172:175], v[106:109]
	v_mfma_f32_16x16x32_bf16 v[94:97], v[130:133], v[182:185], v[94:97]
	v_mfma_f32_16x16x32_bf16 v[90:93], v[156:159], v[182:185], v[90:93]
	v_mfma_f32_16x16x32_bf16 v[78:81], v[130:133], v[190:193], v[78:81]
	v_mfma_f32_16x16x32_bf16 v[74:77], v[156:159], v[190:193], v[74:77]
	v_mfma_f32_16x16x32_bf16 v[126:129], v[146:149], v[168:171], v[126:129]
	v_mfma_f32_16x16x32_bf16 v[122:125], v[160:163], v[168:171], v[122:125]
	v_mfma_f32_16x16x32_bf16 v[110:113], v[146:149], v[176:179], v[110:113]
	v_mfma_f32_16x16x32_bf16 v[106:109], v[160:163], v[176:179], v[106:109]
	v_mfma_f32_16x16x32_bf16 v[94:97], v[146:149], v[186:189], v[94:97]
	v_mfma_f32_16x16x32_bf16 v[90:93], v[160:163], v[186:189], v[90:93]
	v_mfma_f32_16x16x32_bf16 v[78:81], v[146:149], v[194:197], v[78:81]
	v_mfma_f32_16x16x32_bf16 v[74:77], v[160:163], v[194:197], v[74:77]
	s_setprio 0
	s_barrier
	s_mov_b32 m0, s4
	v_add_u32_e32 v0, 0x1c000, v154
	v_lshl_add_u64 v[150:151], v[150:151], 0, s[84:85]
	ds_read_b128 v[198:201], v0
	ds_read_b128 v[202:205], v0 offset:1024
	ds_read_b128 v[206:209], v0 offset:2048
	ds_read_b128 v[210:213], v0 offset:3072
	global_load_lds_dwordx4 v[150:151], off
	v_lshl_add_u64 v[150:151], v[214:215], 0, s[84:85]
	s_mov_b32 m0, s5
	s_nop 0
	global_load_lds_dwordx4 v[150:151], off
	s_barrier
	s_waitcnt lgkmcnt(0)
	s_setprio 1
	s_waitcnt lgkmcnt(0)
	v_mfma_f32_16x16x32_bf16 v[118:121], v[198:201], v[164:167], v[118:121]
	v_mfma_f32_16x16x32_bf16 v[114:117], v[206:209], v[164:167], v[114:117]
	v_mfma_f32_16x16x32_bf16 v[102:105], v[198:201], v[172:175], v[102:105]
	v_mfma_f32_16x16x32_bf16 v[98:101], v[206:209], v[172:175], v[98:101]
	v_mfma_f32_16x16x32_bf16 v[86:89], v[198:201], v[182:185], v[86:89]
	v_mfma_f32_16x16x32_bf16 v[82:85], v[206:209], v[182:185], v[82:85]
	v_mfma_f32_16x16x32_bf16 v[70:73], v[198:201], v[190:193], v[70:73]
	v_mfma_f32_16x16x32_bf16 v[66:69], v[206:209], v[190:193], v[66:69]
	v_mfma_f32_16x16x32_bf16 v[118:121], v[202:205], v[168:171], v[118:121]
	v_mfma_f32_16x16x32_bf16 v[114:117], v[210:213], v[168:171], v[114:117]
	v_mfma_f32_16x16x32_bf16 v[102:105], v[202:205], v[176:179], v[102:105]
	v_mfma_f32_16x16x32_bf16 v[98:101], v[210:213], v[176:179], v[98:101]
	v_mfma_f32_16x16x32_bf16 v[86:89], v[202:205], v[186:189], v[86:89]
	v_mfma_f32_16x16x32_bf16 v[82:85], v[210:213], v[186:189], v[82:85]
	v_mfma_f32_16x16x32_bf16 v[70:73], v[202:205], v[194:197], v[70:73]
	v_mfma_f32_16x16x32_bf16 v[66:69], v[210:213], v[194:197], v[66:69]
	s_setprio 0
	s_mov_b32 m0, s60
	v_lshl_add_u64 v[150:151], v[216:217], 0, s[84:85]
	s_barrier
	ds_read_b128 v[164:167], v153 offset:49152
	ds_read_b128 v[168:171], v153 offset:50176
	ds_read_b128 v[172:175], v153 offset:51200
	ds_read_b128 v[176:179], v153 offset:52224
	ds_read_b128 v[182:185], v153 offset:53248
	ds_read_b128 v[186:189], v153 offset:54272
	ds_read_b128 v[190:193], v153 offset:55296
	ds_read_b128 v[194:197], v153 offset:56320
	global_load_lds_dwordx4 v[150:151], off
	v_lshl_add_u64 v[150:151], v[222:223], 0, s[84:85]
	s_mov_b32 m0, s92
	s_nop 0
	global_load_lds_dwordx4 v[150:151], off
	s_barrier
	s_waitcnt lgkmcnt(0)
	s_setprio 1
	s_waitcnt lgkmcnt(0)
	v_mfma_f32_16x16x32_bf16 v[62:65], v[130:133], v[164:167], v[62:65]
	v_mfma_f32_16x16x32_bf16 v[58:61], v[156:159], v[164:167], v[58:61]
	v_mfma_f32_16x16x32_bf16 v[46:49], v[130:133], v[172:175], v[46:49]
	v_mfma_f32_16x16x32_bf16 v[42:45], v[156:159], v[172:175], v[42:45]
	v_mfma_f32_16x16x32_bf16 v[30:33], v[130:133], v[182:185], v[30:33]
	v_mfma_f32_16x16x32_bf16 v[26:29], v[156:159], v[182:185], v[26:29]
	v_mfma_f32_16x16x32_bf16 v[14:17], v[130:133], v[190:193], v[14:17]
	v_mfma_f32_16x16x32_bf16 v[10:13], v[156:159], v[190:193], v[10:13]
	v_mfma_f32_16x16x32_bf16 v[62:65], v[146:149], v[168:171], v[62:65]
	v_mfma_f32_16x16x32_bf16 v[58:61], v[160:163], v[168:171], v[58:61]
	v_mfma_f32_16x16x32_bf16 v[46:49], v[146:149], v[176:179], v[46:49]
	v_mfma_f32_16x16x32_bf16 v[42:45], v[160:163], v[176:179], v[42:45]
	v_mfma_f32_16x16x32_bf16 v[30:33], v[146:149], v[186:189], v[30:33]
	v_mfma_f32_16x16x32_bf16 v[26:29], v[160:163], v[186:189], v[26:29]
	v_mfma_f32_16x16x32_bf16 v[14:17], v[146:149], v[194:197], v[14:17]
	v_mfma_f32_16x16x32_bf16 v[10:13], v[160:163], v[194:197], v[10:13]
	s_setprio 0
	s_barrier
	s_add_u32 s28, s28, 0x40080
	s_addc_u32 s29, s29, 0
	s_mov_b32 m0, s93
	v_lshl_add_u64 v[130:131], s[28:29], 0, v[138:139]
	global_load_lds_dwordx4 v[130:131], off
	v_lshl_add_u64 v[130:131], s[28:29], 0, v[134:135]
	s_mov_b32 m0, s3
	s_nop 0
	global_load_lds_dwordx4 v[130:131], off
	s_waitcnt vmcnt(6)
	s_barrier
	s_setprio 1
	v_mfma_f32_16x16x32_bf16 v[54:57], v[198:201], v[164:167], v[54:57]
	v_mfma_f32_16x16x32_bf16 v[50:53], v[206:209], v[164:167], v[50:53]
	v_mfma_f32_16x16x32_bf16 v[38:41], v[198:201], v[172:175], v[38:41]
	v_mfma_f32_16x16x32_bf16 v[34:37], v[206:209], v[172:175], v[34:37]
	v_mfma_f32_16x16x32_bf16 v[22:25], v[198:201], v[182:185], v[22:25]
	v_mfma_f32_16x16x32_bf16 v[18:21], v[206:209], v[182:185], v[18:21]
	v_mfma_f32_16x16x32_bf16 v[6:9], v[198:201], v[190:193], v[6:9]
	v_mfma_f32_16x16x32_bf16 v[2:5], v[206:209], v[190:193], v[2:5]
	v_mfma_f32_16x16x32_bf16 v[54:57], v[202:205], v[168:171], v[54:57]
	v_mfma_f32_16x16x32_bf16 v[50:53], v[210:213], v[168:171], v[50:53]
	v_mfma_f32_16x16x32_bf16 v[38:41], v[202:205], v[176:179], v[38:41]
	v_mfma_f32_16x16x32_bf16 v[34:37], v[210:213], v[176:179], v[34:37]
	v_mfma_f32_16x16x32_bf16 v[22:25], v[202:205], v[186:189], v[22:25]
	v_mfma_f32_16x16x32_bf16 v[18:21], v[210:213], v[186:189], v[18:21]
	v_mfma_f32_16x16x32_bf16 v[6:9], v[202:205], v[194:197], v[6:9]
	v_mfma_f32_16x16x32_bf16 v[2:5], v[210:213], v[194:197], v[2:5]
	s_setprio 0
	s_add_i32 vcc_lo, vcc_lo, 2
	s_add_u32 s26, s26, 0x100
	s_addc_u32 s27, s27, 0
	s_add_u32 s90, s90, 0x100
	s_addc_u32 s94, s94, 0
	s_cmp_gt_u32 vcc_lo, 13
	s_barrier
	s_cbranch_scc0 .LBB0_1359
	v_lshl_add_u32 v159, s24, 8, v152
	v_lshl_add_u32 v156, s22, 8, v155
	v_mul_lo_u32 v157, v159, s71
	v_add_u32_e32 v0, v157, v156
	v_lshl_add_u64 v[130:131], v[0:1], 1, s[6:7]
	global_load_dwordx4 v[130:133], v[130:131], off
	v_mul_lo_u32 v158, v159, s61
	v_mov_b32_e32 v210, v0
	v_add_u32_e32 v211, v0, v158
	v_mov_b32_e32 v213, 0
	v_add_u32_e32 v212, 0x80, v210
	v_lshl_add_u64 v[168:169], v[212:213], 1, s[6:7]
	global_load_dwordx4 v[168:171], v[168:169], off
	v_add_u32_e32 v212, 0x80, v211
	v_lshl_add_u64 v[172:173], v[212:213], 1, s[10:11]
	global_load_dwordx4 v[172:175], v[172:173], off
	v_add_u32_e32 v212, 0x16c00, v210
	v_lshl_add_u64 v[176:177], v[212:213], 1, s[6:7]
	global_load_dwordx4 v[176:179], v[176:177], off
	v_add_u32_e32 v212, 0x4000, v211
	v_lshl_add_u64 v[182:183], v[212:213], 1, s[10:11]
	global_load_dwordx4 v[182:185], v[182:183], off
	v_add_u32_e32 v212, 0x16c80, v210
	v_lshl_add_u64 v[186:187], v[212:213], 1, s[6:7]
	global_load_dwordx4 v[186:189], v[186:187], off
	v_add_u32_e32 v212, 0x4080, v211
	v_lshl_add_u64 v[190:191], v[212:213], 1, s[10:11]
	global_load_dwordx4 v[190:193], v[190:191], off
	v_add_u32_e32 v212, 0x2d800, v210
	v_lshl_add_u64 v[194:195], v[212:213], 1, s[6:7]
	global_load_dwordx4 v[194:197], v[194:195], off
	v_add_u32_e32 v212, 0x8000, v211
	v_lshl_add_u64 v[198:199], v[212:213], 1, s[10:11]
	global_load_dwordx4 v[198:201], v[198:199], off
	v_add_u32_e32 v212, 0x2d880, v210
	v_lshl_add_u64 v[202:203], v[212:213], 1, s[6:7]
	global_load_dwordx4 v[202:205], v[202:203], off
	v_add_u32_e32 v212, 0x8080, v211
	v_lshl_add_u64 v[206:207], v[212:213], 1, s[10:11]
	global_load_dwordx4 v[206:209], v[206:207], off
	v_add_u32_e32 v0, v0, v158
	v_lshl_add_u64 v[146:147], v[0:1], 1, s[10:11]
	s_mov_b32 s22, s14
	s_mov_b32 s24, s16
	s_mov_b64 s[28:29], s[20:21]
	s_waitcnt vmcnt(10)
	v_lshlrev_b32_e32 v148, 16, v130
	v_and_b32_e32 v149, 0xffff0000, v130
	v_lshlrev_b32_e32 v151, 16, v131
	v_and_b32_e32 v163, 0xffff0000, v131
	v_lshlrev_b32_e32 v150, 16, v132
	v_and_b32_e32 v161, 0xffff0000, v132
	v_lshlrev_b32_e32 v164, 16, v133
	v_and_b32_e32 v165, 0xffff0000, v133
	global_load_dwordx4 v[130:133], v[146:147], off
	v_mul_f32_e32 v0, 0xbfb8aa3b, v148
	v_exp_f32_e32 v160, v0
	v_mul_f32_e32 v0, 0xbfb8aa3b, v150
	v_exp_f32_e32 v150, v0
	v_mul_f32_e32 v0, 0xbfb8aa3b, v149
	v_exp_f32_e32 v162, v0
	v_mul_f32_e32 v0, 0xbfb8aa3b, v161
	v_exp_f32_e32 v148, v0
	v_mul_f32_e32 v0, 0xbfb8aa3b, v151
	v_exp_f32_e32 v161, v0
	v_mul_f32_e32 v0, 0xbfb8aa3b, v164
	v_exp_f32_e32 v151, v0
	v_mul_f32_e32 v0, 0xbfb8aa3b, v163
	v_exp_f32_e32 v163, v0
	v_mul_f32_e32 v0, 0xbfb8aa3b, v165
	v_pk_add_f32 v[160:161], v[160:161], 1.0 op_sel_hi:[1,0]
	v_exp_f32_e32 v149, v0
	v_pk_add_f32 v[162:163], v[162:163], 1.0 op_sel_hi:[1,0]
	v_rcp_f32_e32 v161, v161
	s_nop 0
	s_waitcnt vmcnt(0)
	v_lshlrev_b32_e32 v165, 16, v131
	v_rcp_f32_e32 v160, v160
	s_nop 0
	v_mov_b32_e32 v166, v126
	v_mov_b32_e32 v167, v128
	v_lshlrev_b32_e32 v164, 16, v130
	v_pk_fma_f32 v[160:161], v[166:167], v[160:161], v[164:165]
	v_rcp_f32_e32 v163, v163
	s_nop 0
	v_and_b32_e32 v131, 0xffff0000, v131
	v_and_b32_e32 v130, 0xffff0000, v130
	v_rcp_f32_e32 v162, v162
	s_nop 0
	v_mov_b32_e32 v128, v127
	v_pk_fma_f32 v[126:127], v[128:129], v[162:163], v[130:131]
	v_cvt_pk_bf16_f32 v0, v160, v161
	v_cvt_pk_bf16_f32 v126, v126, v127
	v_and_b32_e32 v127, 0xffff0000, v126
	v_lshlrev_b32_e32 v126, 16, v126
	v_lshlrev_b32_e32 v131, 16, v133
	v_lshlrev_b32_e32 v130, 16, v132
	v_and_b32_e32 v129, 0xffff0000, v133
	v_and_b32_e32 v128, 0xffff0000, v132
	v_pk_add_f32 v[132:133], v[150:151], 1.0 op_sel_hi:[1,0]
	v_or_b32_sdwa v127, v127, v0 dst_sel:DWORD dst_unused:UNUSED_PAD src0_sel:DWORD src1_sel:WORD_1
	v_or_b32_sdwa v126, v126, v0 dst_sel:DWORD dst_unused:UNUSED_PAD src0_sel:DWORD src1_sel:WORD_0
	s_nop 0
	v_rcp_f32_e32 v133, v133
	s_nop 0
	s_nop 0
	v_rcp_f32_e32 v132, v132
	s_nop 0
	v_mov_b32_e32 v150, v122
	v_mov_b32_e32 v151, v124
	v_pk_fma_f32 v[130:131], v[150:151], v[132:133], v[130:131]
	v_pk_add_f32 v[132:133], v[148:149], 1.0 op_sel_hi:[1,0]
	s_nop 0
	s_nop 0
	v_rcp_f32_e32 v133, v133
	s_nop 0
	s_nop 0
	v_rcp_f32_e32 v132, v132
	s_nop 0
	v_mov_b32_e32 v124, v123
	v_pk_fma_f32 v[122:123], v[124:125], v[132:133], v[128:129]
	v_cvt_pk_bf16_f32 v0, v130, v131
	v_cvt_pk_bf16_f32 v122, v122, v123
	v_and_b32_e32 v123, 0xffff0000, v122
	v_lshlrev_b32_e32 v122, 16, v122
	v_or_b32_sdwa v129, v123, v0 dst_sel:DWORD dst_unused:UNUSED_PAD src0_sel:DWORD src1_sel:WORD_1
	v_or_b32_sdwa v128, v122, v0 dst_sel:DWORD dst_unused:UNUSED_PAD src0_sel:DWORD src1_sel:WORD_0
	global_store_dwordx4 v[146:147], v[126:129], off
	s_nop 1
	v_add_u32_e32 v126, 0x80, v156
	v_add_u32_e32 v0, v157, v126
	v_add_u32_e32 v0, v0, v158
	s_waitcnt vmcnt(11)
	v_lshlrev_b32_e32 v127, 16, v168
	v_and_b32_e32 v133, 0xffff0000, v168
	v_lshlrev_b32_e32 v147, 16, v169
	v_and_b32_e32 v149, 0xffff0000, v169
	v_lshl_add_u64 v[122:123], v[0:1], 1, s[10:11]
	v_lshlrev_b32_e32 v146, 16, v170
	v_mul_f32_e32 v0, 0xbfb8aa3b, v127
	v_exp_f32_e32 v132, v0
	v_mul_f32_e32 v0, 0xbfb8aa3b, v146
	v_and_b32_e32 v124, 0xffff0000, v170
	v_exp_f32_e32 v146, v0
	v_mul_f32_e32 v0, 0xbfb8aa3b, v133
	v_exp_f32_e32 v148, v0
	v_mul_f32_e32 v0, 0xbfb8aa3b, v124
	v_exp_f32_e32 v124, v0
	v_mul_f32_e32 v0, 0xbfb8aa3b, v147
	v_exp_f32_e32 v133, v0
	v_lshlrev_b32_e32 v150, 16, v171
	v_mul_f32_e32 v0, 0xbfb8aa3b, v150
	v_and_b32_e32 v125, 0xffff0000, v171
	v_exp_f32_e32 v147, v0
	v_mul_f32_e32 v0, 0xbfb8aa3b, v149
	v_exp_f32_e32 v149, v0
	v_mul_f32_e32 v0, 0xbfb8aa3b, v125
	v_pk_add_f32 v[132:133], v[132:133], 1.0 op_sel_hi:[1,0]
	v_exp_f32_e32 v125, v0
	v_pk_add_f32 v[148:149], v[148:149], 1.0 op_sel_hi:[1,0]
	v_pk_add_f32 v[124:125], v[124:125], 1.0 op_sel_hi:[1,0]
	v_rcp_f32_e32 v133, v133
	s_nop 0
	s_waitcnt vmcnt(10)
	v_lshlrev_b32_e32 v151, 16, v173
	v_rcp_f32_e32 v132, v132
	s_nop 0
	v_mov_b32_e32 v160, v118
	v_mov_b32_e32 v161, v120
	v_lshlrev_b32_e32 v150, 16, v172
	v_pk_fma_f32 v[132:133], v[160:161], v[132:133], v[150:151]
	v_rcp_f32_e32 v149, v149
	s_nop 0
	v_and_b32_e32 v129, 0xffff0000, v173
	v_and_b32_e32 v128, 0xffff0000, v172
	v_rcp_f32_e32 v148, v148
	s_nop 0
	v_mov_b32_e32 v120, v119
	v_pk_fma_f32 v[118:119], v[120:121], v[148:149], v[128:129]
	v_cvt_pk_bf16_f32 v0, v132, v133
	v_cvt_pk_bf16_f32 v118, v118, v119
	v_and_b32_e32 v119, 0xffff0000, v118
	v_lshlrev_b32_e32 v118, 16, v118
	v_lshlrev_b32_e32 v121, 16, v175
	v_lshlrev_b32_e32 v120, 16, v174
	v_and_b32_e32 v129, 0xffff0000, v175
	v_and_b32_e32 v128, 0xffff0000, v174
	v_pk_add_f32 v[130:131], v[146:147], 1.0 op_sel_hi:[1,0]
	v_or_b32_sdwa v119, v119, v0 dst_sel:DWORD dst_unused:UNUSED_PAD src0_sel:DWORD src1_sel:WORD_1
	v_or_b32_sdwa v118, v118, v0 dst_sel:DWORD dst_unused:UNUSED_PAD src0_sel:DWORD src1_sel:WORD_0
	s_nop 0
	v_rcp_f32_e32 v131, v131
	s_nop 0
	s_nop 0
	v_rcp_f32_e32 v130, v130
	s_nop 0
	v_mov_b32_e32 v132, v114
	v_mov_b32_e32 v133, v116
	v_pk_fma_f32 v[120:121], v[132:133], v[130:131], v[120:121]
	v_rcp_f32_e32 v125, v125
	s_nop 0
	s_nop 0
	v_rcp_f32_e32 v124, v124
	s_nop 0
	v_mov_b32_e32 v116, v115
	v_pk_fma_f32 v[114:115], v[116:117], v[124:125], v[128:129]
	v_cvt_pk_bf16_f32 v0, v120, v121
	v_cvt_pk_bf16_f32 v114, v114, v115
	v_and_b32_e32 v115, 0xffff0000, v114
	v_lshlrev_b32_e32 v114, 16, v114
	v_add_u32_e32 v127, 0x16c00, v157
	v_or_b32_sdwa v121, v115, v0 dst_sel:DWORD dst_unused:UNUSED_PAD src0_sel:DWORD src1_sel:WORD_1
	v_or_b32_sdwa v120, v114, v0 dst_sel:DWORD dst_unused:UNUSED_PAD src0_sel:DWORD src1_sel:WORD_0
	v_add_u32_e32 v0, v127, v156
	v_add_u32_e32 v212, 0x44400, v210
	v_lshl_add_u64 v[168:169], v[212:213], 1, s[6:7]
	global_load_dwordx4 v[168:171], v[168:169], off
	v_add_u32_e32 v212, 0xc000, v211
	v_lshl_add_u64 v[172:173], v[212:213], 1, s[10:11]
	global_load_dwordx4 v[172:175], v[172:173], off
	global_store_dwordx4 v[122:123], v[118:121], off
	s_nop 1
	v_or_b32_e32 v118, 16, v159
	v_mul_lo_u32 v146, v118, s61
	v_add_u32_e32 v0, v0, v146
	s_waitcnt vmcnt(12)
	v_lshlrev_b32_e32 v122, 16, v176
	v_and_b32_e32 v123, 0xffff0000, v176
	v_lshlrev_b32_e32 v125, 16, v177
	v_and_b32_e32 v129, 0xffff0000, v177
	v_lshl_add_u64 v[114:115], v[0:1], 1, s[10:11]
	v_lshlrev_b32_e32 v124, 16, v178
	v_mul_f32_e32 v0, 0xbfb8aa3b, v122
	v_exp_f32_e32 v122, v0
	v_mul_f32_e32 v0, 0xbfb8aa3b, v124
	v_and_b32_e32 v116, 0xffff0000, v178
	v_exp_f32_e32 v124, v0
	v_mul_f32_e32 v0, 0xbfb8aa3b, v123
	v_exp_f32_e32 v128, v0
	v_mul_f32_e32 v0, 0xbfb8aa3b, v116
	v_exp_f32_e32 v116, v0
	v_mul_f32_e32 v0, 0xbfb8aa3b, v125
	v_exp_f32_e32 v123, v0
	v_lshlrev_b32_e32 v130, 16, v179
	v_mul_f32_e32 v0, 0xbfb8aa3b, v130
	v_and_b32_e32 v117, 0xffff0000, v179
	v_exp_f32_e32 v125, v0
	v_mul_f32_e32 v0, 0xbfb8aa3b, v129
	v_exp_f32_e32 v129, v0
	v_mul_f32_e32 v0, 0xbfb8aa3b, v117
	v_pk_add_f32 v[122:123], v[122:123], 1.0 op_sel_hi:[1,0]
	v_exp_f32_e32 v117, v0
	v_pk_add_f32 v[128:129], v[128:129], 1.0 op_sel_hi:[1,0]
	v_pk_add_f32 v[116:117], v[116:117], 1.0 op_sel_hi:[1,0]
	v_rcp_f32_e32 v123, v123
	s_nop 0
	s_waitcnt vmcnt(11)
	v_lshlrev_b32_e32 v131, 16, v183
	v_rcp_f32_e32 v122, v122
	s_nop 0
	v_mov_b32_e32 v132, v110
	v_mov_b32_e32 v133, v112
	v_lshlrev_b32_e32 v130, 16, v182
	v_pk_fma_f32 v[122:123], v[132:133], v[122:123], v[130:131]
	v_rcp_f32_e32 v129, v129
	s_nop 0
	v_and_b32_e32 v119, 0xffff0000, v183
	v_and_b32_e32 v118, 0xffff0000, v182
	v_rcp_f32_e32 v128, v128
	s_nop 0
	v_mov_b32_e32 v112, v111
	v_pk_fma_f32 v[110:111], v[112:113], v[128:129], v[118:119]
	v_cvt_pk_bf16_f32 v0, v122, v123
	v_cvt_pk_bf16_f32 v110, v110, v111
	v_and_b32_e32 v111, 0xffff0000, v110
	v_lshlrev_b32_e32 v110, 16, v110
	v_lshlrev_b32_e32 v113, 16, v185
	v_lshlrev_b32_e32 v112, 16, v184
	v_and_b32_e32 v119, 0xffff0000, v185
	v_and_b32_e32 v118, 0xffff0000, v184
	v_pk_add_f32 v[120:121], v[124:125], 1.0 op_sel_hi:[1,0]
	v_or_b32_sdwa v111, v111, v0 dst_sel:DWORD dst_unused:UNUSED_PAD src0_sel:DWORD src1_sel:WORD_1
	v_or_b32_sdwa v110, v110, v0 dst_sel:DWORD dst_unused:UNUSED_PAD src0_sel:DWORD src1_sel:WORD_0
	s_nop 0
	v_rcp_f32_e32 v121, v121
	s_nop 0
	s_nop 0
	v_rcp_f32_e32 v120, v120
	s_nop 0
	v_mov_b32_e32 v122, v106
	v_mov_b32_e32 v123, v108
	v_pk_fma_f32 v[112:113], v[122:123], v[120:121], v[112:113]
	v_rcp_f32_e32 v117, v117
	s_nop 0
	s_nop 0
	v_rcp_f32_e32 v116, v116
	s_nop 0
	v_mov_b32_e32 v108, v107
	v_pk_fma_f32 v[106:107], v[108:109], v[116:117], v[118:119]
	v_cvt_pk_bf16_f32 v0, v112, v113
	v_cvt_pk_bf16_f32 v106, v106, v107
	v_and_b32_e32 v107, 0xffff0000, v106
	v_lshlrev_b32_e32 v106, 16, v106
	v_or_b32_sdwa v113, v107, v0 dst_sel:DWORD dst_unused:UNUSED_PAD src0_sel:DWORD src1_sel:WORD_1
	v_or_b32_sdwa v112, v106, v0 dst_sel:DWORD dst_unused:UNUSED_PAD src0_sel:DWORD src1_sel:WORD_0
	v_add_u32_e32 v0, v127, v126
	v_add_u32_e32 v212, 0x44480, v210
	v_lshl_add_u64 v[176:177], v[212:213], 1, s[6:7]
	global_load_dwordx4 v[176:179], v[176:177], off
	v_add_u32_e32 v212, 0xc080, v211
	v_lshl_add_u64 v[182:183], v[212:213], 1, s[10:11]
	global_load_dwordx4 v[182:185], v[182:183], off
	global_store_dwordx4 v[114:115], v[110:113], off
	v_add_u32_e32 v0, v0, v146
	s_waitcnt vmcnt(13)
	v_lshlrev_b32_e32 v114, 16, v186
	v_and_b32_e32 v115, 0xffff0000, v186
	v_lshlrev_b32_e32 v117, 16, v187
	v_and_b32_e32 v119, 0xffff0000, v187
	v_lshl_add_u64 v[106:107], v[0:1], 1, s[10:11]
	v_lshlrev_b32_e32 v116, 16, v188
	v_mul_f32_e32 v0, 0xbfb8aa3b, v114
	v_exp_f32_e32 v114, v0
	v_mul_f32_e32 v0, 0xbfb8aa3b, v116
	v_and_b32_e32 v108, 0xffff0000, v188
	v_exp_f32_e32 v116, v0
	v_mul_f32_e32 v0, 0xbfb8aa3b, v115
	v_exp_f32_e32 v118, v0
	v_mul_f32_e32 v0, 0xbfb8aa3b, v108
	v_exp_f32_e32 v108, v0
	v_mul_f32_e32 v0, 0xbfb8aa3b, v117
	v_exp_f32_e32 v115, v0
	v_lshlrev_b32_e32 v120, 16, v189
	v_mul_f32_e32 v0, 0xbfb8aa3b, v120
	v_and_b32_e32 v109, 0xffff0000, v189
	v_exp_f32_e32 v117, v0
	v_mul_f32_e32 v0, 0xbfb8aa3b, v119
	v_exp_f32_e32 v119, v0
	v_mul_f32_e32 v0, 0xbfb8aa3b, v109
	v_pk_add_f32 v[114:115], v[114:115], 1.0 op_sel_hi:[1,0]
	v_exp_f32_e32 v109, v0
	v_pk_add_f32 v[118:119], v[118:119], 1.0 op_sel_hi:[1,0]
	v_pk_add_f32 v[108:109], v[108:109], 1.0 op_sel_hi:[1,0]
	v_rcp_f32_e32 v115, v115
	s_nop 0
	s_waitcnt vmcnt(12)
	v_lshlrev_b32_e32 v121, 16, v191
	v_rcp_f32_e32 v114, v114
	s_nop 0
	v_mov_b32_e32 v122, v102
	v_mov_b32_e32 v123, v104
	v_lshlrev_b32_e32 v120, 16, v190
	v_pk_fma_f32 v[114:115], v[122:123], v[114:115], v[120:121]
	v_rcp_f32_e32 v119, v119
	s_nop 0
	v_and_b32_e32 v111, 0xffff0000, v191
	v_and_b32_e32 v110, 0xffff0000, v190
	v_rcp_f32_e32 v118, v118
	s_nop 0
	v_mov_b32_e32 v104, v103
	v_pk_fma_f32 v[102:103], v[104:105], v[118:119], v[110:111]
	v_cvt_pk_bf16_f32 v0, v114, v115
	v_cvt_pk_bf16_f32 v102, v102, v103
	v_and_b32_e32 v103, 0xffff0000, v102
	v_lshlrev_b32_e32 v102, 16, v102
	v_lshlrev_b32_e32 v105, 16, v193
	v_lshlrev_b32_e32 v104, 16, v192
	v_and_b32_e32 v111, 0xffff0000, v193
	v_and_b32_e32 v110, 0xffff0000, v192
	v_pk_add_f32 v[112:113], v[116:117], 1.0 op_sel_hi:[1,0]
	v_or_b32_sdwa v103, v103, v0 dst_sel:DWORD dst_unused:UNUSED_PAD src0_sel:DWORD src1_sel:WORD_1
	v_or_b32_sdwa v102, v102, v0 dst_sel:DWORD dst_unused:UNUSED_PAD src0_sel:DWORD src1_sel:WORD_0
	s_nop 0
	v_rcp_f32_e32 v113, v113
	s_nop 0
	s_nop 0
	v_rcp_f32_e32 v112, v112
	s_nop 0
	v_mov_b32_e32 v114, v98
	v_mov_b32_e32 v115, v100
	v_pk_fma_f32 v[104:105], v[114:115], v[112:113], v[104:105]
	v_add_u32_e32 v116, 0x2d800, v157
	v_rcp_f32_e32 v109, v109
	s_nop 0
	s_nop 0
	v_rcp_f32_e32 v108, v108
	s_nop 0
	v_mov_b32_e32 v100, v99
	v_pk_fma_f32 v[98:99], v[100:101], v[108:109], v[110:111]
	v_cvt_pk_bf16_f32 v0, v104, v105
	v_cvt_pk_bf16_f32 v98, v98, v99
	v_and_b32_e32 v99, 0xffff0000, v98
	v_lshlrev_b32_e32 v98, 16, v98
	v_or_b32_sdwa v105, v99, v0 dst_sel:DWORD dst_unused:UNUSED_PAD src0_sel:DWORD src1_sel:WORD_1
	v_or_b32_sdwa v104, v98, v0 dst_sel:DWORD dst_unused:UNUSED_PAD src0_sel:DWORD src1_sel:WORD_0
	v_add_u32_e32 v0, v116, v156
	v_add_u32_e32 v212, 0xb6000, v210
	v_lshl_add_u64 v[186:187], v[212:213], 1, s[6:7]
	global_load_dwordx4 v[186:189], v[186:187], off
	v_add_u32_e32 v212, 0x20000, v211
	v_lshl_add_u64 v[190:191], v[212:213], 1, s[10:11]
	global_load_dwordx4 v[190:193], v[190:191], off
	global_store_dwordx4 v[106:107], v[102:105], off
	s_nop 1
	v_or_b32_e32 v102, 32, v159
	v_mul_lo_u32 v117, v102, s61
	v_add_u32_e32 v0, v0, v117
	s_waitcnt vmcnt(14)
	v_lshlrev_b32_e32 v106, 16, v194
	v_and_b32_e32 v107, 0xffff0000, v194
	v_lshlrev_b32_e32 v109, 16, v195
	v_and_b32_e32 v111, 0xffff0000, v195
	v_lshl_add_u64 v[98:99], v[0:1], 1, s[10:11]
	v_lshlrev_b32_e32 v108, 16, v196
	v_mul_f32_e32 v0, 0xbfb8aa3b, v106
	v_exp_f32_e32 v106, v0
	v_mul_f32_e32 v0, 0xbfb8aa3b, v108
	v_and_b32_e32 v100, 0xffff0000, v196
	v_exp_f32_e32 v108, v0
	v_mul_f32_e32 v0, 0xbfb8aa3b, v107
	v_exp_f32_e32 v110, v0
	v_mul_f32_e32 v0, 0xbfb8aa3b, v100
	v_exp_f32_e32 v100, v0
	v_mul_f32_e32 v0, 0xbfb8aa3b, v109
	v_exp_f32_e32 v107, v0
	v_lshlrev_b32_e32 v112, 16, v197
	v_mul_f32_e32 v0, 0xbfb8aa3b, v112
	v_and_b32_e32 v101, 0xffff0000, v197
	v_exp_f32_e32 v109, v0
	v_mul_f32_e32 v0, 0xbfb8aa3b, v111
	v_exp_f32_e32 v111, v0
	v_mul_f32_e32 v0, 0xbfb8aa3b, v101
	v_pk_add_f32 v[106:107], v[106:107], 1.0 op_sel_hi:[1,0]
	v_exp_f32_e32 v101, v0
	v_pk_add_f32 v[110:111], v[110:111], 1.0 op_sel_hi:[1,0]
	v_pk_add_f32 v[100:101], v[100:101], 1.0 op_sel_hi:[1,0]
	v_rcp_f32_e32 v107, v107
	s_nop 0
	s_waitcnt vmcnt(13)
	v_lshlrev_b32_e32 v113, 16, v199
	v_rcp_f32_e32 v106, v106
	s_nop 0
	v_mov_b32_e32 v114, v94
	v_mov_b32_e32 v115, v96
	v_lshlrev_b32_e32 v112, 16, v198
	v_pk_fma_f32 v[106:107], v[114:115], v[106:107], v[112:113]
	v_rcp_f32_e32 v111, v111
	s_nop 0
	v_and_b32_e32 v103, 0xffff0000, v199
	v_and_b32_e32 v102, 0xffff0000, v198
	v_rcp_f32_e32 v110, v110
	s_nop 0
	v_mov_b32_e32 v96, v95
	v_pk_fma_f32 v[94:95], v[96:97], v[110:111], v[102:103]
	v_cvt_pk_bf16_f32 v0, v106, v107
	v_cvt_pk_bf16_f32 v94, v94, v95
	v_and_b32_e32 v95, 0xffff0000, v94
	v_lshlrev_b32_e32 v94, 16, v94
	v_lshlrev_b32_e32 v97, 16, v201
	v_lshlrev_b32_e32 v96, 16, v200
	v_and_b32_e32 v103, 0xffff0000, v201
	v_and_b32_e32 v102, 0xffff0000, v200
	v_pk_add_f32 v[104:105], v[108:109], 1.0 op_sel_hi:[1,0]
	v_or_b32_sdwa v95, v95, v0 dst_sel:DWORD dst_unused:UNUSED_PAD src0_sel:DWORD src1_sel:WORD_1
	v_or_b32_sdwa v94, v94, v0 dst_sel:DWORD dst_unused:UNUSED_PAD src0_sel:DWORD src1_sel:WORD_0
	s_nop 0
	v_rcp_f32_e32 v105, v105
	s_nop 0
	s_nop 0
	v_rcp_f32_e32 v104, v104
	s_nop 0
	v_mov_b32_e32 v106, v90
	v_mov_b32_e32 v107, v92
	v_pk_fma_f32 v[96:97], v[106:107], v[104:105], v[96:97]
	v_rcp_f32_e32 v101, v101
	s_nop 0
	s_nop 0
	v_rcp_f32_e32 v100, v100
	s_nop 0
	v_mov_b32_e32 v92, v91
	v_pk_fma_f32 v[90:91], v[92:93], v[100:101], v[102:103]
	v_cvt_pk_bf16_f32 v0, v96, v97
	v_cvt_pk_bf16_f32 v90, v90, v91
	v_and_b32_e32 v91, 0xffff0000, v90
	v_lshlrev_b32_e32 v90, 16, v90
	v_or_b32_sdwa v97, v91, v0 dst_sel:DWORD dst_unused:UNUSED_PAD src0_sel:DWORD src1_sel:WORD_1
	v_or_b32_sdwa v96, v90, v0 dst_sel:DWORD dst_unused:UNUSED_PAD src0_sel:DWORD src1_sel:WORD_0
	v_add_u32_e32 v0, v116, v126
	v_add_u32_e32 v212, 0xb6080, v210
	v_lshl_add_u64 v[194:195], v[212:213], 1, s[6:7]
	global_load_dwordx4 v[194:197], v[194:195], off
	v_add_u32_e32 v212, 0x20080, v211
	v_lshl_add_u64 v[198:199], v[212:213], 1, s[10:11]
	global_load_dwordx4 v[198:201], v[198:199], off
	global_store_dwordx4 v[98:99], v[94:97], off
	v_add_u32_e32 v0, v0, v117
	s_waitcnt vmcnt(15)
	v_lshlrev_b32_e32 v98, 16, v202
	v_and_b32_e32 v99, 0xffff0000, v202
	v_lshlrev_b32_e32 v101, 16, v203
	v_and_b32_e32 v103, 0xffff0000, v203
	v_lshl_add_u64 v[90:91], v[0:1], 1, s[10:11]
	v_lshlrev_b32_e32 v100, 16, v204
	v_mul_f32_e32 v0, 0xbfb8aa3b, v98
	v_exp_f32_e32 v98, v0
	v_mul_f32_e32 v0, 0xbfb8aa3b, v100
	v_and_b32_e32 v92, 0xffff0000, v204
	v_exp_f32_e32 v100, v0
	v_mul_f32_e32 v0, 0xbfb8aa3b, v99
	v_exp_f32_e32 v102, v0
	v_mul_f32_e32 v0, 0xbfb8aa3b, v92
	v_exp_f32_e32 v92, v0
	v_mul_f32_e32 v0, 0xbfb8aa3b, v101
	v_exp_f32_e32 v99, v0
	v_lshlrev_b32_e32 v104, 16, v205
	v_mul_f32_e32 v0, 0xbfb8aa3b, v104
	v_and_b32_e32 v93, 0xffff0000, v205
	v_exp_f32_e32 v101, v0
	v_mul_f32_e32 v0, 0xbfb8aa3b, v103
	v_exp_f32_e32 v103, v0
	v_mul_f32_e32 v0, 0xbfb8aa3b, v93
	v_pk_add_f32 v[98:99], v[98:99], 1.0 op_sel_hi:[1,0]
	v_exp_f32_e32 v93, v0
	v_pk_add_f32 v[102:103], v[102:103], 1.0 op_sel_hi:[1,0]
	v_pk_add_f32 v[92:93], v[92:93], 1.0 op_sel_hi:[1,0]
	v_rcp_f32_e32 v99, v99
	s_nop 0
	s_waitcnt vmcnt(14)
	v_lshlrev_b32_e32 v105, 16, v207
	v_rcp_f32_e32 v98, v98
	s_nop 0
	v_mov_b32_e32 v106, v86
	v_mov_b32_e32 v107, v88
	v_lshlrev_b32_e32 v104, 16, v206
	v_pk_fma_f32 v[98:99], v[106:107], v[98:99], v[104:105]
	v_rcp_f32_e32 v103, v103
	s_nop 0
	v_and_b32_e32 v95, 0xffff0000, v207
	v_and_b32_e32 v94, 0xffff0000, v206
	v_rcp_f32_e32 v102, v102
	s_nop 0
	v_mov_b32_e32 v88, v87
	v_pk_fma_f32 v[86:87], v[88:89], v[102:103], v[94:95]
	v_cvt_pk_bf16_f32 v0, v98, v99
	v_cvt_pk_bf16_f32 v86, v86, v87
	v_and_b32_e32 v87, 0xffff0000, v86
	v_lshlrev_b32_e32 v86, 16, v86
	v_lshlrev_b32_e32 v89, 16, v209
	v_lshlrev_b32_e32 v88, 16, v208
	v_and_b32_e32 v95, 0xffff0000, v209
	v_and_b32_e32 v94, 0xffff0000, v208
	v_pk_add_f32 v[96:97], v[100:101], 1.0 op_sel_hi:[1,0]
	v_or_b32_sdwa v87, v87, v0 dst_sel:DWORD dst_unused:UNUSED_PAD src0_sel:DWORD src1_sel:WORD_1
	v_or_b32_sdwa v86, v86, v0 dst_sel:DWORD dst_unused:UNUSED_PAD src0_sel:DWORD src1_sel:WORD_0
	s_nop 0
	v_rcp_f32_e32 v97, v97
	s_nop 0
	s_nop 0
	v_rcp_f32_e32 v96, v96
	s_nop 0
	v_mov_b32_e32 v98, v82
	v_mov_b32_e32 v99, v84
	v_pk_fma_f32 v[88:89], v[98:99], v[96:97], v[88:89]
	v_add_u32_e32 v100, 0x44400, v157
	v_rcp_f32_e32 v93, v93
	s_nop 0
	s_nop 0
	v_rcp_f32_e32 v92, v92
	s_nop 0
	v_mov_b32_e32 v84, v83
	v_pk_fma_f32 v[82:83], v[84:85], v[92:93], v[94:95]
	v_cvt_pk_bf16_f32 v0, v88, v89
	v_cvt_pk_bf16_f32 v82, v82, v83
	v_and_b32_e32 v83, 0xffff0000, v82
	v_lshlrev_b32_e32 v82, 16, v82
	v_or_b32_sdwa v89, v83, v0 dst_sel:DWORD dst_unused:UNUSED_PAD src0_sel:DWORD src1_sel:WORD_1
	v_or_b32_sdwa v88, v82, v0 dst_sel:DWORD dst_unused:UNUSED_PAD src0_sel:DWORD src1_sel:WORD_0
	v_add_u32_e32 v0, v100, v156
	v_add_u32_e32 v212, 0xccc00, v210
	v_lshl_add_u64 v[202:203], v[212:213], 1, s[6:7]
	global_load_dwordx4 v[202:205], v[202:203], off
	v_add_u32_e32 v212, 0x24000, v211
	v_lshl_add_u64 v[206:207], v[212:213], 1, s[10:11]
	global_load_dwordx4 v[206:209], v[206:207], off
	global_store_dwordx4 v[90:91], v[86:89], off
	s_nop 1
	v_or_b32_e32 v86, 48, v159
	v_mul_lo_u32 v101, v86, s61
	v_add_u32_e32 v0, v0, v101
	s_waitcnt vmcnt(14)
	v_lshlrev_b32_e32 v90, 16, v168
	v_and_b32_e32 v91, 0xffff0000, v168
	v_lshlrev_b32_e32 v93, 16, v169
	v_and_b32_e32 v95, 0xffff0000, v169
	v_lshl_add_u64 v[82:83], v[0:1], 1, s[10:11]
	v_lshlrev_b32_e32 v92, 16, v170
	v_mul_f32_e32 v0, 0xbfb8aa3b, v90
	v_exp_f32_e32 v90, v0
	v_mul_f32_e32 v0, 0xbfb8aa3b, v92
	v_and_b32_e32 v84, 0xffff0000, v170
	v_exp_f32_e32 v92, v0
	v_mul_f32_e32 v0, 0xbfb8aa3b, v91
	v_exp_f32_e32 v94, v0
	v_mul_f32_e32 v0, 0xbfb8aa3b, v84
	v_exp_f32_e32 v84, v0
	v_mul_f32_e32 v0, 0xbfb8aa3b, v93
	v_exp_f32_e32 v91, v0
	v_lshlrev_b32_e32 v96, 16, v171
	v_mul_f32_e32 v0, 0xbfb8aa3b, v96
	v_and_b32_e32 v85, 0xffff0000, v171
	v_exp_f32_e32 v93, v0
	v_mul_f32_e32 v0, 0xbfb8aa3b, v95
	v_exp_f32_e32 v95, v0
	v_mul_f32_e32 v0, 0xbfb8aa3b, v85
	v_pk_add_f32 v[90:91], v[90:91], 1.0 op_sel_hi:[1,0]
	v_exp_f32_e32 v85, v0
	v_pk_add_f32 v[94:95], v[94:95], 1.0 op_sel_hi:[1,0]
	v_pk_add_f32 v[84:85], v[84:85], 1.0 op_sel_hi:[1,0]
	v_rcp_f32_e32 v91, v91
	s_nop 0
	s_waitcnt vmcnt(13)
	v_lshlrev_b32_e32 v97, 16, v173
	v_rcp_f32_e32 v90, v90
	s_nop 0
	v_mov_b32_e32 v98, v78
	v_mov_b32_e32 v99, v80
	v_lshlrev_b32_e32 v96, 16, v172
	v_pk_fma_f32 v[90:91], v[98:99], v[90:91], v[96:97]
	v_rcp_f32_e32 v95, v95
	s_nop 0
	v_and_b32_e32 v87, 0xffff0000, v173
	v_and_b32_e32 v86, 0xffff0000, v172
	v_rcp_f32_e32 v94, v94
	s_nop 0
	v_mov_b32_e32 v80, v79
	v_pk_fma_f32 v[78:79], v[80:81], v[94:95], v[86:87]
	v_cvt_pk_bf16_f32 v0, v90, v91
	v_cvt_pk_bf16_f32 v78, v78, v79
	v_and_b32_e32 v79, 0xffff0000, v78
	v_lshlrev_b32_e32 v78, 16, v78
	v_lshlrev_b32_e32 v81, 16, v175
	v_lshlrev_b32_e32 v80, 16, v174
	v_and_b32_e32 v87, 0xffff0000, v175
	v_and_b32_e32 v86, 0xffff0000, v174
	v_pk_add_f32 v[88:89], v[92:93], 1.0 op_sel_hi:[1,0]
	v_or_b32_sdwa v79, v79, v0 dst_sel:DWORD dst_unused:UNUSED_PAD src0_sel:DWORD src1_sel:WORD_1
	v_or_b32_sdwa v78, v78, v0 dst_sel:DWORD dst_unused:UNUSED_PAD src0_sel:DWORD src1_sel:WORD_0
	s_nop 0
	v_rcp_f32_e32 v89, v89
	s_nop 0
	s_nop 0
	v_rcp_f32_e32 v88, v88
	s_nop 0
	v_mov_b32_e32 v90, v74
	v_mov_b32_e32 v91, v76
	v_pk_fma_f32 v[80:81], v[90:91], v[88:89], v[80:81]
	v_rcp_f32_e32 v85, v85
	s_nop 0
	s_nop 0
	v_rcp_f32_e32 v84, v84
	s_nop 0
	v_mov_b32_e32 v76, v75
	v_pk_fma_f32 v[74:75], v[76:77], v[84:85], v[86:87]
	v_cvt_pk_bf16_f32 v0, v80, v81
	v_cvt_pk_bf16_f32 v74, v74, v75
	v_and_b32_e32 v75, 0xffff0000, v74
	v_lshlrev_b32_e32 v74, 16, v74
	v_or_b32_sdwa v81, v75, v0 dst_sel:DWORD dst_unused:UNUSED_PAD src0_sel:DWORD src1_sel:WORD_1
	v_or_b32_sdwa v80, v74, v0 dst_sel:DWORD dst_unused:UNUSED_PAD src0_sel:DWORD src1_sel:WORD_0
	v_add_u32_e32 v0, v100, v126
	v_add_u32_e32 v212, 0xccc80, v210
	v_lshl_add_u64 v[168:169], v[212:213], 1, s[6:7]
	global_load_dwordx4 v[168:171], v[168:169], off
	v_add_u32_e32 v212, 0x24080, v211
	v_lshl_add_u64 v[172:173], v[212:213], 1, s[10:11]
	global_load_dwordx4 v[172:175], v[172:173], off
	global_store_dwordx4 v[82:83], v[78:81], off
	v_add_u32_e32 v0, v0, v101
	s_waitcnt vmcnt(14)
	v_lshlrev_b32_e32 v82, 16, v176
	v_and_b32_e32 v83, 0xffff0000, v176
	v_lshlrev_b32_e32 v85, 16, v177
	v_and_b32_e32 v87, 0xffff0000, v177
	v_lshl_add_u64 v[74:75], v[0:1], 1, s[10:11]
	v_lshlrev_b32_e32 v84, 16, v178
	v_mul_f32_e32 v0, 0xbfb8aa3b, v82
	v_exp_f32_e32 v82, v0
	v_mul_f32_e32 v0, 0xbfb8aa3b, v84
	v_and_b32_e32 v76, 0xffff0000, v178
	v_exp_f32_e32 v84, v0
	v_mul_f32_e32 v0, 0xbfb8aa3b, v83
	v_exp_f32_e32 v86, v0
	v_mul_f32_e32 v0, 0xbfb8aa3b, v76
	v_exp_f32_e32 v76, v0
	v_mul_f32_e32 v0, 0xbfb8aa3b, v85
	v_exp_f32_e32 v83, v0
	v_lshlrev_b32_e32 v88, 16, v179
	v_mul_f32_e32 v0, 0xbfb8aa3b, v88
	v_and_b32_e32 v77, 0xffff0000, v179
	v_exp_f32_e32 v85, v0
	v_mul_f32_e32 v0, 0xbfb8aa3b, v87
	v_exp_f32_e32 v87, v0
	v_mul_f32_e32 v0, 0xbfb8aa3b, v77
	v_pk_add_f32 v[82:83], v[82:83], 1.0 op_sel_hi:[1,0]
	v_exp_f32_e32 v77, v0
	v_pk_add_f32 v[86:87], v[86:87], 1.0 op_sel_hi:[1,0]
	v_pk_add_f32 v[76:77], v[76:77], 1.0 op_sel_hi:[1,0]
	v_rcp_f32_e32 v83, v83
	s_nop 0
	s_waitcnt vmcnt(13)
	v_lshlrev_b32_e32 v89, 16, v183
	v_rcp_f32_e32 v82, v82
	s_nop 0
	v_mov_b32_e32 v90, v70
	v_mov_b32_e32 v91, v72
	v_lshlrev_b32_e32 v88, 16, v182
	v_pk_fma_f32 v[82:83], v[90:91], v[82:83], v[88:89]
	v_rcp_f32_e32 v87, v87
	s_nop 0
	v_and_b32_e32 v79, 0xffff0000, v183
	v_and_b32_e32 v78, 0xffff0000, v182
	v_rcp_f32_e32 v86, v86
	s_nop 0
	v_mov_b32_e32 v72, v71
	v_pk_fma_f32 v[70:71], v[72:73], v[86:87], v[78:79]
	v_cvt_pk_bf16_f32 v0, v82, v83
	v_cvt_pk_bf16_f32 v70, v70, v71
	v_and_b32_e32 v71, 0xffff0000, v70
	v_lshlrev_b32_e32 v70, 16, v70
	v_lshlrev_b32_e32 v73, 16, v185
	v_lshlrev_b32_e32 v72, 16, v184
	v_and_b32_e32 v79, 0xffff0000, v185
	v_and_b32_e32 v78, 0xffff0000, v184
	v_pk_add_f32 v[80:81], v[84:85], 1.0 op_sel_hi:[1,0]
	v_or_b32_sdwa v71, v71, v0 dst_sel:DWORD dst_unused:UNUSED_PAD src0_sel:DWORD src1_sel:WORD_1
	v_or_b32_sdwa v70, v70, v0 dst_sel:DWORD dst_unused:UNUSED_PAD src0_sel:DWORD src1_sel:WORD_0
	s_nop 0
	v_rcp_f32_e32 v81, v81
	s_nop 0
	s_nop 0
	v_rcp_f32_e32 v80, v80
	s_nop 0
	v_mov_b32_e32 v82, v66
	v_mov_b32_e32 v83, v68
	v_pk_fma_f32 v[72:73], v[82:83], v[80:81], v[72:73]
	v_add_u32_e32 v84, 0xb6000, v157
	v_rcp_f32_e32 v77, v77
	s_nop 0
	v_add_u32_e32 v85, 0xfff6a000, v158
	v_rcp_f32_e32 v76, v76
	s_nop 0
	v_mov_b32_e32 v68, v67
	v_pk_fma_f32 v[66:67], v[68:69], v[76:77], v[78:79]
	v_cvt_pk_bf16_f32 v0, v72, v73
	v_cvt_pk_bf16_f32 v66, v66, v67
	v_and_b32_e32 v67, 0xffff0000, v66
	v_lshlrev_b32_e32 v66, 16, v66
	v_or_b32_sdwa v73, v67, v0 dst_sel:DWORD dst_unused:UNUSED_PAD src0_sel:DWORD src1_sel:WORD_1
	v_or_b32_sdwa v72, v66, v0 dst_sel:DWORD dst_unused:UNUSED_PAD src0_sel:DWORD src1_sel:WORD_0
	v_add_u32_e32 v0, v84, v156
	v_add_u32_e32 v212, 0xe3800, v210
	v_lshl_add_u64 v[176:177], v[212:213], 1, s[6:7]
	global_load_dwordx4 v[176:179], v[176:177], off
	v_add_u32_e32 v212, 0x28000, v211
	v_lshl_add_u64 v[182:183], v[212:213], 1, s[10:11]
	global_load_dwordx4 v[182:185], v[182:183], off
	global_store_dwordx4 v[74:75], v[70:73], off
	v_add_u32_e32 v0, v0, v85
	s_waitcnt vmcnt(14)
	v_lshlrev_b32_e32 v74, 16, v186
	v_and_b32_e32 v75, 0xffff0000, v186
	v_lshlrev_b32_e32 v77, 16, v187
	v_and_b32_e32 v79, 0xffff0000, v187
	v_lshl_add_u64 v[66:67], v[0:1], 1, s[10:11]
	v_lshlrev_b32_e32 v76, 16, v188
	v_mul_f32_e32 v0, 0xbfb8aa3b, v74
	v_exp_f32_e32 v74, v0
	v_mul_f32_e32 v0, 0xbfb8aa3b, v76
	v_and_b32_e32 v68, 0xffff0000, v188
	v_exp_f32_e32 v76, v0
	v_mul_f32_e32 v0, 0xbfb8aa3b, v75
	v_exp_f32_e32 v78, v0
	v_mul_f32_e32 v0, 0xbfb8aa3b, v68
	v_exp_f32_e32 v68, v0
	v_mul_f32_e32 v0, 0xbfb8aa3b, v77
	v_exp_f32_e32 v75, v0
	v_lshlrev_b32_e32 v80, 16, v189
	v_mul_f32_e32 v0, 0xbfb8aa3b, v80
	v_and_b32_e32 v69, 0xffff0000, v189
	v_exp_f32_e32 v77, v0
	v_mul_f32_e32 v0, 0xbfb8aa3b, v79
	v_exp_f32_e32 v79, v0
	v_mul_f32_e32 v0, 0xbfb8aa3b, v69
	v_pk_add_f32 v[74:75], v[74:75], 1.0 op_sel_hi:[1,0]
	v_exp_f32_e32 v69, v0
	v_pk_add_f32 v[78:79], v[78:79], 1.0 op_sel_hi:[1,0]
	v_pk_add_f32 v[68:69], v[68:69], 1.0 op_sel_hi:[1,0]
	v_rcp_f32_e32 v75, v75
	s_nop 0
	s_waitcnt vmcnt(13)
	v_lshlrev_b32_e32 v81, 16, v191
	v_rcp_f32_e32 v74, v74
	s_nop 0
	v_mov_b32_e32 v82, v62
	v_mov_b32_e32 v83, v64
	v_lshlrev_b32_e32 v80, 16, v190
	v_pk_fma_f32 v[74:75], v[82:83], v[74:75], v[80:81]
	v_rcp_f32_e32 v79, v79
	s_nop 0
	v_and_b32_e32 v71, 0xffff0000, v191
	v_and_b32_e32 v70, 0xffff0000, v190
	v_rcp_f32_e32 v78, v78
	s_nop 0
	v_mov_b32_e32 v64, v63
	v_pk_fma_f32 v[62:63], v[64:65], v[78:79], v[70:71]
	v_cvt_pk_bf16_f32 v0, v74, v75
	v_cvt_pk_bf16_f32 v62, v62, v63
	v_and_b32_e32 v63, 0xffff0000, v62
	v_lshlrev_b32_e32 v62, 16, v62
	v_lshlrev_b32_e32 v65, 16, v193
	v_lshlrev_b32_e32 v64, 16, v192
	v_and_b32_e32 v71, 0xffff0000, v193
	v_and_b32_e32 v70, 0xffff0000, v192
	v_pk_add_f32 v[72:73], v[76:77], 1.0 op_sel_hi:[1,0]
	v_or_b32_sdwa v63, v63, v0 dst_sel:DWORD dst_unused:UNUSED_PAD src0_sel:DWORD src1_sel:WORD_1
	v_or_b32_sdwa v62, v62, v0 dst_sel:DWORD dst_unused:UNUSED_PAD src0_sel:DWORD src1_sel:WORD_0
	s_nop 0
	v_rcp_f32_e32 v73, v73
	s_nop 0
	s_nop 0
	v_rcp_f32_e32 v72, v72
	s_nop 0
	v_mov_b32_e32 v74, v58
	v_mov_b32_e32 v75, v60
	v_pk_fma_f32 v[64:65], v[74:75], v[72:73], v[64:65]
	v_rcp_f32_e32 v69, v69
	s_nop 0
	s_nop 0
	v_rcp_f32_e32 v68, v68
	s_nop 0
	v_mov_b32_e32 v60, v59
	v_pk_fma_f32 v[58:59], v[60:61], v[68:69], v[70:71]
	v_cvt_pk_bf16_f32 v0, v64, v65
	v_cvt_pk_bf16_f32 v58, v58, v59
	v_and_b32_e32 v59, 0xffff0000, v58
	v_lshlrev_b32_e32 v58, 16, v58
	v_or_b32_sdwa v65, v59, v0 dst_sel:DWORD dst_unused:UNUSED_PAD src0_sel:DWORD src1_sel:WORD_1
	v_or_b32_sdwa v64, v58, v0 dst_sel:DWORD dst_unused:UNUSED_PAD src0_sel:DWORD src1_sel:WORD_0
	v_add_u32_e32 v0, v84, v126
	v_add_u32_e32 v212, 0xe3880, v210
	v_lshl_add_u64 v[186:187], v[212:213], 1, s[6:7]
	global_load_dwordx4 v[186:189], v[186:187], off
	v_add_u32_e32 v212, 0x28080, v211
	v_lshl_add_u64 v[190:191], v[212:213], 1, s[10:11]
	global_load_dwordx4 v[190:193], v[190:191], off
	global_store_dwordx4 v[66:67], v[62:65], off
	v_add_u32_e32 v0, v0, v85
	s_waitcnt vmcnt(14)
	v_lshlrev_b32_e32 v66, 16, v194
	v_and_b32_e32 v67, 0xffff0000, v194
	v_lshlrev_b32_e32 v69, 16, v195
	v_and_b32_e32 v71, 0xffff0000, v195
	v_lshl_add_u64 v[58:59], v[0:1], 1, s[10:11]
	v_lshlrev_b32_e32 v68, 16, v196
	v_mul_f32_e32 v0, 0xbfb8aa3b, v66
	v_exp_f32_e32 v66, v0
	v_mul_f32_e32 v0, 0xbfb8aa3b, v68
	v_and_b32_e32 v60, 0xffff0000, v196
	v_exp_f32_e32 v68, v0
	v_mul_f32_e32 v0, 0xbfb8aa3b, v67
	v_exp_f32_e32 v70, v0
	v_mul_f32_e32 v0, 0xbfb8aa3b, v60
	v_exp_f32_e32 v60, v0
	v_mul_f32_e32 v0, 0xbfb8aa3b, v69
	v_exp_f32_e32 v67, v0
	v_lshlrev_b32_e32 v72, 16, v197
	v_mul_f32_e32 v0, 0xbfb8aa3b, v72
	v_and_b32_e32 v61, 0xffff0000, v197
	v_exp_f32_e32 v69, v0
	v_mul_f32_e32 v0, 0xbfb8aa3b, v71
	v_exp_f32_e32 v71, v0
	v_mul_f32_e32 v0, 0xbfb8aa3b, v61
	v_pk_add_f32 v[66:67], v[66:67], 1.0 op_sel_hi:[1,0]
	v_exp_f32_e32 v61, v0
	v_pk_add_f32 v[70:71], v[70:71], 1.0 op_sel_hi:[1,0]
	v_pk_add_f32 v[60:61], v[60:61], 1.0 op_sel_hi:[1,0]
	v_rcp_f32_e32 v67, v67
	s_nop 0
	s_waitcnt vmcnt(13)
	v_lshlrev_b32_e32 v73, 16, v199
	v_rcp_f32_e32 v66, v66
	s_nop 0
	v_mov_b32_e32 v74, v54
	v_mov_b32_e32 v75, v56
	v_lshlrev_b32_e32 v72, 16, v198
	v_pk_fma_f32 v[66:67], v[74:75], v[66:67], v[72:73]
	v_rcp_f32_e32 v71, v71
	s_nop 0
	v_and_b32_e32 v63, 0xffff0000, v199
	v_and_b32_e32 v62, 0xffff0000, v198
	v_rcp_f32_e32 v70, v70
	s_nop 0
	v_mov_b32_e32 v56, v55
	v_pk_fma_f32 v[54:55], v[56:57], v[70:71], v[62:63]
	v_cvt_pk_bf16_f32 v0, v66, v67
	v_cvt_pk_bf16_f32 v54, v54, v55
	v_and_b32_e32 v55, 0xffff0000, v54
	v_lshlrev_b32_e32 v54, 16, v54
	v_lshlrev_b32_e32 v57, 16, v201
	v_lshlrev_b32_e32 v56, 16, v200
	v_and_b32_e32 v63, 0xffff0000, v201
	v_and_b32_e32 v62, 0xffff0000, v200
	v_pk_add_f32 v[64:65], v[68:69], 1.0 op_sel_hi:[1,0]
	v_or_b32_sdwa v55, v55, v0 dst_sel:DWORD dst_unused:UNUSED_PAD src0_sel:DWORD src1_sel:WORD_1
	v_or_b32_sdwa v54, v54, v0 dst_sel:DWORD dst_unused:UNUSED_PAD src0_sel:DWORD src1_sel:WORD_0
	s_nop 0
	v_rcp_f32_e32 v65, v65
	s_nop 0
	s_nop 0
	v_rcp_f32_e32 v64, v64
	s_nop 0
	v_mov_b32_e32 v66, v50
	v_mov_b32_e32 v67, v52
	v_pk_fma_f32 v[56:57], v[66:67], v[64:65], v[56:57]
	v_add_u32_e32 v68, 0xccc00, v157
	v_rcp_f32_e32 v61, v61
	s_nop 0
	v_add_u32_e32 v69, 0xfff57400, v158
	v_rcp_f32_e32 v60, v60
	s_nop 0
	v_mov_b32_e32 v52, v51
	v_pk_fma_f32 v[50:51], v[52:53], v[60:61], v[62:63]
	v_cvt_pk_bf16_f32 v0, v56, v57
	v_cvt_pk_bf16_f32 v50, v50, v51
	v_and_b32_e32 v51, 0xffff0000, v50
	v_lshlrev_b32_e32 v50, 16, v50
	v_or_b32_sdwa v57, v51, v0 dst_sel:DWORD dst_unused:UNUSED_PAD src0_sel:DWORD src1_sel:WORD_1
	v_or_b32_sdwa v56, v50, v0 dst_sel:DWORD dst_unused:UNUSED_PAD src0_sel:DWORD src1_sel:WORD_0
	v_add_u32_e32 v0, v68, v156
	v_add_u32_e32 v212, 0xfa400, v210
	v_lshl_add_u64 v[194:195], v[212:213], 1, s[6:7]
	global_load_dwordx4 v[194:197], v[194:195], off
	v_add_u32_e32 v212, 0x2c000, v211
	v_lshl_add_u64 v[198:199], v[212:213], 1, s[10:11]
	global_load_dwordx4 v[198:201], v[198:199], off
	global_store_dwordx4 v[58:59], v[54:57], off
	v_add_u32_e32 v0, v0, v69
	s_waitcnt vmcnt(14)
	v_lshlrev_b32_e32 v58, 16, v202
	v_and_b32_e32 v59, 0xffff0000, v202
	v_lshlrev_b32_e32 v61, 16, v203
	v_and_b32_e32 v63, 0xffff0000, v203
	v_lshl_add_u64 v[50:51], v[0:1], 1, s[10:11]
	v_lshlrev_b32_e32 v60, 16, v204
	v_mul_f32_e32 v0, 0xbfb8aa3b, v58
	v_exp_f32_e32 v58, v0
	v_mul_f32_e32 v0, 0xbfb8aa3b, v60
	v_and_b32_e32 v52, 0xffff0000, v204
	v_exp_f32_e32 v60, v0
	v_mul_f32_e32 v0, 0xbfb8aa3b, v59
	v_exp_f32_e32 v62, v0
	v_mul_f32_e32 v0, 0xbfb8aa3b, v52
	v_exp_f32_e32 v52, v0
	v_mul_f32_e32 v0, 0xbfb8aa3b, v61
	v_exp_f32_e32 v59, v0
	v_lshlrev_b32_e32 v64, 16, v205
	v_mul_f32_e32 v0, 0xbfb8aa3b, v64
	v_and_b32_e32 v53, 0xffff0000, v205
	v_exp_f32_e32 v61, v0
	v_mul_f32_e32 v0, 0xbfb8aa3b, v63
	v_exp_f32_e32 v63, v0
	v_mul_f32_e32 v0, 0xbfb8aa3b, v53
	v_pk_add_f32 v[58:59], v[58:59], 1.0 op_sel_hi:[1,0]
	v_exp_f32_e32 v53, v0
	v_pk_add_f32 v[62:63], v[62:63], 1.0 op_sel_hi:[1,0]
	v_pk_add_f32 v[52:53], v[52:53], 1.0 op_sel_hi:[1,0]
	v_rcp_f32_e32 v59, v59
	s_nop 0
	s_waitcnt vmcnt(13)
	v_lshlrev_b32_e32 v65, 16, v207
	v_rcp_f32_e32 v58, v58
	s_nop 0
	v_mov_b32_e32 v66, v46
	v_mov_b32_e32 v67, v48
	v_lshlrev_b32_e32 v64, 16, v206
	v_pk_fma_f32 v[58:59], v[66:67], v[58:59], v[64:65]
	v_rcp_f32_e32 v63, v63
	s_nop 0
	v_and_b32_e32 v55, 0xffff0000, v207
	v_and_b32_e32 v54, 0xffff0000, v206
	v_rcp_f32_e32 v62, v62
	s_nop 0
	v_mov_b32_e32 v48, v47
	v_pk_fma_f32 v[46:47], v[48:49], v[62:63], v[54:55]
	v_cvt_pk_bf16_f32 v0, v58, v59
	v_cvt_pk_bf16_f32 v46, v46, v47
	v_and_b32_e32 v47, 0xffff0000, v46
	v_lshlrev_b32_e32 v46, 16, v46
	v_lshlrev_b32_e32 v49, 16, v209
	v_lshlrev_b32_e32 v48, 16, v208
	v_and_b32_e32 v55, 0xffff0000, v209
	v_and_b32_e32 v54, 0xffff0000, v208
	v_pk_add_f32 v[56:57], v[60:61], 1.0 op_sel_hi:[1,0]
	v_or_b32_sdwa v47, v47, v0 dst_sel:DWORD dst_unused:UNUSED_PAD src0_sel:DWORD src1_sel:WORD_1
	v_or_b32_sdwa v46, v46, v0 dst_sel:DWORD dst_unused:UNUSED_PAD src0_sel:DWORD src1_sel:WORD_0
	s_nop 0
	v_rcp_f32_e32 v57, v57
	s_nop 0
	s_nop 0
	v_rcp_f32_e32 v56, v56
	s_nop 0
	v_mov_b32_e32 v58, v42
	v_mov_b32_e32 v59, v44
	v_pk_fma_f32 v[48:49], v[58:59], v[56:57], v[48:49]
	v_rcp_f32_e32 v53, v53
	s_nop 0
	s_nop 0
	v_rcp_f32_e32 v52, v52
	s_nop 0
	v_mov_b32_e32 v44, v43
	v_pk_fma_f32 v[42:43], v[44:45], v[52:53], v[54:55]
	v_cvt_pk_bf16_f32 v0, v48, v49
	v_cvt_pk_bf16_f32 v42, v42, v43
	v_and_b32_e32 v43, 0xffff0000, v42
	v_lshlrev_b32_e32 v42, 16, v42
	v_or_b32_sdwa v49, v43, v0 dst_sel:DWORD dst_unused:UNUSED_PAD src0_sel:DWORD src1_sel:WORD_1
	v_or_b32_sdwa v48, v42, v0 dst_sel:DWORD dst_unused:UNUSED_PAD src0_sel:DWORD src1_sel:WORD_0
	v_add_u32_e32 v0, v68, v126
	v_add_u32_e32 v212, 0xfa480, v210
	v_lshl_add_u64 v[202:203], v[212:213], 1, s[6:7]
	global_load_dwordx4 v[202:205], v[202:203], off
	v_add_u32_e32 v212, 0x2c080, v211
	v_lshl_add_u64 v[206:207], v[212:213], 1, s[10:11]
	global_load_dwordx4 v[206:209], v[206:207], off
	global_store_dwordx4 v[50:51], v[46:49], off
	v_add_u32_e32 v0, v0, v69
	s_waitcnt vmcnt(14)
	v_lshlrev_b32_e32 v50, 16, v168
	v_and_b32_e32 v51, 0xffff0000, v168
	v_lshlrev_b32_e32 v53, 16, v169
	v_and_b32_e32 v55, 0xffff0000, v169
	v_lshl_add_u64 v[42:43], v[0:1], 1, s[10:11]
	v_lshlrev_b32_e32 v52, 16, v170
	v_mul_f32_e32 v0, 0xbfb8aa3b, v50
	v_exp_f32_e32 v50, v0
	v_mul_f32_e32 v0, 0xbfb8aa3b, v52
	v_and_b32_e32 v44, 0xffff0000, v170
	v_exp_f32_e32 v52, v0
	v_mul_f32_e32 v0, 0xbfb8aa3b, v51
	v_exp_f32_e32 v54, v0
	v_mul_f32_e32 v0, 0xbfb8aa3b, v44
	v_exp_f32_e32 v44, v0
	v_mul_f32_e32 v0, 0xbfb8aa3b, v53
	v_exp_f32_e32 v51, v0
	v_lshlrev_b32_e32 v56, 16, v171
	v_mul_f32_e32 v0, 0xbfb8aa3b, v56
	v_and_b32_e32 v45, 0xffff0000, v171
	v_exp_f32_e32 v53, v0
	v_mul_f32_e32 v0, 0xbfb8aa3b, v55
	v_exp_f32_e32 v55, v0
	v_mul_f32_e32 v0, 0xbfb8aa3b, v45
	v_pk_add_f32 v[50:51], v[50:51], 1.0 op_sel_hi:[1,0]
	v_exp_f32_e32 v45, v0
	v_pk_add_f32 v[54:55], v[54:55], 1.0 op_sel_hi:[1,0]
	v_pk_add_f32 v[44:45], v[44:45], 1.0 op_sel_hi:[1,0]
	v_rcp_f32_e32 v51, v51
	s_nop 0
	s_waitcnt vmcnt(13)
	v_lshlrev_b32_e32 v57, 16, v173
	v_rcp_f32_e32 v50, v50
	s_nop 0
	v_mov_b32_e32 v58, v38
	v_mov_b32_e32 v59, v40
	v_lshlrev_b32_e32 v56, 16, v172
	v_pk_fma_f32 v[50:51], v[58:59], v[50:51], v[56:57]
	v_rcp_f32_e32 v55, v55
	s_nop 0
	v_and_b32_e32 v47, 0xffff0000, v173
	v_and_b32_e32 v46, 0xffff0000, v172
	v_rcp_f32_e32 v54, v54
	s_nop 0
	v_mov_b32_e32 v40, v39
	v_pk_fma_f32 v[38:39], v[40:41], v[54:55], v[46:47]
	v_cvt_pk_bf16_f32 v0, v50, v51
	v_cvt_pk_bf16_f32 v38, v38, v39
	v_and_b32_e32 v39, 0xffff0000, v38
	v_lshlrev_b32_e32 v38, 16, v38
	v_lshlrev_b32_e32 v41, 16, v175
	v_lshlrev_b32_e32 v40, 16, v174
	v_and_b32_e32 v47, 0xffff0000, v175
	v_and_b32_e32 v46, 0xffff0000, v174
	v_pk_add_f32 v[48:49], v[52:53], 1.0 op_sel_hi:[1,0]
	v_or_b32_sdwa v39, v39, v0 dst_sel:DWORD dst_unused:UNUSED_PAD src0_sel:DWORD src1_sel:WORD_1
	v_or_b32_sdwa v38, v38, v0 dst_sel:DWORD dst_unused:UNUSED_PAD src0_sel:DWORD src1_sel:WORD_0
	s_nop 0
	v_rcp_f32_e32 v49, v49
	s_nop 0
	s_nop 0
	v_rcp_f32_e32 v48, v48
	s_nop 0
	v_mov_b32_e32 v50, v34
	v_mov_b32_e32 v51, v36
	v_pk_fma_f32 v[40:41], v[50:51], v[48:49], v[40:41]
	v_add_u32_e32 v52, 0xe3800, v157
	v_rcp_f32_e32 v45, v45
	s_nop 0
	v_add_u32_e32 v53, 0xfff44800, v158
	v_rcp_f32_e32 v44, v44
	s_nop 0
	v_mov_b32_e32 v36, v35
	v_pk_fma_f32 v[34:35], v[36:37], v[44:45], v[46:47]
	v_cvt_pk_bf16_f32 v0, v40, v41
	v_cvt_pk_bf16_f32 v34, v34, v35
	v_and_b32_e32 v35, 0xffff0000, v34
	v_lshlrev_b32_e32 v34, 16, v34
	v_or_b32_sdwa v41, v35, v0 dst_sel:DWORD dst_unused:UNUSED_PAD src0_sel:DWORD src1_sel:WORD_1
	v_or_b32_sdwa v40, v34, v0 dst_sel:DWORD dst_unused:UNUSED_PAD src0_sel:DWORD src1_sel:WORD_0
	v_add_u32_e32 v0, v52, v156
	global_store_dwordx4 v[42:43], v[38:41], off
	v_add_u32_e32 v0, v0, v53
	s_waitcnt vmcnt(12)
	v_lshlrev_b32_e32 v42, 16, v176
	v_and_b32_e32 v43, 0xffff0000, v176
	v_lshlrev_b32_e32 v45, 16, v177
	v_and_b32_e32 v47, 0xffff0000, v177
	v_lshl_add_u64 v[34:35], v[0:1], 1, s[10:11]
	v_lshlrev_b32_e32 v44, 16, v178
	v_mul_f32_e32 v0, 0xbfb8aa3b, v42
	v_exp_f32_e32 v42, v0
	v_mul_f32_e32 v0, 0xbfb8aa3b, v44
	v_and_b32_e32 v36, 0xffff0000, v178
	v_exp_f32_e32 v44, v0
	v_mul_f32_e32 v0, 0xbfb8aa3b, v43
	v_exp_f32_e32 v46, v0
	v_mul_f32_e32 v0, 0xbfb8aa3b, v36
	v_exp_f32_e32 v36, v0
	v_mul_f32_e32 v0, 0xbfb8aa3b, v45
	v_exp_f32_e32 v43, v0
	v_lshlrev_b32_e32 v48, 16, v179
	v_mul_f32_e32 v0, 0xbfb8aa3b, v48
	v_and_b32_e32 v37, 0xffff0000, v179
	v_exp_f32_e32 v45, v0
	v_mul_f32_e32 v0, 0xbfb8aa3b, v47
	v_exp_f32_e32 v47, v0
	v_mul_f32_e32 v0, 0xbfb8aa3b, v37
	v_pk_add_f32 v[42:43], v[42:43], 1.0 op_sel_hi:[1,0]
	v_exp_f32_e32 v37, v0
	v_pk_add_f32 v[46:47], v[46:47], 1.0 op_sel_hi:[1,0]
	v_pk_add_f32 v[36:37], v[36:37], 1.0 op_sel_hi:[1,0]
	v_rcp_f32_e32 v43, v43
	s_nop 0
	s_waitcnt vmcnt(11)
	v_lshlrev_b32_e32 v49, 16, v183
	v_rcp_f32_e32 v42, v42
	s_nop 0
	v_mov_b32_e32 v50, v30
	v_mov_b32_e32 v51, v32
	v_lshlrev_b32_e32 v48, 16, v182
	v_pk_fma_f32 v[42:43], v[50:51], v[42:43], v[48:49]
	v_rcp_f32_e32 v47, v47
	s_nop 0
	v_and_b32_e32 v39, 0xffff0000, v183
	v_and_b32_e32 v38, 0xffff0000, v182
	v_rcp_f32_e32 v46, v46
	s_nop 0
	v_mov_b32_e32 v32, v31
	v_pk_fma_f32 v[30:31], v[32:33], v[46:47], v[38:39]
	v_cvt_pk_bf16_f32 v0, v42, v43
	v_cvt_pk_bf16_f32 v30, v30, v31
	v_and_b32_e32 v31, 0xffff0000, v30
	v_lshlrev_b32_e32 v30, 16, v30
	v_lshlrev_b32_e32 v33, 16, v185
	v_lshlrev_b32_e32 v32, 16, v184
	v_and_b32_e32 v39, 0xffff0000, v185
	v_and_b32_e32 v38, 0xffff0000, v184
	v_pk_add_f32 v[40:41], v[44:45], 1.0 op_sel_hi:[1,0]
	v_or_b32_sdwa v31, v31, v0 dst_sel:DWORD dst_unused:UNUSED_PAD src0_sel:DWORD src1_sel:WORD_1
	v_or_b32_sdwa v30, v30, v0 dst_sel:DWORD dst_unused:UNUSED_PAD src0_sel:DWORD src1_sel:WORD_0
	s_nop 0
	v_rcp_f32_e32 v41, v41
	s_nop 0
	s_nop 0
	v_rcp_f32_e32 v40, v40
	s_nop 0
	v_mov_b32_e32 v42, v26
	v_mov_b32_e32 v43, v28
	v_pk_fma_f32 v[32:33], v[42:43], v[40:41], v[32:33]
	v_rcp_f32_e32 v37, v37
	s_nop 0
	s_nop 0
	v_rcp_f32_e32 v36, v36
	s_nop 0
	v_mov_b32_e32 v28, v27
	v_pk_fma_f32 v[26:27], v[28:29], v[36:37], v[38:39]
	v_cvt_pk_bf16_f32 v0, v32, v33
	v_cvt_pk_bf16_f32 v26, v26, v27
	v_and_b32_e32 v27, 0xffff0000, v26
	v_lshlrev_b32_e32 v26, 16, v26
	v_or_b32_sdwa v33, v27, v0 dst_sel:DWORD dst_unused:UNUSED_PAD src0_sel:DWORD src1_sel:WORD_1
	v_or_b32_sdwa v32, v26, v0 dst_sel:DWORD dst_unused:UNUSED_PAD src0_sel:DWORD src1_sel:WORD_0
	v_add_u32_e32 v0, v52, v126
	global_store_dwordx4 v[34:35], v[30:33], off
	v_add_u32_e32 v0, v0, v53
	s_waitcnt vmcnt(10)
	v_lshlrev_b32_e32 v34, 16, v186
	v_and_b32_e32 v35, 0xffff0000, v186
	v_lshlrev_b32_e32 v37, 16, v187
	v_and_b32_e32 v39, 0xffff0000, v187
	v_lshl_add_u64 v[26:27], v[0:1], 1, s[10:11]
	v_lshlrev_b32_e32 v36, 16, v188
	v_mul_f32_e32 v0, 0xbfb8aa3b, v34
	v_exp_f32_e32 v34, v0
	v_mul_f32_e32 v0, 0xbfb8aa3b, v36
	v_and_b32_e32 v28, 0xffff0000, v188
	v_exp_f32_e32 v36, v0
	v_mul_f32_e32 v0, 0xbfb8aa3b, v35
	v_exp_f32_e32 v38, v0
	v_mul_f32_e32 v0, 0xbfb8aa3b, v28
	v_exp_f32_e32 v28, v0
	v_mul_f32_e32 v0, 0xbfb8aa3b, v37
	v_exp_f32_e32 v35, v0
	v_lshlrev_b32_e32 v40, 16, v189
	v_mul_f32_e32 v0, 0xbfb8aa3b, v40
	v_and_b32_e32 v29, 0xffff0000, v189
	v_exp_f32_e32 v37, v0
	v_mul_f32_e32 v0, 0xbfb8aa3b, v39
	v_exp_f32_e32 v39, v0
	v_mul_f32_e32 v0, 0xbfb8aa3b, v29
	v_pk_add_f32 v[34:35], v[34:35], 1.0 op_sel_hi:[1,0]
	v_exp_f32_e32 v29, v0
	v_pk_add_f32 v[38:39], v[38:39], 1.0 op_sel_hi:[1,0]
	v_pk_add_f32 v[28:29], v[28:29], 1.0 op_sel_hi:[1,0]
	v_rcp_f32_e32 v35, v35
	s_nop 0
	s_waitcnt vmcnt(9)
	v_lshlrev_b32_e32 v41, 16, v191
	v_rcp_f32_e32 v34, v34
	s_nop 0
	v_mov_b32_e32 v42, v22
	v_mov_b32_e32 v43, v24
	v_lshlrev_b32_e32 v40, 16, v190
	v_pk_fma_f32 v[34:35], v[42:43], v[34:35], v[40:41]
	v_rcp_f32_e32 v39, v39
	s_nop 0
	v_and_b32_e32 v31, 0xffff0000, v191
	v_and_b32_e32 v30, 0xffff0000, v190
	v_rcp_f32_e32 v38, v38
	s_nop 0
	v_mov_b32_e32 v24, v23
	v_pk_fma_f32 v[22:23], v[24:25], v[38:39], v[30:31]
	v_cvt_pk_bf16_f32 v0, v34, v35
	v_cvt_pk_bf16_f32 v22, v22, v23
	v_and_b32_e32 v23, 0xffff0000, v22
	v_lshlrev_b32_e32 v22, 16, v22
	v_lshlrev_b32_e32 v25, 16, v193
	v_lshlrev_b32_e32 v24, 16, v192
	v_and_b32_e32 v31, 0xffff0000, v193
	v_and_b32_e32 v30, 0xffff0000, v192
	v_pk_add_f32 v[32:33], v[36:37], 1.0 op_sel_hi:[1,0]
	v_or_b32_sdwa v23, v23, v0 dst_sel:DWORD dst_unused:UNUSED_PAD src0_sel:DWORD src1_sel:WORD_1
	v_or_b32_sdwa v22, v22, v0 dst_sel:DWORD dst_unused:UNUSED_PAD src0_sel:DWORD src1_sel:WORD_0
	s_nop 0
	v_rcp_f32_e32 v33, v33
	s_nop 0
	s_nop 0
	v_rcp_f32_e32 v32, v32
	s_nop 0
	v_mov_b32_e32 v34, v18
	v_mov_b32_e32 v35, v20
	v_pk_fma_f32 v[24:25], v[34:35], v[32:33], v[24:25]
	v_add_u32_e32 v36, 0xfa400, v157
	v_rcp_f32_e32 v29, v29
	s_nop 0
	v_add_u32_e32 v37, 0xfff31c00, v158
	v_rcp_f32_e32 v28, v28
	s_nop 0
	v_mov_b32_e32 v20, v19
	v_pk_fma_f32 v[18:19], v[20:21], v[28:29], v[30:31]
	v_cvt_pk_bf16_f32 v0, v24, v25
	v_cvt_pk_bf16_f32 v18, v18, v19
	v_and_b32_e32 v19, 0xffff0000, v18
	v_lshlrev_b32_e32 v18, 16, v18
	v_or_b32_sdwa v25, v19, v0 dst_sel:DWORD dst_unused:UNUSED_PAD src0_sel:DWORD src1_sel:WORD_1
	v_or_b32_sdwa v24, v18, v0 dst_sel:DWORD dst_unused:UNUSED_PAD src0_sel:DWORD src1_sel:WORD_0
	v_add_u32_e32 v0, v36, v156
	global_store_dwordx4 v[26:27], v[22:25], off
	v_add_u32_e32 v0, v0, v37
	s_waitcnt vmcnt(8)
	v_lshlrev_b32_e32 v26, 16, v194
	v_and_b32_e32 v27, 0xffff0000, v194
	v_lshlrev_b32_e32 v29, 16, v195
	v_and_b32_e32 v31, 0xffff0000, v195
	v_lshl_add_u64 v[18:19], v[0:1], 1, s[10:11]
	v_lshlrev_b32_e32 v28, 16, v196
	v_mul_f32_e32 v0, 0xbfb8aa3b, v26
	v_exp_f32_e32 v26, v0
	v_mul_f32_e32 v0, 0xbfb8aa3b, v28
	v_and_b32_e32 v20, 0xffff0000, v196
	v_exp_f32_e32 v28, v0
	v_mul_f32_e32 v0, 0xbfb8aa3b, v27
	v_exp_f32_e32 v30, v0
	v_mul_f32_e32 v0, 0xbfb8aa3b, v20
	v_exp_f32_e32 v20, v0
	v_mul_f32_e32 v0, 0xbfb8aa3b, v29
	v_exp_f32_e32 v27, v0
	v_lshlrev_b32_e32 v32, 16, v197
	v_mul_f32_e32 v0, 0xbfb8aa3b, v32
	v_and_b32_e32 v21, 0xffff0000, v197
	v_exp_f32_e32 v29, v0
	v_mul_f32_e32 v0, 0xbfb8aa3b, v31
	v_exp_f32_e32 v31, v0
	v_mul_f32_e32 v0, 0xbfb8aa3b, v21
	v_pk_add_f32 v[26:27], v[26:27], 1.0 op_sel_hi:[1,0]
	v_exp_f32_e32 v21, v0
	v_pk_add_f32 v[30:31], v[30:31], 1.0 op_sel_hi:[1,0]
	v_pk_add_f32 v[20:21], v[20:21], 1.0 op_sel_hi:[1,0]
	v_rcp_f32_e32 v27, v27
	s_nop 0
	s_waitcnt vmcnt(7)
	v_lshlrev_b32_e32 v33, 16, v199
	v_rcp_f32_e32 v26, v26
	s_nop 0
	v_mov_b32_e32 v34, v14
	v_mov_b32_e32 v35, v16
	v_lshlrev_b32_e32 v32, 16, v198
	v_pk_fma_f32 v[26:27], v[34:35], v[26:27], v[32:33]
	v_rcp_f32_e32 v31, v31
	s_nop 0
	v_and_b32_e32 v23, 0xffff0000, v199
	v_and_b32_e32 v22, 0xffff0000, v198
	v_rcp_f32_e32 v30, v30
	s_nop 0
	v_mov_b32_e32 v16, v15
	v_pk_fma_f32 v[14:15], v[16:17], v[30:31], v[22:23]
	v_cvt_pk_bf16_f32 v0, v26, v27
	v_cvt_pk_bf16_f32 v14, v14, v15
	v_and_b32_e32 v15, 0xffff0000, v14
	v_lshlrev_b32_e32 v14, 16, v14
	v_lshlrev_b32_e32 v17, 16, v201
	v_lshlrev_b32_e32 v16, 16, v200
	v_and_b32_e32 v23, 0xffff0000, v201
	v_and_b32_e32 v22, 0xffff0000, v200
	v_pk_add_f32 v[24:25], v[28:29], 1.0 op_sel_hi:[1,0]
	v_or_b32_sdwa v15, v15, v0 dst_sel:DWORD dst_unused:UNUSED_PAD src0_sel:DWORD src1_sel:WORD_1
	v_or_b32_sdwa v14, v14, v0 dst_sel:DWORD dst_unused:UNUSED_PAD src0_sel:DWORD src1_sel:WORD_0
	s_nop 0
	v_rcp_f32_e32 v25, v25
	s_nop 0
	s_nop 0
	v_rcp_f32_e32 v24, v24
	s_nop 0
	v_mov_b32_e32 v26, v10
	v_mov_b32_e32 v27, v12
	v_pk_fma_f32 v[16:17], v[26:27], v[24:25], v[16:17]
	v_rcp_f32_e32 v21, v21
	s_nop 0
	s_nop 0
	v_rcp_f32_e32 v20, v20
	s_nop 0
	v_mov_b32_e32 v12, v11
	v_pk_fma_f32 v[10:11], v[12:13], v[20:21], v[22:23]
	v_cvt_pk_bf16_f32 v0, v16, v17
	v_cvt_pk_bf16_f32 v10, v10, v11
	v_and_b32_e32 v11, 0xffff0000, v10
	v_lshlrev_b32_e32 v10, 16, v10
	v_or_b32_sdwa v17, v11, v0 dst_sel:DWORD dst_unused:UNUSED_PAD src0_sel:DWORD src1_sel:WORD_1
	v_or_b32_sdwa v16, v10, v0 dst_sel:DWORD dst_unused:UNUSED_PAD src0_sel:DWORD src1_sel:WORD_0
	v_add_u32_e32 v0, v36, v126
	global_store_dwordx4 v[18:19], v[14:17], off
	v_add_u32_e32 v0, v0, v37
	s_waitcnt vmcnt(6)
	v_lshlrev_b32_e32 v18, 16, v202
	v_and_b32_e32 v19, 0xffff0000, v202
	v_lshlrev_b32_e32 v21, 16, v203
	v_and_b32_e32 v23, 0xffff0000, v203
	v_lshl_add_u64 v[10:11], v[0:1], 1, s[10:11]
	v_lshlrev_b32_e32 v20, 16, v204
	v_mul_f32_e32 v0, 0xbfb8aa3b, v18
	v_exp_f32_e32 v18, v0
	v_mul_f32_e32 v0, 0xbfb8aa3b, v20
	v_and_b32_e32 v12, 0xffff0000, v204
	v_exp_f32_e32 v20, v0
	v_mul_f32_e32 v0, 0xbfb8aa3b, v19
	v_exp_f32_e32 v22, v0
	v_mul_f32_e32 v0, 0xbfb8aa3b, v12
	v_exp_f32_e32 v12, v0
	v_mul_f32_e32 v0, 0xbfb8aa3b, v21
	v_exp_f32_e32 v19, v0
	v_lshlrev_b32_e32 v24, 16, v205
	v_mul_f32_e32 v0, 0xbfb8aa3b, v24
	v_and_b32_e32 v13, 0xffff0000, v205
	v_exp_f32_e32 v21, v0
	v_mul_f32_e32 v0, 0xbfb8aa3b, v23
	v_exp_f32_e32 v23, v0
	v_mul_f32_e32 v0, 0xbfb8aa3b, v13
	v_pk_add_f32 v[18:19], v[18:19], 1.0 op_sel_hi:[1,0]
	v_exp_f32_e32 v13, v0
	v_pk_add_f32 v[22:23], v[22:23], 1.0 op_sel_hi:[1,0]
	v_pk_add_f32 v[12:13], v[12:13], 1.0 op_sel_hi:[1,0]
	v_rcp_f32_e32 v19, v19
	s_nop 0
	s_waitcnt vmcnt(5)
	v_lshlrev_b32_e32 v25, 16, v207
	v_rcp_f32_e32 v18, v18
	s_nop 0
	v_mov_b32_e32 v26, v6
	v_mov_b32_e32 v27, v8
	v_lshlrev_b32_e32 v24, 16, v206
	v_pk_fma_f32 v[18:19], v[26:27], v[18:19], v[24:25]
	v_rcp_f32_e32 v23, v23
	s_nop 0
	v_and_b32_e32 v15, 0xffff0000, v207
	v_and_b32_e32 v14, 0xffff0000, v206
	v_rcp_f32_e32 v22, v22
	s_nop 0
	v_mov_b32_e32 v8, v7
	v_pk_fma_f32 v[6:7], v[8:9], v[22:23], v[14:15]
	v_cvt_pk_bf16_f32 v0, v18, v19
	v_cvt_pk_bf16_f32 v6, v6, v7
	v_and_b32_e32 v7, 0xffff0000, v6
	v_lshlrev_b32_e32 v6, 16, v6
	v_lshlrev_b32_e32 v9, 16, v209
	v_lshlrev_b32_e32 v8, 16, v208
	v_and_b32_e32 v15, 0xffff0000, v209
	v_and_b32_e32 v14, 0xffff0000, v208
	v_pk_add_f32 v[16:17], v[20:21], 1.0 op_sel_hi:[1,0]
	v_or_b32_sdwa v7, v7, v0 dst_sel:DWORD dst_unused:UNUSED_PAD src0_sel:DWORD src1_sel:WORD_1
	v_or_b32_sdwa v6, v6, v0 dst_sel:DWORD dst_unused:UNUSED_PAD src0_sel:DWORD src1_sel:WORD_0
	s_nop 0
	v_rcp_f32_e32 v17, v17
	s_nop 0
	s_nop 0
	v_rcp_f32_e32 v16, v16
	s_nop 0
	v_mov_b32_e32 v18, v2
	v_mov_b32_e32 v19, v4
	v_pk_fma_f32 v[8:9], v[18:19], v[16:17], v[8:9]
	v_rcp_f32_e32 v13, v13
	s_nop 0
	s_mov_b64 s[26:27], s[18:19]
	v_rcp_f32_e32 v12, v12
	s_nop 0
	v_mov_b32_e32 v4, v3
	v_pk_fma_f32 v[2:3], v[4:5], v[12:13], v[14:15]
	v_cvt_pk_bf16_f32 v0, v8, v9
	v_cvt_pk_bf16_f32 v2, v2, v3
	v_and_b32_e32 v3, 0xffff0000, v2
	v_lshlrev_b32_e32 v2, 16, v2
	v_or_b32_sdwa v9, v3, v0 dst_sel:DWORD dst_unused:UNUSED_PAD src0_sel:DWORD src1_sel:WORD_1
	v_or_b32_sdwa v8, v2, v0 dst_sel:DWORD dst_unused:UNUSED_PAD src0_sel:DWORD src1_sel:WORD_0
	s_and_b64 vcc, exec, s[12:13]
	global_store_dwordx4 v[10:11], v[6:9], off
	s_cbranch_vccz .LBB0_1356
	s_waitcnt vmcnt(0)
	v_readlane_b32 s76, v255, 8
	s_mov_b32 s92, 0x3b2aaaab
	s_cmp_gt_u32 s36, 3
	v_readlane_b32 s77, v255, 9
	s_mul_i32 s60, s33, 0x1800
	s_mul_hi_i32 s62, s64, 0x300
	s_mul_i32 s75, s33, 0x16c00
	s_mov_b32 s93, 0x3c800000
	s_cbranch_scc1 .LBB0_1363
	s_barrier

.LBB0_1372:
	v_add_u32_e32 v0, 0x10000, v154
	ds_read_b128 v[130:133], v0
	ds_read_b128 v[146:149], v0 offset:1024
	ds_read_b128 v[156:159], v0 offset:2048
	ds_read_b128 v[160:163], v0 offset:3072
	s_add_u32 s28, s26, 0xfffc0080
	s_addc_u32 s29, s27, -1
	s_cmp_eq_u32 s97, 12
	s_cselect_b32 s31, s2, s29
	s_cselect_b32 s30, s17, s28
	s_cselect_b32 s29, s15, s94
	s_cselect_b32 s28, s89, s90
	v_lshl_add_u64 v[150:151], s[26:27], 0, v[142:143]
	s_add_i32 m0, s38, 0xc000
	ds_read_b128 v[164:167], v153
	ds_read_b128 v[168:171], v153 offset:1024
	ds_read_b128 v[172:175], v153 offset:2048
	ds_read_b128 v[176:179], v153 offset:3072
	ds_read_b128 v[182:185], v153 offset:4096
	ds_read_b128 v[186:189], v153 offset:5120
	ds_read_b128 v[190:193], v153 offset:6144
	ds_read_b128 v[194:197], v153 offset:7168
	global_load_lds_dwordx4 v[150:151], off
	v_lshl_add_u64 v[150:151], s[26:27], 0, v[144:145]
	s_add_i32 m0, s38, 0xe000
	s_nop 0
	global_load_lds_dwordx4 v[150:151], off
	s_waitcnt lgkmcnt(8)
	s_barrier
	s_waitcnt lgkmcnt(0)
	s_setprio 1
	s_waitcnt lgkmcnt(0)
	v_mfma_f32_16x16x32_bf16 v[126:129], v[130:133], v[164:167], v[126:129]
	v_mfma_f32_16x16x32_bf16 v[122:125], v[156:159], v[164:167], v[122:125]
	v_mfma_f32_16x16x32_bf16 v[110:113], v[130:133], v[172:175], v[110:113]
	v_mfma_f32_16x16x32_bf16 v[106:109], v[156:159], v[172:175], v[106:109]
	v_mfma_f32_16x16x32_bf16 v[94:97], v[130:133], v[182:185], v[94:97]
	v_mfma_f32_16x16x32_bf16 v[90:93], v[156:159], v[182:185], v[90:93]
	v_mfma_f32_16x16x32_bf16 v[78:81], v[130:133], v[190:193], v[78:81]
	v_mfma_f32_16x16x32_bf16 v[74:77], v[156:159], v[190:193], v[74:77]
	v_mfma_f32_16x16x32_bf16 v[126:129], v[146:149], v[168:171], v[126:129]
	v_mfma_f32_16x16x32_bf16 v[122:125], v[160:163], v[168:171], v[122:125]
	v_mfma_f32_16x16x32_bf16 v[110:113], v[146:149], v[176:179], v[110:113]
	v_mfma_f32_16x16x32_bf16 v[106:109], v[160:163], v[176:179], v[106:109]
	v_mfma_f32_16x16x32_bf16 v[94:97], v[146:149], v[186:189], v[94:97]
	v_mfma_f32_16x16x32_bf16 v[90:93], v[160:163], v[186:189], v[90:93]
	v_mfma_f32_16x16x32_bf16 v[78:81], v[146:149], v[194:197], v[78:81]
	v_mfma_f32_16x16x32_bf16 v[74:77], v[160:163], v[194:197], v[74:77]
	s_setprio 0
	s_barrier
	s_mov_b32 m0, s23
	v_add_u32_e32 v0, 0x14000, v154
	v_lshl_add_u64 v[150:151], s[28:29], 0, v[138:139]
	ds_read_b128 v[198:201], v0
	ds_read_b128 v[202:205], v0 offset:1024
	ds_read_b128 v[206:209], v0 offset:2048
	ds_read_b128 v[210:213], v0 offset:3072
	global_load_lds_dwordx4 v[150:151], off
	v_lshl_add_u64 v[214:215], s[28:29], 0, v[134:135]
	s_mov_b32 m0, s25
	s_nop 0
	global_load_lds_dwordx4 v[214:215], off
	s_barrier
	s_waitcnt lgkmcnt(0)
	s_setprio 1
	s_waitcnt lgkmcnt(0)
	v_mfma_f32_16x16x32_bf16 v[118:121], v[198:201], v[164:167], v[118:121]
	v_mfma_f32_16x16x32_bf16 v[114:117], v[206:209], v[164:167], v[114:117]
	v_mfma_f32_16x16x32_bf16 v[102:105], v[198:201], v[172:175], v[102:105]
	v_mfma_f32_16x16x32_bf16 v[98:101], v[206:209], v[172:175], v[98:101]
	v_mfma_f32_16x16x32_bf16 v[86:89], v[198:201], v[182:185], v[86:89]
	v_mfma_f32_16x16x32_bf16 v[82:85], v[206:209], v[182:185], v[82:85]
	v_mfma_f32_16x16x32_bf16 v[70:73], v[198:201], v[190:193], v[70:73]
	v_mfma_f32_16x16x32_bf16 v[66:69], v[206:209], v[190:193], v[66:69]
	v_mfma_f32_16x16x32_bf16 v[118:121], v[202:205], v[168:171], v[118:121]
	v_mfma_f32_16x16x32_bf16 v[114:117], v[210:213], v[168:171], v[114:117]
	v_mfma_f32_16x16x32_bf16 v[102:105], v[202:205], v[176:179], v[102:105]
	v_mfma_f32_16x16x32_bf16 v[98:101], v[210:213], v[176:179], v[98:101]
	v_mfma_f32_16x16x32_bf16 v[86:89], v[202:205], v[186:189], v[86:89]
	v_mfma_f32_16x16x32_bf16 v[82:85], v[210:213], v[186:189], v[82:85]
	v_mfma_f32_16x16x32_bf16 v[70:73], v[202:205], v[194:197], v[70:73]
	v_mfma_f32_16x16x32_bf16 v[66:69], v[210:213], v[194:197], v[66:69]
	s_setprio 0
	s_mov_b32 m0, s38
	v_lshl_add_u64 v[216:217], s[30:31], 0, v[140:141]
	s_barrier
	ds_read_b128 v[164:167], v153 offset:16384
	ds_read_b128 v[168:171], v153 offset:17408
	ds_read_b128 v[172:175], v153 offset:18432
	ds_read_b128 v[176:179], v153 offset:19456
	ds_read_b128 v[182:185], v153 offset:20480
	ds_read_b128 v[186:189], v153 offset:21504
	ds_read_b128 v[190:193], v153 offset:22528
	ds_read_b128 v[194:197], v153 offset:23552
	global_load_lds_dwordx4 v[216:217], off
	v_lshl_add_u64 v[222:223], s[30:31], 0, v[136:137]
	s_mov_b32 m0, s39
	s_nop 0
	global_load_lds_dwordx4 v[222:223], off
	s_barrier
	s_waitcnt lgkmcnt(0)
	s_setprio 1
	s_waitcnt lgkmcnt(0)
	v_mfma_f32_16x16x32_bf16 v[62:65], v[130:133], v[164:167], v[62:65]
	v_mfma_f32_16x16x32_bf16 v[58:61], v[156:159], v[164:167], v[58:61]
	v_mfma_f32_16x16x32_bf16 v[46:49], v[130:133], v[172:175], v[46:49]
	v_mfma_f32_16x16x32_bf16 v[42:45], v[156:159], v[172:175], v[42:45]
	v_mfma_f32_16x16x32_bf16 v[30:33], v[130:133], v[182:185], v[30:33]
	v_mfma_f32_16x16x32_bf16 v[26:29], v[156:159], v[182:185], v[26:29]
	v_mfma_f32_16x16x32_bf16 v[14:17], v[130:133], v[190:193], v[14:17]
	v_mfma_f32_16x16x32_bf16 v[10:13], v[156:159], v[190:193], v[10:13]
	v_mfma_f32_16x16x32_bf16 v[62:65], v[146:149], v[168:171], v[62:65]
	v_mfma_f32_16x16x32_bf16 v[58:61], v[160:163], v[168:171], v[58:61]
	v_mfma_f32_16x16x32_bf16 v[46:49], v[146:149], v[176:179], v[46:49]
	v_mfma_f32_16x16x32_bf16 v[42:45], v[160:163], v[176:179], v[42:45]
	v_mfma_f32_16x16x32_bf16 v[30:33], v[146:149], v[186:189], v[30:33]
	v_mfma_f32_16x16x32_bf16 v[26:29], v[160:163], v[186:189], v[26:29]
	v_mfma_f32_16x16x32_bf16 v[14:17], v[146:149], v[194:197], v[14:17]
	v_mfma_f32_16x16x32_bf16 v[10:13], v[160:163], v[194:197], v[10:13]
	s_setprio 0
	s_barrier
	s_add_u32 s76, s28, 0x40000
	s_addc_u32 s77, s29, 0
	s_mov_b32 m0, s68
	v_lshl_add_u64 v[130:131], s[76:77], 0, v[138:139]
	global_load_lds_dwordx4 v[130:131], off
	v_lshl_add_u64 v[130:131], s[76:77], 0, v[134:135]
	s_mov_b32 m0, s69
	s_nop 0
	global_load_lds_dwordx4 v[130:131], off
	s_waitcnt vmcnt(6)
	s_barrier
	s_setprio 1
	v_mfma_f32_16x16x32_bf16 v[54:57], v[198:201], v[164:167], v[54:57]
	v_mfma_f32_16x16x32_bf16 v[50:53], v[206:209], v[164:167], v[50:53]
	v_mfma_f32_16x16x32_bf16 v[38:41], v[198:201], v[172:175], v[38:41]
	v_mfma_f32_16x16x32_bf16 v[34:37], v[206:209], v[172:175], v[34:37]
	v_mfma_f32_16x16x32_bf16 v[22:25], v[198:201], v[182:185], v[22:25]
	v_mfma_f32_16x16x32_bf16 v[18:21], v[206:209], v[182:185], v[18:21]
	v_mfma_f32_16x16x32_bf16 v[6:9], v[198:201], v[190:193], v[6:9]
	v_mfma_f32_16x16x32_bf16 v[2:5], v[206:209], v[190:193], v[2:5]
	v_mfma_f32_16x16x32_bf16 v[54:57], v[202:205], v[168:171], v[54:57]
	v_mfma_f32_16x16x32_bf16 v[50:53], v[210:213], v[168:171], v[50:53]
	v_mfma_f32_16x16x32_bf16 v[38:41], v[202:205], v[176:179], v[38:41]
	v_mfma_f32_16x16x32_bf16 v[34:37], v[210:213], v[176:179], v[34:37]
	v_mfma_f32_16x16x32_bf16 v[22:25], v[202:205], v[186:189], v[22:25]
	v_mfma_f32_16x16x32_bf16 v[18:21], v[210:213], v[186:189], v[18:21]
	v_mfma_f32_16x16x32_bf16 v[6:9], v[202:205], v[194:197], v[6:9]
	v_mfma_f32_16x16x32_bf16 v[2:5], v[210:213], v[194:197], v[2:5]
	s_setprio 0
	v_add_u32_e32 v0, 0x18000, v154
	s_barrier
	ds_read_b128 v[130:133], v0
	ds_read_b128 v[146:149], v0 offset:1024
	ds_read_b128 v[156:159], v0 offset:2048
	ds_read_b128 v[160:163], v0 offset:3072
	s_add_u32 s30, s30, 0x40000
	s_addc_u32 s31, s31, 0
	s_mov_b32 m0, s82
	v_lshl_add_u64 v[198:199], s[30:31], 0, v[140:141]
	ds_read_b128 v[164:167], v153 offset:32768
	ds_read_b128 v[168:171], v153 offset:33792
	ds_read_b128 v[172:175], v153 offset:34816
	ds_read_b128 v[176:179], v153 offset:35840
	ds_read_b128 v[182:185], v153 offset:36864
	ds_read_b128 v[186:189], v153 offset:37888
	ds_read_b128 v[190:193], v153 offset:38912
	ds_read_b128 v[194:197], v153 offset:39936
	global_load_lds_dwordx4 v[198:199], off
	v_lshl_add_u64 v[198:199], s[30:31], 0, v[136:137]
	s_mov_b32 m0, s96
	s_nop 0
	global_load_lds_dwordx4 v[198:199], off
	s_waitcnt lgkmcnt(8)
	s_barrier
	s_waitcnt lgkmcnt(0)
	s_setprio 1
	s_waitcnt lgkmcnt(0)
	v_mfma_f32_16x16x32_bf16 v[126:129], v[130:133], v[164:167], v[126:129]
	v_mfma_f32_16x16x32_bf16 v[122:125], v[156:159], v[164:167], v[122:125]
	v_mfma_f32_16x16x32_bf16 v[110:113], v[130:133], v[172:175], v[110:113]
	v_mfma_f32_16x16x32_bf16 v[106:109], v[156:159], v[172:175], v[106:109]
	v_mfma_f32_16x16x32_bf16 v[94:97], v[130:133], v[182:185], v[94:97]
	v_mfma_f32_16x16x32_bf16 v[90:93], v[156:159], v[182:185], v[90:93]
	v_mfma_f32_16x16x32_bf16 v[78:81], v[130:133], v[190:193], v[78:81]
	v_mfma_f32_16x16x32_bf16 v[74:77], v[156:159], v[190:193], v[74:77]
	v_mfma_f32_16x16x32_bf16 v[126:129], v[146:149], v[168:171], v[126:129]
	v_mfma_f32_16x16x32_bf16 v[122:125], v[160:163], v[168:171], v[122:125]
	v_mfma_f32_16x16x32_bf16 v[110:113], v[146:149], v[176:179], v[110:113]
	v_mfma_f32_16x16x32_bf16 v[106:109], v[160:163], v[176:179], v[106:109]
	v_mfma_f32_16x16x32_bf16 v[94:97], v[146:149], v[186:189], v[94:97]
	v_mfma_f32_16x16x32_bf16 v[90:93], v[160:163], v[186:189], v[90:93]
	v_mfma_f32_16x16x32_bf16 v[78:81], v[146:149], v[194:197], v[78:81]
	v_mfma_f32_16x16x32_bf16 v[74:77], v[160:163], v[194:197], v[74:77]
	s_setprio 0
	s_barrier
	s_mov_b32 m0, s4
	v_add_u32_e32 v0, 0x1c000, v154
	v_lshl_add_u64 v[150:151], v[150:151], 0, s[84:85]
	ds_read_b128 v[198:201], v0
	ds_read_b128 v[202:205], v0 offset:1024
	ds_read_b128 v[206:209], v0 offset:2048
	ds_read_b128 v[210:213], v0 offset:3072
	global_load_lds_dwordx4 v[150:151], off
	v_lshl_add_u64 v[150:151], v[214:215], 0, s[84:85]
	s_mov_b32 m0, s5
	s_nop 0
	global_load_lds_dwordx4 v[150:151], off
	s_barrier
	s_waitcnt lgkmcnt(0)
	s_setprio 1
	s_waitcnt lgkmcnt(0)
	v_mfma_f32_16x16x32_bf16 v[118:121], v[198:201], v[164:167], v[118:121]
	v_mfma_f32_16x16x32_bf16 v[114:117], v[206:209], v[164:167], v[114:117]
	v_mfma_f32_16x16x32_bf16 v[102:105], v[198:201], v[172:175], v[102:105]
	v_mfma_f32_16x16x32_bf16 v[98:101], v[206:209], v[172:175], v[98:101]
	v_mfma_f32_16x16x32_bf16 v[86:89], v[198:201], v[182:185], v[86:89]
	v_mfma_f32_16x16x32_bf16 v[82:85], v[206:209], v[182:185], v[82:85]
	v_mfma_f32_16x16x32_bf16 v[70:73], v[198:201], v[190:193], v[70:73]
	v_mfma_f32_16x16x32_bf16 v[66:69], v[206:209], v[190:193], v[66:69]
	v_mfma_f32_16x16x32_bf16 v[118:121], v[202:205], v[168:171], v[118:121]
	v_mfma_f32_16x16x32_bf16 v[114:117], v[210:213], v[168:171], v[114:117]
	v_mfma_f32_16x16x32_bf16 v[102:105], v[202:205], v[176:179], v[102:105]
	v_mfma_f32_16x16x32_bf16 v[98:101], v[210:213], v[176:179], v[98:101]
	v_mfma_f32_16x16x32_bf16 v[86:89], v[202:205], v[186:189], v[86:89]
	v_mfma_f32_16x16x32_bf16 v[82:85], v[210:213], v[186:189], v[82:85]
	v_mfma_f32_16x16x32_bf16 v[70:73], v[202:205], v[194:197], v[70:73]
	v_mfma_f32_16x16x32_bf16 v[66:69], v[210:213], v[194:197], v[66:69]
	s_setprio 0
	s_mov_b32 m0, s60
	v_lshl_add_u64 v[150:151], v[216:217], 0, s[84:85]
	s_barrier
	ds_read_b128 v[164:167], v153 offset:49152
	ds_read_b128 v[168:171], v153 offset:50176
	ds_read_b128 v[172:175], v153 offset:51200
	ds_read_b128 v[176:179], v153 offset:52224
	ds_read_b128 v[182:185], v153 offset:53248
	ds_read_b128 v[186:189], v153 offset:54272
	ds_read_b128 v[190:193], v153 offset:55296
	ds_read_b128 v[194:197], v153 offset:56320
	global_load_lds_dwordx4 v[150:151], off
	v_lshl_add_u64 v[150:151], v[222:223], 0, s[84:85]
	s_mov_b32 m0, s92
	s_nop 0
	global_load_lds_dwordx4 v[150:151], off
	s_barrier
	s_waitcnt lgkmcnt(0)
	s_setprio 1
	s_waitcnt lgkmcnt(0)
	v_mfma_f32_16x16x32_bf16 v[62:65], v[130:133], v[164:167], v[62:65]
	v_mfma_f32_16x16x32_bf16 v[58:61], v[156:159], v[164:167], v[58:61]
	v_mfma_f32_16x16x32_bf16 v[46:49], v[130:133], v[172:175], v[46:49]
	v_mfma_f32_16x16x32_bf16 v[42:45], v[156:159], v[172:175], v[42:45]
	v_mfma_f32_16x16x32_bf16 v[30:33], v[130:133], v[182:185], v[30:33]
	v_mfma_f32_16x16x32_bf16 v[26:29], v[156:159], v[182:185], v[26:29]
	v_mfma_f32_16x16x32_bf16 v[14:17], v[130:133], v[190:193], v[14:17]
	v_mfma_f32_16x16x32_bf16 v[10:13], v[156:159], v[190:193], v[10:13]
	v_mfma_f32_16x16x32_bf16 v[62:65], v[146:149], v[168:171], v[62:65]
	v_mfma_f32_16x16x32_bf16 v[58:61], v[160:163], v[168:171], v[58:61]
	v_mfma_f32_16x16x32_bf16 v[46:49], v[146:149], v[176:179], v[46:49]
	v_mfma_f32_16x16x32_bf16 v[42:45], v[160:163], v[176:179], v[42:45]
	v_mfma_f32_16x16x32_bf16 v[30:33], v[146:149], v[186:189], v[30:33]
	v_mfma_f32_16x16x32_bf16 v[26:29], v[160:163], v[186:189], v[26:29]
	v_mfma_f32_16x16x32_bf16 v[14:17], v[146:149], v[194:197], v[14:17]
	v_mfma_f32_16x16x32_bf16 v[10:13], v[160:163], v[194:197], v[10:13]
	s_setprio 0
	s_barrier
	s_add_u32 s28, s28, 0x40080
	s_addc_u32 s29, s29, 0
	s_mov_b32 m0, s93
	v_lshl_add_u64 v[130:131], s[28:29], 0, v[138:139]
	global_load_lds_dwordx4 v[130:131], off
	v_lshl_add_u64 v[130:131], s[28:29], 0, v[134:135]
	s_mov_b32 m0, s3
	s_nop 0
	global_load_lds_dwordx4 v[130:131], off
	s_waitcnt vmcnt(6)
	s_barrier
	s_setprio 1
	v_mfma_f32_16x16x32_bf16 v[54:57], v[198:201], v[164:167], v[54:57]
	v_mfma_f32_16x16x32_bf16 v[50:53], v[206:209], v[164:167], v[50:53]
	v_mfma_f32_16x16x32_bf16 v[38:41], v[198:201], v[172:175], v[38:41]
	v_mfma_f32_16x16x32_bf16 v[34:37], v[206:209], v[172:175], v[34:37]
	v_mfma_f32_16x16x32_bf16 v[22:25], v[198:201], v[182:185], v[22:25]
	v_mfma_f32_16x16x32_bf16 v[18:21], v[206:209], v[182:185], v[18:21]
	v_mfma_f32_16x16x32_bf16 v[6:9], v[198:201], v[190:193], v[6:9]
	v_mfma_f32_16x16x32_bf16 v[2:5], v[206:209], v[190:193], v[2:5]
	v_mfma_f32_16x16x32_bf16 v[54:57], v[202:205], v[168:171], v[54:57]
	v_mfma_f32_16x16x32_bf16 v[50:53], v[210:213], v[168:171], v[50:53]
	v_mfma_f32_16x16x32_bf16 v[38:41], v[202:205], v[176:179], v[38:41]
	v_mfma_f32_16x16x32_bf16 v[34:37], v[210:213], v[176:179], v[34:37]
	v_mfma_f32_16x16x32_bf16 v[22:25], v[202:205], v[186:189], v[22:25]
	v_mfma_f32_16x16x32_bf16 v[18:21], v[210:213], v[186:189], v[18:21]
	v_mfma_f32_16x16x32_bf16 v[6:9], v[202:205], v[194:197], v[6:9]
	v_mfma_f32_16x16x32_bf16 v[2:5], v[210:213], v[194:197], v[2:5]
	s_setprio 0
	s_add_i32 s97, s97, 2
	s_add_u32 s26, s26, 0x100
	s_addc_u32 s27, s27, 0
	s_add_u32 s90, s90, 0x100
	s_addc_u32 s94, s94, 0
	s_cmp_gt_u32 s97, 13
	s_barrier
	s_cbranch_scc0 .LBB0_1372
	v_lshl_add_u32 v159, s24, 8, v152
	v_lshl_add_u32 v156, s22, 8, v155
	v_mul_lo_u32 v157, v159, s71
	v_add_u32_e32 v0, v157, v156
	v_lshl_add_u64 v[130:131], v[0:1], 1, s[6:7]
	global_load_dwordx4 v[130:133], v[130:131], off
	v_mul_lo_u32 v158, v159, s61
	v_mov_b32_e32 v210, v0
	v_add_u32_e32 v211, v0, v158
	v_mov_b32_e32 v213, 0
	v_add_u32_e32 v212, 0x80, v210
	v_lshl_add_u64 v[168:169], v[212:213], 1, s[6:7]
	global_load_dwordx4 v[168:171], v[168:169], off
	v_add_u32_e32 v212, 0x80, v211
	v_lshl_add_u64 v[172:173], v[212:213], 1, s[10:11]
	global_load_dwordx4 v[172:175], v[172:173], off
	v_add_u32_e32 v212, 0x16c00, v210
	v_lshl_add_u64 v[176:177], v[212:213], 1, s[6:7]
	global_load_dwordx4 v[176:179], v[176:177], off
	v_add_u32_e32 v212, 0x4000, v211
	v_lshl_add_u64 v[182:183], v[212:213], 1, s[10:11]
	global_load_dwordx4 v[182:185], v[182:183], off
	v_add_u32_e32 v212, 0x16c80, v210
	v_lshl_add_u64 v[186:187], v[212:213], 1, s[6:7]
	global_load_dwordx4 v[186:189], v[186:187], off
	v_add_u32_e32 v212, 0x4080, v211
	v_lshl_add_u64 v[190:191], v[212:213], 1, s[10:11]
	global_load_dwordx4 v[190:193], v[190:191], off
	v_add_u32_e32 v212, 0x2d800, v210
	v_lshl_add_u64 v[194:195], v[212:213], 1, s[6:7]
	global_load_dwordx4 v[194:197], v[194:195], off
	v_add_u32_e32 v212, 0x8000, v211
	v_lshl_add_u64 v[198:199], v[212:213], 1, s[10:11]
	global_load_dwordx4 v[198:201], v[198:199], off
	v_add_u32_e32 v212, 0x2d880, v210
	v_lshl_add_u64 v[202:203], v[212:213], 1, s[6:7]
	global_load_dwordx4 v[202:205], v[202:203], off
	v_add_u32_e32 v212, 0x8080, v211
	v_lshl_add_u64 v[206:207], v[212:213], 1, s[10:11]
	global_load_dwordx4 v[206:209], v[206:207], off
	v_add_u32_e32 v0, v0, v158
	v_lshl_add_u64 v[146:147], v[0:1], 1, s[10:11]
	s_mov_b32 s22, s14
	s_mov_b32 s24, s16
	s_mov_b64 s[28:29], s[20:21]
	s_waitcnt vmcnt(10)
	v_lshlrev_b32_e32 v148, 16, v130
	v_and_b32_e32 v149, 0xffff0000, v130
	v_lshlrev_b32_e32 v151, 16, v131
	v_and_b32_e32 v163, 0xffff0000, v131
	v_lshlrev_b32_e32 v150, 16, v132
	v_and_b32_e32 v161, 0xffff0000, v132
	v_lshlrev_b32_e32 v164, 16, v133
	v_and_b32_e32 v165, 0xffff0000, v133
	global_load_dwordx4 v[130:133], v[146:147], off
	v_mul_f32_e32 v0, 0xbfb8aa3b, v148
	v_exp_f32_e32 v160, v0
	v_mul_f32_e32 v0, 0xbfb8aa3b, v150
	v_exp_f32_e32 v150, v0
	v_mul_f32_e32 v0, 0xbfb8aa3b, v149
	v_exp_f32_e32 v162, v0
	v_mul_f32_e32 v0, 0xbfb8aa3b, v161
	v_exp_f32_e32 v148, v0
	v_mul_f32_e32 v0, 0xbfb8aa3b, v151
	v_exp_f32_e32 v161, v0
	v_mul_f32_e32 v0, 0xbfb8aa3b, v164
	v_exp_f32_e32 v151, v0
	v_mul_f32_e32 v0, 0xbfb8aa3b, v163
	v_exp_f32_e32 v163, v0
	v_mul_f32_e32 v0, 0xbfb8aa3b, v165
	v_pk_add_f32 v[160:161], v[160:161], 1.0 op_sel_hi:[1,0]
	v_exp_f32_e32 v149, v0
	v_pk_add_f32 v[162:163], v[162:163], 1.0 op_sel_hi:[1,0]
	v_rcp_f32_e32 v161, v161
	s_nop 0
	s_waitcnt vmcnt(0)
	v_lshlrev_b32_e32 v165, 16, v131
	v_rcp_f32_e32 v160, v160
	s_nop 0
	v_mov_b32_e32 v166, v126
	v_mov_b32_e32 v167, v128
	v_lshlrev_b32_e32 v164, 16, v130
	v_pk_fma_f32 v[160:161], v[166:167], v[160:161], v[164:165]
	v_rcp_f32_e32 v163, v163
	s_nop 0
	v_and_b32_e32 v131, 0xffff0000, v131
	v_and_b32_e32 v130, 0xffff0000, v130
	v_rcp_f32_e32 v162, v162
	s_nop 0
	v_mov_b32_e32 v128, v127
	v_pk_fma_f32 v[126:127], v[128:129], v[162:163], v[130:131]
	v_cvt_pk_bf16_f32 v0, v160, v161
	v_cvt_pk_bf16_f32 v126, v126, v127
	v_and_b32_e32 v127, 0xffff0000, v126
	v_lshlrev_b32_e32 v126, 16, v126
	v_lshlrev_b32_e32 v131, 16, v133
	v_lshlrev_b32_e32 v130, 16, v132
	v_and_b32_e32 v129, 0xffff0000, v133
	v_and_b32_e32 v128, 0xffff0000, v132
	v_pk_add_f32 v[132:133], v[150:151], 1.0 op_sel_hi:[1,0]
	v_or_b32_sdwa v127, v127, v0 dst_sel:DWORD dst_unused:UNUSED_PAD src0_sel:DWORD src1_sel:WORD_1
	v_or_b32_sdwa v126, v126, v0 dst_sel:DWORD dst_unused:UNUSED_PAD src0_sel:DWORD src1_sel:WORD_0
	s_nop 0
	v_rcp_f32_e32 v133, v133
	s_nop 0
	s_nop 0
	v_rcp_f32_e32 v132, v132
	s_nop 0
	v_mov_b32_e32 v150, v122
	v_mov_b32_e32 v151, v124
	v_pk_fma_f32 v[130:131], v[150:151], v[132:133], v[130:131]
	v_pk_add_f32 v[132:133], v[148:149], 1.0 op_sel_hi:[1,0]
	s_nop 0
	s_nop 0
	v_rcp_f32_e32 v133, v133
	s_nop 0
	s_nop 0
	v_rcp_f32_e32 v132, v132
	s_nop 0
	v_mov_b32_e32 v124, v123
	v_pk_fma_f32 v[122:123], v[124:125], v[132:133], v[128:129]
	v_cvt_pk_bf16_f32 v0, v130, v131
	v_cvt_pk_bf16_f32 v122, v122, v123
	v_and_b32_e32 v123, 0xffff0000, v122
	v_lshlrev_b32_e32 v122, 16, v122
	v_or_b32_sdwa v129, v123, v0 dst_sel:DWORD dst_unused:UNUSED_PAD src0_sel:DWORD src1_sel:WORD_1
	v_or_b32_sdwa v128, v122, v0 dst_sel:DWORD dst_unused:UNUSED_PAD src0_sel:DWORD src1_sel:WORD_0
	global_store_dwordx4 v[146:147], v[126:129], off
	s_nop 1
	v_add_u32_e32 v126, 0x80, v156
	v_add_u32_e32 v0, v157, v126
	v_add_u32_e32 v0, v0, v158
	s_waitcnt vmcnt(11)
	v_lshlrev_b32_e32 v127, 16, v168
	v_and_b32_e32 v133, 0xffff0000, v168
	v_lshlrev_b32_e32 v147, 16, v169
	v_and_b32_e32 v149, 0xffff0000, v169
	v_lshl_add_u64 v[122:123], v[0:1], 1, s[10:11]
	v_lshlrev_b32_e32 v146, 16, v170
	v_mul_f32_e32 v0, 0xbfb8aa3b, v127
	v_exp_f32_e32 v132, v0
	v_mul_f32_e32 v0, 0xbfb8aa3b, v146
	v_and_b32_e32 v124, 0xffff0000, v170
	v_exp_f32_e32 v146, v0
	v_mul_f32_e32 v0, 0xbfb8aa3b, v133
	v_exp_f32_e32 v148, v0
	v_mul_f32_e32 v0, 0xbfb8aa3b, v124
	v_exp_f32_e32 v124, v0
	v_mul_f32_e32 v0, 0xbfb8aa3b, v147
	v_exp_f32_e32 v133, v0
	v_lshlrev_b32_e32 v150, 16, v171
	v_mul_f32_e32 v0, 0xbfb8aa3b, v150
	v_and_b32_e32 v125, 0xffff0000, v171
	v_exp_f32_e32 v147, v0
	v_mul_f32_e32 v0, 0xbfb8aa3b, v149
	v_exp_f32_e32 v149, v0
	v_mul_f32_e32 v0, 0xbfb8aa3b, v125
	v_pk_add_f32 v[132:133], v[132:133], 1.0 op_sel_hi:[1,0]
	v_exp_f32_e32 v125, v0
	v_pk_add_f32 v[148:149], v[148:149], 1.0 op_sel_hi:[1,0]
	v_pk_add_f32 v[124:125], v[124:125], 1.0 op_sel_hi:[1,0]
	v_rcp_f32_e32 v133, v133
	s_nop 0
	s_waitcnt vmcnt(10)
	v_lshlrev_b32_e32 v151, 16, v173
	v_rcp_f32_e32 v132, v132
	s_nop 0
	v_mov_b32_e32 v160, v118
	v_mov_b32_e32 v161, v120
	v_lshlrev_b32_e32 v150, 16, v172
	v_pk_fma_f32 v[132:133], v[160:161], v[132:133], v[150:151]
	v_rcp_f32_e32 v149, v149
	s_nop 0
	v_and_b32_e32 v129, 0xffff0000, v173
	v_and_b32_e32 v128, 0xffff0000, v172
	v_rcp_f32_e32 v148, v148
	s_nop 0
	v_mov_b32_e32 v120, v119
	v_pk_fma_f32 v[118:119], v[120:121], v[148:149], v[128:129]
	v_cvt_pk_bf16_f32 v0, v132, v133
	v_cvt_pk_bf16_f32 v118, v118, v119
	v_and_b32_e32 v119, 0xffff0000, v118
	v_lshlrev_b32_e32 v118, 16, v118
	v_lshlrev_b32_e32 v121, 16, v175
	v_lshlrev_b32_e32 v120, 16, v174
	v_and_b32_e32 v129, 0xffff0000, v175
	v_and_b32_e32 v128, 0xffff0000, v174
	v_pk_add_f32 v[130:131], v[146:147], 1.0 op_sel_hi:[1,0]
	v_or_b32_sdwa v119, v119, v0 dst_sel:DWORD dst_unused:UNUSED_PAD src0_sel:DWORD src1_sel:WORD_1
	v_or_b32_sdwa v118, v118, v0 dst_sel:DWORD dst_unused:UNUSED_PAD src0_sel:DWORD src1_sel:WORD_0
	s_nop 0
	v_rcp_f32_e32 v131, v131
	s_nop 0
	s_nop 0
	v_rcp_f32_e32 v130, v130
	s_nop 0
	v_mov_b32_e32 v132, v114
	v_mov_b32_e32 v133, v116
	v_pk_fma_f32 v[120:121], v[132:133], v[130:131], v[120:121]
	v_rcp_f32_e32 v125, v125
	s_nop 0
	s_nop 0
	v_rcp_f32_e32 v124, v124
	s_nop 0
	v_mov_b32_e32 v116, v115
	v_pk_fma_f32 v[114:115], v[116:117], v[124:125], v[128:129]
	v_cvt_pk_bf16_f32 v0, v120, v121
	v_cvt_pk_bf16_f32 v114, v114, v115
	v_and_b32_e32 v115, 0xffff0000, v114
	v_lshlrev_b32_e32 v114, 16, v114
	v_add_u32_e32 v127, 0x16c00, v157
	v_or_b32_sdwa v121, v115, v0 dst_sel:DWORD dst_unused:UNUSED_PAD src0_sel:DWORD src1_sel:WORD_1
	v_or_b32_sdwa v120, v114, v0 dst_sel:DWORD dst_unused:UNUSED_PAD src0_sel:DWORD src1_sel:WORD_0
	v_add_u32_e32 v0, v127, v156
	v_add_u32_e32 v212, 0x44400, v210
	v_lshl_add_u64 v[168:169], v[212:213], 1, s[6:7]
	global_load_dwordx4 v[168:171], v[168:169], off
	v_add_u32_e32 v212, 0xc000, v211
	v_lshl_add_u64 v[172:173], v[212:213], 1, s[10:11]
	global_load_dwordx4 v[172:175], v[172:173], off
	global_store_dwordx4 v[122:123], v[118:121], off
	s_nop 1
	v_or_b32_e32 v118, 16, v159
	v_mul_lo_u32 v146, v118, s61
	v_add_u32_e32 v0, v0, v146
	s_waitcnt vmcnt(12)
	v_lshlrev_b32_e32 v122, 16, v176
	v_and_b32_e32 v123, 0xffff0000, v176
	v_lshlrev_b32_e32 v125, 16, v177
	v_and_b32_e32 v129, 0xffff0000, v177
	v_lshl_add_u64 v[114:115], v[0:1], 1, s[10:11]
	v_lshlrev_b32_e32 v124, 16, v178
	v_mul_f32_e32 v0, 0xbfb8aa3b, v122
	v_exp_f32_e32 v122, v0
	v_mul_f32_e32 v0, 0xbfb8aa3b, v124
	v_and_b32_e32 v116, 0xffff0000, v178
	v_exp_f32_e32 v124, v0
	v_mul_f32_e32 v0, 0xbfb8aa3b, v123
	v_exp_f32_e32 v128, v0
	v_mul_f32_e32 v0, 0xbfb8aa3b, v116
	v_exp_f32_e32 v116, v0
	v_mul_f32_e32 v0, 0xbfb8aa3b, v125
	v_exp_f32_e32 v123, v0
	v_lshlrev_b32_e32 v130, 16, v179
	v_mul_f32_e32 v0, 0xbfb8aa3b, v130
	v_and_b32_e32 v117, 0xffff0000, v179
	v_exp_f32_e32 v125, v0
	v_mul_f32_e32 v0, 0xbfb8aa3b, v129
	v_exp_f32_e32 v129, v0
	v_mul_f32_e32 v0, 0xbfb8aa3b, v117
	v_pk_add_f32 v[122:123], v[122:123], 1.0 op_sel_hi:[1,0]
	v_exp_f32_e32 v117, v0
	v_pk_add_f32 v[128:129], v[128:129], 1.0 op_sel_hi:[1,0]
	v_pk_add_f32 v[116:117], v[116:117], 1.0 op_sel_hi:[1,0]
	v_rcp_f32_e32 v123, v123
	s_nop 0
	s_waitcnt vmcnt(11)
	v_lshlrev_b32_e32 v131, 16, v183
	v_rcp_f32_e32 v122, v122
	s_nop 0
	v_mov_b32_e32 v132, v110
	v_mov_b32_e32 v133, v112
	v_lshlrev_b32_e32 v130, 16, v182
	v_pk_fma_f32 v[122:123], v[132:133], v[122:123], v[130:131]
	v_rcp_f32_e32 v129, v129
	s_nop 0
	v_and_b32_e32 v119, 0xffff0000, v183
	v_and_b32_e32 v118, 0xffff0000, v182
	v_rcp_f32_e32 v128, v128
	s_nop 0
	v_mov_b32_e32 v112, v111
	v_pk_fma_f32 v[110:111], v[112:113], v[128:129], v[118:119]
	v_cvt_pk_bf16_f32 v0, v122, v123
	v_cvt_pk_bf16_f32 v110, v110, v111
	v_and_b32_e32 v111, 0xffff0000, v110
	v_lshlrev_b32_e32 v110, 16, v110
	v_lshlrev_b32_e32 v113, 16, v185
	v_lshlrev_b32_e32 v112, 16, v184
	v_and_b32_e32 v119, 0xffff0000, v185
	v_and_b32_e32 v118, 0xffff0000, v184
	v_pk_add_f32 v[120:121], v[124:125], 1.0 op_sel_hi:[1,0]
	v_or_b32_sdwa v111, v111, v0 dst_sel:DWORD dst_unused:UNUSED_PAD src0_sel:DWORD src1_sel:WORD_1
	v_or_b32_sdwa v110, v110, v0 dst_sel:DWORD dst_unused:UNUSED_PAD src0_sel:DWORD src1_sel:WORD_0
	s_nop 0
	v_rcp_f32_e32 v121, v121
	s_nop 0
	s_nop 0
	v_rcp_f32_e32 v120, v120
	s_nop 0
	v_mov_b32_e32 v122, v106
	v_mov_b32_e32 v123, v108
	v_pk_fma_f32 v[112:113], v[122:123], v[120:121], v[112:113]
	v_rcp_f32_e32 v117, v117
	s_nop 0
	s_nop 0
	v_rcp_f32_e32 v116, v116
	s_nop 0
	v_mov_b32_e32 v108, v107
	v_pk_fma_f32 v[106:107], v[108:109], v[116:117], v[118:119]
	v_cvt_pk_bf16_f32 v0, v112, v113
	v_cvt_pk_bf16_f32 v106, v106, v107
	v_and_b32_e32 v107, 0xffff0000, v106
	v_lshlrev_b32_e32 v106, 16, v106
	v_or_b32_sdwa v113, v107, v0 dst_sel:DWORD dst_unused:UNUSED_PAD src0_sel:DWORD src1_sel:WORD_1
	v_or_b32_sdwa v112, v106, v0 dst_sel:DWORD dst_unused:UNUSED_PAD src0_sel:DWORD src1_sel:WORD_0
	v_add_u32_e32 v0, v127, v126
	v_add_u32_e32 v212, 0x44480, v210
	v_lshl_add_u64 v[176:177], v[212:213], 1, s[6:7]
	global_load_dwordx4 v[176:179], v[176:177], off
	v_add_u32_e32 v212, 0xc080, v211
	v_lshl_add_u64 v[182:183], v[212:213], 1, s[10:11]
	global_load_dwordx4 v[182:185], v[182:183], off
	global_store_dwordx4 v[114:115], v[110:113], off
	v_add_u32_e32 v0, v0, v146
	s_waitcnt vmcnt(13)
	v_lshlrev_b32_e32 v114, 16, v186
	v_and_b32_e32 v115, 0xffff0000, v186
	v_lshlrev_b32_e32 v117, 16, v187
	v_and_b32_e32 v119, 0xffff0000, v187
	v_lshl_add_u64 v[106:107], v[0:1], 1, s[10:11]
	v_lshlrev_b32_e32 v116, 16, v188
	v_mul_f32_e32 v0, 0xbfb8aa3b, v114
	v_exp_f32_e32 v114, v0
	v_mul_f32_e32 v0, 0xbfb8aa3b, v116
	v_and_b32_e32 v108, 0xffff0000, v188
	v_exp_f32_e32 v116, v0
	v_mul_f32_e32 v0, 0xbfb8aa3b, v115
	v_exp_f32_e32 v118, v0
	v_mul_f32_e32 v0, 0xbfb8aa3b, v108
	v_exp_f32_e32 v108, v0
	v_mul_f32_e32 v0, 0xbfb8aa3b, v117
	v_exp_f32_e32 v115, v0
	v_lshlrev_b32_e32 v120, 16, v189
	v_mul_f32_e32 v0, 0xbfb8aa3b, v120
	v_and_b32_e32 v109, 0xffff0000, v189
	v_exp_f32_e32 v117, v0
	v_mul_f32_e32 v0, 0xbfb8aa3b, v119
	v_exp_f32_e32 v119, v0
	v_mul_f32_e32 v0, 0xbfb8aa3b, v109
	v_pk_add_f32 v[114:115], v[114:115], 1.0 op_sel_hi:[1,0]
	v_exp_f32_e32 v109, v0
	v_pk_add_f32 v[118:119], v[118:119], 1.0 op_sel_hi:[1,0]
	v_pk_add_f32 v[108:109], v[108:109], 1.0 op_sel_hi:[1,0]
	v_rcp_f32_e32 v115, v115
	s_nop 0
	s_waitcnt vmcnt(12)
	v_lshlrev_b32_e32 v121, 16, v191
	v_rcp_f32_e32 v114, v114
	s_nop 0
	v_mov_b32_e32 v122, v102
	v_mov_b32_e32 v123, v104
	v_lshlrev_b32_e32 v120, 16, v190
	v_pk_fma_f32 v[114:115], v[122:123], v[114:115], v[120:121]
	v_rcp_f32_e32 v119, v119
	s_nop 0
	v_and_b32_e32 v111, 0xffff0000, v191
	v_and_b32_e32 v110, 0xffff0000, v190
	v_rcp_f32_e32 v118, v118
	s_nop 0
	v_mov_b32_e32 v104, v103
	v_pk_fma_f32 v[102:103], v[104:105], v[118:119], v[110:111]
	v_cvt_pk_bf16_f32 v0, v114, v115
	v_cvt_pk_bf16_f32 v102, v102, v103
	v_and_b32_e32 v103, 0xffff0000, v102
	v_lshlrev_b32_e32 v102, 16, v102
	v_lshlrev_b32_e32 v105, 16, v193
	v_lshlrev_b32_e32 v104, 16, v192
	v_and_b32_e32 v111, 0xffff0000, v193
	v_and_b32_e32 v110, 0xffff0000, v192
	v_pk_add_f32 v[112:113], v[116:117], 1.0 op_sel_hi:[1,0]
	v_or_b32_sdwa v103, v103, v0 dst_sel:DWORD dst_unused:UNUSED_PAD src0_sel:DWORD src1_sel:WORD_1
	v_or_b32_sdwa v102, v102, v0 dst_sel:DWORD dst_unused:UNUSED_PAD src0_sel:DWORD src1_sel:WORD_0
	s_nop 0
	v_rcp_f32_e32 v113, v113
	s_nop 0
	s_nop 0
	v_rcp_f32_e32 v112, v112
	s_nop 0
	v_mov_b32_e32 v114, v98
	v_mov_b32_e32 v115, v100
	v_pk_fma_f32 v[104:105], v[114:115], v[112:113], v[104:105]
	v_add_u32_e32 v116, 0x2d800, v157
	v_rcp_f32_e32 v109, v109
	s_nop 0
	s_nop 0
	v_rcp_f32_e32 v108, v108
	s_nop 0
	v_mov_b32_e32 v100, v99
	v_pk_fma_f32 v[98:99], v[100:101], v[108:109], v[110:111]
	v_cvt_pk_bf16_f32 v0, v104, v105
	v_cvt_pk_bf16_f32 v98, v98, v99
	v_and_b32_e32 v99, 0xffff0000, v98
	v_lshlrev_b32_e32 v98, 16, v98
	v_or_b32_sdwa v105, v99, v0 dst_sel:DWORD dst_unused:UNUSED_PAD src0_sel:DWORD src1_sel:WORD_1
	v_or_b32_sdwa v104, v98, v0 dst_sel:DWORD dst_unused:UNUSED_PAD src0_sel:DWORD src1_sel:WORD_0
	v_add_u32_e32 v0, v116, v156
	v_add_u32_e32 v212, 0xb6000, v210
	v_lshl_add_u64 v[186:187], v[212:213], 1, s[6:7]
	global_load_dwordx4 v[186:189], v[186:187], off
	v_add_u32_e32 v212, 0x20000, v211
	v_lshl_add_u64 v[190:191], v[212:213], 1, s[10:11]
	global_load_dwordx4 v[190:193], v[190:191], off
	global_store_dwordx4 v[106:107], v[102:105], off
	s_nop 1
	v_or_b32_e32 v102, 32, v159
	v_mul_lo_u32 v117, v102, s61
	v_add_u32_e32 v0, v0, v117
	s_waitcnt vmcnt(14)
	v_lshlrev_b32_e32 v106, 16, v194
	v_and_b32_e32 v107, 0xffff0000, v194
	v_lshlrev_b32_e32 v109, 16, v195
	v_and_b32_e32 v111, 0xffff0000, v195
	v_lshl_add_u64 v[98:99], v[0:1], 1, s[10:11]
	v_lshlrev_b32_e32 v108, 16, v196
	v_mul_f32_e32 v0, 0xbfb8aa3b, v106
	v_exp_f32_e32 v106, v0
	v_mul_f32_e32 v0, 0xbfb8aa3b, v108
	v_and_b32_e32 v100, 0xffff0000, v196
	v_exp_f32_e32 v108, v0
	v_mul_f32_e32 v0, 0xbfb8aa3b, v107
	v_exp_f32_e32 v110, v0
	v_mul_f32_e32 v0, 0xbfb8aa3b, v100
	v_exp_f32_e32 v100, v0
	v_mul_f32_e32 v0, 0xbfb8aa3b, v109
	v_exp_f32_e32 v107, v0
	v_lshlrev_b32_e32 v112, 16, v197
	v_mul_f32_e32 v0, 0xbfb8aa3b, v112
	v_and_b32_e32 v101, 0xffff0000, v197
	v_exp_f32_e32 v109, v0
	v_mul_f32_e32 v0, 0xbfb8aa3b, v111
	v_exp_f32_e32 v111, v0
	v_mul_f32_e32 v0, 0xbfb8aa3b, v101
	v_pk_add_f32 v[106:107], v[106:107], 1.0 op_sel_hi:[1,0]
	v_exp_f32_e32 v101, v0
	v_pk_add_f32 v[110:111], v[110:111], 1.0 op_sel_hi:[1,0]
	v_pk_add_f32 v[100:101], v[100:101], 1.0 op_sel_hi:[1,0]
	v_rcp_f32_e32 v107, v107
	s_nop 0
	s_waitcnt vmcnt(13)
	v_lshlrev_b32_e32 v113, 16, v199
	v_rcp_f32_e32 v106, v106
	s_nop 0
	v_mov_b32_e32 v114, v94
	v_mov_b32_e32 v115, v96
	v_lshlrev_b32_e32 v112, 16, v198
	v_pk_fma_f32 v[106:107], v[114:115], v[106:107], v[112:113]
	v_rcp_f32_e32 v111, v111
	s_nop 0
	v_and_b32_e32 v103, 0xffff0000, v199
	v_and_b32_e32 v102, 0xffff0000, v198
	v_rcp_f32_e32 v110, v110
	s_nop 0
	v_mov_b32_e32 v96, v95
	v_pk_fma_f32 v[94:95], v[96:97], v[110:111], v[102:103]
	v_cvt_pk_bf16_f32 v0, v106, v107
	v_cvt_pk_bf16_f32 v94, v94, v95
	v_and_b32_e32 v95, 0xffff0000, v94
	v_lshlrev_b32_e32 v94, 16, v94
	v_lshlrev_b32_e32 v97, 16, v201
	v_lshlrev_b32_e32 v96, 16, v200
	v_and_b32_e32 v103, 0xffff0000, v201
	v_and_b32_e32 v102, 0xffff0000, v200
	v_pk_add_f32 v[104:105], v[108:109], 1.0 op_sel_hi:[1,0]
	v_or_b32_sdwa v95, v95, v0 dst_sel:DWORD dst_unused:UNUSED_PAD src0_sel:DWORD src1_sel:WORD_1
	v_or_b32_sdwa v94, v94, v0 dst_sel:DWORD dst_unused:UNUSED_PAD src0_sel:DWORD src1_sel:WORD_0
	s_nop 0
	v_rcp_f32_e32 v105, v105
	s_nop 0
	s_nop 0
	v_rcp_f32_e32 v104, v104
	s_nop 0
	v_mov_b32_e32 v106, v90
	v_mov_b32_e32 v107, v92
	v_pk_fma_f32 v[96:97], v[106:107], v[104:105], v[96:97]
	v_rcp_f32_e32 v101, v101
	s_nop 0
	s_nop 0
	v_rcp_f32_e32 v100, v100
	s_nop 0
	v_mov_b32_e32 v92, v91
	v_pk_fma_f32 v[90:91], v[92:93], v[100:101], v[102:103]
	v_cvt_pk_bf16_f32 v0, v96, v97
	v_cvt_pk_bf16_f32 v90, v90, v91
	v_and_b32_e32 v91, 0xffff0000, v90
	v_lshlrev_b32_e32 v90, 16, v90
	v_or_b32_sdwa v97, v91, v0 dst_sel:DWORD dst_unused:UNUSED_PAD src0_sel:DWORD src1_sel:WORD_1
	v_or_b32_sdwa v96, v90, v0 dst_sel:DWORD dst_unused:UNUSED_PAD src0_sel:DWORD src1_sel:WORD_0
	v_add_u32_e32 v0, v116, v126
	v_add_u32_e32 v212, 0xb6080, v210
	v_lshl_add_u64 v[194:195], v[212:213], 1, s[6:7]
	global_load_dwordx4 v[194:197], v[194:195], off
	v_add_u32_e32 v212, 0x20080, v211
	v_lshl_add_u64 v[198:199], v[212:213], 1, s[10:11]
	global_load_dwordx4 v[198:201], v[198:199], off
	global_store_dwordx4 v[98:99], v[94:97], off
	v_add_u32_e32 v0, v0, v117
	s_waitcnt vmcnt(15)
	v_lshlrev_b32_e32 v98, 16, v202
	v_and_b32_e32 v99, 0xffff0000, v202
	v_lshlrev_b32_e32 v101, 16, v203
	v_and_b32_e32 v103, 0xffff0000, v203
	v_lshl_add_u64 v[90:91], v[0:1], 1, s[10:11]
	v_lshlrev_b32_e32 v100, 16, v204
	v_mul_f32_e32 v0, 0xbfb8aa3b, v98
	v_exp_f32_e32 v98, v0
	v_mul_f32_e32 v0, 0xbfb8aa3b, v100
	v_and_b32_e32 v92, 0xffff0000, v204
	v_exp_f32_e32 v100, v0
	v_mul_f32_e32 v0, 0xbfb8aa3b, v99
	v_exp_f32_e32 v102, v0
	v_mul_f32_e32 v0, 0xbfb8aa3b, v92
	v_exp_f32_e32 v92, v0
	v_mul_f32_e32 v0, 0xbfb8aa3b, v101
	v_exp_f32_e32 v99, v0
	v_lshlrev_b32_e32 v104, 16, v205
	v_mul_f32_e32 v0, 0xbfb8aa3b, v104
	v_and_b32_e32 v93, 0xffff0000, v205
	v_exp_f32_e32 v101, v0
	v_mul_f32_e32 v0, 0xbfb8aa3b, v103
	v_exp_f32_e32 v103, v0
	v_mul_f32_e32 v0, 0xbfb8aa3b, v93
	v_pk_add_f32 v[98:99], v[98:99], 1.0 op_sel_hi:[1,0]
	v_exp_f32_e32 v93, v0
	v_pk_add_f32 v[102:103], v[102:103], 1.0 op_sel_hi:[1,0]
	v_pk_add_f32 v[92:93], v[92:93], 1.0 op_sel_hi:[1,0]
	v_rcp_f32_e32 v99, v99
	s_nop 0
	s_waitcnt vmcnt(14)
	v_lshlrev_b32_e32 v105, 16, v207
	v_rcp_f32_e32 v98, v98
	s_nop 0
	v_mov_b32_e32 v106, v86
	v_mov_b32_e32 v107, v88
	v_lshlrev_b32_e32 v104, 16, v206
	v_pk_fma_f32 v[98:99], v[106:107], v[98:99], v[104:105]
	v_rcp_f32_e32 v103, v103
	s_nop 0
	v_and_b32_e32 v95, 0xffff0000, v207
	v_and_b32_e32 v94, 0xffff0000, v206
	v_rcp_f32_e32 v102, v102
	s_nop 0
	v_mov_b32_e32 v88, v87
	v_pk_fma_f32 v[86:87], v[88:89], v[102:103], v[94:95]
	v_cvt_pk_bf16_f32 v0, v98, v99
	v_cvt_pk_bf16_f32 v86, v86, v87
	v_and_b32_e32 v87, 0xffff0000, v86
	v_lshlrev_b32_e32 v86, 16, v86
	v_lshlrev_b32_e32 v89, 16, v209
	v_lshlrev_b32_e32 v88, 16, v208
	v_and_b32_e32 v95, 0xffff0000, v209
	v_and_b32_e32 v94, 0xffff0000, v208
	v_pk_add_f32 v[96:97], v[100:101], 1.0 op_sel_hi:[1,0]
	v_or_b32_sdwa v87, v87, v0 dst_sel:DWORD dst_unused:UNUSED_PAD src0_sel:DWORD src1_sel:WORD_1
	v_or_b32_sdwa v86, v86, v0 dst_sel:DWORD dst_unused:UNUSED_PAD src0_sel:DWORD src1_sel:WORD_0
	s_nop 0
	v_rcp_f32_e32 v97, v97
	s_nop 0
	s_nop 0
	v_rcp_f32_e32 v96, v96
	s_nop 0
	v_mov_b32_e32 v98, v82
	v_mov_b32_e32 v99, v84
	v_pk_fma_f32 v[88:89], v[98:99], v[96:97], v[88:89]
	v_add_u32_e32 v100, 0x44400, v157
	v_rcp_f32_e32 v93, v93
	s_nop 0
	s_nop 0
	v_rcp_f32_e32 v92, v92
	s_nop 0
	v_mov_b32_e32 v84, v83
	v_pk_fma_f32 v[82:83], v[84:85], v[92:93], v[94:95]
	v_cvt_pk_bf16_f32 v0, v88, v89
	v_cvt_pk_bf16_f32 v82, v82, v83
	v_and_b32_e32 v83, 0xffff0000, v82
	v_lshlrev_b32_e32 v82, 16, v82
	v_or_b32_sdwa v89, v83, v0 dst_sel:DWORD dst_unused:UNUSED_PAD src0_sel:DWORD src1_sel:WORD_1
	v_or_b32_sdwa v88, v82, v0 dst_sel:DWORD dst_unused:UNUSED_PAD src0_sel:DWORD src1_sel:WORD_0
	v_add_u32_e32 v0, v100, v156
	v_add_u32_e32 v212, 0xccc00, v210
	v_lshl_add_u64 v[202:203], v[212:213], 1, s[6:7]
	global_load_dwordx4 v[202:205], v[202:203], off
	v_add_u32_e32 v212, 0x24000, v211
	v_lshl_add_u64 v[206:207], v[212:213], 1, s[10:11]
	global_load_dwordx4 v[206:209], v[206:207], off
	global_store_dwordx4 v[90:91], v[86:89], off
	s_nop 1
	v_or_b32_e32 v86, 48, v159
	v_mul_lo_u32 v101, v86, s61
	v_add_u32_e32 v0, v0, v101
	s_waitcnt vmcnt(14)
	v_lshlrev_b32_e32 v90, 16, v168
	v_and_b32_e32 v91, 0xffff0000, v168
	v_lshlrev_b32_e32 v93, 16, v169
	v_and_b32_e32 v95, 0xffff0000, v169
	v_lshl_add_u64 v[82:83], v[0:1], 1, s[10:11]
	v_lshlrev_b32_e32 v92, 16, v170
	v_mul_f32_e32 v0, 0xbfb8aa3b, v90
	v_exp_f32_e32 v90, v0
	v_mul_f32_e32 v0, 0xbfb8aa3b, v92
	v_and_b32_e32 v84, 0xffff0000, v170
	v_exp_f32_e32 v92, v0
	v_mul_f32_e32 v0, 0xbfb8aa3b, v91
	v_exp_f32_e32 v94, v0
	v_mul_f32_e32 v0, 0xbfb8aa3b, v84
	v_exp_f32_e32 v84, v0
	v_mul_f32_e32 v0, 0xbfb8aa3b, v93
	v_exp_f32_e32 v91, v0
	v_lshlrev_b32_e32 v96, 16, v171
	v_mul_f32_e32 v0, 0xbfb8aa3b, v96
	v_and_b32_e32 v85, 0xffff0000, v171
	v_exp_f32_e32 v93, v0
	v_mul_f32_e32 v0, 0xbfb8aa3b, v95
	v_exp_f32_e32 v95, v0
	v_mul_f32_e32 v0, 0xbfb8aa3b, v85
	v_pk_add_f32 v[90:91], v[90:91], 1.0 op_sel_hi:[1,0]
	v_exp_f32_e32 v85, v0
	v_pk_add_f32 v[94:95], v[94:95], 1.0 op_sel_hi:[1,0]
	v_pk_add_f32 v[84:85], v[84:85], 1.0 op_sel_hi:[1,0]
	v_rcp_f32_e32 v91, v91
	s_nop 0
	s_waitcnt vmcnt(13)
	v_lshlrev_b32_e32 v97, 16, v173
	v_rcp_f32_e32 v90, v90
	s_nop 0
	v_mov_b32_e32 v98, v78
	v_mov_b32_e32 v99, v80
	v_lshlrev_b32_e32 v96, 16, v172
	v_pk_fma_f32 v[90:91], v[98:99], v[90:91], v[96:97]
	v_rcp_f32_e32 v95, v95
	s_nop 0
	v_and_b32_e32 v87, 0xffff0000, v173
	v_and_b32_e32 v86, 0xffff0000, v172
	v_rcp_f32_e32 v94, v94
	s_nop 0
	v_mov_b32_e32 v80, v79
	v_pk_fma_f32 v[78:79], v[80:81], v[94:95], v[86:87]
	v_cvt_pk_bf16_f32 v0, v90, v91
	v_cvt_pk_bf16_f32 v78, v78, v79
	v_and_b32_e32 v79, 0xffff0000, v78
	v_lshlrev_b32_e32 v78, 16, v78
	v_lshlrev_b32_e32 v81, 16, v175
	v_lshlrev_b32_e32 v80, 16, v174
	v_and_b32_e32 v87, 0xffff0000, v175
	v_and_b32_e32 v86, 0xffff0000, v174
	v_pk_add_f32 v[88:89], v[92:93], 1.0 op_sel_hi:[1,0]
	v_or_b32_sdwa v79, v79, v0 dst_sel:DWORD dst_unused:UNUSED_PAD src0_sel:DWORD src1_sel:WORD_1
	v_or_b32_sdwa v78, v78, v0 dst_sel:DWORD dst_unused:UNUSED_PAD src0_sel:DWORD src1_sel:WORD_0
	s_nop 0
	v_rcp_f32_e32 v89, v89
	s_nop 0
	s_nop 0
	v_rcp_f32_e32 v88, v88
	s_nop 0
	v_mov_b32_e32 v90, v74
	v_mov_b32_e32 v91, v76
	v_pk_fma_f32 v[80:81], v[90:91], v[88:89], v[80:81]
	v_rcp_f32_e32 v85, v85
	s_nop 0
	s_nop 0
	v_rcp_f32_e32 v84, v84
	s_nop 0
	v_mov_b32_e32 v76, v75
	v_pk_fma_f32 v[74:75], v[76:77], v[84:85], v[86:87]
	v_cvt_pk_bf16_f32 v0, v80, v81
	v_cvt_pk_bf16_f32 v74, v74, v75
	v_and_b32_e32 v75, 0xffff0000, v74
	v_lshlrev_b32_e32 v74, 16, v74
	v_or_b32_sdwa v81, v75, v0 dst_sel:DWORD dst_unused:UNUSED_PAD src0_sel:DWORD src1_sel:WORD_1
	v_or_b32_sdwa v80, v74, v0 dst_sel:DWORD dst_unused:UNUSED_PAD src0_sel:DWORD src1_sel:WORD_0
	v_add_u32_e32 v0, v100, v126
	v_add_u32_e32 v212, 0xccc80, v210
	v_lshl_add_u64 v[168:169], v[212:213], 1, s[6:7]
	global_load_dwordx4 v[168:171], v[168:169], off
	v_add_u32_e32 v212, 0x24080, v211
	v_lshl_add_u64 v[172:173], v[212:213], 1, s[10:11]
	global_load_dwordx4 v[172:175], v[172:173], off
	global_store_dwordx4 v[82:83], v[78:81], off
	v_add_u32_e32 v0, v0, v101
	s_waitcnt vmcnt(14)
	v_lshlrev_b32_e32 v82, 16, v176
	v_and_b32_e32 v83, 0xffff0000, v176
	v_lshlrev_b32_e32 v85, 16, v177
	v_and_b32_e32 v87, 0xffff0000, v177
	v_lshl_add_u64 v[74:75], v[0:1], 1, s[10:11]
	v_lshlrev_b32_e32 v84, 16, v178
	v_mul_f32_e32 v0, 0xbfb8aa3b, v82
	v_exp_f32_e32 v82, v0
	v_mul_f32_e32 v0, 0xbfb8aa3b, v84
	v_and_b32_e32 v76, 0xffff0000, v178
	v_exp_f32_e32 v84, v0
	v_mul_f32_e32 v0, 0xbfb8aa3b, v83
	v_exp_f32_e32 v86, v0
	v_mul_f32_e32 v0, 0xbfb8aa3b, v76
	v_exp_f32_e32 v76, v0
	v_mul_f32_e32 v0, 0xbfb8aa3b, v85
	v_exp_f32_e32 v83, v0
	v_lshlrev_b32_e32 v88, 16, v179
	v_mul_f32_e32 v0, 0xbfb8aa3b, v88
	v_and_b32_e32 v77, 0xffff0000, v179
	v_exp_f32_e32 v85, v0
	v_mul_f32_e32 v0, 0xbfb8aa3b, v87
	v_exp_f32_e32 v87, v0
	v_mul_f32_e32 v0, 0xbfb8aa3b, v77
	v_pk_add_f32 v[82:83], v[82:83], 1.0 op_sel_hi:[1,0]
	v_exp_f32_e32 v77, v0
	v_pk_add_f32 v[86:87], v[86:87], 1.0 op_sel_hi:[1,0]
	v_pk_add_f32 v[76:77], v[76:77], 1.0 op_sel_hi:[1,0]
	v_rcp_f32_e32 v83, v83
	s_nop 0
	s_waitcnt vmcnt(13)
	v_lshlrev_b32_e32 v89, 16, v183
	v_rcp_f32_e32 v82, v82
	s_nop 0
	v_mov_b32_e32 v90, v70
	v_mov_b32_e32 v91, v72
	v_lshlrev_b32_e32 v88, 16, v182
	v_pk_fma_f32 v[82:83], v[90:91], v[82:83], v[88:89]
	v_rcp_f32_e32 v87, v87
	s_nop 0
	v_and_b32_e32 v79, 0xffff0000, v183
	v_and_b32_e32 v78, 0xffff0000, v182
	v_rcp_f32_e32 v86, v86
	s_nop 0
	v_mov_b32_e32 v72, v71
	v_pk_fma_f32 v[70:71], v[72:73], v[86:87], v[78:79]
	v_cvt_pk_bf16_f32 v0, v82, v83
	v_cvt_pk_bf16_f32 v70, v70, v71
	v_and_b32_e32 v71, 0xffff0000, v70
	v_lshlrev_b32_e32 v70, 16, v70
	v_lshlrev_b32_e32 v73, 16, v185
	v_lshlrev_b32_e32 v72, 16, v184
	v_and_b32_e32 v79, 0xffff0000, v185
	v_and_b32_e32 v78, 0xffff0000, v184
	v_pk_add_f32 v[80:81], v[84:85], 1.0 op_sel_hi:[1,0]
	v_or_b32_sdwa v71, v71, v0 dst_sel:DWORD dst_unused:UNUSED_PAD src0_sel:DWORD src1_sel:WORD_1
	v_or_b32_sdwa v70, v70, v0 dst_sel:DWORD dst_unused:UNUSED_PAD src0_sel:DWORD src1_sel:WORD_0
	s_nop 0
	v_rcp_f32_e32 v81, v81
	s_nop 0
	s_nop 0
	v_rcp_f32_e32 v80, v80
	s_nop 0
	v_mov_b32_e32 v82, v66
	v_mov_b32_e32 v83, v68
	v_pk_fma_f32 v[72:73], v[82:83], v[80:81], v[72:73]
	v_add_u32_e32 v84, 0xb6000, v157
	v_rcp_f32_e32 v77, v77
	s_nop 0
	v_add_u32_e32 v85, 0xfff6a000, v158
	v_rcp_f32_e32 v76, v76
	s_nop 0
	v_mov_b32_e32 v68, v67
	v_pk_fma_f32 v[66:67], v[68:69], v[76:77], v[78:79]
	v_cvt_pk_bf16_f32 v0, v72, v73
	v_cvt_pk_bf16_f32 v66, v66, v67
	v_and_b32_e32 v67, 0xffff0000, v66
	v_lshlrev_b32_e32 v66, 16, v66
	v_or_b32_sdwa v73, v67, v0 dst_sel:DWORD dst_unused:UNUSED_PAD src0_sel:DWORD src1_sel:WORD_1
	v_or_b32_sdwa v72, v66, v0 dst_sel:DWORD dst_unused:UNUSED_PAD src0_sel:DWORD src1_sel:WORD_0
	v_add_u32_e32 v0, v84, v156
	v_add_u32_e32 v212, 0xe3800, v210
	v_lshl_add_u64 v[176:177], v[212:213], 1, s[6:7]
	global_load_dwordx4 v[176:179], v[176:177], off
	v_add_u32_e32 v212, 0x28000, v211
	v_lshl_add_u64 v[182:183], v[212:213], 1, s[10:11]
	global_load_dwordx4 v[182:185], v[182:183], off
	global_store_dwordx4 v[74:75], v[70:73], off
	v_add_u32_e32 v0, v0, v85
	s_waitcnt vmcnt(14)
	v_lshlrev_b32_e32 v74, 16, v186
	v_and_b32_e32 v75, 0xffff0000, v186
	v_lshlrev_b32_e32 v77, 16, v187
	v_and_b32_e32 v79, 0xffff0000, v187
	v_lshl_add_u64 v[66:67], v[0:1], 1, s[10:11]
	v_lshlrev_b32_e32 v76, 16, v188
	v_mul_f32_e32 v0, 0xbfb8aa3b, v74
	v_exp_f32_e32 v74, v0
	v_mul_f32_e32 v0, 0xbfb8aa3b, v76
	v_and_b32_e32 v68, 0xffff0000, v188
	v_exp_f32_e32 v76, v0
	v_mul_f32_e32 v0, 0xbfb8aa3b, v75
	v_exp_f32_e32 v78, v0
	v_mul_f32_e32 v0, 0xbfb8aa3b, v68
	v_exp_f32_e32 v68, v0
	v_mul_f32_e32 v0, 0xbfb8aa3b, v77
	v_exp_f32_e32 v75, v0
	v_lshlrev_b32_e32 v80, 16, v189
	v_mul_f32_e32 v0, 0xbfb8aa3b, v80
	v_and_b32_e32 v69, 0xffff0000, v189
	v_exp_f32_e32 v77, v0
	v_mul_f32_e32 v0, 0xbfb8aa3b, v79
	v_exp_f32_e32 v79, v0
	v_mul_f32_e32 v0, 0xbfb8aa3b, v69
	v_pk_add_f32 v[74:75], v[74:75], 1.0 op_sel_hi:[1,0]
	v_exp_f32_e32 v69, v0
	v_pk_add_f32 v[78:79], v[78:79], 1.0 op_sel_hi:[1,0]
	v_pk_add_f32 v[68:69], v[68:69], 1.0 op_sel_hi:[1,0]
	v_rcp_f32_e32 v75, v75
	s_nop 0
	s_waitcnt vmcnt(13)
	v_lshlrev_b32_e32 v81, 16, v191
	v_rcp_f32_e32 v74, v74
	s_nop 0
	v_mov_b32_e32 v82, v62
	v_mov_b32_e32 v83, v64
	v_lshlrev_b32_e32 v80, 16, v190
	v_pk_fma_f32 v[74:75], v[82:83], v[74:75], v[80:81]
	v_rcp_f32_e32 v79, v79
	s_nop 0
	v_and_b32_e32 v71, 0xffff0000, v191
	v_and_b32_e32 v70, 0xffff0000, v190
	v_rcp_f32_e32 v78, v78
	s_nop 0
	v_mov_b32_e32 v64, v63
	v_pk_fma_f32 v[62:63], v[64:65], v[78:79], v[70:71]
	v_cvt_pk_bf16_f32 v0, v74, v75
	v_cvt_pk_bf16_f32 v62, v62, v63
	v_and_b32_e32 v63, 0xffff0000, v62
	v_lshlrev_b32_e32 v62, 16, v62
	v_lshlrev_b32_e32 v65, 16, v193
	v_lshlrev_b32_e32 v64, 16, v192
	v_and_b32_e32 v71, 0xffff0000, v193
	v_and_b32_e32 v70, 0xffff0000, v192
	v_pk_add_f32 v[72:73], v[76:77], 1.0 op_sel_hi:[1,0]
	v_or_b32_sdwa v63, v63, v0 dst_sel:DWORD dst_unused:UNUSED_PAD src0_sel:DWORD src1_sel:WORD_1
	v_or_b32_sdwa v62, v62, v0 dst_sel:DWORD dst_unused:UNUSED_PAD src0_sel:DWORD src1_sel:WORD_0
	s_nop 0
	v_rcp_f32_e32 v73, v73
	s_nop 0
	s_nop 0
	v_rcp_f32_e32 v72, v72
	s_nop 0
	v_mov_b32_e32 v74, v58
	v_mov_b32_e32 v75, v60
	v_pk_fma_f32 v[64:65], v[74:75], v[72:73], v[64:65]
	v_rcp_f32_e32 v69, v69
	s_nop 0
	s_nop 0
	v_rcp_f32_e32 v68, v68
	s_nop 0
	v_mov_b32_e32 v60, v59
	v_pk_fma_f32 v[58:59], v[60:61], v[68:69], v[70:71]
	v_cvt_pk_bf16_f32 v0, v64, v65
	v_cvt_pk_bf16_f32 v58, v58, v59
	v_and_b32_e32 v59, 0xffff0000, v58
	v_lshlrev_b32_e32 v58, 16, v58
	v_or_b32_sdwa v65, v59, v0 dst_sel:DWORD dst_unused:UNUSED_PAD src0_sel:DWORD src1_sel:WORD_1
	v_or_b32_sdwa v64, v58, v0 dst_sel:DWORD dst_unused:UNUSED_PAD src0_sel:DWORD src1_sel:WORD_0
	v_add_u32_e32 v0, v84, v126
	v_add_u32_e32 v212, 0xe3880, v210
	v_lshl_add_u64 v[186:187], v[212:213], 1, s[6:7]
	global_load_dwordx4 v[186:189], v[186:187], off
	v_add_u32_e32 v212, 0x28080, v211
	v_lshl_add_u64 v[190:191], v[212:213], 1, s[10:11]
	global_load_dwordx4 v[190:193], v[190:191], off
	global_store_dwordx4 v[66:67], v[62:65], off
	v_add_u32_e32 v0, v0, v85
	s_waitcnt vmcnt(14)
	v_lshlrev_b32_e32 v66, 16, v194
	v_and_b32_e32 v67, 0xffff0000, v194
	v_lshlrev_b32_e32 v69, 16, v195
	v_and_b32_e32 v71, 0xffff0000, v195
	v_lshl_add_u64 v[58:59], v[0:1], 1, s[10:11]
	v_lshlrev_b32_e32 v68, 16, v196
	v_mul_f32_e32 v0, 0xbfb8aa3b, v66
	v_exp_f32_e32 v66, v0
	v_mul_f32_e32 v0, 0xbfb8aa3b, v68
	v_and_b32_e32 v60, 0xffff0000, v196
	v_exp_f32_e32 v68, v0
	v_mul_f32_e32 v0, 0xbfb8aa3b, v67
	v_exp_f32_e32 v70, v0
	v_mul_f32_e32 v0, 0xbfb8aa3b, v60
	v_exp_f32_e32 v60, v0
	v_mul_f32_e32 v0, 0xbfb8aa3b, v69
	v_exp_f32_e32 v67, v0
	v_lshlrev_b32_e32 v72, 16, v197
	v_mul_f32_e32 v0, 0xbfb8aa3b, v72
	v_and_b32_e32 v61, 0xffff0000, v197
	v_exp_f32_e32 v69, v0
	v_mul_f32_e32 v0, 0xbfb8aa3b, v71
	v_exp_f32_e32 v71, v0
	v_mul_f32_e32 v0, 0xbfb8aa3b, v61
	v_pk_add_f32 v[66:67], v[66:67], 1.0 op_sel_hi:[1,0]
	v_exp_f32_e32 v61, v0
	v_pk_add_f32 v[70:71], v[70:71], 1.0 op_sel_hi:[1,0]
	v_pk_add_f32 v[60:61], v[60:61], 1.0 op_sel_hi:[1,0]
	v_rcp_f32_e32 v67, v67
	s_nop 0
	s_waitcnt vmcnt(13)
	v_lshlrev_b32_e32 v73, 16, v199
	v_rcp_f32_e32 v66, v66
	s_nop 0
	v_mov_b32_e32 v74, v54
	v_mov_b32_e32 v75, v56
	v_lshlrev_b32_e32 v72, 16, v198
	v_pk_fma_f32 v[66:67], v[74:75], v[66:67], v[72:73]
	v_rcp_f32_e32 v71, v71
	s_nop 0
	v_and_b32_e32 v63, 0xffff0000, v199
	v_and_b32_e32 v62, 0xffff0000, v198
	v_rcp_f32_e32 v70, v70
	s_nop 0
	v_mov_b32_e32 v56, v55
	v_pk_fma_f32 v[54:55], v[56:57], v[70:71], v[62:63]
	v_cvt_pk_bf16_f32 v0, v66, v67
	v_cvt_pk_bf16_f32 v54, v54, v55
	v_and_b32_e32 v55, 0xffff0000, v54
	v_lshlrev_b32_e32 v54, 16, v54
	v_lshlrev_b32_e32 v57, 16, v201
	v_lshlrev_b32_e32 v56, 16, v200
	v_and_b32_e32 v63, 0xffff0000, v201
	v_and_b32_e32 v62, 0xffff0000, v200
	v_pk_add_f32 v[64:65], v[68:69], 1.0 op_sel_hi:[1,0]
	v_or_b32_sdwa v55, v55, v0 dst_sel:DWORD dst_unused:UNUSED_PAD src0_sel:DWORD src1_sel:WORD_1
	v_or_b32_sdwa v54, v54, v0 dst_sel:DWORD dst_unused:UNUSED_PAD src0_sel:DWORD src1_sel:WORD_0
	s_nop 0
	v_rcp_f32_e32 v65, v65
	s_nop 0
	s_nop 0
	v_rcp_f32_e32 v64, v64
	s_nop 0
	v_mov_b32_e32 v66, v50
	v_mov_b32_e32 v67, v52
	v_pk_fma_f32 v[56:57], v[66:67], v[64:65], v[56:57]
	v_add_u32_e32 v68, 0xccc00, v157
	v_rcp_f32_e32 v61, v61
	s_nop 0
	v_add_u32_e32 v69, 0xfff57400, v158
	v_rcp_f32_e32 v60, v60
	s_nop 0
	v_mov_b32_e32 v52, v51
	v_pk_fma_f32 v[50:51], v[52:53], v[60:61], v[62:63]
	v_cvt_pk_bf16_f32 v0, v56, v57
	v_cvt_pk_bf16_f32 v50, v50, v51
	v_and_b32_e32 v51, 0xffff0000, v50
	v_lshlrev_b32_e32 v50, 16, v50
	v_or_b32_sdwa v57, v51, v0 dst_sel:DWORD dst_unused:UNUSED_PAD src0_sel:DWORD src1_sel:WORD_1
	v_or_b32_sdwa v56, v50, v0 dst_sel:DWORD dst_unused:UNUSED_PAD src0_sel:DWORD src1_sel:WORD_0
	v_add_u32_e32 v0, v68, v156
	v_add_u32_e32 v212, 0xfa400, v210
	v_lshl_add_u64 v[194:195], v[212:213], 1, s[6:7]
	global_load_dwordx4 v[194:197], v[194:195], off
	v_add_u32_e32 v212, 0x2c000, v211
	v_lshl_add_u64 v[198:199], v[212:213], 1, s[10:11]
	global_load_dwordx4 v[198:201], v[198:199], off
	global_store_dwordx4 v[58:59], v[54:57], off
	v_add_u32_e32 v0, v0, v69
	s_waitcnt vmcnt(14)
	v_lshlrev_b32_e32 v58, 16, v202
	v_and_b32_e32 v59, 0xffff0000, v202
	v_lshlrev_b32_e32 v61, 16, v203
	v_and_b32_e32 v63, 0xffff0000, v203
	v_lshl_add_u64 v[50:51], v[0:1], 1, s[10:11]
	v_lshlrev_b32_e32 v60, 16, v204
	v_mul_f32_e32 v0, 0xbfb8aa3b, v58
	v_exp_f32_e32 v58, v0
	v_mul_f32_e32 v0, 0xbfb8aa3b, v60
	v_and_b32_e32 v52, 0xffff0000, v204
	v_exp_f32_e32 v60, v0
	v_mul_f32_e32 v0, 0xbfb8aa3b, v59
	v_exp_f32_e32 v62, v0
	v_mul_f32_e32 v0, 0xbfb8aa3b, v52
	v_exp_f32_e32 v52, v0
	v_mul_f32_e32 v0, 0xbfb8aa3b, v61
	v_exp_f32_e32 v59, v0
	v_lshlrev_b32_e32 v64, 16, v205
	v_mul_f32_e32 v0, 0xbfb8aa3b, v64
	v_and_b32_e32 v53, 0xffff0000, v205
	v_exp_f32_e32 v61, v0
	v_mul_f32_e32 v0, 0xbfb8aa3b, v63
	v_exp_f32_e32 v63, v0
	v_mul_f32_e32 v0, 0xbfb8aa3b, v53
	v_pk_add_f32 v[58:59], v[58:59], 1.0 op_sel_hi:[1,0]
	v_exp_f32_e32 v53, v0
	v_pk_add_f32 v[62:63], v[62:63], 1.0 op_sel_hi:[1,0]
	v_pk_add_f32 v[52:53], v[52:53], 1.0 op_sel_hi:[1,0]
	v_rcp_f32_e32 v59, v59
	s_nop 0
	s_waitcnt vmcnt(13)
	v_lshlrev_b32_e32 v65, 16, v207
	v_rcp_f32_e32 v58, v58
	s_nop 0
	v_mov_b32_e32 v66, v46
	v_mov_b32_e32 v67, v48
	v_lshlrev_b32_e32 v64, 16, v206
	v_pk_fma_f32 v[58:59], v[66:67], v[58:59], v[64:65]
	v_rcp_f32_e32 v63, v63
	s_nop 0
	v_and_b32_e32 v55, 0xffff0000, v207
	v_and_b32_e32 v54, 0xffff0000, v206
	v_rcp_f32_e32 v62, v62
	s_nop 0
	v_mov_b32_e32 v48, v47
	v_pk_fma_f32 v[46:47], v[48:49], v[62:63], v[54:55]
	v_cvt_pk_bf16_f32 v0, v58, v59
	v_cvt_pk_bf16_f32 v46, v46, v47
	v_and_b32_e32 v47, 0xffff0000, v46
	v_lshlrev_b32_e32 v46, 16, v46
	v_lshlrev_b32_e32 v49, 16, v209
	v_lshlrev_b32_e32 v48, 16, v208
	v_and_b32_e32 v55, 0xffff0000, v209
	v_and_b32_e32 v54, 0xffff0000, v208
	v_pk_add_f32 v[56:57], v[60:61], 1.0 op_sel_hi:[1,0]
	v_or_b32_sdwa v47, v47, v0 dst_sel:DWORD dst_unused:UNUSED_PAD src0_sel:DWORD src1_sel:WORD_1
	v_or_b32_sdwa v46, v46, v0 dst_sel:DWORD dst_unused:UNUSED_PAD src0_sel:DWORD src1_sel:WORD_0
	s_nop 0
	v_rcp_f32_e32 v57, v57
	s_nop 0
	s_nop 0
	v_rcp_f32_e32 v56, v56
	s_nop 0
	v_mov_b32_e32 v58, v42
	v_mov_b32_e32 v59, v44
	v_pk_fma_f32 v[48:49], v[58:59], v[56:57], v[48:49]
	v_rcp_f32_e32 v53, v53
	s_nop 0
	s_nop 0
	v_rcp_f32_e32 v52, v52
	s_nop 0
	v_mov_b32_e32 v44, v43
	v_pk_fma_f32 v[42:43], v[44:45], v[52:53], v[54:55]
	v_cvt_pk_bf16_f32 v0, v48, v49
	v_cvt_pk_bf16_f32 v42, v42, v43
	v_and_b32_e32 v43, 0xffff0000, v42
	v_lshlrev_b32_e32 v42, 16, v42
	v_or_b32_sdwa v49, v43, v0 dst_sel:DWORD dst_unused:UNUSED_PAD src0_sel:DWORD src1_sel:WORD_1
	v_or_b32_sdwa v48, v42, v0 dst_sel:DWORD dst_unused:UNUSED_PAD src0_sel:DWORD src1_sel:WORD_0
	v_add_u32_e32 v0, v68, v126
	v_add_u32_e32 v212, 0xfa480, v210
	v_lshl_add_u64 v[202:203], v[212:213], 1, s[6:7]
	global_load_dwordx4 v[202:205], v[202:203], off
	v_add_u32_e32 v212, 0x2c080, v211
	v_lshl_add_u64 v[206:207], v[212:213], 1, s[10:11]
	global_load_dwordx4 v[206:209], v[206:207], off
	global_store_dwordx4 v[50:51], v[46:49], off
	v_add_u32_e32 v0, v0, v69
	s_waitcnt vmcnt(14)
	v_lshlrev_b32_e32 v50, 16, v168
	v_and_b32_e32 v51, 0xffff0000, v168
	v_lshlrev_b32_e32 v53, 16, v169
	v_and_b32_e32 v55, 0xffff0000, v169
	v_lshl_add_u64 v[42:43], v[0:1], 1, s[10:11]
	v_lshlrev_b32_e32 v52, 16, v170
	v_mul_f32_e32 v0, 0xbfb8aa3b, v50
	v_exp_f32_e32 v50, v0
	v_mul_f32_e32 v0, 0xbfb8aa3b, v52
	v_and_b32_e32 v44, 0xffff0000, v170
	v_exp_f32_e32 v52, v0
	v_mul_f32_e32 v0, 0xbfb8aa3b, v51
	v_exp_f32_e32 v54, v0
	v_mul_f32_e32 v0, 0xbfb8aa3b, v44
	v_exp_f32_e32 v44, v0
	v_mul_f32_e32 v0, 0xbfb8aa3b, v53
	v_exp_f32_e32 v51, v0
	v_lshlrev_b32_e32 v56, 16, v171
	v_mul_f32_e32 v0, 0xbfb8aa3b, v56
	v_and_b32_e32 v45, 0xffff0000, v171
	v_exp_f32_e32 v53, v0
	v_mul_f32_e32 v0, 0xbfb8aa3b, v55
	v_exp_f32_e32 v55, v0
	v_mul_f32_e32 v0, 0xbfb8aa3b, v45
	v_pk_add_f32 v[50:51], v[50:51], 1.0 op_sel_hi:[1,0]
	v_exp_f32_e32 v45, v0
	v_pk_add_f32 v[54:55], v[54:55], 1.0 op_sel_hi:[1,0]
	v_pk_add_f32 v[44:45], v[44:45], 1.0 op_sel_hi:[1,0]
	v_rcp_f32_e32 v51, v51
	s_nop 0
	s_waitcnt vmcnt(13)
	v_lshlrev_b32_e32 v57, 16, v173
	v_rcp_f32_e32 v50, v50
	s_nop 0
	v_mov_b32_e32 v58, v38
	v_mov_b32_e32 v59, v40
	v_lshlrev_b32_e32 v56, 16, v172
	v_pk_fma_f32 v[50:51], v[58:59], v[50:51], v[56:57]
	v_rcp_f32_e32 v55, v55
	s_nop 0
	v_and_b32_e32 v47, 0xffff0000, v173
	v_and_b32_e32 v46, 0xffff0000, v172
	v_rcp_f32_e32 v54, v54
	s_nop 0
	v_mov_b32_e32 v40, v39
	v_pk_fma_f32 v[38:39], v[40:41], v[54:55], v[46:47]
	v_cvt_pk_bf16_f32 v0, v50, v51
	v_cvt_pk_bf16_f32 v38, v38, v39
	v_and_b32_e32 v39, 0xffff0000, v38
	v_lshlrev_b32_e32 v38, 16, v38
	v_lshlrev_b32_e32 v41, 16, v175
	v_lshlrev_b32_e32 v40, 16, v174
	v_and_b32_e32 v47, 0xffff0000, v175
	v_and_b32_e32 v46, 0xffff0000, v174
	v_pk_add_f32 v[48:49], v[52:53], 1.0 op_sel_hi:[1,0]
	v_or_b32_sdwa v39, v39, v0 dst_sel:DWORD dst_unused:UNUSED_PAD src0_sel:DWORD src1_sel:WORD_1
	v_or_b32_sdwa v38, v38, v0 dst_sel:DWORD dst_unused:UNUSED_PAD src0_sel:DWORD src1_sel:WORD_0
	s_nop 0
	v_rcp_f32_e32 v49, v49
	s_nop 0
	s_nop 0
	v_rcp_f32_e32 v48, v48
	s_nop 0
	v_mov_b32_e32 v50, v34
	v_mov_b32_e32 v51, v36
	v_pk_fma_f32 v[40:41], v[50:51], v[48:49], v[40:41]
	v_add_u32_e32 v52, 0xe3800, v157
	v_rcp_f32_e32 v45, v45
	s_nop 0
	v_add_u32_e32 v53, 0xfff44800, v158
	v_rcp_f32_e32 v44, v44
	s_nop 0
	v_mov_b32_e32 v36, v35
	v_pk_fma_f32 v[34:35], v[36:37], v[44:45], v[46:47]
	v_cvt_pk_bf16_f32 v0, v40, v41
	v_cvt_pk_bf16_f32 v34, v34, v35
	v_and_b32_e32 v35, 0xffff0000, v34
	v_lshlrev_b32_e32 v34, 16, v34
	v_or_b32_sdwa v41, v35, v0 dst_sel:DWORD dst_unused:UNUSED_PAD src0_sel:DWORD src1_sel:WORD_1
	v_or_b32_sdwa v40, v34, v0 dst_sel:DWORD dst_unused:UNUSED_PAD src0_sel:DWORD src1_sel:WORD_0
	v_add_u32_e32 v0, v52, v156
	global_store_dwordx4 v[42:43], v[38:41], off
	v_add_u32_e32 v0, v0, v53
	s_waitcnt vmcnt(12)
	v_lshlrev_b32_e32 v42, 16, v176
	v_and_b32_e32 v43, 0xffff0000, v176
	v_lshlrev_b32_e32 v45, 16, v177
	v_and_b32_e32 v47, 0xffff0000, v177
	v_lshl_add_u64 v[34:35], v[0:1], 1, s[10:11]
	v_lshlrev_b32_e32 v44, 16, v178
	v_mul_f32_e32 v0, 0xbfb8aa3b, v42
	v_exp_f32_e32 v42, v0
	v_mul_f32_e32 v0, 0xbfb8aa3b, v44
	v_and_b32_e32 v36, 0xffff0000, v178
	v_exp_f32_e32 v44, v0
	v_mul_f32_e32 v0, 0xbfb8aa3b, v43
	v_exp_f32_e32 v46, v0
	v_mul_f32_e32 v0, 0xbfb8aa3b, v36
	v_exp_f32_e32 v36, v0
	v_mul_f32_e32 v0, 0xbfb8aa3b, v45
	v_exp_f32_e32 v43, v0
	v_lshlrev_b32_e32 v48, 16, v179
	v_mul_f32_e32 v0, 0xbfb8aa3b, v48
	v_and_b32_e32 v37, 0xffff0000, v179
	v_exp_f32_e32 v45, v0
	v_mul_f32_e32 v0, 0xbfb8aa3b, v47
	v_exp_f32_e32 v47, v0
	v_mul_f32_e32 v0, 0xbfb8aa3b, v37
	v_pk_add_f32 v[42:43], v[42:43], 1.0 op_sel_hi:[1,0]
	v_exp_f32_e32 v37, v0
	v_pk_add_f32 v[46:47], v[46:47], 1.0 op_sel_hi:[1,0]
	v_pk_add_f32 v[36:37], v[36:37], 1.0 op_sel_hi:[1,0]
	v_rcp_f32_e32 v43, v43
	s_nop 0
	s_waitcnt vmcnt(11)
	v_lshlrev_b32_e32 v49, 16, v183
	v_rcp_f32_e32 v42, v42
	s_nop 0
	v_mov_b32_e32 v50, v30
	v_mov_b32_e32 v51, v32
	v_lshlrev_b32_e32 v48, 16, v182
	v_pk_fma_f32 v[42:43], v[50:51], v[42:43], v[48:49]
	v_rcp_f32_e32 v47, v47
	s_nop 0
	v_and_b32_e32 v39, 0xffff0000, v183
	v_and_b32_e32 v38, 0xffff0000, v182
	v_rcp_f32_e32 v46, v46
	s_nop 0
	v_mov_b32_e32 v32, v31
	v_pk_fma_f32 v[30:31], v[32:33], v[46:47], v[38:39]
	v_cvt_pk_bf16_f32 v0, v42, v43
	v_cvt_pk_bf16_f32 v30, v30, v31
	v_and_b32_e32 v31, 0xffff0000, v30
	v_lshlrev_b32_e32 v30, 16, v30
	v_lshlrev_b32_e32 v33, 16, v185
	v_lshlrev_b32_e32 v32, 16, v184
	v_and_b32_e32 v39, 0xffff0000, v185
	v_and_b32_e32 v38, 0xffff0000, v184
	v_pk_add_f32 v[40:41], v[44:45], 1.0 op_sel_hi:[1,0]
	v_or_b32_sdwa v31, v31, v0 dst_sel:DWORD dst_unused:UNUSED_PAD src0_sel:DWORD src1_sel:WORD_1
	v_or_b32_sdwa v30, v30, v0 dst_sel:DWORD dst_unused:UNUSED_PAD src0_sel:DWORD src1_sel:WORD_0
	s_nop 0
	v_rcp_f32_e32 v41, v41
	s_nop 0
	s_nop 0
	v_rcp_f32_e32 v40, v40
	s_nop 0
	v_mov_b32_e32 v42, v26
	v_mov_b32_e32 v43, v28
	v_pk_fma_f32 v[32:33], v[42:43], v[40:41], v[32:33]
	v_rcp_f32_e32 v37, v37
	s_nop 0
	s_nop 0
	v_rcp_f32_e32 v36, v36
	s_nop 0
	v_mov_b32_e32 v28, v27
	v_pk_fma_f32 v[26:27], v[28:29], v[36:37], v[38:39]
	v_cvt_pk_bf16_f32 v0, v32, v33
	v_cvt_pk_bf16_f32 v26, v26, v27
	v_and_b32_e32 v27, 0xffff0000, v26
	v_lshlrev_b32_e32 v26, 16, v26
	v_or_b32_sdwa v33, v27, v0 dst_sel:DWORD dst_unused:UNUSED_PAD src0_sel:DWORD src1_sel:WORD_1
	v_or_b32_sdwa v32, v26, v0 dst_sel:DWORD dst_unused:UNUSED_PAD src0_sel:DWORD src1_sel:WORD_0
	v_add_u32_e32 v0, v52, v126
	global_store_dwordx4 v[34:35], v[30:33], off
	v_add_u32_e32 v0, v0, v53
	s_waitcnt vmcnt(10)
	v_lshlrev_b32_e32 v34, 16, v186
	v_and_b32_e32 v35, 0xffff0000, v186
	v_lshlrev_b32_e32 v37, 16, v187
	v_and_b32_e32 v39, 0xffff0000, v187
	v_lshl_add_u64 v[26:27], v[0:1], 1, s[10:11]
	v_lshlrev_b32_e32 v36, 16, v188
	v_mul_f32_e32 v0, 0xbfb8aa3b, v34
	v_exp_f32_e32 v34, v0
	v_mul_f32_e32 v0, 0xbfb8aa3b, v36
	v_and_b32_e32 v28, 0xffff0000, v188
	v_exp_f32_e32 v36, v0
	v_mul_f32_e32 v0, 0xbfb8aa3b, v35
	v_exp_f32_e32 v38, v0
	v_mul_f32_e32 v0, 0xbfb8aa3b, v28
	v_exp_f32_e32 v28, v0
	v_mul_f32_e32 v0, 0xbfb8aa3b, v37
	v_exp_f32_e32 v35, v0
	v_lshlrev_b32_e32 v40, 16, v189
	v_mul_f32_e32 v0, 0xbfb8aa3b, v40
	v_and_b32_e32 v29, 0xffff0000, v189
	v_exp_f32_e32 v37, v0
	v_mul_f32_e32 v0, 0xbfb8aa3b, v39
	v_exp_f32_e32 v39, v0
	v_mul_f32_e32 v0, 0xbfb8aa3b, v29
	v_pk_add_f32 v[34:35], v[34:35], 1.0 op_sel_hi:[1,0]
	v_exp_f32_e32 v29, v0
	v_pk_add_f32 v[38:39], v[38:39], 1.0 op_sel_hi:[1,0]
	v_pk_add_f32 v[28:29], v[28:29], 1.0 op_sel_hi:[1,0]
	v_rcp_f32_e32 v35, v35
	s_nop 0
	s_waitcnt vmcnt(9)
	v_lshlrev_b32_e32 v41, 16, v191
	v_rcp_f32_e32 v34, v34
	s_nop 0
	v_mov_b32_e32 v42, v22
	v_mov_b32_e32 v43, v24
	v_lshlrev_b32_e32 v40, 16, v190
	v_pk_fma_f32 v[34:35], v[42:43], v[34:35], v[40:41]
	v_rcp_f32_e32 v39, v39
	s_nop 0
	v_and_b32_e32 v31, 0xffff0000, v191
	v_and_b32_e32 v30, 0xffff0000, v190
	v_rcp_f32_e32 v38, v38
	s_nop 0
	v_mov_b32_e32 v24, v23
	v_pk_fma_f32 v[22:23], v[24:25], v[38:39], v[30:31]
	v_cvt_pk_bf16_f32 v0, v34, v35
	v_cvt_pk_bf16_f32 v22, v22, v23
	v_and_b32_e32 v23, 0xffff0000, v22
	v_lshlrev_b32_e32 v22, 16, v22
	v_lshlrev_b32_e32 v25, 16, v193
	v_lshlrev_b32_e32 v24, 16, v192
	v_and_b32_e32 v31, 0xffff0000, v193
	v_and_b32_e32 v30, 0xffff0000, v192
	v_pk_add_f32 v[32:33], v[36:37], 1.0 op_sel_hi:[1,0]
	v_or_b32_sdwa v23, v23, v0 dst_sel:DWORD dst_unused:UNUSED_PAD src0_sel:DWORD src1_sel:WORD_1
	v_or_b32_sdwa v22, v22, v0 dst_sel:DWORD dst_unused:UNUSED_PAD src0_sel:DWORD src1_sel:WORD_0
	s_nop 0
	v_rcp_f32_e32 v33, v33
	s_nop 0
	s_nop 0
	v_rcp_f32_e32 v32, v32
	s_nop 0
	v_mov_b32_e32 v34, v18
	v_mov_b32_e32 v35, v20
	v_pk_fma_f32 v[24:25], v[34:35], v[32:33], v[24:25]
	v_add_u32_e32 v36, 0xfa400, v157
	v_rcp_f32_e32 v29, v29
	s_nop 0
	v_add_u32_e32 v37, 0xfff31c00, v158
	v_rcp_f32_e32 v28, v28
	s_nop 0
	v_mov_b32_e32 v20, v19
	v_pk_fma_f32 v[18:19], v[20:21], v[28:29], v[30:31]
	v_cvt_pk_bf16_f32 v0, v24, v25
	v_cvt_pk_bf16_f32 v18, v18, v19
	v_and_b32_e32 v19, 0xffff0000, v18
	v_lshlrev_b32_e32 v18, 16, v18
	v_or_b32_sdwa v25, v19, v0 dst_sel:DWORD dst_unused:UNUSED_PAD src0_sel:DWORD src1_sel:WORD_1
	v_or_b32_sdwa v24, v18, v0 dst_sel:DWORD dst_unused:UNUSED_PAD src0_sel:DWORD src1_sel:WORD_0
	v_add_u32_e32 v0, v36, v156
	global_store_dwordx4 v[26:27], v[22:25], off
	v_add_u32_e32 v0, v0, v37
	s_waitcnt vmcnt(8)
	v_lshlrev_b32_e32 v26, 16, v194
	v_and_b32_e32 v27, 0xffff0000, v194
	v_lshlrev_b32_e32 v29, 16, v195
	v_and_b32_e32 v31, 0xffff0000, v195
	v_lshl_add_u64 v[18:19], v[0:1], 1, s[10:11]
	v_lshlrev_b32_e32 v28, 16, v196
	v_mul_f32_e32 v0, 0xbfb8aa3b, v26
	v_exp_f32_e32 v26, v0
	v_mul_f32_e32 v0, 0xbfb8aa3b, v28
	v_and_b32_e32 v20, 0xffff0000, v196
	v_exp_f32_e32 v28, v0
	v_mul_f32_e32 v0, 0xbfb8aa3b, v27
	v_exp_f32_e32 v30, v0
	v_mul_f32_e32 v0, 0xbfb8aa3b, v20
	v_exp_f32_e32 v20, v0
	v_mul_f32_e32 v0, 0xbfb8aa3b, v29
	v_exp_f32_e32 v27, v0
	v_lshlrev_b32_e32 v32, 16, v197
	v_mul_f32_e32 v0, 0xbfb8aa3b, v32
	v_and_b32_e32 v21, 0xffff0000, v197
	v_exp_f32_e32 v29, v0
	v_mul_f32_e32 v0, 0xbfb8aa3b, v31
	v_exp_f32_e32 v31, v0
	v_mul_f32_e32 v0, 0xbfb8aa3b, v21
	v_pk_add_f32 v[26:27], v[26:27], 1.0 op_sel_hi:[1,0]
	v_exp_f32_e32 v21, v0
	v_pk_add_f32 v[30:31], v[30:31], 1.0 op_sel_hi:[1,0]
	v_pk_add_f32 v[20:21], v[20:21], 1.0 op_sel_hi:[1,0]
	v_rcp_f32_e32 v27, v27
	s_nop 0
	s_waitcnt vmcnt(7)
	v_lshlrev_b32_e32 v33, 16, v199
	v_rcp_f32_e32 v26, v26
	s_nop 0
	v_mov_b32_e32 v34, v14
	v_mov_b32_e32 v35, v16
	v_lshlrev_b32_e32 v32, 16, v198
	v_pk_fma_f32 v[26:27], v[34:35], v[26:27], v[32:33]
	v_rcp_f32_e32 v31, v31
	s_nop 0
	v_and_b32_e32 v23, 0xffff0000, v199
	v_and_b32_e32 v22, 0xffff0000, v198
	v_rcp_f32_e32 v30, v30
	s_nop 0
	v_mov_b32_e32 v16, v15
	v_pk_fma_f32 v[14:15], v[16:17], v[30:31], v[22:23]
	v_cvt_pk_bf16_f32 v0, v26, v27
	v_cvt_pk_bf16_f32 v14, v14, v15
	v_and_b32_e32 v15, 0xffff0000, v14
	v_lshlrev_b32_e32 v14, 16, v14
	v_lshlrev_b32_e32 v17, 16, v201
	v_lshlrev_b32_e32 v16, 16, v200
	v_and_b32_e32 v23, 0xffff0000, v201
	v_and_b32_e32 v22, 0xffff0000, v200
	v_pk_add_f32 v[24:25], v[28:29], 1.0 op_sel_hi:[1,0]
	v_or_b32_sdwa v15, v15, v0 dst_sel:DWORD dst_unused:UNUSED_PAD src0_sel:DWORD src1_sel:WORD_1
	v_or_b32_sdwa v14, v14, v0 dst_sel:DWORD dst_unused:UNUSED_PAD src0_sel:DWORD src1_sel:WORD_0
	s_nop 0
	v_rcp_f32_e32 v25, v25
	s_nop 0
	s_nop 0
	v_rcp_f32_e32 v24, v24
	s_nop 0
	v_mov_b32_e32 v26, v10
	v_mov_b32_e32 v27, v12
	v_pk_fma_f32 v[16:17], v[26:27], v[24:25], v[16:17]
	v_rcp_f32_e32 v21, v21
	s_nop 0
	s_nop 0
	v_rcp_f32_e32 v20, v20
	s_nop 0
	v_mov_b32_e32 v12, v11
	v_pk_fma_f32 v[10:11], v[12:13], v[20:21], v[22:23]
	v_cvt_pk_bf16_f32 v0, v16, v17
	v_cvt_pk_bf16_f32 v10, v10, v11
	v_and_b32_e32 v11, 0xffff0000, v10
	v_lshlrev_b32_e32 v10, 16, v10
	v_or_b32_sdwa v17, v11, v0 dst_sel:DWORD dst_unused:UNUSED_PAD src0_sel:DWORD src1_sel:WORD_1
	v_or_b32_sdwa v16, v10, v0 dst_sel:DWORD dst_unused:UNUSED_PAD src0_sel:DWORD src1_sel:WORD_0
	v_add_u32_e32 v0, v36, v126
	global_store_dwordx4 v[18:19], v[14:17], off
	v_add_u32_e32 v0, v0, v37
	s_waitcnt vmcnt(6)
	v_lshlrev_b32_e32 v18, 16, v202
	v_and_b32_e32 v19, 0xffff0000, v202
	v_lshlrev_b32_e32 v21, 16, v203
	v_and_b32_e32 v23, 0xffff0000, v203
	v_lshl_add_u64 v[10:11], v[0:1], 1, s[10:11]
	v_lshlrev_b32_e32 v20, 16, v204
	v_mul_f32_e32 v0, 0xbfb8aa3b, v18
	v_exp_f32_e32 v18, v0
	v_mul_f32_e32 v0, 0xbfb8aa3b, v20
	v_and_b32_e32 v12, 0xffff0000, v204
	v_exp_f32_e32 v20, v0
	v_mul_f32_e32 v0, 0xbfb8aa3b, v19
	v_exp_f32_e32 v22, v0
	v_mul_f32_e32 v0, 0xbfb8aa3b, v12
	v_exp_f32_e32 v12, v0
	v_mul_f32_e32 v0, 0xbfb8aa3b, v21
	v_exp_f32_e32 v19, v0
	v_lshlrev_b32_e32 v24, 16, v205
	v_mul_f32_e32 v0, 0xbfb8aa3b, v24
	v_and_b32_e32 v13, 0xffff0000, v205
	v_exp_f32_e32 v21, v0
	v_mul_f32_e32 v0, 0xbfb8aa3b, v23
	v_exp_f32_e32 v23, v0
	v_mul_f32_e32 v0, 0xbfb8aa3b, v13
	v_pk_add_f32 v[18:19], v[18:19], 1.0 op_sel_hi:[1,0]
	v_exp_f32_e32 v13, v0
	v_pk_add_f32 v[22:23], v[22:23], 1.0 op_sel_hi:[1,0]
	v_pk_add_f32 v[12:13], v[12:13], 1.0 op_sel_hi:[1,0]
	v_rcp_f32_e32 v19, v19
	s_nop 0
	s_waitcnt vmcnt(5)
	v_lshlrev_b32_e32 v25, 16, v207
	v_rcp_f32_e32 v18, v18
	s_nop 0
	v_mov_b32_e32 v26, v6
	v_mov_b32_e32 v27, v8
	v_lshlrev_b32_e32 v24, 16, v206
	v_pk_fma_f32 v[18:19], v[26:27], v[18:19], v[24:25]
	v_rcp_f32_e32 v23, v23
	s_nop 0
	v_and_b32_e32 v15, 0xffff0000, v207
	v_and_b32_e32 v14, 0xffff0000, v206
	v_rcp_f32_e32 v22, v22
	s_nop 0
	v_mov_b32_e32 v8, v7
	v_pk_fma_f32 v[6:7], v[8:9], v[22:23], v[14:15]
	v_cvt_pk_bf16_f32 v0, v18, v19
	v_cvt_pk_bf16_f32 v6, v6, v7
	v_and_b32_e32 v7, 0xffff0000, v6
	v_lshlrev_b32_e32 v6, 16, v6
	v_lshlrev_b32_e32 v9, 16, v209
	v_lshlrev_b32_e32 v8, 16, v208
	v_and_b32_e32 v15, 0xffff0000, v209
	v_and_b32_e32 v14, 0xffff0000, v208
	v_pk_add_f32 v[16:17], v[20:21], 1.0 op_sel_hi:[1,0]
	v_or_b32_sdwa v7, v7, v0 dst_sel:DWORD dst_unused:UNUSED_PAD src0_sel:DWORD src1_sel:WORD_1
	v_or_b32_sdwa v6, v6, v0 dst_sel:DWORD dst_unused:UNUSED_PAD src0_sel:DWORD src1_sel:WORD_0
	s_nop 0
	v_rcp_f32_e32 v17, v17
	s_nop 0
	s_nop 0
	v_rcp_f32_e32 v16, v16
	s_nop 0
	v_mov_b32_e32 v18, v2
	v_mov_b32_e32 v19, v4
	v_pk_fma_f32 v[8:9], v[18:19], v[16:17], v[8:9]
	v_rcp_f32_e32 v13, v13
	s_nop 0
	s_mov_b64 s[26:27], s[18:19]
	v_rcp_f32_e32 v12, v12
	s_nop 0
	v_mov_b32_e32 v4, v3
	v_pk_fma_f32 v[2:3], v[4:5], v[12:13], v[14:15]
	v_cvt_pk_bf16_f32 v0, v8, v9
	v_cvt_pk_bf16_f32 v2, v2, v3
	v_and_b32_e32 v3, 0xffff0000, v2
	v_lshlrev_b32_e32 v2, 16, v2
	v_or_b32_sdwa v9, v3, v0 dst_sel:DWORD dst_unused:UNUSED_PAD src0_sel:DWORD src1_sel:WORD_1
	v_or_b32_sdwa v8, v2, v0 dst_sel:DWORD dst_unused:UNUSED_PAD src0_sel:DWORD src1_sel:WORD_0
	s_and_b64 vcc, exec, s[12:13]
	global_store_dwordx4 v[10:11], v[6:9], off
	s_cbranch_vccz .LBB0_1369
	s_waitcnt vmcnt(0)
	v_readlane_b32 s76, v255, 8
	s_mov_b32 s92, 0x3b2aaaab
	s_cmp_gt_u32 s35, 3
	v_readlane_b32 s77, v255, 9
	s_mul_i32 s60, s33, 0x1800
	s_mul_hi_i32 s62, s64, 0x300
	s_mul_i32 s75, s33, 0x16c00
	s_mov_b32 s93, 0x3c800000
	s_cbranch_scc1 .LBB0_1376
	s_barrier

.LBB0_1428:
	v_add_u32_e32 v0, 0x10000, v139
	ds_read_b128 v[142:145], v0
	ds_read_b128 v[146:149], v0 offset:1024
	ds_read_b128 v[150:153], v0 offset:2048
	ds_read_b128 v[154:157], v0 offset:3072
	s_add_u32 s28, s26, 0xfffc0080
	s_addc_u32 s29, s27, -1
	s_cmp_eq_u32 vcc_lo, 12
	s_cselect_b32 s31, s15, s29
	s_cselect_b32 s30, s89, s28
	s_cselect_b32 s29, s13, s97
	s_cselect_b32 s28, s90, s94
	v_lshl_add_u64 v[178:179], s[26:27], 0, v[134:135]
	s_add_i32 m0, s35, 0xc000
	ds_read_b128 v[158:161], v138
	ds_read_b128 v[162:165], v138 offset:1024
	ds_read_b128 v[166:169], v138 offset:2048
	ds_read_b128 v[170:173], v138 offset:3072
	ds_read_b128 v[174:177], v138 offset:4096
	ds_read_b128 v[182:185], v138 offset:5120
	ds_read_b128 v[186:189], v138 offset:6144
	ds_read_b128 v[190:193], v138 offset:7168
	global_load_lds_dwordx4 v[178:179], off
	v_lshl_add_u64 v[178:179], s[26:27], 0, v[136:137]
	s_add_i32 m0, s35, 0xe000
	s_nop 0
	global_load_lds_dwordx4 v[178:179], off
	s_waitcnt lgkmcnt(8)
	s_barrier
	s_waitcnt lgkmcnt(0)
	s_setprio 1
	s_waitcnt lgkmcnt(0)
	v_mfma_f32_16x16x32_bf16 v[126:129], v[142:145], v[158:161], v[126:129]
	v_mfma_f32_16x16x32_bf16 v[122:125], v[150:153], v[158:161], v[122:125]
	v_mfma_f32_16x16x32_bf16 v[110:113], v[142:145], v[166:169], v[110:113]
	v_mfma_f32_16x16x32_bf16 v[106:109], v[150:153], v[166:169], v[106:109]
	v_mfma_f32_16x16x32_bf16 v[94:97], v[142:145], v[174:177], v[94:97]
	v_mfma_f32_16x16x32_bf16 v[90:93], v[150:153], v[174:177], v[90:93]
	v_mfma_f32_16x16x32_bf16 v[78:81], v[142:145], v[186:189], v[78:81]
	v_mfma_f32_16x16x32_bf16 v[74:77], v[150:153], v[186:189], v[74:77]
	v_mfma_f32_16x16x32_bf16 v[126:129], v[146:149], v[162:165], v[126:129]
	v_mfma_f32_16x16x32_bf16 v[122:125], v[154:157], v[162:165], v[122:125]
	v_mfma_f32_16x16x32_bf16 v[110:113], v[146:149], v[170:173], v[110:113]
	v_mfma_f32_16x16x32_bf16 v[106:109], v[154:157], v[170:173], v[106:109]
	v_mfma_f32_16x16x32_bf16 v[94:97], v[146:149], v[182:185], v[94:97]
	v_mfma_f32_16x16x32_bf16 v[90:93], v[154:157], v[182:185], v[90:93]
	v_mfma_f32_16x16x32_bf16 v[78:81], v[146:149], v[190:193], v[78:81]
	v_mfma_f32_16x16x32_bf16 v[74:77], v[154:157], v[190:193], v[74:77]
	s_setprio 0
	s_barrier
	s_mov_b32 m0, s23
	v_add_u32_e32 v0, 0x14000, v139
	v_lshl_add_u64 v[178:179], s[28:29], 0, v[132:133]
	ds_read_b128 v[194:197], v0
	ds_read_b128 v[198:201], v0 offset:1024
	ds_read_b128 v[202:205], v0 offset:2048
	ds_read_b128 v[206:209], v0 offset:3072
	global_load_lds_dwordx4 v[178:179], off
	v_lshl_add_u64 v[210:211], s[28:29], 0, v[130:131]
	s_mov_b32 m0, s25
	s_nop 0
	global_load_lds_dwordx4 v[210:211], off
	s_barrier
	s_waitcnt lgkmcnt(0)
	s_setprio 1
	s_waitcnt lgkmcnt(0)
	v_mfma_f32_16x16x32_bf16 v[118:121], v[194:197], v[158:161], v[118:121]
	v_mfma_f32_16x16x32_bf16 v[114:117], v[202:205], v[158:161], v[114:117]
	v_mfma_f32_16x16x32_bf16 v[102:105], v[194:197], v[166:169], v[102:105]
	v_mfma_f32_16x16x32_bf16 v[98:101], v[202:205], v[166:169], v[98:101]
	v_mfma_f32_16x16x32_bf16 v[86:89], v[194:197], v[174:177], v[86:89]
	v_mfma_f32_16x16x32_bf16 v[82:85], v[202:205], v[174:177], v[82:85]
	v_mfma_f32_16x16x32_bf16 v[70:73], v[194:197], v[186:189], v[70:73]
	v_mfma_f32_16x16x32_bf16 v[66:69], v[202:205], v[186:189], v[66:69]
	v_mfma_f32_16x16x32_bf16 v[118:121], v[198:201], v[162:165], v[118:121]
	v_mfma_f32_16x16x32_bf16 v[114:117], v[206:209], v[162:165], v[114:117]
	v_mfma_f32_16x16x32_bf16 v[102:105], v[198:201], v[170:173], v[102:105]
	v_mfma_f32_16x16x32_bf16 v[98:101], v[206:209], v[170:173], v[98:101]
	v_mfma_f32_16x16x32_bf16 v[86:89], v[198:201], v[182:185], v[86:89]
	v_mfma_f32_16x16x32_bf16 v[82:85], v[206:209], v[182:185], v[82:85]
	v_mfma_f32_16x16x32_bf16 v[70:73], v[198:201], v[190:193], v[70:73]
	v_mfma_f32_16x16x32_bf16 v[66:69], v[206:209], v[190:193], v[66:69]
	s_setprio 0
	s_mov_b32 m0, s35
	v_lshl_add_u64 v[212:213], s[30:31], 0, v[132:133]
	s_barrier
	ds_read_b128 v[158:161], v138 offset:16384
	ds_read_b128 v[162:165], v138 offset:17408
	ds_read_b128 v[166:169], v138 offset:18432
	ds_read_b128 v[170:173], v138 offset:19456
	ds_read_b128 v[174:177], v138 offset:20480
	ds_read_b128 v[182:185], v138 offset:21504
	ds_read_b128 v[186:189], v138 offset:22528
	ds_read_b128 v[190:193], v138 offset:23552
	global_load_lds_dwordx4 v[212:213], off
	v_lshl_add_u64 v[214:215], s[30:31], 0, v[130:131]
	s_mov_b32 m0, s36
	s_nop 0
	global_load_lds_dwordx4 v[214:215], off
	s_barrier
	s_waitcnt lgkmcnt(0)
	s_setprio 1
	s_waitcnt lgkmcnt(0)
	v_mfma_f32_16x16x32_bf16 v[62:65], v[142:145], v[158:161], v[62:65]
	v_mfma_f32_16x16x32_bf16 v[58:61], v[150:153], v[158:161], v[58:61]
	v_mfma_f32_16x16x32_bf16 v[46:49], v[142:145], v[166:169], v[46:49]
	v_mfma_f32_16x16x32_bf16 v[42:45], v[150:153], v[166:169], v[42:45]
	v_mfma_f32_16x16x32_bf16 v[30:33], v[142:145], v[174:177], v[30:33]
	v_mfma_f32_16x16x32_bf16 v[26:29], v[150:153], v[174:177], v[26:29]
	v_mfma_f32_16x16x32_bf16 v[14:17], v[142:145], v[186:189], v[14:17]
	v_mfma_f32_16x16x32_bf16 v[10:13], v[150:153], v[186:189], v[10:13]
	v_mfma_f32_16x16x32_bf16 v[62:65], v[146:149], v[162:165], v[62:65]
	v_mfma_f32_16x16x32_bf16 v[58:61], v[154:157], v[162:165], v[58:61]
	v_mfma_f32_16x16x32_bf16 v[46:49], v[146:149], v[170:173], v[46:49]
	v_mfma_f32_16x16x32_bf16 v[42:45], v[154:157], v[170:173], v[42:45]
	v_mfma_f32_16x16x32_bf16 v[30:33], v[146:149], v[182:185], v[30:33]
	v_mfma_f32_16x16x32_bf16 v[26:29], v[154:157], v[182:185], v[26:29]
	v_mfma_f32_16x16x32_bf16 v[14:17], v[146:149], v[190:193], v[14:17]
	v_mfma_f32_16x16x32_bf16 v[10:13], v[154:157], v[190:193], v[10:13]
	s_setprio 0
	s_barrier
	s_add_u32 s76, s28, 0x40000
	s_addc_u32 s77, s29, 0
	s_mov_b32 m0, s37
	v_lshl_add_u64 v[142:143], s[76:77], 0, v[132:133]
	global_load_lds_dwordx4 v[142:143], off
	v_lshl_add_u64 v[142:143], s[76:77], 0, v[130:131]
	s_mov_b32 m0, s38
	s_nop 0
	global_load_lds_dwordx4 v[142:143], off
	s_waitcnt vmcnt(6)
	s_barrier
	s_setprio 1
	v_mfma_f32_16x16x32_bf16 v[54:57], v[194:197], v[158:161], v[54:57]
	v_mfma_f32_16x16x32_bf16 v[50:53], v[202:205], v[158:161], v[50:53]
	v_mfma_f32_16x16x32_bf16 v[38:41], v[194:197], v[166:169], v[38:41]
	v_mfma_f32_16x16x32_bf16 v[34:37], v[202:205], v[166:169], v[34:37]
	v_mfma_f32_16x16x32_bf16 v[22:25], v[194:197], v[174:177], v[22:25]
	v_mfma_f32_16x16x32_bf16 v[18:21], v[202:205], v[174:177], v[18:21]
	v_mfma_f32_16x16x32_bf16 v[6:9], v[194:197], v[186:189], v[6:9]
	v_mfma_f32_16x16x32_bf16 v[2:5], v[202:205], v[186:189], v[2:5]
	v_mfma_f32_16x16x32_bf16 v[54:57], v[198:201], v[162:165], v[54:57]
	v_mfma_f32_16x16x32_bf16 v[50:53], v[206:209], v[162:165], v[50:53]
	v_mfma_f32_16x16x32_bf16 v[38:41], v[198:201], v[170:173], v[38:41]
	v_mfma_f32_16x16x32_bf16 v[34:37], v[206:209], v[170:173], v[34:37]
	v_mfma_f32_16x16x32_bf16 v[22:25], v[198:201], v[182:185], v[22:25]
	v_mfma_f32_16x16x32_bf16 v[18:21], v[206:209], v[182:185], v[18:21]
	v_mfma_f32_16x16x32_bf16 v[6:9], v[198:201], v[190:193], v[6:9]
	v_mfma_f32_16x16x32_bf16 v[2:5], v[206:209], v[190:193], v[2:5]
	s_setprio 0
	v_add_u32_e32 v0, 0x18000, v139
	s_barrier
	ds_read_b128 v[142:145], v0
	ds_read_b128 v[146:149], v0 offset:1024
	ds_read_b128 v[150:153], v0 offset:2048
	ds_read_b128 v[154:157], v0 offset:3072
	s_add_u32 s30, s30, 0x40000
	s_addc_u32 s31, s31, 0
	s_mov_b32 m0, s39
	v_lshl_add_u64 v[194:195], s[30:31], 0, v[132:133]
	ds_read_b128 v[158:161], v138 offset:32768
	ds_read_b128 v[162:165], v138 offset:33792
	ds_read_b128 v[166:169], v138 offset:34816
	ds_read_b128 v[170:173], v138 offset:35840
	ds_read_b128 v[174:177], v138 offset:36864
	ds_read_b128 v[182:185], v138 offset:37888
	ds_read_b128 v[186:189], v138 offset:38912
	ds_read_b128 v[190:193], v138 offset:39936
	global_load_lds_dwordx4 v[194:195], off
	v_lshl_add_u64 v[194:195], s[30:31], 0, v[130:131]
	s_mov_b32 m0, s60
	s_nop 0
	global_load_lds_dwordx4 v[194:195], off
	s_waitcnt lgkmcnt(8)
	s_barrier
	s_waitcnt lgkmcnt(0)
	s_setprio 1
	s_waitcnt lgkmcnt(0)
	v_mfma_f32_16x16x32_bf16 v[126:129], v[142:145], v[158:161], v[126:129]
	v_mfma_f32_16x16x32_bf16 v[122:125], v[150:153], v[158:161], v[122:125]
	v_mfma_f32_16x16x32_bf16 v[110:113], v[142:145], v[166:169], v[110:113]
	v_mfma_f32_16x16x32_bf16 v[106:109], v[150:153], v[166:169], v[106:109]
	v_mfma_f32_16x16x32_bf16 v[94:97], v[142:145], v[174:177], v[94:97]
	v_mfma_f32_16x16x32_bf16 v[90:93], v[150:153], v[174:177], v[90:93]
	v_mfma_f32_16x16x32_bf16 v[78:81], v[142:145], v[186:189], v[78:81]
	v_mfma_f32_16x16x32_bf16 v[74:77], v[150:153], v[186:189], v[74:77]
	v_mfma_f32_16x16x32_bf16 v[126:129], v[146:149], v[162:165], v[126:129]
	v_mfma_f32_16x16x32_bf16 v[122:125], v[154:157], v[162:165], v[122:125]
	v_mfma_f32_16x16x32_bf16 v[110:113], v[146:149], v[170:173], v[110:113]
	v_mfma_f32_16x16x32_bf16 v[106:109], v[154:157], v[170:173], v[106:109]
	v_mfma_f32_16x16x32_bf16 v[94:97], v[146:149], v[182:185], v[94:97]
	v_mfma_f32_16x16x32_bf16 v[90:93], v[154:157], v[182:185], v[90:93]
	v_mfma_f32_16x16x32_bf16 v[78:81], v[146:149], v[190:193], v[78:81]
	v_mfma_f32_16x16x32_bf16 v[74:77], v[154:157], v[190:193], v[74:77]
	s_setprio 0
	s_barrier
	s_mov_b32 m0, s68
	v_add_u32_e32 v0, 0x1c000, v139
	v_lshl_add_u64 v[178:179], v[178:179], 0, s[84:85]
	ds_read_b128 v[194:197], v0
	ds_read_b128 v[198:201], v0 offset:1024
	ds_read_b128 v[202:205], v0 offset:2048
	ds_read_b128 v[206:209], v0 offset:3072
	global_load_lds_dwordx4 v[178:179], off
	v_lshl_add_u64 v[178:179], v[210:211], 0, s[84:85]
	s_mov_b32 m0, s69
	s_nop 0
	global_load_lds_dwordx4 v[178:179], off
	s_barrier
	s_waitcnt lgkmcnt(0)
	s_setprio 1
	s_waitcnt lgkmcnt(0)
	v_mfma_f32_16x16x32_bf16 v[118:121], v[194:197], v[158:161], v[118:121]
	v_mfma_f32_16x16x32_bf16 v[114:117], v[202:205], v[158:161], v[114:117]
	v_mfma_f32_16x16x32_bf16 v[102:105], v[194:197], v[166:169], v[102:105]
	v_mfma_f32_16x16x32_bf16 v[98:101], v[202:205], v[166:169], v[98:101]
	v_mfma_f32_16x16x32_bf16 v[86:89], v[194:197], v[174:177], v[86:89]
	v_mfma_f32_16x16x32_bf16 v[82:85], v[202:205], v[174:177], v[82:85]
	v_mfma_f32_16x16x32_bf16 v[70:73], v[194:197], v[186:189], v[70:73]
	v_mfma_f32_16x16x32_bf16 v[66:69], v[202:205], v[186:189], v[66:69]
	v_mfma_f32_16x16x32_bf16 v[118:121], v[198:201], v[162:165], v[118:121]
	v_mfma_f32_16x16x32_bf16 v[114:117], v[206:209], v[162:165], v[114:117]
	v_mfma_f32_16x16x32_bf16 v[102:105], v[198:201], v[170:173], v[102:105]
	v_mfma_f32_16x16x32_bf16 v[98:101], v[206:209], v[170:173], v[98:101]
	v_mfma_f32_16x16x32_bf16 v[86:89], v[198:201], v[182:185], v[86:89]
	v_mfma_f32_16x16x32_bf16 v[82:85], v[206:209], v[182:185], v[82:85]
	v_mfma_f32_16x16x32_bf16 v[70:73], v[198:201], v[190:193], v[70:73]
	v_mfma_f32_16x16x32_bf16 v[66:69], v[206:209], v[190:193], v[66:69]
	s_setprio 0
	s_mov_b32 m0, s75
	v_lshl_add_u64 v[178:179], v[212:213], 0, s[84:85]
	s_barrier
	ds_read_b128 v[158:161], v138 offset:49152
	ds_read_b128 v[162:165], v138 offset:50176
	ds_read_b128 v[166:169], v138 offset:51200
	ds_read_b128 v[170:173], v138 offset:52224
	ds_read_b128 v[174:177], v138 offset:53248
	ds_read_b128 v[182:185], v138 offset:54272
	ds_read_b128 v[186:189], v138 offset:55296
	ds_read_b128 v[190:193], v138 offset:56320
	global_load_lds_dwordx4 v[178:179], off
	v_lshl_add_u64 v[178:179], v[214:215], 0, s[84:85]
	s_mov_b32 m0, s82
	s_nop 0
	global_load_lds_dwordx4 v[178:179], off
	s_barrier
	s_waitcnt lgkmcnt(0)
	s_setprio 1
	s_waitcnt lgkmcnt(0)
	v_mfma_f32_16x16x32_bf16 v[62:65], v[142:145], v[158:161], v[62:65]
	v_mfma_f32_16x16x32_bf16 v[58:61], v[150:153], v[158:161], v[58:61]
	v_mfma_f32_16x16x32_bf16 v[46:49], v[142:145], v[166:169], v[46:49]
	v_mfma_f32_16x16x32_bf16 v[42:45], v[150:153], v[166:169], v[42:45]
	v_mfma_f32_16x16x32_bf16 v[30:33], v[142:145], v[174:177], v[30:33]
	v_mfma_f32_16x16x32_bf16 v[26:29], v[150:153], v[174:177], v[26:29]
	v_mfma_f32_16x16x32_bf16 v[14:17], v[142:145], v[186:189], v[14:17]
	v_mfma_f32_16x16x32_bf16 v[10:13], v[150:153], v[186:189], v[10:13]
	v_mfma_f32_16x16x32_bf16 v[62:65], v[146:149], v[162:165], v[62:65]
	v_mfma_f32_16x16x32_bf16 v[58:61], v[154:157], v[162:165], v[58:61]
	v_mfma_f32_16x16x32_bf16 v[46:49], v[146:149], v[170:173], v[46:49]
	v_mfma_f32_16x16x32_bf16 v[42:45], v[154:157], v[170:173], v[42:45]
	v_mfma_f32_16x16x32_bf16 v[30:33], v[146:149], v[182:185], v[30:33]
	v_mfma_f32_16x16x32_bf16 v[26:29], v[154:157], v[182:185], v[26:29]
	v_mfma_f32_16x16x32_bf16 v[14:17], v[146:149], v[190:193], v[14:17]
	v_mfma_f32_16x16x32_bf16 v[10:13], v[154:157], v[190:193], v[10:13]
	s_setprio 0
	s_barrier
	s_add_u32 s28, s28, 0x40080
	s_addc_u32 s29, s29, 0
	s_mov_b32 m0, s92
	v_lshl_add_u64 v[142:143], s[28:29], 0, v[132:133]
	global_load_lds_dwordx4 v[142:143], off
	v_lshl_add_u64 v[142:143], s[28:29], 0, v[130:131]
	s_mov_b32 m0, s93
	s_nop 0
	global_load_lds_dwordx4 v[142:143], off
	s_waitcnt vmcnt(6)
	s_barrier
	s_setprio 1
	v_mfma_f32_16x16x32_bf16 v[54:57], v[194:197], v[158:161], v[54:57]
	v_mfma_f32_16x16x32_bf16 v[50:53], v[202:205], v[158:161], v[50:53]
	v_mfma_f32_16x16x32_bf16 v[38:41], v[194:197], v[166:169], v[38:41]
	v_mfma_f32_16x16x32_bf16 v[34:37], v[202:205], v[166:169], v[34:37]
	v_mfma_f32_16x16x32_bf16 v[22:25], v[194:197], v[174:177], v[22:25]
	v_mfma_f32_16x16x32_bf16 v[18:21], v[202:205], v[174:177], v[18:21]
	v_mfma_f32_16x16x32_bf16 v[6:9], v[194:197], v[186:189], v[6:9]
	v_mfma_f32_16x16x32_bf16 v[2:5], v[202:205], v[186:189], v[2:5]
	v_mfma_f32_16x16x32_bf16 v[54:57], v[198:201], v[162:165], v[54:57]
	v_mfma_f32_16x16x32_bf16 v[50:53], v[206:209], v[162:165], v[50:53]
	v_mfma_f32_16x16x32_bf16 v[38:41], v[198:201], v[170:173], v[38:41]
	v_mfma_f32_16x16x32_bf16 v[34:37], v[206:209], v[170:173], v[34:37]
	v_mfma_f32_16x16x32_bf16 v[22:25], v[198:201], v[182:185], v[22:25]
	v_mfma_f32_16x16x32_bf16 v[18:21], v[206:209], v[182:185], v[18:21]
	v_mfma_f32_16x16x32_bf16 v[6:9], v[198:201], v[190:193], v[6:9]
	v_mfma_f32_16x16x32_bf16 v[2:5], v[206:209], v[190:193], v[2:5]
	s_setprio 0
	s_add_i32 vcc_lo, vcc_lo, 2
	s_add_u32 s26, s26, 0x100
	s_addc_u32 s27, s27, 0
	s_add_u32 s94, s94, 0x100
	s_addc_u32 s97, s97, 0
	s_cmp_gt_u32 vcc_lo, 13
	s_barrier
	s_cbranch_scc0 .LBB0_1428
	s_lshl_b32 s13, s22, 8
	s_lshl_b32 s15, s24, 18
	s_add_i32 s15, s15, s13
	v_add_u32_e32 v0, s15, v140
	v_mov_b32_e32 v148, v0
	v_mov_b32_e32 v207, 0
	v_mov_b32_e32 v206, v148
	v_lshlrev_b64 v[150:151], 2, v[206:207]
	v_lshl_add_u64 v[150:151], s[8:9], 0, v[150:151]
	global_load_dwordx4 v[150:153], v[150:151], off
	v_add_u32_e32 v206, 0x10, v148
	v_lshlrev_b64 v[154:155], 2, v[206:207]
	v_lshl_add_u64 v[154:155], s[8:9], 0, v[154:155]
	global_load_dwordx4 v[154:157], v[154:155], off
	v_add_u32_e32 v206, 0x80, v148
	v_lshlrev_b64 v[158:159], 2, v[206:207]
	v_lshl_add_u64 v[158:159], s[8:9], 0, v[158:159]
	global_load_dwordx4 v[158:161], v[158:159], off
	v_add_u32_e32 v206, 0x90, v148
	v_lshlrev_b64 v[162:163], 2, v[206:207]
	v_lshl_add_u64 v[162:163], s[8:9], 0, v[162:163]
	global_load_dwordx4 v[162:165], v[162:163], off
	v_add_u32_e32 v206, 0x4000, v148
	v_lshlrev_b64 v[166:167], 2, v[206:207]
	v_lshl_add_u64 v[166:167], s[8:9], 0, v[166:167]
	global_load_dwordx4 v[166:169], v[166:167], off
	v_add_u32_e32 v206, 0x4010, v148
	v_lshlrev_b64 v[170:171], 2, v[206:207]
	v_lshl_add_u64 v[170:171], s[8:9], 0, v[170:171]
	global_load_dwordx4 v[170:173], v[170:171], off
	v_add_u32_e32 v206, 0x4080, v148
	v_lshlrev_b64 v[174:175], 2, v[206:207]
	v_lshl_add_u64 v[174:175], s[8:9], 0, v[174:175]
	global_load_dwordx4 v[174:177], v[174:175], off
	v_add_u32_e32 v206, 0x4090, v148
	v_lshlrev_b64 v[182:183], 2, v[206:207]
	v_lshl_add_u64 v[182:183], s[8:9], 0, v[182:183]
	global_load_dwordx4 v[182:185], v[182:183], off
	v_add_u32_e32 v206, 0x8000, v148
	v_lshlrev_b64 v[186:187], 2, v[206:207]
	v_lshl_add_u64 v[186:187], s[8:9], 0, v[186:187]
	global_load_dwordx4 v[186:189], v[186:187], off
	v_add_u32_e32 v206, 0x8010, v148
	v_lshlrev_b64 v[190:191], 2, v[206:207]
	v_lshl_add_u64 v[190:191], s[8:9], 0, v[190:191]
	global_load_dwordx4 v[190:193], v[190:191], off
	v_add_u32_e32 v206, 0x8080, v148
	v_lshlrev_b64 v[194:195], 2, v[206:207]
	v_lshl_add_u64 v[194:195], s[8:9], 0, v[194:195]
	global_load_dwordx4 v[194:197], v[194:195], off
	v_add_u32_e32 v206, 0x8090, v148
	v_lshlrev_b64 v[198:199], 2, v[206:207]
	v_lshl_add_u64 v[198:199], s[8:9], 0, v[198:199]
	global_load_dwordx4 v[198:201], v[198:199], off
	v_add_u32_e32 v206, 0xc000, v148
	v_lshlrev_b64 v[202:203], 2, v[206:207]
	v_lshl_add_u64 v[202:203], s[8:9], 0, v[202:203]
	global_load_dwordx4 v[202:205], v[202:203], off
	v_lshlrev_b64 v[146:147], 2, v[0:1]
	s_and_b64 vcc, exec, s[16:17]
	s_mov_b32 s22, s12
	s_mov_b32 s24, s14
	s_mov_b64 s[28:29], s[20:21]
	s_mov_b64 s[26:27], s[18:19]
	s_waitcnt vmcnt(12)
	v_pk_add_f32 v[128:129], v[128:129], v[152:153]
	v_pk_add_f32 v[126:127], v[126:127], v[150:151]
	v_lshl_add_u64 v[142:143], s[10:11], 0, v[146:147]
	v_add_u32_e32 v206, 0xc010, v148
	v_lshlrev_b64 v[150:151], 2, v[206:207]
	v_lshl_add_u64 v[150:151], s[8:9], 0, v[150:151]
	global_load_dwordx4 v[150:153], v[150:151], off
	global_store_dwordx4 v[142:143], v[126:129], off
	s_nop 1
	v_add_u32_e32 v126, 16, v0
	v_mov_b32_e32 v127, v1
	v_lshlrev_b64 v[142:143], 2, v[126:127]
	s_waitcnt vmcnt(13)
	v_pk_add_f32 v[124:125], v[124:125], v[156:157]
	v_pk_add_f32 v[122:123], v[122:123], v[154:155]
	v_lshl_add_u64 v[126:127], s[10:11], 0, v[142:143]
	v_add_u32_e32 v206, 0xc080, v148
	v_lshlrev_b64 v[154:155], 2, v[206:207]
	v_lshl_add_u64 v[154:155], s[8:9], 0, v[154:155]
	global_load_dwordx4 v[154:157], v[154:155], off
	global_store_dwordx4 v[126:127], v[122:125], off
	s_nop 1
	v_add_u32_e32 v122, 0x80, v0
	v_mov_b32_e32 v123, v1
	v_lshlrev_b64 v[126:127], 2, v[122:123]
	s_waitcnt vmcnt(14)
	v_pk_add_f32 v[120:121], v[120:121], v[160:161]
	v_pk_add_f32 v[118:119], v[118:119], v[158:159]
	v_lshl_add_u64 v[122:123], s[10:11], 0, v[126:127]
	v_add_u32_e32 v206, 0xc090, v148
	v_lshlrev_b64 v[158:159], 2, v[206:207]
	v_lshl_add_u64 v[158:159], s[8:9], 0, v[158:159]
	global_load_dwordx4 v[158:161], v[158:159], off
	global_store_dwordx4 v[122:123], v[118:121], off
	s_nop 1
	v_add_u32_e32 v118, 0x90, v0
	v_mov_b32_e32 v119, v1
	v_lshlrev_b64 v[122:123], 2, v[118:119]
	s_waitcnt vmcnt(15)
	v_pk_add_f32 v[116:117], v[116:117], v[164:165]
	v_pk_add_f32 v[114:115], v[114:115], v[162:163]
	v_lshl_add_u64 v[118:119], s[10:11], 0, v[122:123]
	v_add_u32_e32 v206, 0x20000, v148
	v_lshlrev_b64 v[162:163], 2, v[206:207]
	v_lshl_add_u64 v[162:163], s[8:9], 0, v[162:163]
	global_load_dwordx4 v[162:165], v[162:163], off
	global_store_dwordx4 v[118:119], v[114:117], off
	s_nop 1
	v_add_u32_e32 v114, 0x4000, v0
	v_mov_b32_e32 v115, v1
	v_lshlrev_b64 v[118:119], 2, v[114:115]
	s_waitcnt vmcnt(16)
	v_pk_add_f32 v[112:113], v[112:113], v[168:169]
	v_pk_add_f32 v[110:111], v[110:111], v[166:167]
	v_lshl_add_u64 v[114:115], s[10:11], 0, v[118:119]
	v_add_u32_e32 v206, 0x20010, v148
	v_lshlrev_b64 v[166:167], 2, v[206:207]
	v_lshl_add_u64 v[166:167], s[8:9], 0, v[166:167]
	global_load_dwordx4 v[166:169], v[166:167], off
	global_store_dwordx4 v[114:115], v[110:113], off
	s_nop 1
	v_add_u32_e32 v110, 0x4010, v0
	v_mov_b32_e32 v111, v1
	v_lshlrev_b64 v[114:115], 2, v[110:111]
	s_waitcnt vmcnt(17)
	v_pk_add_f32 v[108:109], v[108:109], v[172:173]
	v_pk_add_f32 v[106:107], v[106:107], v[170:171]
	v_lshl_add_u64 v[110:111], s[10:11], 0, v[114:115]
	v_add_u32_e32 v206, 0x20080, v148
	v_lshlrev_b64 v[170:171], 2, v[206:207]
	v_lshl_add_u64 v[170:171], s[8:9], 0, v[170:171]
	global_load_dwordx4 v[170:173], v[170:171], off
	global_store_dwordx4 v[110:111], v[106:109], off
	s_nop 1
	v_add_u32_e32 v106, 0x4080, v0
	v_mov_b32_e32 v107, v1
	v_lshlrev_b64 v[110:111], 2, v[106:107]
	s_waitcnt vmcnt(18)
	v_pk_add_f32 v[104:105], v[104:105], v[176:177]
	v_pk_add_f32 v[102:103], v[102:103], v[174:175]
	v_lshl_add_u64 v[106:107], s[10:11], 0, v[110:111]
	v_add_u32_e32 v206, 0x20090, v148
	v_lshlrev_b64 v[174:175], 2, v[206:207]
	v_lshl_add_u64 v[174:175], s[8:9], 0, v[174:175]
	global_load_dwordx4 v[174:177], v[174:175], off
	global_store_dwordx4 v[106:107], v[102:105], off
	s_nop 1
	v_add_u32_e32 v102, 0x4090, v0
	v_mov_b32_e32 v103, v1
	v_lshlrev_b64 v[106:107], 2, v[102:103]
	s_waitcnt vmcnt(19)
	v_pk_add_f32 v[100:101], v[100:101], v[184:185]
	v_pk_add_f32 v[98:99], v[98:99], v[182:183]
	v_lshl_add_u64 v[102:103], s[10:11], 0, v[106:107]
	v_add_u32_e32 v206, 0x24000, v148
	v_lshlrev_b64 v[182:183], 2, v[206:207]
	v_lshl_add_u64 v[182:183], s[8:9], 0, v[182:183]
	global_load_dwordx4 v[182:185], v[182:183], off
	global_store_dwordx4 v[102:103], v[98:101], off
	s_nop 1
	v_add_u32_e32 v98, 0x8000, v0
	v_mov_b32_e32 v99, v1
	v_lshlrev_b64 v[102:103], 2, v[98:99]
	s_waitcnt vmcnt(20)
	v_pk_add_f32 v[96:97], v[96:97], v[188:189]
	v_pk_add_f32 v[94:95], v[94:95], v[186:187]
	v_lshl_add_u64 v[98:99], s[10:11], 0, v[102:103]
	v_add_u32_e32 v206, 0x24010, v148
	v_lshlrev_b64 v[186:187], 2, v[206:207]
	v_lshl_add_u64 v[186:187], s[8:9], 0, v[186:187]
	global_load_dwordx4 v[186:189], v[186:187], off
	global_store_dwordx4 v[98:99], v[94:97], off
	s_nop 1
	v_add_u32_e32 v94, 0x8010, v0
	v_mov_b32_e32 v95, v1
	v_lshlrev_b64 v[98:99], 2, v[94:95]
	s_waitcnt vmcnt(21)
	v_pk_add_f32 v[92:93], v[92:93], v[192:193]
	v_pk_add_f32 v[90:91], v[90:91], v[190:191]
	v_lshl_add_u64 v[94:95], s[10:11], 0, v[98:99]
	v_add_u32_e32 v206, 0x24080, v148
	v_lshlrev_b64 v[190:191], 2, v[206:207]
	v_lshl_add_u64 v[190:191], s[8:9], 0, v[190:191]
	global_load_dwordx4 v[190:193], v[190:191], off
	global_store_dwordx4 v[94:95], v[90:93], off
	s_nop 1
	v_add_u32_e32 v90, 0x8080, v0
	v_mov_b32_e32 v91, v1
	v_lshlrev_b64 v[94:95], 2, v[90:91]
	s_waitcnt vmcnt(22)
	v_pk_add_f32 v[88:89], v[88:89], v[196:197]
	v_pk_add_f32 v[86:87], v[86:87], v[194:195]
	v_lshl_add_u64 v[90:91], s[10:11], 0, v[94:95]
	v_add_u32_e32 v206, 0x24090, v148
	v_lshlrev_b64 v[194:195], 2, v[206:207]
	v_lshl_add_u64 v[194:195], s[8:9], 0, v[194:195]
	global_load_dwordx4 v[194:197], v[194:195], off
	global_store_dwordx4 v[90:91], v[86:89], off
	s_nop 1
	v_add_u32_e32 v86, 0x8090, v0
	v_mov_b32_e32 v87, v1
	v_lshlrev_b64 v[90:91], 2, v[86:87]
	s_waitcnt vmcnt(23)
	v_pk_add_f32 v[84:85], v[84:85], v[200:201]
	v_pk_add_f32 v[82:83], v[82:83], v[198:199]
	v_lshl_add_u64 v[86:87], s[10:11], 0, v[90:91]
	v_add_u32_e32 v206, 0x28000, v148
	v_lshlrev_b64 v[198:199], 2, v[206:207]
	v_lshl_add_u64 v[198:199], s[8:9], 0, v[198:199]
	global_load_dwordx4 v[198:201], v[198:199], off
	global_store_dwordx4 v[86:87], v[82:85], off
	s_nop 1
	v_add_u32_e32 v82, 0xc000, v0
	v_mov_b32_e32 v83, v1
	v_lshlrev_b64 v[86:87], 2, v[82:83]
	s_waitcnt vmcnt(24)
	v_pk_add_f32 v[80:81], v[80:81], v[204:205]
	v_pk_add_f32 v[78:79], v[78:79], v[202:203]
	v_lshl_add_u64 v[82:83], s[10:11], 0, v[86:87]
	v_add_u32_e32 v206, 0x28010, v148
	v_lshlrev_b64 v[202:203], 2, v[206:207]
	v_lshl_add_u64 v[202:203], s[8:9], 0, v[202:203]
	global_load_dwordx4 v[202:205], v[202:203], off
	global_store_dwordx4 v[82:83], v[78:81], off
	s_nop 1
	v_add_u32_e32 v78, 0xc010, v0
	v_mov_b32_e32 v79, v1
	v_lshlrev_b64 v[82:83], 2, v[78:79]
	s_waitcnt vmcnt(25)
	v_pk_add_f32 v[76:77], v[76:77], v[152:153]
	v_pk_add_f32 v[74:75], v[74:75], v[150:151]
	v_lshl_add_u64 v[78:79], s[10:11], 0, v[82:83]
	v_add_u32_e32 v206, 0x28080, v148
	v_lshlrev_b64 v[150:151], 2, v[206:207]
	v_lshl_add_u64 v[150:151], s[8:9], 0, v[150:151]
	global_load_dwordx4 v[150:153], v[150:151], off
	global_store_dwordx4 v[78:79], v[74:77], off
	s_nop 1
	v_add_u32_e32 v74, 0xc080, v0
	v_mov_b32_e32 v75, v1
	v_lshlrev_b64 v[78:79], 2, v[74:75]
	s_waitcnt vmcnt(25)
	v_pk_add_f32 v[72:73], v[72:73], v[156:157]
	v_pk_add_f32 v[70:71], v[70:71], v[154:155]
	v_lshl_add_u64 v[74:75], s[10:11], 0, v[78:79]
	v_add_u32_e32 v206, 0x28090, v148
	v_lshlrev_b64 v[154:155], 2, v[206:207]
	v_lshl_add_u64 v[154:155], s[8:9], 0, v[154:155]
	global_load_dwordx4 v[154:157], v[154:155], off
	global_store_dwordx4 v[74:75], v[70:73], off
	s_nop 1
	v_add_u32_e32 v70, 0xc090, v0
	v_mov_b32_e32 v71, v1
	v_lshlrev_b64 v[74:75], 2, v[70:71]
	s_waitcnt vmcnt(25)
	v_pk_add_f32 v[68:69], v[68:69], v[160:161]
	v_pk_add_f32 v[66:67], v[66:67], v[158:159]
	v_lshl_add_u64 v[70:71], s[10:11], 0, v[74:75]
	v_add_u32_e32 v206, 0x2c000, v148
	v_lshlrev_b64 v[158:159], 2, v[206:207]
	v_lshl_add_u64 v[158:159], s[8:9], 0, v[158:159]
	global_load_dwordx4 v[158:161], v[158:159], off
	global_store_dwordx4 v[70:71], v[66:69], off
	s_nop 1
	v_add_u32_e32 v66, 0x20000, v0
	v_mov_b32_e32 v67, v1
	v_lshlrev_b64 v[70:71], 2, v[66:67]
	s_waitcnt vmcnt(25)
	v_pk_add_f32 v[64:65], v[64:65], v[164:165]
	v_pk_add_f32 v[62:63], v[62:63], v[162:163]
	v_lshl_add_u64 v[66:67], s[10:11], 0, v[70:71]
	v_add_u32_e32 v206, 0x2c010, v148
	v_lshlrev_b64 v[162:163], 2, v[206:207]
	v_lshl_add_u64 v[162:163], s[8:9], 0, v[162:163]
	global_load_dwordx4 v[162:165], v[162:163], off
	global_store_dwordx4 v[66:67], v[62:65], off
	s_nop 1
	v_add_u32_e32 v62, 0x20010, v0
	v_mov_b32_e32 v63, v1
	v_lshlrev_b64 v[66:67], 2, v[62:63]
	s_waitcnt vmcnt(25)
	v_pk_add_f32 v[60:61], v[60:61], v[168:169]
	v_pk_add_f32 v[58:59], v[58:59], v[166:167]
	v_lshl_add_u64 v[62:63], s[10:11], 0, v[66:67]
	v_add_u32_e32 v206, 0x2c080, v148
	v_lshlrev_b64 v[166:167], 2, v[206:207]
	v_lshl_add_u64 v[166:167], s[8:9], 0, v[166:167]
	global_load_dwordx4 v[166:169], v[166:167], off
	global_store_dwordx4 v[62:63], v[58:61], off
	s_nop 1
	v_add_u32_e32 v58, 0x20080, v0
	v_mov_b32_e32 v59, v1
	v_lshlrev_b64 v[62:63], 2, v[58:59]
	s_waitcnt vmcnt(25)
	v_pk_add_f32 v[56:57], v[56:57], v[172:173]
	v_pk_add_f32 v[54:55], v[54:55], v[170:171]
	v_lshl_add_u64 v[58:59], s[10:11], 0, v[62:63]
	v_add_u32_e32 v206, 0x2c090, v148
	v_lshlrev_b64 v[170:171], 2, v[206:207]
	v_lshl_add_u64 v[170:171], s[8:9], 0, v[170:171]
	global_load_dwordx4 v[170:173], v[170:171], off
	global_store_dwordx4 v[58:59], v[54:57], off
	s_nop 1
	v_add_u32_e32 v54, 0x20090, v0
	v_mov_b32_e32 v55, v1
	v_lshlrev_b64 v[58:59], 2, v[54:55]
	s_waitcnt vmcnt(25)
	v_pk_add_f32 v[52:53], v[52:53], v[176:177]
	v_pk_add_f32 v[50:51], v[50:51], v[174:175]
	v_lshl_add_u64 v[54:55], s[10:11], 0, v[58:59]
	global_store_dwordx4 v[54:55], v[50:53], off
	s_nop 1
	v_add_u32_e32 v50, 0x24000, v0
	v_mov_b32_e32 v51, v1
	v_lshlrev_b64 v[54:55], 2, v[50:51]
	s_waitcnt vmcnt(24)
	v_pk_add_f32 v[48:49], v[48:49], v[184:185]
	v_pk_add_f32 v[46:47], v[46:47], v[182:183]
	v_lshl_add_u64 v[50:51], s[10:11], 0, v[54:55]
	global_store_dwordx4 v[50:51], v[46:49], off
	s_nop 1
	v_add_u32_e32 v46, 0x24010, v0
	v_mov_b32_e32 v47, v1
	v_lshlrev_b64 v[50:51], 2, v[46:47]
	s_waitcnt vmcnt(23)
	v_pk_add_f32 v[44:45], v[44:45], v[188:189]
	v_pk_add_f32 v[42:43], v[42:43], v[186:187]
	v_lshl_add_u64 v[46:47], s[10:11], 0, v[50:51]
	global_store_dwordx4 v[46:47], v[42:45], off
	s_nop 1
	v_add_u32_e32 v42, 0x24080, v0
	v_mov_b32_e32 v43, v1
	v_lshlrev_b64 v[46:47], 2, v[42:43]
	s_waitcnt vmcnt(22)
	v_pk_add_f32 v[40:41], v[40:41], v[192:193]
	v_pk_add_f32 v[38:39], v[38:39], v[190:191]
	v_lshl_add_u64 v[42:43], s[10:11], 0, v[46:47]
	global_store_dwordx4 v[42:43], v[38:41], off
	s_nop 1
	v_add_u32_e32 v38, 0x24090, v0
	v_mov_b32_e32 v39, v1
	v_lshlrev_b64 v[42:43], 2, v[38:39]
	s_waitcnt vmcnt(21)
	v_pk_add_f32 v[36:37], v[36:37], v[196:197]
	v_pk_add_f32 v[34:35], v[34:35], v[194:195]
	v_lshl_add_u64 v[38:39], s[10:11], 0, v[42:43]
	global_store_dwordx4 v[38:39], v[34:37], off
	s_nop 1
	v_add_u32_e32 v34, 0x28000, v0
	v_mov_b32_e32 v35, v1
	v_lshlrev_b64 v[38:39], 2, v[34:35]
	s_waitcnt vmcnt(20)
	v_pk_add_f32 v[32:33], v[32:33], v[200:201]
	v_pk_add_f32 v[30:31], v[30:31], v[198:199]
	v_lshl_add_u64 v[34:35], s[10:11], 0, v[38:39]
	global_store_dwordx4 v[34:35], v[30:33], off
	s_nop 1
	v_add_u32_e32 v30, 0x28010, v0
	v_mov_b32_e32 v31, v1
	v_lshlrev_b64 v[34:35], 2, v[30:31]
	s_waitcnt vmcnt(19)
	v_pk_add_f32 v[28:29], v[28:29], v[204:205]
	v_pk_add_f32 v[26:27], v[26:27], v[202:203]
	v_lshl_add_u64 v[30:31], s[10:11], 0, v[34:35]
	global_store_dwordx4 v[30:31], v[26:29], off
	s_nop 1
	v_add_u32_e32 v26, 0x28080, v0
	v_mov_b32_e32 v27, v1
	v_lshlrev_b64 v[30:31], 2, v[26:27]
	s_waitcnt vmcnt(18)
	v_pk_add_f32 v[24:25], v[24:25], v[152:153]
	v_pk_add_f32 v[22:23], v[22:23], v[150:151]
	v_lshl_add_u64 v[26:27], s[10:11], 0, v[30:31]
	global_store_dwordx4 v[26:27], v[22:25], off
	s_nop 1
	v_add_u32_e32 v22, 0x28090, v0
	v_mov_b32_e32 v23, v1
	v_lshlrev_b64 v[26:27], 2, v[22:23]
	s_waitcnt vmcnt(17)
	v_pk_add_f32 v[20:21], v[20:21], v[156:157]
	v_pk_add_f32 v[18:19], v[18:19], v[154:155]
	v_lshl_add_u64 v[22:23], s[10:11], 0, v[26:27]
	global_store_dwordx4 v[22:23], v[18:21], off
	s_nop 1
	v_add_u32_e32 v18, 0x2c000, v0
	v_mov_b32_e32 v19, v1
	v_lshlrev_b64 v[22:23], 2, v[18:19]
	s_waitcnt vmcnt(16)
	v_pk_add_f32 v[16:17], v[16:17], v[160:161]
	v_pk_add_f32 v[14:15], v[14:15], v[158:159]
	v_lshl_add_u64 v[18:19], s[10:11], 0, v[22:23]
	global_store_dwordx4 v[18:19], v[14:17], off
	s_nop 1
	v_add_u32_e32 v14, 0x2c010, v0
	v_mov_b32_e32 v15, v1
	v_lshlrev_b64 v[18:19], 2, v[14:15]
	s_waitcnt vmcnt(15)
	v_pk_add_f32 v[12:13], v[12:13], v[164:165]
	v_pk_add_f32 v[10:11], v[10:11], v[162:163]
	v_lshl_add_u64 v[14:15], s[10:11], 0, v[18:19]
	global_store_dwordx4 v[14:15], v[10:13], off
	s_nop 1
	v_add_u32_e32 v10, 0x2c080, v0
	v_mov_b32_e32 v11, v1
	v_lshlrev_b64 v[14:15], 2, v[10:11]
	v_add_u32_e32 v0, 0x2c090, v0
	s_waitcnt vmcnt(14)
	v_pk_add_f32 v[8:9], v[8:9], v[168:169]
	v_pk_add_f32 v[6:7], v[6:7], v[166:167]
	v_lshl_add_u64 v[10:11], s[10:11], 0, v[14:15]
	global_store_dwordx4 v[10:11], v[6:9], off
	v_lshlrev_b64 v[10:11], 2, v[0:1]
	s_nop 0
	s_waitcnt vmcnt(13)
	v_pk_add_f32 v[4:5], v[4:5], v[172:173]
	v_pk_add_f32 v[2:3], v[2:3], v[170:171]
	v_lshl_add_u64 v[6:7], s[10:11], 0, v[10:11]
	global_store_dwordx4 v[6:7], v[2:5], off
	s_cbranch_vccz .LBB0_1425
	s_waitcnt vmcnt(0)
	v_readlane_b32 s76, v255, 8
	s_mov_b32 s92, 0x3b2aaaab
	s_cmp_gt_u32 s4, 3
	v_readlane_b32 s77, v255, 9
	s_mul_i32 s60, s33, 0x1800
	s_mul_hi_i32 s62, s64, 0x300
	s_mul_i32 s75, s33, 0x16c00
	s_mov_b32 s93, 0x3c800000
	s_cbranch_scc1 .LBB0_1432
	s_barrier

.LBB0_1441:
	v_add_u32_e32 v0, 0x10000, v139
	ds_read_b128 v[142:145], v0
	ds_read_b128 v[146:149], v0 offset:1024
	ds_read_b128 v[150:153], v0 offset:2048
	ds_read_b128 v[154:157], v0 offset:3072
	s_add_u32 s26, s24, 0xfffc0080
	s_addc_u32 s27, s25, -1
	s_cmp_eq_u32 s97, 12
	s_cselect_b32 s29, s13, s27
	s_cselect_b32 s28, s89, s26
	s_cselect_b32 s27, s11, s96
	s_cselect_b32 s26, s90, s94
	v_lshl_add_u64 v[178:179], s[24:25], 0, v[134:135]
	s_add_i32 m0, s34, 0xc000
	ds_read_b128 v[158:161], v138
	ds_read_b128 v[162:165], v138 offset:1024
	ds_read_b128 v[166:169], v138 offset:2048
	ds_read_b128 v[170:173], v138 offset:3072
	ds_read_b128 v[174:177], v138 offset:4096
	ds_read_b128 v[182:185], v138 offset:5120
	ds_read_b128 v[186:189], v138 offset:6144
	ds_read_b128 v[190:193], v138 offset:7168
	global_load_lds_dwordx4 v[178:179], off
	v_lshl_add_u64 v[178:179], s[24:25], 0, v[136:137]
	s_add_i32 m0, s34, 0xe000
	s_nop 0
	global_load_lds_dwordx4 v[178:179], off
	s_waitcnt lgkmcnt(8)
	s_barrier
	s_waitcnt lgkmcnt(0)
	s_setprio 1
	s_waitcnt lgkmcnt(0)
	v_mfma_f32_16x16x32_bf16 v[126:129], v[142:145], v[158:161], v[126:129]
	v_mfma_f32_16x16x32_bf16 v[122:125], v[150:153], v[158:161], v[122:125]
	v_mfma_f32_16x16x32_bf16 v[110:113], v[142:145], v[166:169], v[110:113]
	v_mfma_f32_16x16x32_bf16 v[106:109], v[150:153], v[166:169], v[106:109]
	v_mfma_f32_16x16x32_bf16 v[94:97], v[142:145], v[174:177], v[94:97]
	v_mfma_f32_16x16x32_bf16 v[90:93], v[150:153], v[174:177], v[90:93]
	v_mfma_f32_16x16x32_bf16 v[78:81], v[142:145], v[186:189], v[78:81]
	v_mfma_f32_16x16x32_bf16 v[74:77], v[150:153], v[186:189], v[74:77]
	v_mfma_f32_16x16x32_bf16 v[126:129], v[146:149], v[162:165], v[126:129]
	v_mfma_f32_16x16x32_bf16 v[122:125], v[154:157], v[162:165], v[122:125]
	v_mfma_f32_16x16x32_bf16 v[110:113], v[146:149], v[170:173], v[110:113]
	v_mfma_f32_16x16x32_bf16 v[106:109], v[154:157], v[170:173], v[106:109]
	v_mfma_f32_16x16x32_bf16 v[94:97], v[146:149], v[182:185], v[94:97]
	v_mfma_f32_16x16x32_bf16 v[90:93], v[154:157], v[182:185], v[90:93]
	v_mfma_f32_16x16x32_bf16 v[78:81], v[146:149], v[190:193], v[78:81]
	v_mfma_f32_16x16x32_bf16 v[74:77], v[154:157], v[190:193], v[74:77]
	s_setprio 0
	s_barrier
	s_mov_b32 m0, s21
	v_add_u32_e32 v0, 0x14000, v139
	v_lshl_add_u64 v[178:179], s[26:27], 0, v[132:133]
	ds_read_b128 v[194:197], v0
	ds_read_b128 v[198:201], v0 offset:1024
	ds_read_b128 v[202:205], v0 offset:2048
	ds_read_b128 v[206:209], v0 offset:3072
	global_load_lds_dwordx4 v[178:179], off
	v_lshl_add_u64 v[210:211], s[26:27], 0, v[130:131]
	s_mov_b32 m0, s23
	s_nop 0
	global_load_lds_dwordx4 v[210:211], off
	s_barrier
	s_waitcnt lgkmcnt(0)
	s_setprio 1
	s_waitcnt lgkmcnt(0)
	v_mfma_f32_16x16x32_bf16 v[118:121], v[194:197], v[158:161], v[118:121]
	v_mfma_f32_16x16x32_bf16 v[114:117], v[202:205], v[158:161], v[114:117]
	v_mfma_f32_16x16x32_bf16 v[102:105], v[194:197], v[166:169], v[102:105]
	v_mfma_f32_16x16x32_bf16 v[98:101], v[202:205], v[166:169], v[98:101]
	v_mfma_f32_16x16x32_bf16 v[86:89], v[194:197], v[174:177], v[86:89]
	v_mfma_f32_16x16x32_bf16 v[82:85], v[202:205], v[174:177], v[82:85]
	v_mfma_f32_16x16x32_bf16 v[70:73], v[194:197], v[186:189], v[70:73]
	v_mfma_f32_16x16x32_bf16 v[66:69], v[202:205], v[186:189], v[66:69]
	v_mfma_f32_16x16x32_bf16 v[118:121], v[198:201], v[162:165], v[118:121]
	v_mfma_f32_16x16x32_bf16 v[114:117], v[206:209], v[162:165], v[114:117]
	v_mfma_f32_16x16x32_bf16 v[102:105], v[198:201], v[170:173], v[102:105]
	v_mfma_f32_16x16x32_bf16 v[98:101], v[206:209], v[170:173], v[98:101]
	v_mfma_f32_16x16x32_bf16 v[86:89], v[198:201], v[182:185], v[86:89]
	v_mfma_f32_16x16x32_bf16 v[82:85], v[206:209], v[182:185], v[82:85]
	v_mfma_f32_16x16x32_bf16 v[70:73], v[198:201], v[190:193], v[70:73]
	v_mfma_f32_16x16x32_bf16 v[66:69], v[206:209], v[190:193], v[66:69]
	s_setprio 0
	s_mov_b32 m0, s34
	v_lshl_add_u64 v[212:213], s[28:29], 0, v[132:133]
	s_barrier
	ds_read_b128 v[158:161], v138 offset:16384
	ds_read_b128 v[162:165], v138 offset:17408
	ds_read_b128 v[166:169], v138 offset:18432
	ds_read_b128 v[170:173], v138 offset:19456
	ds_read_b128 v[174:177], v138 offset:20480
	ds_read_b128 v[182:185], v138 offset:21504
	ds_read_b128 v[186:189], v138 offset:22528
	ds_read_b128 v[190:193], v138 offset:23552
	global_load_lds_dwordx4 v[212:213], off
	v_lshl_add_u64 v[214:215], s[28:29], 0, v[130:131]
	s_mov_b32 m0, s35
	s_nop 0
	global_load_lds_dwordx4 v[214:215], off
	s_barrier
	s_waitcnt lgkmcnt(0)
	s_setprio 1
	s_waitcnt lgkmcnt(0)
	v_mfma_f32_16x16x32_bf16 v[62:65], v[142:145], v[158:161], v[62:65]
	v_mfma_f32_16x16x32_bf16 v[58:61], v[150:153], v[158:161], v[58:61]
	v_mfma_f32_16x16x32_bf16 v[46:49], v[142:145], v[166:169], v[46:49]
	v_mfma_f32_16x16x32_bf16 v[42:45], v[150:153], v[166:169], v[42:45]
	v_mfma_f32_16x16x32_bf16 v[30:33], v[142:145], v[174:177], v[30:33]
	v_mfma_f32_16x16x32_bf16 v[26:29], v[150:153], v[174:177], v[26:29]
	v_mfma_f32_16x16x32_bf16 v[14:17], v[142:145], v[186:189], v[14:17]
	v_mfma_f32_16x16x32_bf16 v[10:13], v[150:153], v[186:189], v[10:13]
	v_mfma_f32_16x16x32_bf16 v[62:65], v[146:149], v[162:165], v[62:65]
	v_mfma_f32_16x16x32_bf16 v[58:61], v[154:157], v[162:165], v[58:61]
	v_mfma_f32_16x16x32_bf16 v[46:49], v[146:149], v[170:173], v[46:49]
	v_mfma_f32_16x16x32_bf16 v[42:45], v[154:157], v[170:173], v[42:45]
	v_mfma_f32_16x16x32_bf16 v[30:33], v[146:149], v[182:185], v[30:33]
	v_mfma_f32_16x16x32_bf16 v[26:29], v[154:157], v[182:185], v[26:29]
	v_mfma_f32_16x16x32_bf16 v[14:17], v[146:149], v[190:193], v[14:17]
	v_mfma_f32_16x16x32_bf16 v[10:13], v[154:157], v[190:193], v[10:13]
	s_setprio 0
	s_barrier
	s_add_u32 s76, s26, 0x40000
	s_addc_u32 s77, s27, 0
	s_mov_b32 m0, s36
	v_lshl_add_u64 v[142:143], s[76:77], 0, v[132:133]
	global_load_lds_dwordx4 v[142:143], off
	v_lshl_add_u64 v[142:143], s[76:77], 0, v[130:131]
	s_mov_b32 m0, s37
	s_nop 0
	global_load_lds_dwordx4 v[142:143], off
	s_waitcnt vmcnt(6)
	s_barrier
	s_setprio 1
	v_mfma_f32_16x16x32_bf16 v[54:57], v[194:197], v[158:161], v[54:57]
	v_mfma_f32_16x16x32_bf16 v[50:53], v[202:205], v[158:161], v[50:53]
	v_mfma_f32_16x16x32_bf16 v[38:41], v[194:197], v[166:169], v[38:41]
	v_mfma_f32_16x16x32_bf16 v[34:37], v[202:205], v[166:169], v[34:37]
	v_mfma_f32_16x16x32_bf16 v[22:25], v[194:197], v[174:177], v[22:25]
	v_mfma_f32_16x16x32_bf16 v[18:21], v[202:205], v[174:177], v[18:21]
	v_mfma_f32_16x16x32_bf16 v[6:9], v[194:197], v[186:189], v[6:9]
	v_mfma_f32_16x16x32_bf16 v[2:5], v[202:205], v[186:189], v[2:5]
	v_mfma_f32_16x16x32_bf16 v[54:57], v[198:201], v[162:165], v[54:57]
	v_mfma_f32_16x16x32_bf16 v[50:53], v[206:209], v[162:165], v[50:53]
	v_mfma_f32_16x16x32_bf16 v[38:41], v[198:201], v[170:173], v[38:41]
	v_mfma_f32_16x16x32_bf16 v[34:37], v[206:209], v[170:173], v[34:37]
	v_mfma_f32_16x16x32_bf16 v[22:25], v[198:201], v[182:185], v[22:25]
	v_mfma_f32_16x16x32_bf16 v[18:21], v[206:209], v[182:185], v[18:21]
	v_mfma_f32_16x16x32_bf16 v[6:9], v[198:201], v[190:193], v[6:9]
	v_mfma_f32_16x16x32_bf16 v[2:5], v[206:209], v[190:193], v[2:5]
	s_setprio 0
	v_add_u32_e32 v0, 0x18000, v139
	s_barrier
	ds_read_b128 v[142:145], v0
	ds_read_b128 v[146:149], v0 offset:1024
	ds_read_b128 v[150:153], v0 offset:2048
	ds_read_b128 v[154:157], v0 offset:3072
	s_add_u32 s28, s28, 0x40000
	s_addc_u32 s29, s29, 0
	s_mov_b32 m0, s38
	v_lshl_add_u64 v[194:195], s[28:29], 0, v[132:133]
	ds_read_b128 v[158:161], v138 offset:32768
	ds_read_b128 v[162:165], v138 offset:33792
	ds_read_b128 v[166:169], v138 offset:34816
	ds_read_b128 v[170:173], v138 offset:35840
	ds_read_b128 v[174:177], v138 offset:36864
	ds_read_b128 v[182:185], v138 offset:37888
	ds_read_b128 v[186:189], v138 offset:38912
	ds_read_b128 v[190:193], v138 offset:39936
	global_load_lds_dwordx4 v[194:195], off
	v_lshl_add_u64 v[194:195], s[28:29], 0, v[130:131]
	s_mov_b32 m0, s39
	s_nop 0
	global_load_lds_dwordx4 v[194:195], off
	s_waitcnt lgkmcnt(8)
	s_barrier
	s_waitcnt lgkmcnt(0)
	s_setprio 1
	s_waitcnt lgkmcnt(0)
	v_mfma_f32_16x16x32_bf16 v[126:129], v[142:145], v[158:161], v[126:129]
	v_mfma_f32_16x16x32_bf16 v[122:125], v[150:153], v[158:161], v[122:125]
	v_mfma_f32_16x16x32_bf16 v[110:113], v[142:145], v[166:169], v[110:113]
	v_mfma_f32_16x16x32_bf16 v[106:109], v[150:153], v[166:169], v[106:109]
	v_mfma_f32_16x16x32_bf16 v[94:97], v[142:145], v[174:177], v[94:97]
	v_mfma_f32_16x16x32_bf16 v[90:93], v[150:153], v[174:177], v[90:93]
	v_mfma_f32_16x16x32_bf16 v[78:81], v[142:145], v[186:189], v[78:81]
	v_mfma_f32_16x16x32_bf16 v[74:77], v[150:153], v[186:189], v[74:77]
	v_mfma_f32_16x16x32_bf16 v[126:129], v[146:149], v[162:165], v[126:129]
	v_mfma_f32_16x16x32_bf16 v[122:125], v[154:157], v[162:165], v[122:125]
	v_mfma_f32_16x16x32_bf16 v[110:113], v[146:149], v[170:173], v[110:113]
	v_mfma_f32_16x16x32_bf16 v[106:109], v[154:157], v[170:173], v[106:109]
	v_mfma_f32_16x16x32_bf16 v[94:97], v[146:149], v[182:185], v[94:97]
	v_mfma_f32_16x16x32_bf16 v[90:93], v[154:157], v[182:185], v[90:93]
	v_mfma_f32_16x16x32_bf16 v[78:81], v[146:149], v[190:193], v[78:81]
	v_mfma_f32_16x16x32_bf16 v[74:77], v[154:157], v[190:193], v[74:77]
	s_setprio 0
	s_barrier
	s_mov_b32 m0, s60
	v_add_u32_e32 v0, 0x1c000, v139
	v_lshl_add_u64 v[178:179], v[178:179], 0, s[84:85]
	ds_read_b128 v[194:197], v0
	ds_read_b128 v[198:201], v0 offset:1024
	ds_read_b128 v[202:205], v0 offset:2048
	ds_read_b128 v[206:209], v0 offset:3072
	global_load_lds_dwordx4 v[178:179], off
	v_lshl_add_u64 v[178:179], v[210:211], 0, s[84:85]
	s_mov_b32 m0, s68
	s_nop 0
	global_load_lds_dwordx4 v[178:179], off
	s_barrier
	s_waitcnt lgkmcnt(0)
	s_setprio 1
	s_waitcnt lgkmcnt(0)
	v_mfma_f32_16x16x32_bf16 v[118:121], v[194:197], v[158:161], v[118:121]
	v_mfma_f32_16x16x32_bf16 v[114:117], v[202:205], v[158:161], v[114:117]
	v_mfma_f32_16x16x32_bf16 v[102:105], v[194:197], v[166:169], v[102:105]
	v_mfma_f32_16x16x32_bf16 v[98:101], v[202:205], v[166:169], v[98:101]
	v_mfma_f32_16x16x32_bf16 v[86:89], v[194:197], v[174:177], v[86:89]
	v_mfma_f32_16x16x32_bf16 v[82:85], v[202:205], v[174:177], v[82:85]
	v_mfma_f32_16x16x32_bf16 v[70:73], v[194:197], v[186:189], v[70:73]
	v_mfma_f32_16x16x32_bf16 v[66:69], v[202:205], v[186:189], v[66:69]
	v_mfma_f32_16x16x32_bf16 v[118:121], v[198:201], v[162:165], v[118:121]
	v_mfma_f32_16x16x32_bf16 v[114:117], v[206:209], v[162:165], v[114:117]
	v_mfma_f32_16x16x32_bf16 v[102:105], v[198:201], v[170:173], v[102:105]
	v_mfma_f32_16x16x32_bf16 v[98:101], v[206:209], v[170:173], v[98:101]
	v_mfma_f32_16x16x32_bf16 v[86:89], v[198:201], v[182:185], v[86:89]
	v_mfma_f32_16x16x32_bf16 v[82:85], v[206:209], v[182:185], v[82:85]
	v_mfma_f32_16x16x32_bf16 v[70:73], v[198:201], v[190:193], v[70:73]
	v_mfma_f32_16x16x32_bf16 v[66:69], v[206:209], v[190:193], v[66:69]
	s_setprio 0
	s_mov_b32 m0, s69
	v_lshl_add_u64 v[178:179], v[212:213], 0, s[84:85]
	s_barrier
	ds_read_b128 v[158:161], v138 offset:49152
	ds_read_b128 v[162:165], v138 offset:50176
	ds_read_b128 v[166:169], v138 offset:51200
	ds_read_b128 v[170:173], v138 offset:52224
	ds_read_b128 v[174:177], v138 offset:53248
	ds_read_b128 v[182:185], v138 offset:54272
	ds_read_b128 v[186:189], v138 offset:55296
	ds_read_b128 v[190:193], v138 offset:56320
	global_load_lds_dwordx4 v[178:179], off
	v_lshl_add_u64 v[178:179], v[214:215], 0, s[84:85]
	s_mov_b32 m0, s75
	s_nop 0
	global_load_lds_dwordx4 v[178:179], off
	s_barrier
	s_waitcnt lgkmcnt(0)
	s_setprio 1
	s_waitcnt lgkmcnt(0)
	v_mfma_f32_16x16x32_bf16 v[62:65], v[142:145], v[158:161], v[62:65]
	v_mfma_f32_16x16x32_bf16 v[58:61], v[150:153], v[158:161], v[58:61]
	v_mfma_f32_16x16x32_bf16 v[46:49], v[142:145], v[166:169], v[46:49]
	v_mfma_f32_16x16x32_bf16 v[42:45], v[150:153], v[166:169], v[42:45]
	v_mfma_f32_16x16x32_bf16 v[30:33], v[142:145], v[174:177], v[30:33]
	v_mfma_f32_16x16x32_bf16 v[26:29], v[150:153], v[174:177], v[26:29]
	v_mfma_f32_16x16x32_bf16 v[14:17], v[142:145], v[186:189], v[14:17]
	v_mfma_f32_16x16x32_bf16 v[10:13], v[150:153], v[186:189], v[10:13]
	v_mfma_f32_16x16x32_bf16 v[62:65], v[146:149], v[162:165], v[62:65]
	v_mfma_f32_16x16x32_bf16 v[58:61], v[154:157], v[162:165], v[58:61]
	v_mfma_f32_16x16x32_bf16 v[46:49], v[146:149], v[170:173], v[46:49]
	v_mfma_f32_16x16x32_bf16 v[42:45], v[154:157], v[170:173], v[42:45]
	v_mfma_f32_16x16x32_bf16 v[30:33], v[146:149], v[182:185], v[30:33]
	v_mfma_f32_16x16x32_bf16 v[26:29], v[154:157], v[182:185], v[26:29]
	v_mfma_f32_16x16x32_bf16 v[14:17], v[146:149], v[190:193], v[14:17]
	v_mfma_f32_16x16x32_bf16 v[10:13], v[154:157], v[190:193], v[10:13]
	s_setprio 0
	s_barrier
	s_add_u32 s26, s26, 0x40080
	s_addc_u32 s27, s27, 0
	s_mov_b32 m0, s82
	v_lshl_add_u64 v[142:143], s[26:27], 0, v[132:133]
	global_load_lds_dwordx4 v[142:143], off
	v_lshl_add_u64 v[142:143], s[26:27], 0, v[130:131]
	s_mov_b32 m0, s92
	s_nop 0
	global_load_lds_dwordx4 v[142:143], off
	s_waitcnt vmcnt(6)
	s_barrier
	s_setprio 1
	v_mfma_f32_16x16x32_bf16 v[54:57], v[194:197], v[158:161], v[54:57]
	v_mfma_f32_16x16x32_bf16 v[50:53], v[202:205], v[158:161], v[50:53]
	v_mfma_f32_16x16x32_bf16 v[38:41], v[194:197], v[166:169], v[38:41]
	v_mfma_f32_16x16x32_bf16 v[34:37], v[202:205], v[166:169], v[34:37]
	v_mfma_f32_16x16x32_bf16 v[22:25], v[194:197], v[174:177], v[22:25]
	v_mfma_f32_16x16x32_bf16 v[18:21], v[202:205], v[174:177], v[18:21]
	v_mfma_f32_16x16x32_bf16 v[6:9], v[194:197], v[186:189], v[6:9]
	v_mfma_f32_16x16x32_bf16 v[2:5], v[202:205], v[186:189], v[2:5]
	v_mfma_f32_16x16x32_bf16 v[54:57], v[198:201], v[162:165], v[54:57]
	v_mfma_f32_16x16x32_bf16 v[50:53], v[206:209], v[162:165], v[50:53]
	v_mfma_f32_16x16x32_bf16 v[38:41], v[198:201], v[170:173], v[38:41]
	v_mfma_f32_16x16x32_bf16 v[34:37], v[206:209], v[170:173], v[34:37]
	v_mfma_f32_16x16x32_bf16 v[22:25], v[198:201], v[182:185], v[22:25]
	v_mfma_f32_16x16x32_bf16 v[18:21], v[206:209], v[182:185], v[18:21]
	v_mfma_f32_16x16x32_bf16 v[6:9], v[198:201], v[190:193], v[6:9]
	v_mfma_f32_16x16x32_bf16 v[2:5], v[206:209], v[190:193], v[2:5]
	s_setprio 0
	s_add_i32 s97, s97, 2
	s_add_u32 s24, s24, 0x100
	s_addc_u32 s25, s25, 0
	s_add_u32 s94, s94, 0x100
	s_addc_u32 s96, s96, 0
	s_cmp_gt_u32 s97, 13
	s_barrier
	s_cbranch_scc0 .LBB0_1441
	s_lshl_b32 s11, s20, 8
	s_lshl_b32 s13, s22, 18
	s_add_i32 s13, s13, s11
	v_add_u32_e32 v0, s13, v140
	v_mov_b32_e32 v148, v0
	v_mov_b32_e32 v207, 0
	v_mov_b32_e32 v206, v148
	v_lshlrev_b64 v[150:151], 2, v[206:207]
	v_lshl_add_u64 v[150:151], s[6:7], 0, v[150:151]
	global_load_dwordx4 v[150:153], v[150:151], off
	v_add_u32_e32 v206, 0x10, v148
	v_lshlrev_b64 v[154:155], 2, v[206:207]
	v_lshl_add_u64 v[154:155], s[6:7], 0, v[154:155]
	global_load_dwordx4 v[154:157], v[154:155], off
	v_add_u32_e32 v206, 0x80, v148
	v_lshlrev_b64 v[158:159], 2, v[206:207]
	v_lshl_add_u64 v[158:159], s[6:7], 0, v[158:159]
	global_load_dwordx4 v[158:161], v[158:159], off
	v_add_u32_e32 v206, 0x90, v148
	v_lshlrev_b64 v[162:163], 2, v[206:207]
	v_lshl_add_u64 v[162:163], s[6:7], 0, v[162:163]
	global_load_dwordx4 v[162:165], v[162:163], off
	v_add_u32_e32 v206, 0x4000, v148
	v_lshlrev_b64 v[166:167], 2, v[206:207]
	v_lshl_add_u64 v[166:167], s[6:7], 0, v[166:167]
	global_load_dwordx4 v[166:169], v[166:167], off
	v_add_u32_e32 v206, 0x4010, v148
	v_lshlrev_b64 v[170:171], 2, v[206:207]
	v_lshl_add_u64 v[170:171], s[6:7], 0, v[170:171]
	global_load_dwordx4 v[170:173], v[170:171], off
	v_add_u32_e32 v206, 0x4080, v148
	v_lshlrev_b64 v[174:175], 2, v[206:207]
	v_lshl_add_u64 v[174:175], s[6:7], 0, v[174:175]
	global_load_dwordx4 v[174:177], v[174:175], off
	v_add_u32_e32 v206, 0x4090, v148
	v_lshlrev_b64 v[182:183], 2, v[206:207]
	v_lshl_add_u64 v[182:183], s[6:7], 0, v[182:183]
	global_load_dwordx4 v[182:185], v[182:183], off
	v_add_u32_e32 v206, 0x8000, v148
	v_lshlrev_b64 v[186:187], 2, v[206:207]
	v_lshl_add_u64 v[186:187], s[6:7], 0, v[186:187]
	global_load_dwordx4 v[186:189], v[186:187], off
	v_add_u32_e32 v206, 0x8010, v148
	v_lshlrev_b64 v[190:191], 2, v[206:207]
	v_lshl_add_u64 v[190:191], s[6:7], 0, v[190:191]
	global_load_dwordx4 v[190:193], v[190:191], off
	v_add_u32_e32 v206, 0x8080, v148
	v_lshlrev_b64 v[194:195], 2, v[206:207]
	v_lshl_add_u64 v[194:195], s[6:7], 0, v[194:195]
	global_load_dwordx4 v[194:197], v[194:195], off
	v_add_u32_e32 v206, 0x8090, v148
	v_lshlrev_b64 v[198:199], 2, v[206:207]
	v_lshl_add_u64 v[198:199], s[6:7], 0, v[198:199]
	global_load_dwordx4 v[198:201], v[198:199], off
	v_add_u32_e32 v206, 0xc000, v148
	v_lshlrev_b64 v[202:203], 2, v[206:207]
	v_lshl_add_u64 v[202:203], s[6:7], 0, v[202:203]
	global_load_dwordx4 v[202:205], v[202:203], off
	v_lshlrev_b64 v[146:147], 2, v[0:1]
	s_and_b64 vcc, exec, s[14:15]
	s_mov_b32 s20, s10
	s_mov_b32 s22, s12
	s_mov_b64 s[26:27], s[18:19]
	s_mov_b64 s[24:25], s[16:17]
	s_waitcnt vmcnt(12)
	v_pk_add_f32 v[128:129], v[128:129], v[152:153]
	v_pk_add_f32 v[126:127], v[126:127], v[150:151]
	v_lshl_add_u64 v[142:143], s[8:9], 0, v[146:147]
	v_add_u32_e32 v206, 0xc010, v148
	v_lshlrev_b64 v[150:151], 2, v[206:207]
	v_lshl_add_u64 v[150:151], s[6:7], 0, v[150:151]
	global_load_dwordx4 v[150:153], v[150:151], off
	global_store_dwordx4 v[142:143], v[126:129], off
	s_nop 1
	v_add_u32_e32 v126, 16, v0
	v_mov_b32_e32 v127, v1
	v_lshlrev_b64 v[142:143], 2, v[126:127]
	s_waitcnt vmcnt(13)
	v_pk_add_f32 v[124:125], v[124:125], v[156:157]
	v_pk_add_f32 v[122:123], v[122:123], v[154:155]
	v_lshl_add_u64 v[126:127], s[8:9], 0, v[142:143]
	v_add_u32_e32 v206, 0xc080, v148
	v_lshlrev_b64 v[154:155], 2, v[206:207]
	v_lshl_add_u64 v[154:155], s[6:7], 0, v[154:155]
	global_load_dwordx4 v[154:157], v[154:155], off
	global_store_dwordx4 v[126:127], v[122:125], off
	s_nop 1
	v_add_u32_e32 v122, 0x80, v0
	v_mov_b32_e32 v123, v1
	v_lshlrev_b64 v[126:127], 2, v[122:123]
	s_waitcnt vmcnt(14)
	v_pk_add_f32 v[120:121], v[120:121], v[160:161]
	v_pk_add_f32 v[118:119], v[118:119], v[158:159]
	v_lshl_add_u64 v[122:123], s[8:9], 0, v[126:127]
	v_add_u32_e32 v206, 0xc090, v148
	v_lshlrev_b64 v[158:159], 2, v[206:207]
	v_lshl_add_u64 v[158:159], s[6:7], 0, v[158:159]
	global_load_dwordx4 v[158:161], v[158:159], off
	global_store_dwordx4 v[122:123], v[118:121], off
	s_nop 1
	v_add_u32_e32 v118, 0x90, v0
	v_mov_b32_e32 v119, v1
	v_lshlrev_b64 v[122:123], 2, v[118:119]
	s_waitcnt vmcnt(15)
	v_pk_add_f32 v[116:117], v[116:117], v[164:165]
	v_pk_add_f32 v[114:115], v[114:115], v[162:163]
	v_lshl_add_u64 v[118:119], s[8:9], 0, v[122:123]
	v_add_u32_e32 v206, 0x20000, v148
	v_lshlrev_b64 v[162:163], 2, v[206:207]
	v_lshl_add_u64 v[162:163], s[6:7], 0, v[162:163]
	global_load_dwordx4 v[162:165], v[162:163], off
	global_store_dwordx4 v[118:119], v[114:117], off
	s_nop 1
	v_add_u32_e32 v114, 0x4000, v0
	v_mov_b32_e32 v115, v1
	v_lshlrev_b64 v[118:119], 2, v[114:115]
	s_waitcnt vmcnt(16)
	v_pk_add_f32 v[112:113], v[112:113], v[168:169]
	v_pk_add_f32 v[110:111], v[110:111], v[166:167]
	v_lshl_add_u64 v[114:115], s[8:9], 0, v[118:119]
	v_add_u32_e32 v206, 0x20010, v148
	v_lshlrev_b64 v[166:167], 2, v[206:207]
	v_lshl_add_u64 v[166:167], s[6:7], 0, v[166:167]
	global_load_dwordx4 v[166:169], v[166:167], off
	global_store_dwordx4 v[114:115], v[110:113], off
	s_nop 1
	v_add_u32_e32 v110, 0x4010, v0
	v_mov_b32_e32 v111, v1
	v_lshlrev_b64 v[114:115], 2, v[110:111]
	s_waitcnt vmcnt(17)
	v_pk_add_f32 v[108:109], v[108:109], v[172:173]
	v_pk_add_f32 v[106:107], v[106:107], v[170:171]
	v_lshl_add_u64 v[110:111], s[8:9], 0, v[114:115]
	v_add_u32_e32 v206, 0x20080, v148
	v_lshlrev_b64 v[170:171], 2, v[206:207]
	v_lshl_add_u64 v[170:171], s[6:7], 0, v[170:171]
	global_load_dwordx4 v[170:173], v[170:171], off
	global_store_dwordx4 v[110:111], v[106:109], off
	s_nop 1
	v_add_u32_e32 v106, 0x4080, v0
	v_mov_b32_e32 v107, v1
	v_lshlrev_b64 v[110:111], 2, v[106:107]
	s_waitcnt vmcnt(18)
	v_pk_add_f32 v[104:105], v[104:105], v[176:177]
	v_pk_add_f32 v[102:103], v[102:103], v[174:175]
	v_lshl_add_u64 v[106:107], s[8:9], 0, v[110:111]
	v_add_u32_e32 v206, 0x20090, v148
	v_lshlrev_b64 v[174:175], 2, v[206:207]
	v_lshl_add_u64 v[174:175], s[6:7], 0, v[174:175]
	global_load_dwordx4 v[174:177], v[174:175], off
	global_store_dwordx4 v[106:107], v[102:105], off
	s_nop 1
	v_add_u32_e32 v102, 0x4090, v0
	v_mov_b32_e32 v103, v1
	v_lshlrev_b64 v[106:107], 2, v[102:103]
	s_waitcnt vmcnt(19)
	v_pk_add_f32 v[100:101], v[100:101], v[184:185]
	v_pk_add_f32 v[98:99], v[98:99], v[182:183]
	v_lshl_add_u64 v[102:103], s[8:9], 0, v[106:107]
	v_add_u32_e32 v206, 0x24000, v148
	v_lshlrev_b64 v[182:183], 2, v[206:207]
	v_lshl_add_u64 v[182:183], s[6:7], 0, v[182:183]
	global_load_dwordx4 v[182:185], v[182:183], off
	global_store_dwordx4 v[102:103], v[98:101], off
	s_nop 1
	v_add_u32_e32 v98, 0x8000, v0
	v_mov_b32_e32 v99, v1
	v_lshlrev_b64 v[102:103], 2, v[98:99]
	s_waitcnt vmcnt(20)
	v_pk_add_f32 v[96:97], v[96:97], v[188:189]
	v_pk_add_f32 v[94:95], v[94:95], v[186:187]
	v_lshl_add_u64 v[98:99], s[8:9], 0, v[102:103]
	v_add_u32_e32 v206, 0x24010, v148
	v_lshlrev_b64 v[186:187], 2, v[206:207]
	v_lshl_add_u64 v[186:187], s[6:7], 0, v[186:187]
	global_load_dwordx4 v[186:189], v[186:187], off
	global_store_dwordx4 v[98:99], v[94:97], off
	s_nop 1
	v_add_u32_e32 v94, 0x8010, v0
	v_mov_b32_e32 v95, v1
	v_lshlrev_b64 v[98:99], 2, v[94:95]
	s_waitcnt vmcnt(21)
	v_pk_add_f32 v[92:93], v[92:93], v[192:193]
	v_pk_add_f32 v[90:91], v[90:91], v[190:191]
	v_lshl_add_u64 v[94:95], s[8:9], 0, v[98:99]
	v_add_u32_e32 v206, 0x24080, v148
	v_lshlrev_b64 v[190:191], 2, v[206:207]
	v_lshl_add_u64 v[190:191], s[6:7], 0, v[190:191]
	global_load_dwordx4 v[190:193], v[190:191], off
	global_store_dwordx4 v[94:95], v[90:93], off
	s_nop 1
	v_add_u32_e32 v90, 0x8080, v0
	v_mov_b32_e32 v91, v1
	v_lshlrev_b64 v[94:95], 2, v[90:91]
	s_waitcnt vmcnt(22)
	v_pk_add_f32 v[88:89], v[88:89], v[196:197]
	v_pk_add_f32 v[86:87], v[86:87], v[194:195]
	v_lshl_add_u64 v[90:91], s[8:9], 0, v[94:95]
	v_add_u32_e32 v206, 0x24090, v148
	v_lshlrev_b64 v[194:195], 2, v[206:207]
	v_lshl_add_u64 v[194:195], s[6:7], 0, v[194:195]
	global_load_dwordx4 v[194:197], v[194:195], off
	global_store_dwordx4 v[90:91], v[86:89], off
	s_nop 1
	v_add_u32_e32 v86, 0x8090, v0
	v_mov_b32_e32 v87, v1
	v_lshlrev_b64 v[90:91], 2, v[86:87]
	s_waitcnt vmcnt(23)
	v_pk_add_f32 v[84:85], v[84:85], v[200:201]
	v_pk_add_f32 v[82:83], v[82:83], v[198:199]
	v_lshl_add_u64 v[86:87], s[8:9], 0, v[90:91]
	v_add_u32_e32 v206, 0x28000, v148
	v_lshlrev_b64 v[198:199], 2, v[206:207]
	v_lshl_add_u64 v[198:199], s[6:7], 0, v[198:199]
	global_load_dwordx4 v[198:201], v[198:199], off
	global_store_dwordx4 v[86:87], v[82:85], off
	s_nop 1
	v_add_u32_e32 v82, 0xc000, v0
	v_mov_b32_e32 v83, v1
	v_lshlrev_b64 v[86:87], 2, v[82:83]
	s_waitcnt vmcnt(24)
	v_pk_add_f32 v[80:81], v[80:81], v[204:205]
	v_pk_add_f32 v[78:79], v[78:79], v[202:203]
	v_lshl_add_u64 v[82:83], s[8:9], 0, v[86:87]
	v_add_u32_e32 v206, 0x28010, v148
	v_lshlrev_b64 v[202:203], 2, v[206:207]
	v_lshl_add_u64 v[202:203], s[6:7], 0, v[202:203]
	global_load_dwordx4 v[202:205], v[202:203], off
	global_store_dwordx4 v[82:83], v[78:81], off
	s_nop 1
	v_add_u32_e32 v78, 0xc010, v0
	v_mov_b32_e32 v79, v1
	v_lshlrev_b64 v[82:83], 2, v[78:79]
	s_waitcnt vmcnt(25)
	v_pk_add_f32 v[76:77], v[76:77], v[152:153]
	v_pk_add_f32 v[74:75], v[74:75], v[150:151]
	v_lshl_add_u64 v[78:79], s[8:9], 0, v[82:83]
	v_add_u32_e32 v206, 0x28080, v148
	v_lshlrev_b64 v[150:151], 2, v[206:207]
	v_lshl_add_u64 v[150:151], s[6:7], 0, v[150:151]
	global_load_dwordx4 v[150:153], v[150:151], off
	global_store_dwordx4 v[78:79], v[74:77], off
	s_nop 1
	v_add_u32_e32 v74, 0xc080, v0
	v_mov_b32_e32 v75, v1
	v_lshlrev_b64 v[78:79], 2, v[74:75]
	s_waitcnt vmcnt(25)
	v_pk_add_f32 v[72:73], v[72:73], v[156:157]
	v_pk_add_f32 v[70:71], v[70:71], v[154:155]
	v_lshl_add_u64 v[74:75], s[8:9], 0, v[78:79]
	v_add_u32_e32 v206, 0x28090, v148
	v_lshlrev_b64 v[154:155], 2, v[206:207]
	v_lshl_add_u64 v[154:155], s[6:7], 0, v[154:155]
	global_load_dwordx4 v[154:157], v[154:155], off
	global_store_dwordx4 v[74:75], v[70:73], off
	s_nop 1
	v_add_u32_e32 v70, 0xc090, v0
	v_mov_b32_e32 v71, v1
	v_lshlrev_b64 v[74:75], 2, v[70:71]
	s_waitcnt vmcnt(25)
	v_pk_add_f32 v[68:69], v[68:69], v[160:161]
	v_pk_add_f32 v[66:67], v[66:67], v[158:159]
	v_lshl_add_u64 v[70:71], s[8:9], 0, v[74:75]
	v_add_u32_e32 v206, 0x2c000, v148
	v_lshlrev_b64 v[158:159], 2, v[206:207]
	v_lshl_add_u64 v[158:159], s[6:7], 0, v[158:159]
	global_load_dwordx4 v[158:161], v[158:159], off
	global_store_dwordx4 v[70:71], v[66:69], off
	s_nop 1
	v_add_u32_e32 v66, 0x20000, v0
	v_mov_b32_e32 v67, v1
	v_lshlrev_b64 v[70:71], 2, v[66:67]
	s_waitcnt vmcnt(25)
	v_pk_add_f32 v[64:65], v[64:65], v[164:165]
	v_pk_add_f32 v[62:63], v[62:63], v[162:163]
	v_lshl_add_u64 v[66:67], s[8:9], 0, v[70:71]
	v_add_u32_e32 v206, 0x2c010, v148
	v_lshlrev_b64 v[162:163], 2, v[206:207]
	v_lshl_add_u64 v[162:163], s[6:7], 0, v[162:163]
	global_load_dwordx4 v[162:165], v[162:163], off
	global_store_dwordx4 v[66:67], v[62:65], off
	s_nop 1
	v_add_u32_e32 v62, 0x20010, v0
	v_mov_b32_e32 v63, v1
	v_lshlrev_b64 v[66:67], 2, v[62:63]
	s_waitcnt vmcnt(25)
	v_pk_add_f32 v[60:61], v[60:61], v[168:169]
	v_pk_add_f32 v[58:59], v[58:59], v[166:167]
	v_lshl_add_u64 v[62:63], s[8:9], 0, v[66:67]
	v_add_u32_e32 v206, 0x2c080, v148
	v_lshlrev_b64 v[166:167], 2, v[206:207]
	v_lshl_add_u64 v[166:167], s[6:7], 0, v[166:167]
	global_load_dwordx4 v[166:169], v[166:167], off
	global_store_dwordx4 v[62:63], v[58:61], off
	s_nop 1
	v_add_u32_e32 v58, 0x20080, v0
	v_mov_b32_e32 v59, v1
	v_lshlrev_b64 v[62:63], 2, v[58:59]
	s_waitcnt vmcnt(25)
	v_pk_add_f32 v[56:57], v[56:57], v[172:173]
	v_pk_add_f32 v[54:55], v[54:55], v[170:171]
	v_lshl_add_u64 v[58:59], s[8:9], 0, v[62:63]
	v_add_u32_e32 v206, 0x2c090, v148
	v_lshlrev_b64 v[170:171], 2, v[206:207]
	v_lshl_add_u64 v[170:171], s[6:7], 0, v[170:171]
	global_load_dwordx4 v[170:173], v[170:171], off
	global_store_dwordx4 v[58:59], v[54:57], off
	s_nop 1
	v_add_u32_e32 v54, 0x20090, v0
	v_mov_b32_e32 v55, v1
	v_lshlrev_b64 v[58:59], 2, v[54:55]
	s_waitcnt vmcnt(25)
	v_pk_add_f32 v[52:53], v[52:53], v[176:177]
	v_pk_add_f32 v[50:51], v[50:51], v[174:175]
	v_lshl_add_u64 v[54:55], s[8:9], 0, v[58:59]
	global_store_dwordx4 v[54:55], v[50:53], off
	s_nop 1
	v_add_u32_e32 v50, 0x24000, v0
	v_mov_b32_e32 v51, v1
	v_lshlrev_b64 v[54:55], 2, v[50:51]
	s_waitcnt vmcnt(24)
	v_pk_add_f32 v[48:49], v[48:49], v[184:185]
	v_pk_add_f32 v[46:47], v[46:47], v[182:183]
	v_lshl_add_u64 v[50:51], s[8:9], 0, v[54:55]
	global_store_dwordx4 v[50:51], v[46:49], off
	s_nop 1
	v_add_u32_e32 v46, 0x24010, v0
	v_mov_b32_e32 v47, v1
	v_lshlrev_b64 v[50:51], 2, v[46:47]
	s_waitcnt vmcnt(23)
	v_pk_add_f32 v[44:45], v[44:45], v[188:189]
	v_pk_add_f32 v[42:43], v[42:43], v[186:187]
	v_lshl_add_u64 v[46:47], s[8:9], 0, v[50:51]
	global_store_dwordx4 v[46:47], v[42:45], off
	s_nop 1
	v_add_u32_e32 v42, 0x24080, v0
	v_mov_b32_e32 v43, v1
	v_lshlrev_b64 v[46:47], 2, v[42:43]
	s_waitcnt vmcnt(22)
	v_pk_add_f32 v[40:41], v[40:41], v[192:193]
	v_pk_add_f32 v[38:39], v[38:39], v[190:191]
	v_lshl_add_u64 v[42:43], s[8:9], 0, v[46:47]
	global_store_dwordx4 v[42:43], v[38:41], off
	s_nop 1
	v_add_u32_e32 v38, 0x24090, v0
	v_mov_b32_e32 v39, v1
	v_lshlrev_b64 v[42:43], 2, v[38:39]
	s_waitcnt vmcnt(21)
	v_pk_add_f32 v[36:37], v[36:37], v[196:197]
	v_pk_add_f32 v[34:35], v[34:35], v[194:195]
	v_lshl_add_u64 v[38:39], s[8:9], 0, v[42:43]
	global_store_dwordx4 v[38:39], v[34:37], off
	s_nop 1
	v_add_u32_e32 v34, 0x28000, v0
	v_mov_b32_e32 v35, v1
	v_lshlrev_b64 v[38:39], 2, v[34:35]
	s_waitcnt vmcnt(20)
	v_pk_add_f32 v[32:33], v[32:33], v[200:201]
	v_pk_add_f32 v[30:31], v[30:31], v[198:199]
	v_lshl_add_u64 v[34:35], s[8:9], 0, v[38:39]
	global_store_dwordx4 v[34:35], v[30:33], off
	s_nop 1
	v_add_u32_e32 v30, 0x28010, v0
	v_mov_b32_e32 v31, v1
	v_lshlrev_b64 v[34:35], 2, v[30:31]
	s_waitcnt vmcnt(19)
	v_pk_add_f32 v[28:29], v[28:29], v[204:205]
	v_pk_add_f32 v[26:27], v[26:27], v[202:203]
	v_lshl_add_u64 v[30:31], s[8:9], 0, v[34:35]
	global_store_dwordx4 v[30:31], v[26:29], off
	s_nop 1
	v_add_u32_e32 v26, 0x28080, v0
	v_mov_b32_e32 v27, v1
	v_lshlrev_b64 v[30:31], 2, v[26:27]
	s_waitcnt vmcnt(18)
	v_pk_add_f32 v[24:25], v[24:25], v[152:153]
	v_pk_add_f32 v[22:23], v[22:23], v[150:151]
	v_lshl_add_u64 v[26:27], s[8:9], 0, v[30:31]
	global_store_dwordx4 v[26:27], v[22:25], off
	s_nop 1
	v_add_u32_e32 v22, 0x28090, v0
	v_mov_b32_e32 v23, v1
	v_lshlrev_b64 v[26:27], 2, v[22:23]
	s_waitcnt vmcnt(17)
	v_pk_add_f32 v[20:21], v[20:21], v[156:157]
	v_pk_add_f32 v[18:19], v[18:19], v[154:155]
	v_lshl_add_u64 v[22:23], s[8:9], 0, v[26:27]
	global_store_dwordx4 v[22:23], v[18:21], off
	s_nop 1
	v_add_u32_e32 v18, 0x2c000, v0
	v_mov_b32_e32 v19, v1
	v_lshlrev_b64 v[22:23], 2, v[18:19]
	s_waitcnt vmcnt(16)
	v_pk_add_f32 v[16:17], v[16:17], v[160:161]
	v_pk_add_f32 v[14:15], v[14:15], v[158:159]
	v_lshl_add_u64 v[18:19], s[8:9], 0, v[22:23]
	global_store_dwordx4 v[18:19], v[14:17], off
	s_nop 1
	v_add_u32_e32 v14, 0x2c010, v0
	v_mov_b32_e32 v15, v1
	v_lshlrev_b64 v[18:19], 2, v[14:15]
	s_waitcnt vmcnt(15)
	v_pk_add_f32 v[12:13], v[12:13], v[164:165]
	v_pk_add_f32 v[10:11], v[10:11], v[162:163]
	v_lshl_add_u64 v[14:15], s[8:9], 0, v[18:19]
	global_store_dwordx4 v[14:15], v[10:13], off
	s_nop 1
	v_add_u32_e32 v10, 0x2c080, v0
	v_mov_b32_e32 v11, v1
	v_lshlrev_b64 v[14:15], 2, v[10:11]
	v_add_u32_e32 v0, 0x2c090, v0
	s_waitcnt vmcnt(14)
	v_pk_add_f32 v[8:9], v[8:9], v[168:169]
	v_pk_add_f32 v[6:7], v[6:7], v[166:167]
	v_lshl_add_u64 v[10:11], s[8:9], 0, v[14:15]
	global_store_dwordx4 v[10:11], v[6:9], off
	v_lshlrev_b64 v[10:11], 2, v[0:1]
	s_nop 0
	s_waitcnt vmcnt(13)
	v_pk_add_f32 v[4:5], v[4:5], v[172:173]
	v_pk_add_f32 v[2:3], v[2:3], v[170:171]
	v_lshl_add_u64 v[6:7], s[8:9], 0, v[10:11]
	global_store_dwordx4 v[6:7], v[2:5], off
	s_cbranch_vccz .LBB0_1438
	s_waitcnt vmcnt(0)
	v_readlane_b32 s76, v255, 8
	s_mov_b32 s92, 0x3b2aaaab
	s_cmp_gt_u32 s3, 3
	v_readlane_b32 s77, v255, 9
	s_mul_i32 s60, s33, 0x1800
	s_mul_hi_i32 s62, s64, 0x300
	s_mul_i32 s75, s33, 0x16c00
	s_mov_b32 s93, 0x3c800000
	s_cbranch_scc1 .LBB0_1445
	s_barrier
